# attention NOMAX variants: K tile LDS-DMA coalesced (8 lanes per 128-B key row) with XOR-swizzled [key][chunk] LDS image, all K fragment reads re-addressed; on top of v17
# speedup vs baseline: 1.0218x; 1.0041x over previous
; __device__ __forceinline__ void qkt(f32x16&p0,f32x16&p1,const char*Kslot,const bf16x8*qr,const f32x16&negm,int r32,int hi){
;   const char*kb=Kslot+hi*1024+r32*16;
;   #pragma unroll
;   for(int d0=0;d0<4;++d0){
;     const bf16x8 b0=*reinterpret_cast<const bf16x8*>(kb+d0*2048);
;     const bf16x8 b1=*reinterpret_cast<const bf16x8*>(kb+d0*2048+512);
;     if(d0==0){p0=__builtin_amdgcn_mfma_f32_32x32x16_bf16(b0,qr[0],negm,0,0,0);p1=__builtin_amdgcn_mfma_f32_32x32x16_bf16(b1,qr[0],negm,0,0,0);}
;     else{p0=__builtin_amdgcn_mfma_f32_32x32x16_bf16(b0,qr[d0],p0,0,0,0);p1=__builtin_amdgcn_mfma_f32_32x32x16_bf16(b1,qr[d0],p1,0,0,0);}}
; }
; template<int THRL,int VM,bool NOMAX> __device__ __forceinline__ void attn_unit(const bf16*Qb,const bf16*__restrict__ Kh,const bf16*__restrict__ Vh,bf16*Ob,const int NT,const int sp,float*wscr,char*shm){
;     ...
;   const bf16*ksrc=Kh+(long)lane*KVP+wid*8;
;   const bf16*vsrc=Vh+(long)(16*(wid&3)+(lane>>2))*KVP+(wid>>2)*32+(lane&3)*8;
;   const unsigned kdst=lds0+LDS_K+wid*1024, vdst=lds0+LDS_V+wid*1024;
;     ...
;   const int vb0=(int)(lds0+LDS_V)+((lane>>4)&1)*32+(lane&3)*8+(4*hi+((lane&15)>>2))*64;
;   const char*Kbase=shm+LDS_K; bf16x8 kf[8];
;   const lds_cptr shm3=(lds_cptr)shm; const lds_cptr kp0=shm3+LDS_K+hi*1024+r32*16; const lds_cptr vp0=shm3+LDS_V+((lane>>4)&1)*32+(lane&3)*8+(4*hi+((lane&15)>>2))*64;
;   if(wid>=4)__builtin_amdgcn_s_setprio(1);
;   DMA_K(0,0);DMA_V(0,0);DMA_K(1,SLOTB);
;   bf16x8 qr[4];
;   #pragma unroll
;   for(int d0=0;d0<4;++d0)qr[d0]=*reinterpret_cast<const bf16x8*>(&Qw[(long)r32*QOP+d0*16+hi*8]);
;   const lds_cptr qpk=shm3+LDS_OST_+wid*4096+lane*16;
;   if constexpr(VM==2){
;     #pragma unroll
;     for(int d0=0;d0<4;++d0)*(__attribute__((address_space(3))) bf16x8*)(const_cast<__attribute__((address_space(3))) char*>(qpk)+d0*1024)=qr[d0]; }
;   float mhat=0.f,l_reg=0.f;f32x16 o[2*VM];
;   #pragma unroll
;   for(int d_=0;d_<2*VM;++d_)o[d_]=f32x16{};
;  f32x16 negm=f32x16{}; if constexpr(VM==1){asm volatile("":"+v"(negm));}
;   bool resc=false;
;     ...
;   f32x16 pA0,pA1,pB0,pB1;
;   int sl_prev=0,sl_cur=0,sl_next=SLOTB;
;     ...
;   DMA_K(2,2*SLOTB);
;   WAIT_BAR(3);
;   qkt(pA0,pA1,Kbase,qr,negm,r32,hi);asm volatile("s_nop 15\n\ts_nop 7":"+v"(pA0),"+v"(pA1));
;   START(pA0,pA1);
;   _Pragma("unroll") for(int r=0;r<16;++r)pA1[r]=__builtin_amdgcn_exp2f(pA1[r]);
;   WAIT_BAR(0);
.LBB0_862:
	s_xor_b64 s[6:7], s[16:17], -1
	s_lshl_b32 s16, s8, 7
	s_add_u32 s35, s83, s16
	s_addc_u32 s88, s84, 0
	s_add_u32 s16, s0, s16
	s_addc_u32 s17, s1, 0
	s_lshl_b32 s86, s85, 5
	v_and_b32_e32 v187, 63, v32
	s_ashr_i32 s87, s86, 31
	s_lshl_b64 s[86:87], s[86:87], 11
	v_mul_u32_u24_e32 v0, 0x500, v187
	s_add_u32 s86, s35, s86
	v_lshlrev_b32_e32 v168, 1, v0
	s_addc_u32 s87, s88, s87
	v_lshl_add_u64 v[0:1], s[16:17], 0, v[168:169]
	s_lshl_b32 s16, s85, 3
	s_ashr_i32 s17, s16, 31
	v_lshl_add_u64 v[54:55], s[16:17], 1, v[0:1]
	v_and_b32_e32 v246, 63, v210
	v_lshrrev_b32_e32 v247, 6, v210
	v_lshrrev_b32_e32 v248, 3, v246
	v_lshl_add_u32 v248, v247, 3, v248
	v_and_b32_e32 v249, 1, v247
	v_lshrrev_b32_e32 v250, 4, v246
	v_lshl_or_b32 v249, v249, 2, v250
	v_and_b32_e32 v250, 7, v246
	v_xor_b32_e32 v250, v250, v249
	v_sub_u32_e32 v248, v248, v246
	v_mul_i32_i24_e32 v248, 0xa00, v248
	v_sub_u32_e32 v250, v250, v247
	v_lshl_add_u32 v248, v250, 4, v248
	v_ashrrev_i32_e32 v249, 31, v248
	v_lshl_add_u64 v[54:55], v[248:249], 0, v[54:55]
	s_mov_b64 s[16:17], 0x200
	v_lshl_add_u64 v[174:175], v[54:55], 0, s[16:17]
	s_lshl_b32 s16, s85, 4
	v_bfe_u32 v0, v32, 2, 4
	v_and_or_b32 v0, s16, 48, v0
	v_mul_u32_u24_e32 v0, 0x500, v0
	s_ashr_i32 s16, s34, 3
	v_lshlrev_b32_e32 v168, 1, v0
	s_andn2_b32 s16, s16, 31
	v_lshlrev_b32_e32 v2, 3, v32
	v_lshl_add_u64 v[0:1], s[0:1], 0, v[168:169]
	s_ashr_i32 s17, s16, 31
	v_and_b32_e32 v190, 24, v2
	v_lshl_add_u64 v[0:1], s[16:17], 1, v[0:1]
	v_lshlrev_b32_e32 v168, 1, v190
	v_lshl_add_u64 v[56:57], v[0:1], 0, v[168:169]
	s_mov_b64 s[16:17], 0x600
	v_lshl_add_u64 v[170:171], v[56:57], 0, s[16:17]
	s_lshl_b32 s17, s85, 10
	s_cmp_lg_u32 0, -1
	s_cselect_b32 s16, 0, 0
	s_add_i32 s35, s17, s16
	s_mov_b32 s88, m0
	s_mov_b32 m0, s35
	s_nop 0
	global_load_lds_dwordx4 v[174:175], off
	s_mov_b32 m0, s88
	s_add_i32 s16, s35, 0x6000
	s_mov_b32 s88, m0
	s_mov_b32 m0, s16
	s_nop 0
	global_load_lds_dwordx4 v[170:171], off
	s_mov_b32 m0, s88
	v_and_b32_e32 v186, 31, v32
	v_lshl_add_u64 v[172:173], v[56:57], 0, s[12:13]
	s_add_i32 s88, s35, 0x8000
	s_mov_b32 s89, m0
	s_mov_b32 m0, s88
	s_nop 0
	global_load_lds_dwordx4 v[172:173], off
	s_mov_b32 m0, s89
	v_lshl_add_u64 v[0:1], v[54:55], 0, s[14:15]
	v_bfe_u32 v185, v32, 5, 1
	s_add_i32 s88, s35, 0x2000
	s_mov_b32 s89, m0
	s_mov_b32 m0, s88
	s_nop 0
	global_load_lds_dwordx4 v[0:1], off
	s_mov_b32 m0, s89
	v_lshlrev_b32_e32 v0, 11, v186
	v_lshl_or_b32 v4, v185, 4, v0
	global_load_dwordx4 v[0:3], v4, s[86:87] offset:1024
	global_load_dwordx4 v[34:37], v4, s[86:87] offset:1056
	global_load_dwordx4 v[38:41], v4, s[86:87] offset:1088
	global_load_dwordx4 v[42:45], v4, s[86:87] offset:1120
	s_lshl_b32 s85, s85, 12
	s_add_i32 s85, s85, 0
	v_lshlrev_b32_e32 v6, 4, v187
	s_add_i32 s85, s85, 0x12800
	v_add_u32_e32 v188, s85, v6
	v_lshlrev_b32_e32 v4, 10, v185
	v_lshlrev_b32_e32 v5, 4, v186
	v_add3_u32 v189, 0, v4, v5
	v_bfe_u32 v246, v189, 4, 5
	v_bfe_u32 v247, v189, 10, 1
	v_bfe_u32 v248, v189, 5, 1
	v_bfe_u32 v249, v189, 6, 2
	v_xor_b32_e32 v247, v247, v248
	v_lshlrev_b32_e32 v246, 7, v246
	v_lshl_or_b32 v246, v247, 4, v246
	v_lshl_add_u32 v234, v249, 5, v246
	v_xor_b32_e32 v248, 1, v249
	v_lshl_add_u32 v235, v248, 5, v246
	v_xor_b32_e32 v248, 2, v249
	v_lshl_add_u32 v236, v248, 5, v246
	v_xor_b32_e32 v248, 3, v249
	v_lshl_add_u32 v237, v248, 5, v246
	v_lshl_add_u64 v[4:5], v[54:55], 0, s[36:37]
	s_add_i32 s86, s35, 0x4000
	v_lshlrev_b32_e32 v33, 1, v32
	v_lshlrev_b32_e32 v32, 4, v32
	v_and_b32_e32 v191, 32, v33
	v_and_b32_e32 v32, 0xc0, v32
	v_lshl_or_b32 v192, v185, 8, v32
	v_add_u32_e32 v32, 0, v191
	v_add3_u32 v168, v32, v190, v192
	v_lshl_add_u64 v[32:33], v[54:55], 0, s[40:41]
	s_add_i32 s88, s35, 0xa000
	s_add_i32 s90, s35, 0xc000
	v_mov_b32_e32 v193, 0
	s_mov_b32 s89, 0
	s_movk_i32 s87, 0x2000
	v_lshl_add_u64 v[176:177], v[56:57], 0, s[48:49]
	v_lshl_add_u64 v[178:179], v[56:57], 0, s[50:51]
	v_lshl_add_u64 v[180:181], v[54:55], 0, s[52:53]
	v_mov_b32_e32 v54, v193
	v_mov_b32_e32 v55, v193
	v_mov_b32_e32 v58, v193
	v_mov_b32_e32 v59, v193
	v_mov_b32_e32 v60, v193
	v_mov_b32_e32 v61, v193
	v_mov_b32_e32 v62, v193
	v_mov_b32_e32 v63, v193
	s_waitcnt vmcnt(3)
	ds_write_b128 v188, v[0:3]
	s_waitcnt vmcnt(2)
	ds_write_b128 v188, v[34:37] offset:1024
	s_waitcnt vmcnt(1)
	ds_write_b128 v188, v[38:41] offset:2048
	s_waitcnt vmcnt(0)
	ds_write_b128 v188, v[42:45] offset:3072
	s_mov_b32 s85, m0
	s_mov_b32 m0, s86
	s_nop 0
	global_load_lds_dwordx4 v[4:5], off
	s_mov_b32 m0, s85
	s_waitcnt vmcnt(3) lgkmcnt(0)
	s_barrier
	ds_read_b128 v[4:7], v234
	ds_read_b128 v[8:11], v234 offset:4096
	s_waitcnt lgkmcnt(1)
	v_mfma_f32_32x32x16_bf16 v[16:31], v[4:7], v[0:3], 0
	ds_read_b128 v[46:49], v235
	ds_read_b128 v[50:53], v235 offset:4096
	s_mov_b32 s85, -1
	s_movk_i32 s86, 0x4000
	s_waitcnt lgkmcnt(2)
	v_mfma_f32_32x32x16_bf16 v[0:15], v[8:11], v[0:3], 0
	s_waitcnt lgkmcnt(1)
	v_mfma_f32_32x32x16_bf16 v[16:31], v[46:49], v[34:37], v[16:31]
	s_waitcnt lgkmcnt(0)
	v_mfma_f32_32x32x16_bf16 v[0:15], v[50:53], v[34:37], v[0:15]
	ds_read_b128 v[34:37], v236
	ds_read_b128 v[46:49], v236 offset:4096
	s_waitcnt lgkmcnt(1)
	v_mfma_f32_32x32x16_bf16 v[16:31], v[34:37], v[38:41], v[16:31]
	ds_read_b128 v[34:37], v237 offset:4096
	ds_read_b128 v[50:53], v237
	s_waitcnt lgkmcnt(2)
	v_mfma_f32_32x32x16_bf16 v[0:15], v[46:49], v[38:41], v[0:15]
	v_lshl_add_u64 v[38:39], v[56:57], 0, s[42:43]
	v_lshl_add_u64 v[40:41], v[56:57], 0, s[44:45]
	v_mov_b32_e32 v48, 0
	v_mov_b32_e32 v49, v193
	v_mov_b32_e32 v56, v193
	v_mov_b32_e32 v57, v193
	v_mov_b32_e32 v46, v193
	s_waitcnt lgkmcnt(0)
	v_mfma_f32_32x32x16_bf16 v[16:31], v[50:53], v[42:45], v[16:31]
	v_mov_b32_e32 v50, v193
	v_mov_b32_e32 v51, v193
	v_mov_b32_e32 v52, v193
	v_mov_b32_e32 v53, v193
	v_mov_b32_e32 v47, v193
	v_mfma_f32_32x32x16_bf16 v[0:15], v[34:37], v[42:45], v[0:15]
	s_nop 15
	s_nop 7
	s_waitcnt vmcnt(0) lgkmcnt(0)
	s_barrier
; #define WAIT_BAR(N) asm volatile("s_waitcnt vmcnt(" #N ") lgkmcnt(0)\n\ts_barrier":::"memory")
;   #define DMA_K(t,slot) glds16(ksrc+(long)(t)*KVBLK*KVP,(unsigned)__builtin_amdgcn_readfirstlane(kdst+(slot)))
;   #define DMA_V(t,slot) do{ glds16(vsrc+(long)(t)*KVBLK*KVP,(unsigned)__builtin_amdgcn_readfirstlane(vdst+VM*(slot))); if constexpr(VM==2) glds16(vsrc+64+(long)(t)*KVBLK*KVP,(unsigned)__builtin_amdgcn_readfirstlane(vdst+VM*(slot)+8192)); }while(0)
;   #define ROT() do{sl_prev=sl_cur;sl_cur=sl_next;sl_next=(sl_next==(NSLOT-1)*SLOTB)?0:sl_next+SLOTB;}while(0)
; template<int THRL,int VM,bool NOMAX> __device__ __forceinline__ void attn_unit(const bf16*Qb,const bf16*__restrict__ Kh,const bf16*__restrict__ Vh,bf16*Ob,const int NT,const int sp,float*wscr,char*shm){
;     ...
;   START(pA0,pA1);
;   _Pragma("unroll") for(int r=0;r<16;++r)pA1[r]=__builtin_amdgcn_exp2f(pA1[r]);
;   WAIT_BAR(0);
;   DMA_K(3,0);DMA_V(1,SLOTB);
;   ROT();
;   kload8(kf,kp0+sl_cur);
;   if constexpr(VM==2){WAIT_BAR(3);}else{WAIT_BAR(2);}
;   s16x4 vlo[8],vhi[8]; u32x4 pw0,pw1,pw2,pw3;
	s_mov_b32 s91, m0
	s_mov_b32 m0, s35
	s_nop 0
	global_load_lds_dwordx4 v[32:33], off
	s_mov_b32 m0, s91
	v_mov_b32_e32 v32, 0
	s_mov_b32 s91, m0
	s_mov_b32 m0, s88
	s_nop 0
	global_load_lds_dwordx4 v[38:39], off
	s_mov_b32 m0, s91
	s_mov_b32 s88, m0
	s_mov_b32 m0, s90
	s_nop 0
	global_load_lds_dwordx4 v[40:41], off
	s_mov_b32 m0, s88
	ds_read_b128 v[100:103], v234 offset:8192
	ds_read_b128 v[96:99], v234 offset:12288
	ds_read_b128 v[164:167], v235 offset:8192
	ds_read_b128 v[160:163], v235 offset:12288
	ds_read_b128 v[140:143], v236 offset:8192
	ds_read_b128 v[136:139], v236 offset:12288
	ds_read_b128 v[132:135], v237 offset:8192
	ds_read_b128 v[128:131], v237 offset:12288
	v_exp_f32_e32 v80, v16
	v_exp_f32_e32 v81, v17
	v_exp_f32_e32 v82, v18
	v_exp_f32_e32 v83, v19
	v_exp_f32_e32 v84, v20
	v_exp_f32_e32 v85, v21
	v_exp_f32_e32 v86, v22
	v_exp_f32_e32 v87, v23
	v_exp_f32_e32 v88, v24
	v_exp_f32_e32 v89, v25
	v_exp_f32_e32 v90, v26
	v_exp_f32_e32 v91, v27
	v_exp_f32_e32 v92, v28
	v_exp_f32_e32 v93, v29
	v_exp_f32_e32 v94, v30
	v_exp_f32_e32 v95, v31
	v_exp_f32_e32 v64, v0
	v_exp_f32_e32 v65, v1
	v_exp_f32_e32 v66, v2
	v_exp_f32_e32 v67, v3
	v_exp_f32_e32 v68, v4
	v_exp_f32_e32 v69, v5
	v_exp_f32_e32 v70, v6
	v_exp_f32_e32 v71, v7
	v_exp_f32_e32 v72, v8
	v_exp_f32_e32 v73, v9
	v_exp_f32_e32 v74, v10
	v_exp_f32_e32 v75, v11
	v_exp_f32_e32 v76, v12
	v_exp_f32_e32 v77, v13
	v_exp_f32_e32 v78, v14
	v_exp_f32_e32 v79, v15
	ds_read_b128 v[218:221], v188
	ds_read_b128 v[222:225], v188 offset:1024
	ds_read_b128 v[226:229], v188 offset:2048
	ds_read_b128 v[230:233], v188 offset:3072
	s_waitcnt vmcnt(3) lgkmcnt(0)
	s_barrier
	v_mov_b32_e32 v33, v193
	v_mov_b32_e32 v34, v193
	v_mov_b32_e32 v35, v193
	v_mov_b32_e32 v36, v193
	v_mov_b32_e32 v37, v193
	v_mov_b32_e32 v38, v193
	v_mov_b32_e32 v39, v193
	v_mov_b32_e32 v40, v193
	v_mov_b32_e32 v41, v193
	v_mov_b32_e32 v42, v193
	v_mov_b32_e32 v43, v193
	v_mov_b32_e32 v44, v193
	v_mov_b32_e32 v45, v193
	v_mov_b32_e32 v16, 0
	v_mov_b32_e32 v17, v193
	v_mov_b32_e32 v18, v193
	v_mov_b32_e32 v19, v193
	v_mov_b32_e32 v20, v193
	v_mov_b32_e32 v21, v193
	v_mov_b32_e32 v22, v193
	v_mov_b32_e32 v23, v193
	v_mov_b32_e32 v24, v193
	v_mov_b32_e32 v25, v193
	v_mov_b32_e32 v26, v193
	v_mov_b32_e32 v27, v193
	v_mov_b32_e32 v28, v193
	v_mov_b32_e32 v29, v193
	v_mov_b32_e32 v30, v193
	v_mov_b32_e32 v31, v193
	v_mov_b32_e32 v0, 0
	v_mov_b32_e32 v1, v193
	v_mov_b32_e32 v2, v193
	v_mov_b32_e32 v3, v193
	v_mov_b32_e32 v4, v193
	v_mov_b32_e32 v5, v193
	v_mov_b32_e32 v6, v193
	v_mov_b32_e32 v7, v193
	v_mov_b32_e32 v8, v193
	v_mov_b32_e32 v9, v193
	v_mov_b32_e32 v10, v193
	v_mov_b32_e32 v11, v193
	v_mov_b32_e32 v12, v193
	v_mov_b32_e32 v13, v193
	v_mov_b32_e32 v14, v193
	v_mov_b32_e32 v15, v193
.LBB0_863:
	v_mfma_f32_32x32x16_bf16 v[112:127], v[100:103], v[218:221], 0
	v_lshl_add_u32 v206, s89, 1, v168
	ds_read_b64_tr_b16 v[194:195], v206 offset:24576
	ds_read_b64_tr_b16 v[196:197], v206 offset:25088
	v_add_f32_e32 v108, v80, v81
	v_add_f32_e32 v108, v82, v108
	v_add_f32_e32 v108, v83, v108
	v_add_f32_e32 v108, v84, v108
	v_add_f32_e32 v108, v85, v108
	v_cvt_pk_bf16_f32 v156, v80, v81
	v_cvt_pk_bf16_f32 v157, v82, v83
	ds_read_b64_tr_b16 v[80:81], v206 offset:28672
	ds_read_b64_tr_b16 v[82:83], v206 offset:29184
	v_add_f32_e32 v104, v86, v108
	v_add_f32_e32 v104, v87, v104
	v_add_f32_e32 v104, v88, v104
	v_add_f32_e32 v144, v89, v104
	v_mfma_f32_32x32x16_bf16 v[96:111], v[96:99], v[218:221], 0
	v_cvt_pk_bf16_f32 v158, v84, v85
	v_cvt_pk_bf16_f32 v159, v86, v87
	ds_read_b64_tr_b16 v[84:85], v206 offset:25600
	ds_read_b64_tr_b16 v[86:87], v206 offset:26112
	v_add_f32_e32 v144, v90, v144
	v_add_f32_e32 v144, v91, v144
	v_add_f32_e32 v144, v92, v144
	v_add_f32_e32 v144, v93, v144
	v_cvt_pk_bf16_f32 v152, v88, v89
	v_cvt_pk_bf16_f32 v153, v90, v91
	v_mfma_f32_32x32x16_bf16 v[112:127], v[164:167], v[222:225], v[112:127]
	ds_read_b64_tr_b16 v[88:89], v206 offset:29696
	ds_read_b64_tr_b16 v[90:91], v206 offset:30208
	v_add_f32_e32 v144, v94, v144
	v_add_f32_e32 v144, v95, v144
	v_add_f32_e32 v144, v64, v144
	v_add_f32_e32 v144, v65, v144
	v_mfma_f32_32x32x16_bf16 v[96:111], v[160:163], v[222:225], v[96:111]
	v_cvt_pk_bf16_f32 v154, v92, v93
	v_cvt_pk_bf16_f32 v155, v94, v95
	ds_read_b64_tr_b16 v[92:93], v206 offset:26624
	ds_read_b64_tr_b16 v[94:95], v206 offset:27136
	v_add_f32_e32 v144, v66, v144
	v_add_f32_e32 v144, v67, v144
	v_add_f32_e32 v144, v68, v144
	v_add_f32_e32 v144, v69, v144
	v_cvt_pk_bf16_f32 v148, v64, v65
	v_cvt_pk_bf16_f32 v149, v66, v67
	v_mfma_f32_32x32x16_bf16 v[112:127], v[140:143], v[226:229], v[112:127]
	ds_read_b64_tr_b16 v[198:199], v206 offset:30720
	ds_read_b64_tr_b16 v[200:201], v206 offset:31232
	v_add_f32_e32 v140, v70, v144
	v_add_f32_e32 v140, v71, v140
	v_add_f32_e32 v140, v72, v140
	v_add_f32_e32 v140, v73, v140
	v_mfma_f32_32x32x16_bf16 v[96:111], v[136:139], v[226:229], v[96:111]
	v_cvt_pk_bf16_f32 v150, v68, v69
	v_cvt_pk_bf16_f32 v151, v70, v71
	ds_read_b64_tr_b16 v[202:203], v206 offset:27648
	ds_read_b64_tr_b16 v[204:205], v206 offset:28160
	v_add_f32_e32 v68, v74, v140
	v_add_f32_e32 v68, v75, v68
	v_add_f32_e32 v68, v76, v68
	v_add_f32_e32 v68, v77, v68
	v_cvt_pk_bf16_f32 v144, v72, v73
	v_cvt_pk_bf16_f32 v145, v74, v75
	v_mfma_f32_32x32x16_bf16 v[112:127], v[132:135], v[230:233], v[112:127]
	ds_read_b64_tr_b16 v[72:73], v206 offset:31744
	ds_read_b64_tr_b16 v[74:75], v206 offset:32256
	v_add_f32_e32 v68, v78, v68
	v_add_f32_e32 v68, v79, v68
	v_add_f32_e32 v68, 0, v68
	v_cvt_pk_bf16_f32 v146, v76, v77
	v_mfma_f32_32x32x16_bf16 v[96:111], v[128:131], v[230:233], v[96:111]
	v_cvt_pk_bf16_f32 v147, v78, v79
	s_add_i32 s88, s87, s35
	v_lshl_add_u64 v[64:65], v[180:181], 0, s[54:55]
	s_mov_b32 s89, m0
	s_mov_b32 m0, s88
	s_nop 0
	global_load_lds_dwordx4 v[64:65], off
	s_mov_b32 m0, s89
	s_lshl_b32 s88, s86, 1
	v_lshl_add_u64 v[64:65], v[178:179], 0, s[54:55]
	s_add_i32 s88, s88, s16
	s_mov_b32 s89, m0
	s_mov_b32 m0, s88
	s_nop 0
	global_load_lds_dwordx4 v[64:65], off
	s_mov_b32 m0, s89
	v_lshl_add_u64 v[64:65], v[176:177], 0, s[54:55]
	s_addk_i32 s88, 0x2000
	s_mov_b32 s89, m0
	s_mov_b32 m0, s88
	s_nop 0
	global_load_lds_dwordx4 v[64:65], off
	s_mov_b32 m0, s89
	v_add_f32_e32 v193, v193, v68
	s_waitcnt lgkmcnt(12)
	v_mfma_f32_32x32x16_bf16 v[48:63], v[156:159], v[194:197], v[48:63]
	ds_read_b64_tr_b16 v[76:77], v206 offset:32768
	ds_read_b64_tr_b16 v[78:79], v206 offset:33280
	v_exp_f32_e32 v112, v112
	v_exp_f32_e32 v113, v113
	v_mfma_f32_32x32x16_bf16 v[32:47], v[156:159], v[80:83], v[32:47]
	ds_read_b64_tr_b16 v[194:195], v206 offset:36864
	ds_read_b64_tr_b16 v[196:197], v206 offset:37376
	v_exp_f32_e32 v114, v114
	v_exp_f32_e32 v115, v115
	v_add_u32_e32 v242, s86, v234
	v_add_u32_e32 v243, s86, v235
	v_add_u32_e32 v244, s86, v236
	v_add_u32_e32 v245, s86, v237
	ds_read_b128 v[68:71], v242
	ds_read_b128 v[64:67], v242 offset:4096
	s_waitcnt lgkmcnt(14)
	v_mfma_f32_32x32x16_bf16 v[48:63], v[152:155], v[84:87], v[48:63]
	ds_read_b64_tr_b16 v[80:81], v206 offset:33792
	ds_read_b64_tr_b16 v[82:83], v206 offset:34304
	v_exp_f32_e32 v116, v116
	v_exp_f32_e32 v117, v117
	ds_read_b128 v[164:167], v243
	ds_read_b128 v[140:143], v243 offset:4096
	v_mfma_f32_32x32x16_bf16 v[32:47], v[152:155], v[88:91], v[32:47]
	ds_read_b64_tr_b16 v[84:85], v206 offset:37888
	ds_read_b64_tr_b16 v[86:87], v206 offset:38400
	v_exp_f32_e32 v118, v118
	v_exp_f32_e32 v119, v119
	ds_read_b128 v[160:163], v244
	ds_read_b128 v[132:135], v244 offset:4096
	s_waitcnt lgkmcnt(14)
	v_mfma_f32_32x32x16_bf16 v[48:63], v[148:151], v[92:95], v[48:63]
	ds_read_b64_tr_b16 v[88:89], v206 offset:34816
	ds_read_b64_tr_b16 v[90:91], v206 offset:35328
	v_exp_f32_e32 v120, v120
	v_exp_f32_e32 v121, v121
	ds_read_b128 v[136:139], v245
	ds_read_b128 v[128:131], v245 offset:4096
	v_mfma_f32_32x32x16_bf16 v[32:47], v[148:151], v[198:201], v[32:47]
	ds_read_b64_tr_b16 v[92:93], v206 offset:38912
	ds_read_b64_tr_b16 v[94:95], v206 offset:39424
	v_exp_f32_e32 v122, v122
	v_exp_f32_e32 v123, v123
	s_waitcnt lgkmcnt(14)
	v_mfma_f32_32x32x16_bf16 v[48:63], v[144:147], v[202:205], v[48:63]
	ds_read_b64_tr_b16 v[198:199], v206 offset:35840
	ds_read_b64_tr_b16 v[200:201], v206 offset:36352
	v_exp_f32_e32 v124, v124
	v_exp_f32_e32 v125, v125
	v_mfma_f32_32x32x16_bf16 v[32:47], v[144:147], v[72:75], v[32:47]
	ds_read_b64_tr_b16 v[202:203], v206 offset:39936
	ds_read_b64_tr_b16 v[204:205], v206 offset:40448
	v_exp_f32_e32 v126, v126
	v_exp_f32_e32 v127, v127
	s_waitcnt lgkmcnt(14)
	v_mfma_f32_32x32x16_bf16 v[16:31], v[156:159], v[76:79], v[16:31]
	v_exp_f32_e32 v96, v96
	v_exp_f32_e32 v97, v97
	v_mfma_f32_32x32x16_bf16 v[0:15], v[156:159], v[194:197], v[0:15]
	v_exp_f32_e32 v98, v98
	v_exp_f32_e32 v99, v99
	v_mfma_f32_32x32x16_bf16 v[16:31], v[152:155], v[80:83], v[16:31]
	v_exp_f32_e32 v100, v100
	v_exp_f32_e32 v101, v101
	s_waitcnt lgkmcnt(12)
	v_mfma_f32_32x32x16_bf16 v[0:15], v[152:155], v[84:87], v[0:15]
	v_exp_f32_e32 v102, v102
	v_exp_f32_e32 v103, v103
	s_waitcnt lgkmcnt(8)
	v_mfma_f32_32x32x16_bf16 v[16:31], v[148:151], v[88:91], v[16:31]
	v_exp_f32_e32 v104, v104
	v_exp_f32_e32 v105, v105
	s_waitcnt lgkmcnt(4)
	v_mfma_f32_32x32x16_bf16 v[0:15], v[148:151], v[92:95], v[0:15]
	v_exp_f32_e32 v106, v106
	v_exp_f32_e32 v107, v107
	s_waitcnt lgkmcnt(2)
	v_mfma_f32_32x32x16_bf16 v[16:31], v[144:147], v[198:201], v[16:31]
	v_exp_f32_e32 v108, v108
	v_exp_f32_e32 v109, v109
	s_waitcnt lgkmcnt(0)
	v_mfma_f32_32x32x16_bf16 v[0:15], v[144:147], v[202:205], v[0:15]
	v_exp_f32_e32 v110, v110
	v_exp_f32_e32 v111, v111
	s_waitcnt vmcnt(3) lgkmcnt(0)
	s_barrier
	v_mfma_f32_32x32x16_bf16 v[80:95], v[68:71], v[218:221], 0
	s_add_i32 s88, s86, 0x2000
	s_cmpk_lg_i32 s86, 0x4000
	s_cselect_b32 s88, s88, 0
	v_lshl_add_u32 v206, s87, 1, v168
	ds_read_b64_tr_b16 v[194:195], v206 offset:24576
	ds_read_b64_tr_b16 v[196:197], v206 offset:25088
	v_add_f32_e32 v76, v112, v113
	v_add_f32_e32 v76, v114, v76
	v_add_f32_e32 v76, v115, v76
	v_add_f32_e32 v76, v116, v76
	v_add_f32_e32 v76, v117, v76
	v_cvt_pk_bf16_f32 v156, v112, v113
	v_cvt_pk_bf16_f32 v157, v114, v115
	ds_read_b64_tr_b16 v[112:113], v206 offset:28672
	ds_read_b64_tr_b16 v[114:115], v206 offset:29184
	v_add_f32_e32 v72, v118, v76
	v_add_f32_e32 v72, v119, v72
	v_add_f32_e32 v72, v120, v72
	v_add_f32_e32 v144, v121, v72
	v_mfma_f32_32x32x16_bf16 v[64:79], v[64:67], v[218:221], 0
	v_cvt_pk_bf16_f32 v158, v116, v117
	v_cvt_pk_bf16_f32 v159, v118, v119
	ds_read_b64_tr_b16 v[116:117], v206 offset:25600
	ds_read_b64_tr_b16 v[118:119], v206 offset:26112
	v_add_f32_e32 v144, v122, v144
	v_add_f32_e32 v144, v123, v144
	v_add_f32_e32 v144, v124, v144
	v_add_f32_e32 v144, v125, v144
	v_mfma_f32_32x32x16_bf16 v[80:95], v[164:167], v[222:225], v[80:95]
	v_cvt_pk_bf16_f32 v152, v120, v121
	v_cvt_pk_bf16_f32 v153, v122, v123
	ds_read_b64_tr_b16 v[120:121], v206 offset:29696
	ds_read_b64_tr_b16 v[122:123], v206 offset:30208
	v_add_f32_e32 v144, v126, v144
	v_add_f32_e32 v144, v127, v144
	v_add_f32_e32 v144, v96, v144
	v_add_f32_e32 v144, v97, v144
	v_mfma_f32_32x32x16_bf16 v[64:79], v[140:143], v[222:225], v[64:79]
	v_cvt_pk_bf16_f32 v154, v124, v125
	v_cvt_pk_bf16_f32 v155, v126, v127
	ds_read_b64_tr_b16 v[124:125], v206 offset:26624
	ds_read_b64_tr_b16 v[126:127], v206 offset:27136
	v_add_f32_e32 v144, v98, v144
	v_add_f32_e32 v144, v99, v144
	v_add_f32_e32 v144, v100, v144
	v_add_f32_e32 v144, v101, v144
	v_mfma_f32_32x32x16_bf16 v[80:95], v[160:163], v[226:229], v[80:95]
	v_cvt_pk_bf16_f32 v148, v96, v97
	v_cvt_pk_bf16_f32 v149, v98, v99
	ds_read_b64_tr_b16 v[198:199], v206 offset:30720
	ds_read_b64_tr_b16 v[200:201], v206 offset:31232
	v_add_f32_e32 v140, v102, v144
	v_add_f32_e32 v140, v103, v140
	v_add_f32_e32 v140, v104, v140
	v_add_f32_e32 v140, v105, v140
	v_mfma_f32_32x32x16_bf16 v[64:79], v[132:135], v[226:229], v[64:79]
	v_cvt_pk_bf16_f32 v150, v100, v101
	v_cvt_pk_bf16_f32 v151, v102, v103
	ds_read_b64_tr_b16 v[202:203], v206 offset:27648
	ds_read_b64_tr_b16 v[204:205], v206 offset:28160
	v_add_f32_e32 v100, v106, v140
	v_add_f32_e32 v100, v107, v100
	v_add_f32_e32 v100, v108, v100
	v_add_f32_e32 v100, v109, v100
	v_mfma_f32_32x32x16_bf16 v[80:95], v[136:139], v[230:233], v[80:95]
	v_cvt_pk_bf16_f32 v144, v104, v105
	v_cvt_pk_bf16_f32 v145, v106, v107
	ds_read_b64_tr_b16 v[104:105], v206 offset:31744
	ds_read_b64_tr_b16 v[106:107], v206 offset:32256
	v_add_f32_e32 v100, v110, v100
	v_add_f32_e32 v100, v111, v100
	v_add_f32_e32 v100, 0, v100
	v_cvt_pk_bf16_f32 v146, v108, v109
	v_mfma_f32_32x32x16_bf16 v[64:79], v[128:131], v[230:233], v[64:79]
	v_cvt_pk_bf16_f32 v147, v110, v111
	s_add_i32 s87, s86, s35
	s_mov_b32 s89, m0
	s_mov_b32 m0, s87
	s_nop 0
	global_load_lds_dwordx4 v[180:181], off
	s_mov_b32 m0, s89
	s_lshl_b32 s87, s88, 1
	s_add_i32 s87, s87, s16
	s_mov_b32 s89, m0
	s_mov_b32 m0, s87
	s_nop 0
	global_load_lds_dwordx4 v[178:179], off
	s_mov_b32 m0, s89
	s_addk_i32 s87, 0x2000
	s_mov_b32 s89, m0
	s_mov_b32 m0, s87
	s_nop 0
	global_load_lds_dwordx4 v[176:177], off
	s_mov_b32 m0, s89
	v_add_f32_e32 v193, v193, v100
	s_waitcnt lgkmcnt(12)
; #define WAIT_BAR(N) asm volatile("s_waitcnt vmcnt(" #N ") lgkmcnt(0)\n\ts_barrier":::"memory")
;   #define RESC() do{ if(!NOMAX&&resc){ asm volatile("s_waitcnt lgkmcnt(0)":::"memory"); \
;       _Pragma("unroll") for(int d_=0;d_<2*VM;++d_) _Pragma("unroll") for(int r=0;r<16;++r)o[d_][r]*=wsf[crow(r,hi)]; } }while(0)
;   #define ROT() do{sl_prev=sl_cur;sl_cur=sl_next;sl_next=(sl_next==(NSLOT-1)*SLOTB)?0:sl_next+SLOTB;}while(0)
;   #define ENDW(tt) do{ if((tt)+3<NT){ if constexpr(VM==2){WAIT_BAR(3);}else{WAIT_BAR(2);} } else if((tt)+2<NT){ if constexpr(VM==2){WAIT_BAR(2);}else{WAIT_BAR(1);} } else {WAIT_BAR(0);} }while(0)
; template<int THRL,int VM,bool NOMAX> __device__ __forceinline__ void attn_unit(const bf16*Qb,const bf16*__restrict__ Kh,const bf16*__restrict__ Vh,bf16*Ob,const int NT,const int sp,float*wscr,char*shm){
;     ...
;   int t=1;
;   for(;t+5<NT;t+=2){
;     STEP(pB0,pB1,pA0,pA1,t,true,true,true);     if constexpr(VM==2){WAIT_BAR(3);}else{WAIT_BAR(2);} RESC(); ROT();
;     STEP(pA0,pA1,pB0,pB1,t+1,true,true,true);   if constexpr(VM==2){WAIT_BAR(3);}else{WAIT_BAR(2);} RESC(); ROT();
;   }
;     ...
;   for(;t+1<NT;t+=2){
;     STEP(pB0,pB1,pA0,pA1,t,(t+3<NT),(t+1<NT),(t+1<NT));       ENDW(t);   RESC(); ROT();
;     STEP(pA0,pA1,pB0,pB1,t+1,(t+4<NT),(t+2<NT),(t+2<NT));     ENDW(t+1); RESC(); ROT();
	v_mfma_f32_32x32x16_bf16 v[48:63], v[156:159], v[194:197], v[48:63]
	ds_read_b64_tr_b16 v[108:109], v206 offset:32768
	ds_read_b64_tr_b16 v[110:111], v206 offset:33280
	v_exp_f32_e32 v80, v80
	v_exp_f32_e32 v81, v81
	v_mfma_f32_32x32x16_bf16 v[32:47], v[156:159], v[112:115], v[32:47]
	ds_read_b64_tr_b16 v[194:195], v206 offset:36864
	ds_read_b64_tr_b16 v[196:197], v206 offset:37376
	v_exp_f32_e32 v82, v82
	v_exp_f32_e32 v83, v83
	v_add_u32_e32 v242, s88, v234
	v_add_u32_e32 v243, s88, v235
	v_add_u32_e32 v244, s88, v236
	v_add_u32_e32 v245, s88, v237
	ds_read_b128 v[100:103], v242
	ds_read_b128 v[96:99], v242 offset:4096
	s_waitcnt lgkmcnt(14)
	v_mfma_f32_32x32x16_bf16 v[48:63], v[152:155], v[116:119], v[48:63]
	ds_read_b64_tr_b16 v[112:113], v206 offset:33792
	ds_read_b64_tr_b16 v[114:115], v206 offset:34304
	v_exp_f32_e32 v84, v84
	v_exp_f32_e32 v85, v85
	ds_read_b128 v[164:167], v243
	ds_read_b128 v[160:163], v243 offset:4096
	v_mfma_f32_32x32x16_bf16 v[32:47], v[152:155], v[120:123], v[32:47]
	ds_read_b64_tr_b16 v[116:117], v206 offset:37888
	ds_read_b64_tr_b16 v[118:119], v206 offset:38400
	v_exp_f32_e32 v86, v86
	v_exp_f32_e32 v87, v87
	ds_read_b128 v[140:143], v244
	ds_read_b128 v[136:139], v244 offset:4096
	s_waitcnt lgkmcnt(14)
	v_mfma_f32_32x32x16_bf16 v[48:63], v[148:151], v[124:127], v[48:63]
	ds_read_b64_tr_b16 v[120:121], v206 offset:34816
	ds_read_b64_tr_b16 v[122:123], v206 offset:35328
	v_exp_f32_e32 v88, v88
	v_exp_f32_e32 v89, v89
	ds_read_b128 v[132:135], v245
	ds_read_b128 v[128:131], v245 offset:4096
	v_mfma_f32_32x32x16_bf16 v[32:47], v[148:151], v[198:201], v[32:47]
	ds_read_b64_tr_b16 v[124:125], v206 offset:38912
	ds_read_b64_tr_b16 v[126:127], v206 offset:39424
	v_exp_f32_e32 v90, v90
	v_exp_f32_e32 v91, v91
	s_waitcnt lgkmcnt(14)
	v_mfma_f32_32x32x16_bf16 v[48:63], v[144:147], v[202:205], v[48:63]
	ds_read_b64_tr_b16 v[198:199], v206 offset:35840
	ds_read_b64_tr_b16 v[200:201], v206 offset:36352
	v_exp_f32_e32 v92, v92
	v_exp_f32_e32 v93, v93
	v_mfma_f32_32x32x16_bf16 v[32:47], v[144:147], v[104:107], v[32:47]
	ds_read_b64_tr_b16 v[202:203], v206 offset:39936
	ds_read_b64_tr_b16 v[204:205], v206 offset:40448
	v_exp_f32_e32 v94, v94
	v_exp_f32_e32 v95, v95
	s_waitcnt lgkmcnt(14)
	v_mfma_f32_32x32x16_bf16 v[16:31], v[156:159], v[108:111], v[16:31]
	v_exp_f32_e32 v64, v64
	v_exp_f32_e32 v65, v65
	v_mfma_f32_32x32x16_bf16 v[0:15], v[156:159], v[194:197], v[0:15]
	v_exp_f32_e32 v66, v66
	v_exp_f32_e32 v67, v67
	v_mfma_f32_32x32x16_bf16 v[16:31], v[152:155], v[112:115], v[16:31]
	v_exp_f32_e32 v68, v68
	v_exp_f32_e32 v69, v69
	s_waitcnt lgkmcnt(12)
	v_mfma_f32_32x32x16_bf16 v[0:15], v[152:155], v[116:119], v[0:15]
	v_exp_f32_e32 v70, v70
	v_exp_f32_e32 v71, v71
	s_waitcnt lgkmcnt(8)
	v_mfma_f32_32x32x16_bf16 v[16:31], v[148:151], v[120:123], v[16:31]
	v_exp_f32_e32 v72, v72
	v_exp_f32_e32 v73, v73
	s_waitcnt lgkmcnt(4)
	v_mfma_f32_32x32x16_bf16 v[0:15], v[148:151], v[124:127], v[0:15]
	v_exp_f32_e32 v74, v74
	v_exp_f32_e32 v75, v75
	s_waitcnt lgkmcnt(2)
	v_mfma_f32_32x32x16_bf16 v[16:31], v[144:147], v[198:201], v[16:31]
	v_exp_f32_e32 v76, v76
	v_exp_f32_e32 v77, v77
	s_waitcnt lgkmcnt(0)
	v_mfma_f32_32x32x16_bf16 v[0:15], v[144:147], v[202:205], v[0:15]
	v_exp_f32_e32 v78, v78
	v_exp_f32_e32 v79, v79
	s_add_i32 s90, s88, 0x2000
	s_waitcnt vmcnt(3) lgkmcnt(0)
	s_barrier
	s_cmpk_lg_i32 s88, 0x4000
	s_mov_b32 s89, s86
	s_cselect_b32 s86, s90, 0
	s_add_i32 s85, s85, 2
	v_lshl_add_u64 v[176:177], v[176:177], 0, s[56:57]
	v_lshl_add_u64 v[178:179], v[178:179], 0, s[56:57]
	v_lshl_add_u64 v[180:181], v[180:181], 0, s[56:57]
	s_mov_b32 s87, s88
	s_cmpk_lt_u32 s85, 0x79
	s_cbranch_scc1 .LBB0_863
	s_and_b32 s34, s34, 0x3fffffc0
	s_lshl_b32 s34, s34, 2
	s_add_i32 s34, s34, 0
	s_add_i32 s34, s34, 0x12000
	s_cmp_lg_u32 0, -1
	s_cselect_b32 s85, 0, 0
	s_add_i32 s86, s85, 0x6000
	v_add_u32_e32 v104, s86, v191
	v_add3_u32 v176, v104, v190, v192
	v_add_u32_e32 v177, 0x6000, v168
	ds_read_b64_tr_b16 v[178:179], v168 offset:57344
	ds_read_b64_tr_b16 v[180:181], v168 offset:57856
	v_add_f32_e32 v108, v80, v81
	ds_read_b128 v[104:107], v188
	v_add_f32_e32 v108, v82, v108
	v_add_f32_e32 v108, v83, v108
	v_add_f32_e32 v108, v84, v108
	v_add_f32_e32 v108, v85, v108
	v_cvt_pk_bf16_f32 v156, v80, v81
	v_cvt_pk_bf16_f32 v157, v82, v83
	s_waitcnt lgkmcnt(0)
	v_mfma_f32_32x32x16_bf16 v[112:127], v[100:103], v[104:107], 0
	ds_read_b64_tr_b16 v[80:81], v168 offset:61440
	ds_read_b64_tr_b16 v[82:83], v168 offset:61952
	ds_read_b128 v[100:103], v188
	v_add_f32_e32 v104, v86, v108
	v_add_f32_e32 v104, v87, v104
	v_add_f32_e32 v104, v88, v104
	v_add_f32_e32 v144, v89, v104
	v_cvt_pk_bf16_f32 v158, v84, v85
	v_cvt_pk_bf16_f32 v159, v86, v87
	s_waitcnt lgkmcnt(0)
	v_mfma_f32_32x32x16_bf16 v[96:111], v[96:99], v[100:103], 0
	ds_read_b64_tr_b16 v[84:85], v168 offset:58368
	ds_read_b64_tr_b16 v[86:87], v168 offset:58880
	ds_read_b128 v[194:197], v188 offset:1024
	v_add_f32_e32 v144, v90, v144
	v_add_f32_e32 v144, v91, v144
	v_add_f32_e32 v144, v92, v144
	v_add_f32_e32 v144, v93, v144
	v_cvt_pk_bf16_f32 v152, v88, v89
	v_cvt_pk_bf16_f32 v153, v90, v91
	s_waitcnt lgkmcnt(0)
	v_mfma_f32_32x32x16_bf16 v[112:127], v[164:167], v[194:197], v[112:127]
	ds_read_b64_tr_b16 v[88:89], v168 offset:62464
	ds_read_b64_tr_b16 v[90:91], v168 offset:62976
	ds_read_b128 v[164:167], v188 offset:1024
	v_add_f32_e32 v144, v94, v144
	v_add_f32_e32 v144, v95, v144
	v_add_f32_e32 v144, v64, v144
	v_add_f32_e32 v144, v65, v144
	v_cvt_pk_bf16_f32 v154, v92, v93
	v_cvt_pk_bf16_f32 v155, v94, v95
	s_waitcnt lgkmcnt(0)
	v_mfma_f32_32x32x16_bf16 v[96:111], v[160:163], v[164:167], v[96:111]
	ds_read_b64_tr_b16 v[194:195], v168 offset:59392
	ds_read_b64_tr_b16 v[196:197], v168 offset:59904
	ds_read_b128 v[92:95], v188 offset:2048
	v_add_f32_e32 v144, v66, v144
	v_add_f32_e32 v144, v67, v144
	v_add_f32_e32 v144, v68, v144
	v_add_f32_e32 v144, v69, v144
	v_cvt_pk_bf16_f32 v148, v64, v65
	v_cvt_pk_bf16_f32 v149, v66, v67
	s_waitcnt lgkmcnt(0)
	v_mfma_f32_32x32x16_bf16 v[112:127], v[140:143], v[92:95], v[112:127]
	ds_read_b64_tr_b16 v[140:141], v168 offset:63488
	ds_read_b64_tr_b16 v[142:143], v168 offset:64000
	ds_read_b128 v[64:67], v188 offset:2048
	v_add_f32_e32 v92, v70, v144
	v_add_f32_e32 v92, v71, v92
	v_add_f32_e32 v92, v72, v92
	v_add_f32_e32 v92, v73, v92
	v_cvt_pk_bf16_f32 v150, v68, v69
	v_cvt_pk_bf16_f32 v151, v70, v71
	s_waitcnt lgkmcnt(0)
	v_mfma_f32_32x32x16_bf16 v[96:111], v[136:139], v[64:67], v[96:111]
	ds_read_b64_tr_b16 v[136:137], v168 offset:60416
	ds_read_b64_tr_b16 v[138:139], v168 offset:60928
	ds_read_b128 v[64:67], v188 offset:3072
	v_add_f32_e32 v68, v74, v92
	v_add_f32_e32 v68, v75, v68
	v_add_f32_e32 v68, v76, v68
	v_add_f32_e32 v68, v77, v68
	v_cvt_pk_bf16_f32 v144, v72, v73
	v_cvt_pk_bf16_f32 v145, v74, v75
	s_waitcnt lgkmcnt(0)
	v_mfma_f32_32x32x16_bf16 v[112:127], v[132:135], v[64:67], v[112:127]
	ds_read_b64_tr_b16 v[72:73], v168 offset:64512
	ds_read_b64_tr_b16 v[74:75], v168 offset:65024
	ds_read_b128 v[64:67], v188 offset:3072
	v_add_f32_e32 v68, v78, v68
	v_add_f32_e32 v68, v79, v68
	v_add_f32_e32 v68, 0, v68
	v_cvt_pk_bf16_f32 v146, v76, v77
	v_cvt_pk_bf16_f32 v147, v78, v79
	s_waitcnt lgkmcnt(0)
	v_mfma_f32_32x32x16_bf16 v[96:111], v[128:131], v[64:67], v[96:111]
	v_lshl_add_u64 v[64:65], v[174:175], 0, s[58:59]
	s_mov_b32 s86, m0
	s_mov_b32 m0, s35
	s_nop 0
	global_load_lds_dwordx4 v[64:65], off
	s_mov_b32 m0, s86
	s_add_i32 s85, s85, s17
	v_lshl_add_u64 v[64:65], v[170:171], 0, s[60:61]
	s_add_i32 s17, s85, 0xa000
	s_mov_b32 s35, m0
	s_mov_b32 m0, s17
	s_nop 0
	global_load_lds_dwordx4 v[64:65], off
	s_mov_b32 m0, s35
	v_lshl_add_u64 v[64:65], v[172:173], 0, s[60:61]
	s_add_i32 s35, s17, 0x2000
	s_mov_b32 s86, m0
	s_mov_b32 m0, s35
	s_nop 0
	global_load_lds_dwordx4 v[64:65], off
	s_mov_b32 m0, s86
	v_add_f32_e32 v198, v193, v68
	v_mfma_f32_32x32x16_bf16 v[48:63], v[156:159], v[178:181], v[48:63]
	ds_read_b64_tr_b16 v[76:77], v177 offset:40960
	ds_read_b64_tr_b16 v[78:79], v177 offset:41472
	v_exp_f32_e32 v112, v112
	v_exp_f32_e32 v113, v113
	v_mfma_f32_32x32x16_bf16 v[32:47], v[156:159], v[80:83], v[32:47]
	ds_read_b64_tr_b16 v[128:129], v177 offset:45056
	ds_read_b64_tr_b16 v[130:131], v177 offset:45568
	v_exp_f32_e32 v114, v114
	v_exp_f32_e32 v115, v115
	ds_read_b128 v[68:71], v234 offset:8192
	ds_read_b128 v[64:67], v234 offset:12288
	v_mfma_f32_32x32x16_bf16 v[48:63], v[152:155], v[84:87], v[48:63]
	ds_read_b64_tr_b16 v[132:133], v177 offset:41984
	ds_read_b64_tr_b16 v[134:135], v177 offset:42496
	v_exp_f32_e32 v116, v116
	v_exp_f32_e32 v117, v117
	ds_read_b128 v[164:167], v235 offset:8192
	ds_read_b128 v[92:95], v235 offset:12288
	v_mfma_f32_32x32x16_bf16 v[32:47], v[152:155], v[88:91], v[32:47]
	ds_read_b64_tr_b16 v[178:179], v177 offset:46080
	ds_read_b64_tr_b16 v[180:181], v177 offset:46592
	v_exp_f32_e32 v118, v118
	v_exp_f32_e32 v119, v119
	ds_read_b128 v[160:163], v236 offset:8192
	ds_read_b128 v[84:87], v236 offset:12288
	v_mfma_f32_32x32x16_bf16 v[48:63], v[148:151], v[194:197], v[48:63]
	ds_read_b64_tr_b16 v[190:191], v177 offset:43008
	ds_read_b64_tr_b16 v[192:193], v177 offset:43520
	v_exp_f32_e32 v120, v120
	v_exp_f32_e32 v121, v121
	ds_read_b128 v[88:91], v237 offset:8192
	ds_read_b128 v[80:83], v237 offset:12288
	v_mfma_f32_32x32x16_bf16 v[32:47], v[148:151], v[140:143], v[32:47]
	ds_read_b64_tr_b16 v[194:195], v177 offset:47104
	ds_read_b64_tr_b16 v[196:197], v177 offset:47616
	v_exp_f32_e32 v122, v122
	v_exp_f32_e32 v123, v123
	v_mfma_f32_32x32x16_bf16 v[48:63], v[144:147], v[136:139], v[48:63]
	ds_read_b64_tr_b16 v[140:141], v177 offset:44032
	ds_read_b64_tr_b16 v[142:143], v177 offset:44544
	v_exp_f32_e32 v124, v124
	v_exp_f32_e32 v125, v125
	v_mfma_f32_32x32x16_bf16 v[32:47], v[144:147], v[72:75], v[32:47]
	ds_read_b64_tr_b16 v[136:137], v177 offset:48128
	ds_read_b64_tr_b16 v[138:139], v177 offset:48640
	v_exp_f32_e32 v126, v126
	v_exp_f32_e32 v127, v127
	s_waitcnt lgkmcnt(14)
	v_mfma_f32_32x32x16_bf16 v[16:31], v[156:159], v[76:79], v[16:31]
	v_exp_f32_e32 v96, v96
	v_exp_f32_e32 v97, v97
	v_mfma_f32_32x32x16_bf16 v[0:15], v[156:159], v[128:131], v[0:15]
	v_exp_f32_e32 v98, v98
	v_exp_f32_e32 v99, v99
	v_mfma_f32_32x32x16_bf16 v[16:31], v[152:155], v[132:135], v[16:31]
	v_exp_f32_e32 v100, v100
	v_exp_f32_e32 v101, v101
	s_waitcnt lgkmcnt(12)
	v_mfma_f32_32x32x16_bf16 v[0:15], v[152:155], v[178:181], v[0:15]
	v_exp_f32_e32 v102, v102
	v_exp_f32_e32 v103, v103
	s_waitcnt lgkmcnt(8)
	v_mfma_f32_32x32x16_bf16 v[16:31], v[148:151], v[190:193], v[16:31]
	v_exp_f32_e32 v104, v104
	v_exp_f32_e32 v105, v105
	s_waitcnt lgkmcnt(4)
	v_mfma_f32_32x32x16_bf16 v[0:15], v[148:151], v[194:197], v[0:15]
	v_exp_f32_e32 v106, v106
	v_exp_f32_e32 v107, v107
	s_waitcnt lgkmcnt(2)
	v_mfma_f32_32x32x16_bf16 v[16:31], v[144:147], v[140:143], v[16:31]
	v_exp_f32_e32 v108, v108
	v_exp_f32_e32 v109, v109
	s_waitcnt lgkmcnt(0)
	v_mfma_f32_32x32x16_bf16 v[0:15], v[144:147], v[136:139], v[0:15]
	v_exp_f32_e32 v110, v110
	v_exp_f32_e32 v111, v111
	s_waitcnt vmcnt(3) lgkmcnt(0)
	s_barrier
	ds_read_b64_tr_b16 v[178:179], v168 offset:24576
	ds_read_b64_tr_b16 v[180:181], v168 offset:25088
	v_add_f32_e32 v76, v112, v113
	ds_read_b128 v[72:75], v188
	v_add_f32_e32 v76, v114, v76
	v_add_f32_e32 v76, v115, v76
	v_add_f32_e32 v76, v116, v76
	v_add_f32_e32 v76, v117, v76
	v_cvt_pk_bf16_f32 v156, v112, v113
	v_cvt_pk_bf16_f32 v157, v114, v115
	s_waitcnt lgkmcnt(0)
	v_mfma_f32_32x32x16_bf16 v[128:143], v[68:71], v[72:75], 0
	ds_read_b64_tr_b16 v[112:113], v168 offset:28672
	ds_read_b64_tr_b16 v[114:115], v168 offset:29184
	ds_read_b128 v[68:71], v188
	v_add_f32_e32 v72, v118, v76
	v_add_f32_e32 v72, v119, v72
	v_add_f32_e32 v72, v120, v72
	v_add_f32_e32 v144, v121, v72
	s_waitcnt lgkmcnt(0)
	v_mfma_f32_32x32x16_bf16 v[64:79], v[64:67], v[68:71], 0
	v_cvt_pk_bf16_f32 v158, v116, v117
	v_cvt_pk_bf16_f32 v159, v118, v119
	ds_read_b64_tr_b16 v[116:117], v168 offset:25600
	ds_read_b64_tr_b16 v[118:119], v168 offset:26112
	ds_read_b128 v[190:193], v188 offset:1024
	v_add_f32_e32 v144, v122, v144
	v_add_f32_e32 v144, v123, v144
	v_add_f32_e32 v144, v124, v144
	v_add_f32_e32 v144, v125, v144
	v_cvt_pk_bf16_f32 v152, v120, v121
	v_cvt_pk_bf16_f32 v153, v122, v123
	s_waitcnt lgkmcnt(0)
	v_mfma_f32_32x32x16_bf16 v[128:143], v[164:167], v[190:193], v[128:143]
	ds_read_b64_tr_b16 v[120:121], v168 offset:29696
	ds_read_b64_tr_b16 v[122:123], v168 offset:30208
	ds_read_b128 v[164:167], v188 offset:1024
	v_add_f32_e32 v144, v126, v144
	v_add_f32_e32 v144, v127, v144
	v_add_f32_e32 v144, v96, v144
	v_add_f32_e32 v144, v97, v144
	s_waitcnt lgkmcnt(0)
	v_mfma_f32_32x32x16_bf16 v[64:79], v[92:95], v[164:167], v[64:79]
	v_cvt_pk_bf16_f32 v154, v124, v125
	v_cvt_pk_bf16_f32 v155, v126, v127
	ds_read_b64_tr_b16 v[92:93], v168 offset:26624
	ds_read_b64_tr_b16 v[94:95], v168 offset:27136
	ds_read_b128 v[124:127], v188 offset:2048
	v_add_f32_e32 v144, v98, v144
	v_add_f32_e32 v144, v99, v144
	v_add_f32_e32 v144, v100, v144
	v_add_f32_e32 v144, v101, v144
	v_cvt_pk_bf16_f32 v148, v96, v97
	v_cvt_pk_bf16_f32 v149, v98, v99
	s_waitcnt lgkmcnt(0)
	v_mfma_f32_32x32x16_bf16 v[128:143], v[160:163], v[124:127], v[128:143]
	ds_read_b64_tr_b16 v[96:97], v168 offset:30720
	ds_read_b64_tr_b16 v[98:99], v168 offset:31232
	ds_read_b128 v[124:127], v188 offset:2048
	v_add_f32_e32 v144, v102, v144
	v_add_f32_e32 v144, v103, v144
	v_add_f32_e32 v144, v104, v144
	v_add_f32_e32 v144, v105, v144
	s_waitcnt lgkmcnt(0)
	v_mfma_f32_32x32x16_bf16 v[64:79], v[84:87], v[124:127], v[64:79]
	v_cvt_pk_bf16_f32 v150, v100, v101
	v_cvt_pk_bf16_f32 v151, v102, v103
	ds_read_b64_tr_b16 v[100:101], v168 offset:27648
	ds_read_b64_tr_b16 v[102:103], v168 offset:28160
	ds_read_b128 v[84:87], v188 offset:3072
	v_add_f32_e32 v124, v106, v144
	v_add_f32_e32 v124, v107, v124
	v_add_f32_e32 v124, v108, v124
	v_add_f32_e32 v124, v109, v124
	v_cvt_pk_bf16_f32 v144, v104, v105
	v_cvt_pk_bf16_f32 v145, v106, v107
	s_waitcnt lgkmcnt(0)
	v_mfma_f32_32x32x16_bf16 v[128:143], v[88:91], v[84:87], v[128:143]
	ds_read_b64_tr_b16 v[88:89], v168 offset:31744
	ds_read_b64_tr_b16 v[90:91], v168 offset:32256
	ds_read_b128 v[84:87], v188 offset:3072
	v_add_f32_e32 v104, v110, v124
	v_add_f32_e32 v104, v111, v104
	v_add_f32_e32 v104, 0, v104
	v_cvt_pk_bf16_f32 v146, v108, v109
	s_waitcnt lgkmcnt(0)
	v_mfma_f32_32x32x16_bf16 v[64:79], v[80:83], v[84:87], v[64:79]
	v_cvt_pk_bf16_f32 v147, v110, v111
	v_lshl_add_u64 v[80:81], v[174:175], 0, s[62:63]
	s_add_i32 s86, s85, 0x2000
	s_mov_b32 s87, m0
	s_mov_b32 m0, s86
	s_nop 0
	global_load_lds_dwordx4 v[80:81], off
	s_mov_b32 m0, s87
	v_lshl_add_u64 v[80:81], v[170:171], 0, s[64:65]
	s_add_i32 s86, s85, 0xe000
	s_mov_b32 s87, m0
	s_mov_b32 m0, s86
	s_nop 0
	global_load_lds_dwordx4 v[80:81], off
	s_mov_b32 m0, s87
	v_lshl_add_u64 v[80:81], v[172:173], 0, s[64:65]
	s_add_i32 s85, s85, 0x10000
	s_mov_b32 s86, m0
	s_mov_b32 m0, s85
	s_nop 0
	global_load_lds_dwordx4 v[80:81], off
	s_mov_b32 m0, s86
	v_add_f32_e32 v198, v198, v104
	v_mfma_f32_32x32x16_bf16 v[48:63], v[156:159], v[178:181], v[48:63]
	ds_read_b64_tr_b16 v[104:105], v168 offset:32768
	ds_read_b64_tr_b16 v[106:107], v168 offset:33280
	v_exp_f32_e32 v128, v128
	v_exp_f32_e32 v129, v129
	v_mfma_f32_32x32x16_bf16 v[32:47], v[156:159], v[112:115], v[32:47]
	ds_read_b64_tr_b16 v[108:109], v168 offset:36864
	ds_read_b64_tr_b16 v[110:111], v168 offset:37376
	v_exp_f32_e32 v130, v130
	v_exp_f32_e32 v131, v131
	ds_read_b128 v[84:87], v234 offset:16384
	ds_read_b128 v[80:83], v234 offset:20480
	v_mfma_f32_32x32x16_bf16 v[48:63], v[152:155], v[116:119], v[48:63]
	ds_read_b64_tr_b16 v[178:179], v168 offset:33792
	ds_read_b64_tr_b16 v[180:181], v168 offset:34304
	v_exp_f32_e32 v132, v132
	v_exp_f32_e32 v133, v133
	ds_read_b128 v[164:167], v235 offset:16384
	ds_read_b128 v[124:127], v235 offset:20480
	v_mfma_f32_32x32x16_bf16 v[32:47], v[152:155], v[120:123], v[32:47]
	ds_read_b64_tr_b16 v[190:191], v168 offset:37888
	ds_read_b64_tr_b16 v[192:193], v168 offset:38400
	v_exp_f32_e32 v134, v134
	v_exp_f32_e32 v135, v135
	ds_read_b128 v[160:163], v236 offset:16384
	ds_read_b128 v[116:119], v236 offset:20480
	v_mfma_f32_32x32x16_bf16 v[48:63], v[148:151], v[92:95], v[48:63]
	ds_read_b64_tr_b16 v[194:195], v168 offset:34816
	ds_read_b64_tr_b16 v[196:197], v168 offset:35328
	v_exp_f32_e32 v136, v136
	v_exp_f32_e32 v137, v137
	ds_read_b128 v[120:123], v237 offset:16384
	ds_read_b128 v[112:115], v237 offset:20480
	v_mfma_f32_32x32x16_bf16 v[32:47], v[148:151], v[96:99], v[32:47]
	ds_read_b64_tr_b16 v[92:93], v168 offset:38912
	ds_read_b64_tr_b16 v[94:95], v168 offset:39424
	v_exp_f32_e32 v138, v138
	v_exp_f32_e32 v139, v139
	v_mfma_f32_32x32x16_bf16 v[48:63], v[144:147], v[100:103], v[48:63]
	ds_read_b64_tr_b16 v[96:97], v168 offset:35840
	ds_read_b64_tr_b16 v[98:99], v168 offset:36352
	v_exp_f32_e32 v140, v140
	v_exp_f32_e32 v141, v141
	v_mfma_f32_32x32x16_bf16 v[32:47], v[144:147], v[88:91], v[32:47]
	ds_read_b64_tr_b16 v[100:101], v168 offset:39936
	ds_read_b64_tr_b16 v[102:103], v168 offset:40448
	v_exp_f32_e32 v142, v142
	v_exp_f32_e32 v143, v143
	s_waitcnt lgkmcnt(14)
	v_mfma_f32_32x32x16_bf16 v[16:31], v[156:159], v[104:107], v[16:31]
	v_exp_f32_e32 v64, v64
	v_exp_f32_e32 v65, v65
	v_mfma_f32_32x32x16_bf16 v[0:15], v[156:159], v[108:111], v[0:15]
	v_exp_f32_e32 v66, v66
	v_exp_f32_e32 v67, v67
	v_mfma_f32_32x32x16_bf16 v[16:31], v[152:155], v[178:181], v[16:31]
	v_exp_f32_e32 v68, v68
	v_exp_f32_e32 v69, v69
	s_waitcnt lgkmcnt(12)
	v_mfma_f32_32x32x16_bf16 v[0:15], v[152:155], v[190:193], v[0:15]
	v_exp_f32_e32 v70, v70
	v_exp_f32_e32 v71, v71
	s_waitcnt lgkmcnt(8)
	v_mfma_f32_32x32x16_bf16 v[16:31], v[148:151], v[194:197], v[16:31]
	v_exp_f32_e32 v72, v72
	v_exp_f32_e32 v73, v73
	s_waitcnt lgkmcnt(4)
	v_mfma_f32_32x32x16_bf16 v[0:15], v[148:151], v[92:95], v[0:15]
	v_exp_f32_e32 v74, v74
	v_exp_f32_e32 v75, v75
	s_waitcnt lgkmcnt(2)
	v_mfma_f32_32x32x16_bf16 v[16:31], v[144:147], v[96:99], v[16:31]
	v_exp_f32_e32 v76, v76
	v_exp_f32_e32 v77, v77
	s_waitcnt lgkmcnt(0)
	v_mfma_f32_32x32x16_bf16 v[0:15], v[144:147], v[100:103], v[0:15]
	v_exp_f32_e32 v78, v78
	v_exp_f32_e32 v79, v79
	s_waitcnt vmcnt(3) lgkmcnt(0)
	s_barrier
	ds_read_b64_tr_b16 v[178:179], v168 offset:40960
	ds_read_b64_tr_b16 v[180:181], v168 offset:41472
	v_add_f32_e32 v92, v128, v129
	ds_read_b128 v[88:91], v188
	v_add_f32_e32 v92, v130, v92
	v_add_f32_e32 v92, v131, v92
	v_add_f32_e32 v92, v132, v92
	v_add_f32_e32 v92, v133, v92
	v_cvt_pk_bf16_f32 v156, v128, v129
	v_cvt_pk_bf16_f32 v157, v130, v131
	s_waitcnt lgkmcnt(0)
	v_mfma_f32_32x32x16_bf16 v[96:111], v[84:87], v[88:91], 0
	ds_read_b64_tr_b16 v[128:129], v168 offset:45056
	ds_read_b64_tr_b16 v[130:131], v168 offset:45568
	ds_read_b128 v[84:87], v188
	v_add_f32_e32 v88, v134, v92
	v_add_f32_e32 v88, v135, v88
	v_add_f32_e32 v88, v136, v88
	v_add_f32_e32 v144, v137, v88
	v_cvt_pk_bf16_f32 v158, v132, v133
	v_cvt_pk_bf16_f32 v159, v134, v135
	s_waitcnt lgkmcnt(0)
	v_mfma_f32_32x32x16_bf16 v[80:95], v[80:83], v[84:87], 0
	ds_read_b64_tr_b16 v[132:133], v168 offset:41984
	ds_read_b64_tr_b16 v[134:135], v168 offset:42496
	ds_read_b128 v[190:193], v188 offset:1024
	v_add_f32_e32 v144, v138, v144
	v_add_f32_e32 v144, v139, v144
	v_add_f32_e32 v144, v140, v144
	v_add_f32_e32 v144, v141, v144
	v_cvt_pk_bf16_f32 v152, v136, v137
	v_cvt_pk_bf16_f32 v153, v138, v139
	s_waitcnt lgkmcnt(0)
	v_mfma_f32_32x32x16_bf16 v[96:111], v[164:167], v[190:193], v[96:111]
	ds_read_b64_tr_b16 v[136:137], v168 offset:46080
	ds_read_b64_tr_b16 v[138:139], v168 offset:46592
	ds_read_b128 v[164:167], v188 offset:1024
	v_add_f32_e32 v144, v142, v144
	v_add_f32_e32 v144, v143, v144
	v_add_f32_e32 v144, v64, v144
	v_add_f32_e32 v144, v65, v144
	v_cvt_pk_bf16_f32 v154, v140, v141
	v_cvt_pk_bf16_f32 v155, v142, v143
	s_waitcnt lgkmcnt(0)
	v_mfma_f32_32x32x16_bf16 v[80:95], v[124:127], v[164:167], v[80:95]
	ds_read_b64_tr_b16 v[124:125], v168 offset:43008
	ds_read_b64_tr_b16 v[126:127], v168 offset:43520
	ds_read_b128 v[140:143], v188 offset:2048
	v_add_f32_e32 v144, v66, v144
	v_add_f32_e32 v144, v67, v144
	v_add_f32_e32 v144, v68, v144
	v_add_f32_e32 v144, v69, v144
	v_cvt_pk_bf16_f32 v148, v64, v65
	v_cvt_pk_bf16_f32 v149, v66, v67
	s_waitcnt lgkmcnt(0)
	v_mfma_f32_32x32x16_bf16 v[96:111], v[160:163], v[140:143], v[96:111]
	ds_read_b64_tr_b16 v[190:191], v168 offset:47104
	ds_read_b64_tr_b16 v[192:193], v168 offset:47616
	ds_read_b128 v[64:67], v188 offset:2048
	v_add_f32_e32 v140, v70, v144
	v_add_f32_e32 v140, v71, v140
	v_add_f32_e32 v140, v72, v140
	v_add_f32_e32 v140, v73, v140
	v_cvt_pk_bf16_f32 v150, v68, v69
	v_cvt_pk_bf16_f32 v151, v70, v71
	s_waitcnt lgkmcnt(0)
	v_mfma_f32_32x32x16_bf16 v[80:95], v[116:119], v[64:67], v[80:95]
	ds_read_b64_tr_b16 v[116:117], v168 offset:44032
	ds_read_b64_tr_b16 v[118:119], v168 offset:44544
	ds_read_b128 v[64:67], v188 offset:3072
	v_add_f32_e32 v68, v74, v140
	v_add_f32_e32 v68, v75, v68
	v_add_f32_e32 v68, v76, v68
	v_add_f32_e32 v68, v77, v68
	v_cvt_pk_bf16_f32 v144, v72, v73
	v_cvt_pk_bf16_f32 v145, v74, v75
	s_waitcnt lgkmcnt(0)
	v_mfma_f32_32x32x16_bf16 v[96:111], v[120:123], v[64:67], v[96:111]
	ds_read_b64_tr_b16 v[72:73], v168 offset:48128
	ds_read_b64_tr_b16 v[74:75], v168 offset:48640
	ds_read_b128 v[64:67], v188 offset:3072
	v_add_f32_e32 v68, v78, v68
	v_add_f32_e32 v68, v79, v68
	v_add_f32_e32 v68, 0, v68
	v_cvt_pk_bf16_f32 v146, v76, v77
	v_cvt_pk_bf16_f32 v147, v78, v79
	s_waitcnt lgkmcnt(0)
	v_mfma_f32_32x32x16_bf16 v[80:95], v[112:115], v[64:67], v[80:95]
	v_lshl_add_u64 v[64:65], v[170:171], 0, s[58:59]
	s_mov_b32 s85, m0
	s_mov_b32 m0, s16
	s_nop 0
	global_load_lds_dwordx4 v[64:65], off
	s_mov_b32 m0, s85
	v_lshl_add_u64 v[64:65], v[172:173], 0, s[58:59]
	s_addk_i32 s16, 0x2000
	s_mov_b32 s85, m0
	s_mov_b32 m0, s16
	s_nop 0
	global_load_lds_dwordx4 v[64:65], off
	s_mov_b32 m0, s85
	v_add_f32_e32 v174, v198, v68
	v_mfma_f32_32x32x16_bf16 v[48:63], v[156:159], v[178:181], v[48:63]
	ds_read_b64_tr_b16 v[76:77], v168 offset:49152
	ds_read_b64_tr_b16 v[78:79], v168 offset:49664
	v_exp_f32_e32 v96, v96
	v_exp_f32_e32 v97, v97
	v_mfma_f32_32x32x16_bf16 v[32:47], v[156:159], v[128:131], v[32:47]
	ds_read_b64_tr_b16 v[112:113], v168 offset:53248
	ds_read_b64_tr_b16 v[114:115], v168 offset:53760
	v_exp_f32_e32 v98, v98
	v_exp_f32_e32 v99, v99
	ds_read_b128 v[68:71], v234
	ds_read_b128 v[64:67], v234 offset:4096
	v_mfma_f32_32x32x16_bf16 v[48:63], v[152:155], v[132:135], v[48:63]
	ds_read_b64_tr_b16 v[120:121], v168 offset:50176
	ds_read_b64_tr_b16 v[122:123], v168 offset:50688
	v_exp_f32_e32 v100, v100
	v_exp_f32_e32 v101, v101
	ds_read_b128 v[164:167], v235
	ds_read_b128 v[140:143], v235 offset:4096
	v_mfma_f32_32x32x16_bf16 v[32:47], v[152:155], v[136:139], v[32:47]
	ds_read_b64_tr_b16 v[178:179], v168 offset:54272
	ds_read_b64_tr_b16 v[180:181], v168 offset:54784
	v_exp_f32_e32 v102, v102
	v_exp_f32_e32 v103, v103
	ds_read_b128 v[160:163], v236
	ds_read_b128 v[132:135], v236 offset:4096
	v_mfma_f32_32x32x16_bf16 v[48:63], v[148:151], v[124:127], v[48:63]
	ds_read_b64_tr_b16 v[194:195], v168 offset:51200
	ds_read_b64_tr_b16 v[196:197], v168 offset:51712
	v_exp_f32_e32 v104, v104
	v_exp_f32_e32 v105, v105
	ds_read_b128 v[136:139], v237
	ds_read_b128 v[128:131], v237 offset:4096
	v_mfma_f32_32x32x16_bf16 v[32:47], v[148:151], v[190:193], v[32:47]
	ds_read_b64_tr_b16 v[124:125], v168 offset:55296
	ds_read_b64_tr_b16 v[126:127], v168 offset:55808
	v_exp_f32_e32 v106, v106
	v_exp_f32_e32 v107, v107
	v_mfma_f32_32x32x16_bf16 v[48:63], v[144:147], v[116:119], v[48:63]
	ds_read_b64_tr_b16 v[190:191], v168 offset:52224
	ds_read_b64_tr_b16 v[192:193], v168 offset:52736
	v_exp_f32_e32 v108, v108
	v_exp_f32_e32 v109, v109
	v_mfma_f32_32x32x16_bf16 v[32:47], v[144:147], v[72:75], v[32:47]
	ds_read_b64_tr_b16 v[116:117], v168 offset:56320
	ds_read_b64_tr_b16 v[118:119], v168 offset:56832
	v_exp_f32_e32 v110, v110
	v_exp_f32_e32 v111, v111
	s_waitcnt lgkmcnt(14)
	v_mfma_f32_32x32x16_bf16 v[16:31], v[156:159], v[76:79], v[16:31]
	v_exp_f32_e32 v80, v80
	v_exp_f32_e32 v81, v81
	v_mfma_f32_32x32x16_bf16 v[0:15], v[156:159], v[112:115], v[0:15]
	v_exp_f32_e32 v82, v82
	v_exp_f32_e32 v83, v83
	v_mfma_f32_32x32x16_bf16 v[16:31], v[152:155], v[120:123], v[16:31]
	v_exp_f32_e32 v84, v84
	v_exp_f32_e32 v85, v85
	s_waitcnt lgkmcnt(12)
	v_mfma_f32_32x32x16_bf16 v[0:15], v[152:155], v[178:181], v[0:15]
	v_exp_f32_e32 v86, v86
	v_exp_f32_e32 v87, v87
	s_waitcnt lgkmcnt(8)
	v_mfma_f32_32x32x16_bf16 v[16:31], v[148:151], v[194:197], v[16:31]
	v_exp_f32_e32 v88, v88
	v_exp_f32_e32 v89, v89
	s_waitcnt lgkmcnt(4)
	v_mfma_f32_32x32x16_bf16 v[0:15], v[148:151], v[124:127], v[0:15]
	v_exp_f32_e32 v90, v90
	v_exp_f32_e32 v91, v91
	s_waitcnt lgkmcnt(2)
	v_mfma_f32_32x32x16_bf16 v[16:31], v[144:147], v[190:193], v[16:31]
	v_exp_f32_e32 v92, v92
	v_exp_f32_e32 v93, v93
	s_waitcnt lgkmcnt(0)
	v_mfma_f32_32x32x16_bf16 v[0:15], v[144:147], v[116:119], v[0:15]
	v_exp_f32_e32 v94, v94
	v_exp_f32_e32 v95, v95
	s_waitcnt vmcnt(2) lgkmcnt(0)
	s_barrier
	ds_read_b64_tr_b16 v[178:179], v168 offset:57344
	ds_read_b64_tr_b16 v[180:181], v168 offset:57856
	v_add_f32_e32 v76, v96, v97
	ds_read_b128 v[72:75], v188
	v_add_f32_e32 v76, v98, v76
	v_add_f32_e32 v76, v99, v76
	v_add_f32_e32 v76, v100, v76
	v_add_f32_e32 v76, v101, v76
	v_cvt_pk_bf16_f32 v156, v96, v97
	v_cvt_pk_bf16_f32 v157, v98, v99
	s_waitcnt lgkmcnt(0)
	v_mfma_f32_32x32x16_bf16 v[112:127], v[68:71], v[72:75], 0
	ds_read_b64_tr_b16 v[96:97], v168 offset:61440
	ds_read_b64_tr_b16 v[98:99], v168 offset:61952
	ds_read_b128 v[68:71], v188
	v_add_f32_e32 v72, v102, v76
	v_add_f32_e32 v72, v103, v72
	v_add_f32_e32 v72, v104, v72
	v_add_f32_e32 v144, v105, v72
	s_waitcnt lgkmcnt(0)
	v_mfma_f32_32x32x16_bf16 v[64:79], v[64:67], v[68:71], 0
	v_cvt_pk_bf16_f32 v158, v100, v101
	v_cvt_pk_bf16_f32 v159, v102, v103
	ds_read_b64_tr_b16 v[100:101], v168 offset:58368
	ds_read_b64_tr_b16 v[102:103], v168 offset:58880
	ds_read_b128 v[190:193], v188 offset:1024
	v_add_f32_e32 v144, v106, v144
	v_add_f32_e32 v144, v107, v144
	v_add_f32_e32 v144, v108, v144
	v_add_f32_e32 v144, v109, v144
	v_cvt_pk_bf16_f32 v152, v104, v105
	v_cvt_pk_bf16_f32 v153, v106, v107
	s_waitcnt lgkmcnt(0)
	v_mfma_f32_32x32x16_bf16 v[112:127], v[164:167], v[190:193], v[112:127]
	ds_read_b64_tr_b16 v[104:105], v168 offset:62464
	ds_read_b64_tr_b16 v[106:107], v168 offset:62976
	ds_read_b128 v[164:167], v188 offset:1024
	v_add_f32_e32 v144, v110, v144
	v_add_f32_e32 v144, v111, v144
	v_add_f32_e32 v144, v80, v144
	v_add_f32_e32 v144, v81, v144
	s_waitcnt lgkmcnt(0)
	v_mfma_f32_32x32x16_bf16 v[64:79], v[140:143], v[164:167], v[64:79]
	v_cvt_pk_bf16_f32 v154, v108, v109
	v_cvt_pk_bf16_f32 v155, v110, v111
	ds_read_b64_tr_b16 v[108:109], v168 offset:59392
	ds_read_b64_tr_b16 v[110:111], v168 offset:59904
	ds_read_b128 v[140:143], v188 offset:2048
	v_add_f32_e32 v144, v82, v144
	v_add_f32_e32 v144, v83, v144
	v_add_f32_e32 v144, v84, v144
	v_add_f32_e32 v144, v85, v144
	v_cvt_pk_bf16_f32 v148, v80, v81
	v_cvt_pk_bf16_f32 v149, v82, v83
	s_waitcnt lgkmcnt(0)
	v_mfma_f32_32x32x16_bf16 v[112:127], v[160:163], v[140:143], v[112:127]
	ds_read_b64_tr_b16 v[190:191], v168 offset:63488
	ds_read_b64_tr_b16 v[192:193], v168 offset:64000
	ds_read_b128 v[80:83], v188 offset:2048
	v_add_f32_e32 v140, v86, v144
	v_add_f32_e32 v140, v87, v140
	v_add_f32_e32 v140, v88, v140
	v_add_f32_e32 v140, v89, v140
	s_waitcnt lgkmcnt(0)
	v_mfma_f32_32x32x16_bf16 v[64:79], v[132:135], v[80:83], v[64:79]
	v_cvt_pk_bf16_f32 v150, v84, v85
	v_cvt_pk_bf16_f32 v151, v86, v87
	ds_read_b64_tr_b16 v[84:85], v168 offset:60416
	ds_read_b64_tr_b16 v[86:87], v168 offset:60928
	ds_read_b128 v[80:83], v188 offset:3072
	v_add_f32_e32 v132, v90, v140
	v_add_f32_e32 v132, v91, v132
	v_add_f32_e32 v132, v92, v132
	v_add_f32_e32 v132, v93, v132
	v_cvt_pk_bf16_f32 v144, v88, v89
	v_cvt_pk_bf16_f32 v145, v90, v91
	s_waitcnt lgkmcnt(0)
	v_mfma_f32_32x32x16_bf16 v[112:127], v[136:139], v[80:83], v[112:127]
	ds_read_b64_tr_b16 v[88:89], v168 offset:64512
	ds_read_b64_tr_b16 v[90:91], v168 offset:65024
	ds_read_b128 v[80:83], v188 offset:3072
	v_add_f32_e32 v132, v94, v132
	v_add_f32_e32 v132, v95, v132
	v_add_f32_e32 v132, 0, v132
	v_cvt_pk_bf16_f32 v146, v92, v93
	s_waitcnt lgkmcnt(0)
	v_mfma_f32_32x32x16_bf16 v[64:79], v[128:131], v[80:83], v[64:79]
	v_cvt_pk_bf16_f32 v147, v94, v95
	v_lshl_add_u64 v[80:81], v[170:171], 0, s[62:63]
	s_mov_b32 s16, m0
	s_mov_b32 m0, s17
	s_nop 0
	global_load_lds_dwordx4 v[80:81], off
	s_mov_b32 m0, s16
	v_lshl_add_u64 v[80:81], v[172:173], 0, s[62:63]
	s_mov_b32 s16, m0
	s_mov_b32 m0, s35
	s_nop 0
	global_load_lds_dwordx4 v[80:81], off
	s_mov_b32 m0, s16
	v_add_f32_e32 v174, v174, v132
	v_mfma_f32_32x32x16_bf16 v[48:63], v[156:159], v[178:181], v[48:63]
	ds_read_b64_tr_b16 v[92:93], v177 offset:40960
	ds_read_b64_tr_b16 v[94:95], v177 offset:41472
	v_exp_f32_e32 v112, v112
	v_exp_f32_e32 v113, v113
	v_mfma_f32_32x32x16_bf16 v[32:47], v[156:159], v[96:99], v[32:47]
	ds_read_b64_tr_b16 v[170:171], v177 offset:45056
	ds_read_b64_tr_b16 v[172:173], v177 offset:45568
	v_exp_f32_e32 v114, v114
	v_exp_f32_e32 v115, v115
	ds_read_b128 v[80:83], v234 offset:8192
	ds_read_b128 v[96:99], v234 offset:12288
	v_mfma_f32_32x32x16_bf16 v[48:63], v[152:155], v[100:103], v[48:63]
	ds_read_b64_tr_b16 v[178:179], v177 offset:41984
	ds_read_b64_tr_b16 v[180:181], v177 offset:42496
	v_exp_f32_e32 v116, v116
	v_exp_f32_e32 v117, v117
	ds_read_b128 v[164:167], v235 offset:8192
	ds_read_b128 v[140:143], v235 offset:12288
	v_mfma_f32_32x32x16_bf16 v[32:47], v[152:155], v[104:107], v[32:47]
	ds_read_b64_tr_b16 v[100:101], v177 offset:46080
	ds_read_b64_tr_b16 v[102:103], v177 offset:46592
	v_exp_f32_e32 v118, v118
	v_exp_f32_e32 v119, v119
	ds_read_b128 v[160:163], v236 offset:8192
	ds_read_b128 v[132:135], v236 offset:12288
	v_mfma_f32_32x32x16_bf16 v[48:63], v[148:151], v[108:111], v[48:63]
	ds_read_b64_tr_b16 v[104:105], v177 offset:43008
	ds_read_b64_tr_b16 v[106:107], v177 offset:43520
	v_exp_f32_e32 v120, v120
	v_exp_f32_e32 v121, v121
	ds_read_b128 v[136:139], v237 offset:8192
	ds_read_b128 v[128:131], v237 offset:12288
	v_mfma_f32_32x32x16_bf16 v[32:47], v[148:151], v[190:193], v[32:47]
	ds_read_b64_tr_b16 v[108:109], v177 offset:47104
	ds_read_b64_tr_b16 v[110:111], v177 offset:47616
	v_exp_f32_e32 v122, v122
	v_exp_f32_e32 v123, v123
	v_mfma_f32_32x32x16_bf16 v[48:63], v[144:147], v[84:87], v[48:63]
	ds_read_b64_tr_b16 v[190:191], v177 offset:44032
	ds_read_b64_tr_b16 v[192:193], v177 offset:44544
	v_exp_f32_e32 v124, v124
	v_exp_f32_e32 v125, v125
	v_mfma_f32_32x32x16_bf16 v[32:47], v[144:147], v[88:91], v[32:47]
	ds_read_b64_tr_b16 v[84:85], v177 offset:48128
	ds_read_b64_tr_b16 v[86:87], v177 offset:48640
	v_exp_f32_e32 v126, v126
	v_exp_f32_e32 v127, v127
	s_waitcnt lgkmcnt(14)
;   #define RESC() do{ if(!NOMAX&&resc){ asm volatile("s_waitcnt lgkmcnt(0)":::"memory"); \
;       _Pragma("unroll") for(int d_=0;d_<2*VM;++d_) _Pragma("unroll") for(int r=0;r<16;++r)o[d_][r]*=wsf[crow(r,hi)]; } }while(0)
; template<int THRL,int VM,bool NOMAX> __device__ __forceinline__ void attn_unit(const bf16*Qb,const bf16*__restrict__ Kh,const bf16*__restrict__ Vh,bf16*Ob,const int NT,const int sp,float*wscr,char*shm){
;     ...
;   STEP(pB0,pB1,pA0,pA1,NT-1,false,false,false); RESC();
	v_mfma_f32_32x32x16_bf16 v[16:31], v[156:159], v[92:95], v[16:31]
	v_exp_f32_e32 v64, v64
	v_exp_f32_e32 v65, v65
	v_mfma_f32_32x32x16_bf16 v[0:15], v[156:159], v[170:173], v[0:15]
	v_exp_f32_e32 v66, v66
	v_exp_f32_e32 v67, v67
	v_mfma_f32_32x32x16_bf16 v[16:31], v[152:155], v[178:181], v[16:31]
	v_exp_f32_e32 v68, v68
	v_exp_f32_e32 v69, v69
	s_waitcnt lgkmcnt(12)
	v_mfma_f32_32x32x16_bf16 v[0:15], v[152:155], v[100:103], v[0:15]
	v_exp_f32_e32 v70, v70
	v_exp_f32_e32 v71, v71
	s_waitcnt lgkmcnt(8)
	v_mfma_f32_32x32x16_bf16 v[16:31], v[148:151], v[104:107], v[16:31]
	v_exp_f32_e32 v72, v72
	v_exp_f32_e32 v73, v73
	s_waitcnt lgkmcnt(4)
	v_mfma_f32_32x32x16_bf16 v[0:15], v[148:151], v[108:111], v[0:15]
	v_exp_f32_e32 v74, v74
	v_exp_f32_e32 v75, v75
	s_waitcnt lgkmcnt(2)
	v_mfma_f32_32x32x16_bf16 v[16:31], v[144:147], v[190:193], v[16:31]
	v_exp_f32_e32 v76, v76
	v_exp_f32_e32 v77, v77
	s_waitcnt lgkmcnt(0)
	v_mfma_f32_32x32x16_bf16 v[0:15], v[144:147], v[84:87], v[0:15]
	v_exp_f32_e32 v78, v78
	v_exp_f32_e32 v79, v79
	s_waitcnt vmcnt(0) lgkmcnt(0)
	s_barrier
	ds_read_b64_tr_b16 v[170:171], v168 offset:24576
	ds_read_b64_tr_b16 v[172:173], v168 offset:25088
	v_add_f32_e32 v88, v112, v113
	ds_read_b128 v[84:87], v188
	v_add_f32_e32 v88, v114, v88
	v_add_f32_e32 v88, v115, v88
	v_add_f32_e32 v88, v116, v88
	v_add_f32_e32 v104, v117, v88
	v_cvt_pk_bf16_f32 v156, v112, v113
	v_cvt_pk_bf16_f32 v157, v114, v115
	s_waitcnt lgkmcnt(0)
	v_mfma_f32_32x32x16_bf16 v[80:95], v[80:83], v[84:87], 0
	ds_read_b64_tr_b16 v[112:113], v168 offset:28672
	ds_read_b64_tr_b16 v[114:115], v168 offset:29184
	ds_read_b128 v[100:103], v188
	v_add_f32_e32 v104, v118, v104
	v_add_f32_e32 v104, v119, v104
	v_add_f32_e32 v104, v120, v104
	v_add_f32_e32 v144, v121, v104
	v_cvt_pk_bf16_f32 v158, v116, v117
	v_cvt_pk_bf16_f32 v159, v118, v119
	s_waitcnt lgkmcnt(0)
	v_mfma_f32_32x32x16_bf16 v[96:111], v[96:99], v[100:103], 0
	ds_read_b64_tr_b16 v[116:117], v168 offset:25600
	ds_read_b64_tr_b16 v[118:119], v168 offset:26112
	ds_read_b128 v[178:181], v188 offset:1024
	v_add_f32_e32 v144, v122, v144
	v_add_f32_e32 v144, v123, v144
	v_add_f32_e32 v144, v124, v144
	v_add_f32_e32 v144, v125, v144
	v_cvt_pk_bf16_f32 v152, v120, v121
	v_cvt_pk_bf16_f32 v153, v122, v123
	s_waitcnt lgkmcnt(0)
	v_mfma_f32_32x32x16_bf16 v[80:95], v[164:167], v[178:181], v[80:95]
	ds_read_b64_tr_b16 v[120:121], v168 offset:29696
	ds_read_b64_tr_b16 v[122:123], v168 offset:30208
	ds_read_b128 v[164:167], v188 offset:1024
	v_add_f32_e32 v144, v126, v144
	v_add_f32_e32 v144, v127, v144
	v_add_f32_e32 v144, v64, v144
	v_add_f32_e32 v144, v65, v144
	v_cvt_pk_bf16_f32 v154, v124, v125
	v_cvt_pk_bf16_f32 v155, v126, v127
	s_waitcnt lgkmcnt(0)
	v_mfma_f32_32x32x16_bf16 v[96:111], v[140:143], v[164:167], v[96:111]
	ds_read_b64_tr_b16 v[124:125], v168 offset:26624
	ds_read_b64_tr_b16 v[126:127], v168 offset:27136
	ds_read_b128 v[140:143], v188 offset:2048
	v_add_f32_e32 v144, v66, v144
	v_add_f32_e32 v144, v67, v144
	v_add_f32_e32 v144, v68, v144
	v_add_f32_e32 v144, v69, v144
	v_cvt_pk_bf16_f32 v148, v64, v65
	v_cvt_pk_bf16_f32 v149, v66, v67
	s_waitcnt lgkmcnt(0)
	v_mfma_f32_32x32x16_bf16 v[80:95], v[160:163], v[140:143], v[80:95]
	ds_read_b64_tr_b16 v[64:65], v168 offset:30720
	ds_read_b64_tr_b16 v[66:67], v168 offset:31232
	ds_read_b128 v[140:143], v188 offset:2048
	v_add_f32_e32 v144, v70, v144
	v_add_f32_e32 v144, v71, v144
	v_add_f32_e32 v144, v72, v144
	v_add_f32_e32 v144, v73, v144
	v_cvt_pk_bf16_f32 v150, v68, v69
	v_cvt_pk_bf16_f32 v151, v70, v71
	s_waitcnt lgkmcnt(0)
	v_mfma_f32_32x32x16_bf16 v[96:111], v[132:135], v[140:143], v[96:111]
	ds_read_b64_tr_b16 v[68:69], v168 offset:27648
	ds_read_b64_tr_b16 v[70:71], v168 offset:28160
	ds_read_b128 v[132:135], v188 offset:3072
	v_add_f32_e32 v140, v74, v144
	v_add_f32_e32 v140, v75, v140
	v_add_f32_e32 v140, v76, v140
	v_add_f32_e32 v140, v77, v140
	v_cvt_pk_bf16_f32 v144, v72, v73
	v_cvt_pk_bf16_f32 v145, v74, v75
	s_waitcnt lgkmcnt(0)
	v_mfma_f32_32x32x16_bf16 v[80:95], v[136:139], v[132:135], v[80:95]
	ds_read_b64_tr_b16 v[72:73], v168 offset:31744
	ds_read_b64_tr_b16 v[74:75], v168 offset:32256
	ds_read_b128 v[132:135], v188 offset:3072
	v_add_f32_e32 v136, v78, v140
	v_add_f32_e32 v136, v79, v136
	v_add_f32_e32 v136, 0, v136
	v_cvt_pk_bf16_f32 v146, v76, v77
	v_cvt_pk_bf16_f32 v147, v78, v79
	s_waitcnt lgkmcnt(0)
	v_mfma_f32_32x32x16_bf16 v[96:111], v[128:131], v[132:135], v[96:111]
	v_mfma_f32_32x32x16_bf16 v[48:63], v[156:159], v[170:173], v[48:63]
	ds_read_b64_tr_b16 v[76:77], v168 offset:32768
	ds_read_b64_tr_b16 v[78:79], v168 offset:33280
	v_exp_f32_e32 v80, v80
	v_exp_f32_e32 v81, v81
	v_mfma_f32_32x32x16_bf16 v[32:47], v[156:159], v[112:115], v[32:47]
	ds_read_b64_tr_b16 v[128:129], v168 offset:36864
	ds_read_b64_tr_b16 v[130:131], v168 offset:37376
	v_exp_f32_e32 v82, v82
	v_exp_f32_e32 v83, v83
	v_mfma_f32_32x32x16_bf16 v[48:63], v[152:155], v[116:119], v[48:63]
	ds_read_b64_tr_b16 v[112:113], v168 offset:33792
	ds_read_b64_tr_b16 v[114:115], v168 offset:34304
	v_exp_f32_e32 v84, v84
	v_exp_f32_e32 v85, v85
	v_mfma_f32_32x32x16_bf16 v[32:47], v[152:155], v[120:123], v[32:47]
	ds_read_b64_tr_b16 v[116:117], v168 offset:37888
	ds_read_b64_tr_b16 v[118:119], v168 offset:38400
	v_exp_f32_e32 v86, v86
	v_exp_f32_e32 v87, v87
	v_mfma_f32_32x32x16_bf16 v[48:63], v[148:151], v[124:127], v[48:63]
	ds_read_b64_tr_b16 v[120:121], v168 offset:34816
	ds_read_b64_tr_b16 v[122:123], v168 offset:35328
	v_exp_f32_e32 v88, v88
	v_exp_f32_e32 v89, v89
	v_mfma_f32_32x32x16_bf16 v[32:47], v[148:151], v[64:67], v[32:47]
	ds_read_b64_tr_b16 v[124:125], v168 offset:38912
	ds_read_b64_tr_b16 v[126:127], v168 offset:39424
	v_exp_f32_e32 v90, v90
	v_exp_f32_e32 v91, v91
	v_mfma_f32_32x32x16_bf16 v[48:63], v[144:147], v[68:71], v[48:63]
	ds_read_b64_tr_b16 v[64:65], v168 offset:35840
	ds_read_b64_tr_b16 v[66:67], v168 offset:36352
	v_exp_f32_e32 v92, v92
	v_exp_f32_e32 v93, v93
	v_mfma_f32_32x32x16_bf16 v[32:47], v[144:147], v[72:75], v[32:47]
	ds_read_b64_tr_b16 v[68:69], v168 offset:39936
	ds_read_b64_tr_b16 v[70:71], v168 offset:40448
	v_exp_f32_e32 v94, v94
	v_exp_f32_e32 v95, v95
	s_waitcnt lgkmcnt(14)
; #define SBAR() __builtin_amdgcn_sched_barrier(0)
;   #define RESC() do{ if(!NOMAX&&resc){ asm volatile("s_waitcnt lgkmcnt(0)":::"memory"); \
;       _Pragma("unroll") for(int d_=0;d_<2*VM;++d_) _Pragma("unroll") for(int r=0;r<16;++r)o[d_][r]*=wsf[crow(r,hi)]; } }while(0)
;   #define PKW(P,B) cvtpk_s(P[B],P[B+1])
; __device__ __forceinline__ void pv(f32x16*o,int vb,bf16x8 pa0,bf16x8 pa1,bf16x8 pa2,bf16x8 pa3){
;   #pragma unroll
;   for(int d0=0;d0<2;++d0){s16x4 lo[4],hi[4];
;     #pragma unroll
;     for(int ks=0;ks<4;++ks){
;       asm volatile("ds_read_b64_tr_b16 %0,%1 offset:%c2":"=&v"(lo[ks]):"v"(vb),"i"(d0*4096+ks*1024):"memory");
;       asm volatile("ds_read_b64_tr_b16 %0,%1 offset:%c2":"=&v"(hi[ks]):"v"(vb),"i"(d0*4096+ks*1024+512):"memory");}
;     asm volatile("s_waitcnt lgkmcnt(0)":::"memory");SBAR();
;     ...
;     o[d0]=__builtin_amdgcn_mfma_f32_32x32x16_bf16(pa0,PK(0),o[d0],0,0,0);
;     o[d0]=__builtin_amdgcn_mfma_f32_32x32x16_bf16(pa1,PK(1),o[d0],0,0,0);
;     o[d0]=__builtin_amdgcn_mfma_f32_32x32x16_bf16(pa2,PK(2),o[d0],0,0,0);
;     o[d0]=__builtin_amdgcn_mfma_f32_32x32x16_bf16(pa3,PK(3),o[d0],0,0,0);
;     ...
;   }
; }
; template<int THRL,int VM,bool NOMAX> __device__ __forceinline__ void attn_unit(const bf16*Qb,const bf16*__restrict__ Kh,const bf16*__restrict__ Vh,bf16*Ob,const int NT,const int sp,float*wscr,char*shm){
;     ...
;   STEP(pB0,pB1,pA0,pA1,NT-1,false,false,false); RESC();
;   { float sacc=pB0[0]+pB0[1]; _Pragma("unroll") for(int r=2;r<16;++r)sacc+=pB0[r]; _Pragma("unroll") for(int r=0;r<16;++r)sacc+=pB1[r]; l_reg+=sacc;
;     pw0=(u32x4){PKW(pB0,0),PKW(pB0,2),PKW(pB0,4),PKW(pB0,6)};pw1=(u32x4){PKW(pB0,8),PKW(pB0,10),PKW(pB0,12),PKW(pB0,14)};pw2=(u32x4){PKW(pB1,0),PKW(pB1,2),PKW(pB1,4),PKW(pB1,6)};pw3=(u32x4){PKW(pB1,8),PKW(pB1,10),PKW(pB1,12),PKW(pB1,14)};
;     SBAR(); pv(o,vb0+VM*sl_cur,PAF(0),PAF(1),PAF(2),PAF(3)); if constexpr(VM==2) pv(o+2,vb0+VM*sl_cur+8192,PAF(0),PAF(1),PAF(2),PAF(3)); }
;     ...
;   {auto rr=__builtin_amdgcn_permlane32_swap(__float_as_uint(l_reg),__float_as_uint(l_reg),false,false);l_reg=__uint_as_float(rr[0])+__uint_as_float(rr[1]);}
;   if(hi==0)wsf[32+r32]=l_reg;asm volatile("s_waitcnt lgkmcnt(0)":::"memory");
	v_mfma_f32_32x32x16_bf16 v[16:31], v[156:159], v[76:79], v[16:31]
	v_exp_f32_e32 v96, v96
	v_exp_f32_e32 v97, v97
	s_waitcnt lgkmcnt(12)
	v_mfma_f32_32x32x16_bf16 v[0:15], v[156:159], v[128:131], v[0:15]
	v_exp_f32_e32 v98, v98
	v_exp_f32_e32 v99, v99
	s_waitcnt lgkmcnt(10)
	v_mfma_f32_32x32x16_bf16 v[16:31], v[152:155], v[112:115], v[16:31]
	v_exp_f32_e32 v100, v100
	v_exp_f32_e32 v101, v101
	s_waitcnt lgkmcnt(8)
	v_mfma_f32_32x32x16_bf16 v[0:15], v[152:155], v[116:119], v[0:15]
	v_exp_f32_e32 v102, v102
	v_exp_f32_e32 v103, v103
	s_waitcnt lgkmcnt(6)
	v_mfma_f32_32x32x16_bf16 v[16:31], v[148:151], v[120:123], v[16:31]
	v_exp_f32_e32 v104, v104
	v_exp_f32_e32 v105, v105
	s_waitcnt lgkmcnt(4)
	v_mfma_f32_32x32x16_bf16 v[0:15], v[148:151], v[124:127], v[0:15]
	v_exp_f32_e32 v106, v106
	v_exp_f32_e32 v107, v107
	s_waitcnt lgkmcnt(2)
	v_mfma_f32_32x32x16_bf16 v[16:31], v[144:147], v[64:67], v[16:31]
	v_exp_f32_e32 v108, v108
	v_exp_f32_e32 v109, v109
	s_waitcnt lgkmcnt(0)
	v_mfma_f32_32x32x16_bf16 v[0:15], v[144:147], v[68:71], v[0:15]
	v_exp_f32_e32 v110, v110
	v_exp_f32_e32 v111, v111
	v_add_f32_e32 v64, v80, v81
	v_add_f32_e32 v64, v82, v64
	v_add_f32_e32 v64, v83, v64
	v_add_f32_e32 v64, v84, v64
	v_add_f32_e32 v64, v85, v64
	v_add_f32_e32 v64, v86, v64
	v_add_f32_e32 v64, v87, v64
	v_add_f32_e32 v64, v88, v64
	v_add_f32_e32 v64, v89, v64
	v_add_f32_e32 v64, v90, v64
	v_add_f32_e32 v64, v91, v64
	v_add_f32_e32 v64, v92, v64
	v_add_f32_e32 v64, v93, v64
	v_add_f32_e32 v64, v94, v64
	v_add_f32_e32 v64, v95, v64
	v_add_f32_e32 v64, v64, v96
	v_add_f32_e32 v64, v97, v64
	v_add_f32_e32 v64, v98, v64
	v_add_f32_e32 v64, v99, v64
	v_add_f32_e32 v64, v100, v64
	v_add_f32_e32 v64, v101, v64
	v_add_f32_e32 v64, v102, v64
	v_add_f32_e32 v64, v103, v64
	v_add_f32_e32 v64, v104, v64
	v_add_f32_e32 v64, v105, v64
	v_add_f32_e32 v64, v106, v64
	v_add_f32_e32 v64, v107, v64
	v_add_f32_e32 v64, v108, v64
	v_add_f32_e32 v64, v109, v64
	v_add_f32_e32 v64, v110, v64
	v_add_f32_e32 v64, v111, v64
	v_add_f32_e32 v65, v174, v136
	v_add_f32_e32 v64, v65, v64
	v_cvt_pk_bf16_f32 v66, v80, v81
	v_cvt_pk_bf16_f32 v67, v82, v83
	v_cvt_pk_bf16_f32 v68, v84, v85
	v_cvt_pk_bf16_f32 v69, v86, v87
	v_cvt_pk_bf16_f32 v70, v88, v89
	v_cvt_pk_bf16_f32 v71, v90, v91
	v_cvt_pk_bf16_f32 v72, v92, v93
	v_cvt_pk_bf16_f32 v73, v94, v95
	v_cvt_pk_bf16_f32 v74, v96, v97
	v_cvt_pk_bf16_f32 v75, v98, v99
	v_cvt_pk_bf16_f32 v76, v100, v101
	v_cvt_pk_bf16_f32 v77, v102, v103
	v_cvt_pk_bf16_f32 v78, v104, v105
	v_cvt_pk_bf16_f32 v79, v106, v107
	v_cvt_pk_bf16_f32 v80, v108, v109
	v_cvt_pk_bf16_f32 v81, v110, v111
	v_add_u32_e32 v65, 0x4000, v176
	ds_read_b64_tr_b16 v[82:83],v65 offset:0
	ds_read_b64_tr_b16 v[84:85],v65 offset:512
	ds_read_b64_tr_b16 v[86:87],v65 offset:1024
	ds_read_b64_tr_b16 v[88:89],v65 offset:1536
	ds_read_b64_tr_b16 v[90:91],v65 offset:2048
	ds_read_b64_tr_b16 v[92:93],v65 offset:2560
	ds_read_b64_tr_b16 v[94:95],v65 offset:3072
	ds_read_b64_tr_b16 v[96:97],v65 offset:3584
	s_waitcnt lgkmcnt(0)
	s_nop 0
	v_mfma_f32_32x32x16_bf16 v[48:63], v[66:69], v[82:85], v[48:63]
	ds_read_b64_tr_b16 v[82:83],v65 offset:4096
	ds_read_b64_tr_b16 v[84:85],v65 offset:4608
	v_mfma_f32_32x32x16_bf16 v[48:63], v[70:73], v[86:89], v[48:63]
	ds_read_b64_tr_b16 v[86:87],v65 offset:5120
	ds_read_b64_tr_b16 v[88:89],v65 offset:5632
	v_mfma_f32_32x32x16_bf16 v[48:63], v[74:77], v[90:93], v[48:63]
	ds_read_b64_tr_b16 v[90:91],v65 offset:6144
	ds_read_b64_tr_b16 v[92:93],v65 offset:6656
	ds_read_b64_tr_b16 v[98:99],v65 offset:7168
	ds_read_b64_tr_b16 v[100:101],v65 offset:7680
	s_waitcnt lgkmcnt(0)
	v_mfma_f32_32x32x16_bf16 v[48:63], v[78:81], v[94:97], v[48:63]
	v_mfma_f32_32x32x16_bf16 v[32:47], v[66:69], v[82:85], v[32:47]
	v_add_u32_e32 v65, 0x6000, v176
	ds_read_b64_tr_b16 v[82:83],v65 offset:0
	ds_read_b64_tr_b16 v[84:85],v65 offset:512
	v_mfma_f32_32x32x16_bf16 v[32:47], v[70:73], v[86:89], v[32:47]
	ds_read_b64_tr_b16 v[86:87],v65 offset:1024
	ds_read_b64_tr_b16 v[88:89],v65 offset:1536
	v_mfma_f32_32x32x16_bf16 v[32:47], v[74:77], v[90:93], v[32:47]
	ds_read_b64_tr_b16 v[90:91],v65 offset:2048
	ds_read_b64_tr_b16 v[92:93],v65 offset:2560
	ds_read_b64_tr_b16 v[94:95],v65 offset:3072
	ds_read_b64_tr_b16 v[96:97],v65 offset:3584
	s_waitcnt lgkmcnt(0)
	v_mfma_f32_32x32x16_bf16 v[32:47], v[78:81], v[98:101], v[32:47]
	v_mfma_f32_32x32x16_bf16 v[16:31], v[66:69], v[82:85], v[16:31]
	ds_read_b64_tr_b16 v[82:83],v65 offset:4096
	ds_read_b64_tr_b16 v[84:85],v65 offset:4608
	v_mfma_f32_32x32x16_bf16 v[16:31], v[70:73], v[86:89], v[16:31]
	ds_read_b64_tr_b16 v[86:87],v65 offset:5120
	ds_read_b64_tr_b16 v[88:89],v65 offset:5632
	v_mfma_f32_32x32x16_bf16 v[16:31], v[74:77], v[90:93], v[16:31]
	ds_read_b64_tr_b16 v[90:91],v65 offset:6144
	ds_read_b64_tr_b16 v[92:93],v65 offset:6656
	ds_read_b64_tr_b16 v[98:99],v65 offset:7168
	ds_read_b64_tr_b16 v[100:101],v65 offset:7680
	s_waitcnt lgkmcnt(0)
	v_mfma_f32_32x32x16_bf16 v[16:31], v[78:81], v[94:97], v[16:31]
	v_mfma_f32_32x32x16_bf16 v[0:15], v[66:69], v[82:85], v[0:15]
	v_mov_b32_e32 v65, v64
	s_nop 1
	v_permlane32_swap_b32_e32 v64, v65
	v_cmp_gt_u32_e32 vcc, 32, v187
	v_mfma_f32_32x32x16_bf16 v[0:15], v[70:73], v[86:89], v[0:15]
	v_mfma_f32_32x32x16_bf16 v[0:15], v[74:77], v[90:93], v[0:15]
	v_mfma_f32_32x32x16_bf16 v[0:15], v[78:81], v[98:101], v[0:15]
	s_and_saveexec_b64 s[16:17], vcc
	s_cbranch_execz .LBB0_859
	v_add_f32_e32 v64, v64, v65
	v_lshl_add_u32 v65, v186, 2, s34
	ds_write_b32 v65, v64 offset:128
	s_branch .LBB0_859

; #define WAIT_BAR(N) asm volatile("s_waitcnt vmcnt(" #N ") lgkmcnt(0)\n\ts_barrier":::"memory")
;   #define DMA_K(t,slot) glds16(ksrc+(long)(t)*KVBLK*KVP,(unsigned)__builtin_amdgcn_readfirstlane(kdst+(slot)))
;   #define DMA_V(t,slot) do{ glds16(vsrc+(long)(t)*KVBLK*KVP,(unsigned)__builtin_amdgcn_readfirstlane(vdst+VM*(slot))); if constexpr(VM==2) glds16(vsrc+64+(long)(t)*KVBLK*KVP,(unsigned)__builtin_amdgcn_readfirstlane(vdst+VM*(slot)+8192)); }while(0)
; template<int THRL,int VM,bool NOMAX> __device__ __forceinline__ void attn_unit(const bf16*Qb,const bf16*__restrict__ Kh,const bf16*__restrict__ Vh,bf16*Ob,const int NT,const int sp,float*wscr,char*shm){
;     ...
;   const bf16*Qw=Qb+(long)(wid*QBLK)*QOP;
;   const unsigned lds0=(unsigned)(uintptr_t)shm;
;   constexpr int LDS_WS_=LDS_V+3*VM*SLOTB, LDS_OST_=LDS_WS_+NW*64*4;
;   float*wsf=(float*)(shm+LDS_WS_)+wid*64;
;   const bf16*ksrc=Kh+(long)lane*KVP+wid*8;
;   const bf16*vsrc=Vh+(long)(16*(wid&3)+(lane>>2))*KVP+(wid>>2)*32+(lane&3)*8;
;   const unsigned kdst=lds0+LDS_K+wid*1024, vdst=lds0+LDS_V+wid*1024;
;     ...
;   const int vb0=(int)(lds0+LDS_V)+((lane>>4)&1)*32+(lane&3)*8+(4*hi+((lane&15)>>2))*64;
;   const char*Kbase=shm+LDS_K; bf16x8 kf[8];
;   const lds_cptr shm3=(lds_cptr)shm; const lds_cptr kp0=shm3+LDS_K+hi*1024+r32*16; const lds_cptr vp0=shm3+LDS_V+((lane>>4)&1)*32+(lane&3)*8+(4*hi+((lane&15)>>2))*64;
;   if(wid>=4)__builtin_amdgcn_s_setprio(1);
;   DMA_K(0,0);DMA_V(0,0);DMA_K(1,SLOTB);
;   bf16x8 qr[4];
;   #pragma unroll
;   for(int d0=0;d0<4;++d0)qr[d0]=*reinterpret_cast<const bf16x8*>(&Qw[(long)r32*QOP+d0*16+hi*8]);
;   const lds_cptr qpk=shm3+LDS_OST_+wid*4096+lane*16;
;   if constexpr(VM==2){
;     #pragma unroll
;     for(int d0=0;d0<4;++d0)*(__attribute__((address_space(3))) bf16x8*)(const_cast<__attribute__((address_space(3))) char*>(qpk)+d0*1024)=qr[d0]; }
;   float mhat=0.f,l_reg=0.f;f32x16 o[2*VM];
;   #pragma unroll
;   for(int d_=0;d_<2*VM;++d_)o[d_]=f32x16{};
;  f32x16 negm=f32x16{}; if constexpr(VM==1){asm volatile("":"+v"(negm));}
;   bool resc=false;
;     ...
;   f32x16 pA0,pA1,pB0,pB1;
;   int sl_prev=0,sl_cur=0,sl_next=SLOTB;
;     ...
;   DMA_K(2,2*SLOTB);
;   WAIT_BAR(3);
;   qkt(pA0,pA1,Kbase,qr,negm,r32,hi);asm volatile("s_nop 15\n\ts_nop 7":"+v"(pA0),"+v"(pA1));
;   START(pA0,pA1);
;   _Pragma("unroll") for(int r=0;r<16;++r)pA1[r]=__builtin_amdgcn_exp2f(pA1[r]);
;   WAIT_BAR(0);
.LBB0_873:
	s_xor_b64 s[6:7], s[16:17], -1
	s_lshl_b32 s16, s8, 7
	s_add_u32 s35, s83, s16
	s_addc_u32 s88, s84, 0
	s_add_u32 s16, s0, s16
	s_addc_u32 s17, s1, 0
	s_lshl_b32 s86, s85, 5
	v_and_b32_e32 v187, 63, v32
	s_ashr_i32 s87, s86, 31
	s_lshl_b64 s[86:87], s[86:87], 11
	v_mul_u32_u24_e32 v0, 0x500, v187
	s_add_u32 s86, s35, s86
	v_lshlrev_b32_e32 v168, 1, v0
	s_addc_u32 s87, s88, s87
	v_lshl_add_u64 v[0:1], s[16:17], 0, v[168:169]
	s_lshl_b32 s16, s85, 3
	s_ashr_i32 s17, s16, 31
	v_lshl_add_u64 v[54:55], s[16:17], 1, v[0:1]
	v_and_b32_e32 v246, 63, v210
	v_lshrrev_b32_e32 v247, 6, v210
	v_lshrrev_b32_e32 v248, 3, v246
	v_lshl_add_u32 v248, v247, 3, v248
	v_and_b32_e32 v249, 1, v247
	v_lshrrev_b32_e32 v250, 4, v246
	v_lshl_or_b32 v249, v249, 2, v250
	v_and_b32_e32 v250, 7, v246
	v_xor_b32_e32 v250, v250, v249
	v_sub_u32_e32 v248, v248, v246
	v_mul_i32_i24_e32 v248, 0xa00, v248
	v_sub_u32_e32 v250, v250, v247
	v_lshl_add_u32 v248, v250, 4, v248
	v_ashrrev_i32_e32 v249, 31, v248
	v_lshl_add_u64 v[54:55], v[248:249], 0, v[54:55]
	s_mov_b64 s[16:17], 0x200
	v_lshl_add_u64 v[174:175], v[54:55], 0, s[16:17]
	s_lshl_b32 s16, s85, 4
	v_bfe_u32 v0, v32, 2, 4
	v_and_or_b32 v0, s16, 48, v0
	s_ashr_i32 s16, s34, 3
	v_mul_u32_u24_e32 v0, 0x500, v0
	s_andn2_b32 s16, s16, 31
	v_lshlrev_b32_e32 v168, 1, v0
	s_ashr_i32 s17, s16, 31
	v_lshlrev_b32_e32 v2, 3, v32
	s_lshl_b32 s35, s85, 10
	v_lshl_add_u64 v[0:1], s[0:1], 0, v[168:169]
	v_and_b32_e32 v190, 24, v2
	s_cmp_lg_u32 0, -1
	v_lshl_add_u64 v[0:1], s[16:17], 1, v[0:1]
	v_lshlrev_b32_e32 v168, 1, v190
	s_cselect_b32 s16, 0, 0
	v_lshl_add_u64 v[56:57], v[0:1], 0, v[168:169]
	s_add_i32 s17, s35, s16
	s_mov_b32 s88, m0
	s_mov_b32 m0, s17
	s_nop 0
	global_load_lds_dwordx4 v[174:175], off
	s_mov_b32 m0, s88
	v_lshl_add_u64 v[170:171], v[56:57], 0, s[12:13]
	s_add_i32 s16, s17, 0x6000
	s_mov_b32 s88, m0
	s_mov_b32 m0, s16
	s_nop 0
	global_load_lds_dwordx4 v[170:171], off
	s_mov_b32 m0, s88
	v_and_b32_e32 v186, 31, v32
	v_lshl_add_u64 v[172:173], v[56:57], 0, s[14:15]
	s_add_i32 s88, s17, 0x8000
	s_mov_b32 s89, m0
	s_mov_b32 m0, s88
	s_nop 0
	global_load_lds_dwordx4 v[172:173], off
	s_mov_b32 m0, s89
	v_lshl_add_u64 v[0:1], v[54:55], 0, s[36:37]
	v_bfe_u32 v185, v32, 5, 1
	s_add_i32 s88, s17, 0x2000
	s_mov_b32 s89, m0
	s_mov_b32 m0, s88
	s_nop 0
	global_load_lds_dwordx4 v[0:1], off
	s_mov_b32 m0, s89
	v_lshlrev_b32_e32 v0, 11, v186
	v_lshl_or_b32 v4, v185, 4, v0
	global_load_dwordx4 v[0:3], v4, s[86:87] offset:1024
	global_load_dwordx4 v[34:37], v4, s[86:87] offset:1056
	global_load_dwordx4 v[38:41], v4, s[86:87] offset:1088
	global_load_dwordx4 v[42:45], v4, s[86:87] offset:1120
	s_lshl_b32 s85, s85, 12
	s_add_i32 s85, s85, 0
	v_lshlrev_b32_e32 v6, 4, v187
	s_add_i32 s85, s85, 0x12800
	v_add_u32_e32 v168, s85, v6
	v_lshlrev_b32_e32 v4, 10, v185
	v_lshlrev_b32_e32 v5, 4, v186
	v_add3_u32 v189, 0, v4, v5
	v_bfe_u32 v246, v189, 4, 5
	v_bfe_u32 v247, v189, 10, 1
	v_bfe_u32 v248, v189, 5, 1
	v_bfe_u32 v249, v189, 6, 2
	v_xor_b32_e32 v247, v247, v248
	v_lshlrev_b32_e32 v246, 7, v246
	v_lshl_or_b32 v246, v247, 4, v246
	v_lshl_add_u32 v234, v249, 5, v246
	v_xor_b32_e32 v248, 1, v249
	v_lshl_add_u32 v235, v248, 5, v246
	v_xor_b32_e32 v248, 2, v249
	v_lshl_add_u32 v236, v248, 5, v246
	v_xor_b32_e32 v248, 3, v249
	v_lshl_add_u32 v237, v248, 5, v246
	v_lshl_add_u64 v[4:5], v[54:55], 0, s[40:41]
	s_add_i32 s86, s17, 0x4000
	v_lshlrev_b32_e32 v33, 1, v32
	v_lshlrev_b32_e32 v32, 4, v32
	v_and_b32_e32 v191, 32, v33
	v_and_b32_e32 v32, 0xc0, v32
	v_lshl_or_b32 v192, v185, 8, v32
	v_add_u32_e32 v32, 0, v191
	v_add3_u32 v188, v32, v190, v192
	v_lshl_add_u64 v[32:33], v[54:55], 0, s[42:43]
	s_add_i32 s88, s17, 0xa000
	s_add_i32 s90, s17, 0xc000
	v_mov_b32_e32 v193, 0
	s_mov_b32 s89, 0
	s_movk_i32 s87, 0x2000
	v_lshl_add_u64 v[176:177], v[56:57], 0, s[50:51]
	v_lshl_add_u64 v[178:179], v[56:57], 0, s[52:53]
	v_lshl_add_u64 v[180:181], v[54:55], 0, s[54:55]
	v_mov_b32_e32 v54, v193
	v_mov_b32_e32 v55, v193
	v_mov_b32_e32 v58, v193
	v_mov_b32_e32 v59, v193
	v_mov_b32_e32 v60, v193
	v_mov_b32_e32 v61, v193
	v_mov_b32_e32 v62, v193
	v_mov_b32_e32 v63, v193
	s_waitcnt vmcnt(3)
	ds_write_b128 v168, v[0:3]
	s_waitcnt vmcnt(2)
	ds_write_b128 v168, v[34:37] offset:1024
	s_waitcnt vmcnt(1)
	ds_write_b128 v168, v[38:41] offset:2048
	s_waitcnt vmcnt(0)
	ds_write_b128 v168, v[42:45] offset:3072
	s_mov_b32 s85, m0
	s_mov_b32 m0, s86
	s_nop 0
	global_load_lds_dwordx4 v[4:5], off
	s_mov_b32 m0, s85
	s_waitcnt vmcnt(3) lgkmcnt(0)
	s_barrier
	ds_read_b128 v[4:7], v234
	ds_read_b128 v[8:11], v234 offset:4096
	s_waitcnt lgkmcnt(1)
	v_mfma_f32_32x32x16_bf16 v[16:31], v[4:7], v[0:3], 0
	ds_read_b128 v[46:49], v235
	ds_read_b128 v[50:53], v235 offset:4096
	s_mov_b32 s85, -1
	s_movk_i32 s86, 0x4000
	s_waitcnt lgkmcnt(2)
	v_mfma_f32_32x32x16_bf16 v[0:15], v[8:11], v[0:3], 0
	s_waitcnt lgkmcnt(1)
	v_mfma_f32_32x32x16_bf16 v[16:31], v[46:49], v[34:37], v[16:31]
	s_waitcnt lgkmcnt(0)
	v_mfma_f32_32x32x16_bf16 v[0:15], v[50:53], v[34:37], v[0:15]
	ds_read_b128 v[34:37], v236
	ds_read_b128 v[46:49], v236 offset:4096
	s_waitcnt lgkmcnt(1)
	v_mfma_f32_32x32x16_bf16 v[16:31], v[34:37], v[38:41], v[16:31]
	ds_read_b128 v[34:37], v237 offset:4096
	ds_read_b128 v[50:53], v237
	s_waitcnt lgkmcnt(2)
	v_mfma_f32_32x32x16_bf16 v[0:15], v[46:49], v[38:41], v[0:15]
	v_lshl_add_u64 v[38:39], v[56:57], 0, s[44:45]
	v_lshl_add_u64 v[40:41], v[56:57], 0, s[48:49]
	v_mov_b32_e32 v48, 0
	v_mov_b32_e32 v49, v193
	v_mov_b32_e32 v56, v193
	v_mov_b32_e32 v57, v193
	v_mov_b32_e32 v46, v193
	s_waitcnt lgkmcnt(0)
	v_mfma_f32_32x32x16_bf16 v[16:31], v[50:53], v[42:45], v[16:31]
	v_mov_b32_e32 v50, v193
	v_mov_b32_e32 v51, v193
	v_mov_b32_e32 v52, v193
	v_mov_b32_e32 v53, v193
	v_mov_b32_e32 v47, v193
	v_mfma_f32_32x32x16_bf16 v[0:15], v[34:37], v[42:45], v[0:15]
	s_nop 15
	s_nop 7
	s_waitcnt vmcnt(0) lgkmcnt(0)
	s_barrier
; #define WAIT_BAR(N) asm volatile("s_waitcnt vmcnt(" #N ") lgkmcnt(0)\n\ts_barrier":::"memory")
;   #define DMA_K(t,slot) glds16(ksrc+(long)(t)*KVBLK*KVP,(unsigned)__builtin_amdgcn_readfirstlane(kdst+(slot)))
;   #define DMA_V(t,slot) do{ glds16(vsrc+(long)(t)*KVBLK*KVP,(unsigned)__builtin_amdgcn_readfirstlane(vdst+VM*(slot))); if constexpr(VM==2) glds16(vsrc+64+(long)(t)*KVBLK*KVP,(unsigned)__builtin_amdgcn_readfirstlane(vdst+VM*(slot)+8192)); }while(0)
;   #define RESC() do{ if(!NOMAX&&resc){ asm volatile("s_waitcnt lgkmcnt(0)":::"memory"); \
;       _Pragma("unroll") for(int d_=0;d_<2*VM;++d_) _Pragma("unroll") for(int r=0;r<16;++r)o[d_][r]*=wsf[crow(r,hi)]; } }while(0)
;   #define ROT() do{sl_prev=sl_cur;sl_cur=sl_next;sl_next=(sl_next==(NSLOT-1)*SLOTB)?0:sl_next+SLOTB;}while(0)
; template<int THRL,int VM,bool NOMAX> __device__ __forceinline__ void attn_unit(const bf16*Qb,const bf16*__restrict__ Kh,const bf16*__restrict__ Vh,bf16*Ob,const int NT,const int sp,float*wscr,char*shm){
;     ...
;   DMA_K(3,0);DMA_V(1,SLOTB);
;   ROT();
;   kload8(kf,kp0+sl_cur);
;   if constexpr(VM==2){WAIT_BAR(3);}else{WAIT_BAR(2);}
;   s16x4 vlo[8],vhi[8]; u32x4 pw0,pw1,pw2,pw3;
;     ...
;   int t=1;
;   for(;t+5<NT;t+=2){
;     STEP(pB0,pB1,pA0,pA1,t,true,true,true);     if constexpr(VM==2){WAIT_BAR(3);}else{WAIT_BAR(2);} RESC(); ROT();
;     STEP(pA0,pA1,pB0,pB1,t+1,true,true,true);   if constexpr(VM==2){WAIT_BAR(3);}else{WAIT_BAR(2);} RESC(); ROT();
	s_mov_b32 s91, m0
	s_mov_b32 m0, s17
	s_nop 0
	global_load_lds_dwordx4 v[32:33], off
	s_mov_b32 m0, s91
	v_mov_b32_e32 v32, 0
	s_mov_b32 s91, m0
	s_mov_b32 m0, s88
	s_nop 0
	global_load_lds_dwordx4 v[38:39], off
	s_mov_b32 m0, s91
	s_mov_b32 s88, m0
	s_mov_b32 m0, s90
	s_nop 0
	global_load_lds_dwordx4 v[40:41], off
	s_mov_b32 m0, s88
	ds_read_b128 v[100:103], v234 offset:8192
	ds_read_b128 v[96:99], v234 offset:12288
	ds_read_b128 v[164:167], v235 offset:8192
	ds_read_b128 v[160:163], v235 offset:12288
	ds_read_b128 v[140:143], v236 offset:8192
	ds_read_b128 v[136:139], v236 offset:12288
	ds_read_b128 v[132:135], v237 offset:8192
	ds_read_b128 v[128:131], v237 offset:12288
	v_exp_f32_e32 v80, v16
	v_exp_f32_e32 v81, v17
	v_exp_f32_e32 v82, v18
	v_exp_f32_e32 v83, v19
	v_exp_f32_e32 v84, v20
	v_exp_f32_e32 v85, v21
	v_exp_f32_e32 v86, v22
	v_exp_f32_e32 v87, v23
	v_exp_f32_e32 v88, v24
	v_exp_f32_e32 v89, v25
	v_exp_f32_e32 v90, v26
	v_exp_f32_e32 v91, v27
	v_exp_f32_e32 v92, v28
	v_exp_f32_e32 v93, v29
	v_exp_f32_e32 v94, v30
	v_exp_f32_e32 v95, v31
	v_exp_f32_e32 v64, v0
	v_exp_f32_e32 v65, v1
	v_exp_f32_e32 v66, v2
	v_exp_f32_e32 v67, v3
	v_exp_f32_e32 v68, v4
	v_exp_f32_e32 v69, v5
	v_exp_f32_e32 v70, v6
	v_exp_f32_e32 v71, v7
	v_exp_f32_e32 v72, v8
	v_exp_f32_e32 v73, v9
	v_exp_f32_e32 v74, v10
	v_exp_f32_e32 v75, v11
	v_exp_f32_e32 v76, v12
	v_exp_f32_e32 v77, v13
	v_exp_f32_e32 v78, v14
	v_exp_f32_e32 v79, v15
	ds_read_b128 v[218:221], v168
	ds_read_b128 v[222:225], v168 offset:1024
	ds_read_b128 v[226:229], v168 offset:2048
	ds_read_b128 v[230:233], v168 offset:3072
	s_waitcnt vmcnt(3) lgkmcnt(0)
	s_barrier
	v_mov_b32_e32 v33, v193
	v_mov_b32_e32 v34, v193
	v_mov_b32_e32 v35, v193
	v_mov_b32_e32 v36, v193
	v_mov_b32_e32 v37, v193
	v_mov_b32_e32 v38, v193
	v_mov_b32_e32 v39, v193
	v_mov_b32_e32 v40, v193
	v_mov_b32_e32 v41, v193
	v_mov_b32_e32 v42, v193
	v_mov_b32_e32 v43, v193
	v_mov_b32_e32 v44, v193
	v_mov_b32_e32 v45, v193
	v_mov_b32_e32 v16, 0
	v_mov_b32_e32 v17, v193
	v_mov_b32_e32 v18, v193
	v_mov_b32_e32 v19, v193
	v_mov_b32_e32 v20, v193
	v_mov_b32_e32 v21, v193
	v_mov_b32_e32 v22, v193
	v_mov_b32_e32 v23, v193
	v_mov_b32_e32 v24, v193
	v_mov_b32_e32 v25, v193
	v_mov_b32_e32 v26, v193
	v_mov_b32_e32 v27, v193
	v_mov_b32_e32 v28, v193
	v_mov_b32_e32 v29, v193
	v_mov_b32_e32 v30, v193
	v_mov_b32_e32 v31, v193
	v_mov_b32_e32 v0, 0
	v_mov_b32_e32 v1, v193
	v_mov_b32_e32 v2, v193
	v_mov_b32_e32 v3, v193
	v_mov_b32_e32 v4, v193
	v_mov_b32_e32 v5, v193
	v_mov_b32_e32 v6, v193
	v_mov_b32_e32 v7, v193
	v_mov_b32_e32 v8, v193
	v_mov_b32_e32 v9, v193
	v_mov_b32_e32 v10, v193
	v_mov_b32_e32 v11, v193
	v_mov_b32_e32 v12, v193
	v_mov_b32_e32 v13, v193
	v_mov_b32_e32 v14, v193
	v_mov_b32_e32 v15, v193
.LBB0_874:
	v_mfma_f32_32x32x16_bf16 v[112:127], v[100:103], v[218:221], 0
	v_lshl_add_u32 v206, s89, 1, v188
	ds_read_b64_tr_b16 v[194:195], v206 offset:24576
	ds_read_b64_tr_b16 v[196:197], v206 offset:25088
	v_add_f32_e32 v108, v80, v81
	v_add_f32_e32 v108, v82, v108
	v_add_f32_e32 v108, v83, v108
	v_add_f32_e32 v108, v84, v108
	v_add_f32_e32 v108, v85, v108
	v_cvt_pk_bf16_f32 v156, v80, v81
	v_cvt_pk_bf16_f32 v157, v82, v83
	ds_read_b64_tr_b16 v[80:81], v206 offset:28672
	ds_read_b64_tr_b16 v[82:83], v206 offset:29184
	v_add_f32_e32 v104, v86, v108
	v_add_f32_e32 v104, v87, v104
	v_add_f32_e32 v104, v88, v104
	v_add_f32_e32 v144, v89, v104
	v_mfma_f32_32x32x16_bf16 v[96:111], v[96:99], v[218:221], 0
	v_cvt_pk_bf16_f32 v158, v84, v85
	v_cvt_pk_bf16_f32 v159, v86, v87
	ds_read_b64_tr_b16 v[84:85], v206 offset:25600
	ds_read_b64_tr_b16 v[86:87], v206 offset:26112
	v_add_f32_e32 v144, v90, v144
	v_add_f32_e32 v144, v91, v144
	v_add_f32_e32 v144, v92, v144
	v_add_f32_e32 v144, v93, v144
	v_cvt_pk_bf16_f32 v152, v88, v89
	v_cvt_pk_bf16_f32 v153, v90, v91
	v_mfma_f32_32x32x16_bf16 v[112:127], v[164:167], v[222:225], v[112:127]
	ds_read_b64_tr_b16 v[88:89], v206 offset:29696
	ds_read_b64_tr_b16 v[90:91], v206 offset:30208
	v_add_f32_e32 v144, v94, v144
	v_add_f32_e32 v144, v95, v144
	v_add_f32_e32 v144, v64, v144
	v_add_f32_e32 v144, v65, v144
	v_mfma_f32_32x32x16_bf16 v[96:111], v[160:163], v[222:225], v[96:111]
	v_cvt_pk_bf16_f32 v154, v92, v93
	v_cvt_pk_bf16_f32 v155, v94, v95
	ds_read_b64_tr_b16 v[92:93], v206 offset:26624
	ds_read_b64_tr_b16 v[94:95], v206 offset:27136
	v_add_f32_e32 v144, v66, v144
	v_add_f32_e32 v144, v67, v144
	v_add_f32_e32 v144, v68, v144
	v_add_f32_e32 v144, v69, v144
	v_cvt_pk_bf16_f32 v148, v64, v65
	v_cvt_pk_bf16_f32 v149, v66, v67
	v_mfma_f32_32x32x16_bf16 v[112:127], v[140:143], v[226:229], v[112:127]
	ds_read_b64_tr_b16 v[198:199], v206 offset:30720
	ds_read_b64_tr_b16 v[200:201], v206 offset:31232
	v_add_f32_e32 v140, v70, v144
	v_add_f32_e32 v140, v71, v140
	v_add_f32_e32 v140, v72, v140
	v_add_f32_e32 v140, v73, v140
	v_mfma_f32_32x32x16_bf16 v[96:111], v[136:139], v[226:229], v[96:111]
	v_cvt_pk_bf16_f32 v150, v68, v69
	v_cvt_pk_bf16_f32 v151, v70, v71
	ds_read_b64_tr_b16 v[202:203], v206 offset:27648
	ds_read_b64_tr_b16 v[204:205], v206 offset:28160
	v_add_f32_e32 v68, v74, v140
	v_add_f32_e32 v68, v75, v68
	v_add_f32_e32 v68, v76, v68
	v_add_f32_e32 v68, v77, v68
	v_cvt_pk_bf16_f32 v144, v72, v73
	v_cvt_pk_bf16_f32 v145, v74, v75
	v_mfma_f32_32x32x16_bf16 v[112:127], v[132:135], v[230:233], v[112:127]
	ds_read_b64_tr_b16 v[72:73], v206 offset:31744
	ds_read_b64_tr_b16 v[74:75], v206 offset:32256
	v_add_f32_e32 v68, v78, v68
	v_add_f32_e32 v68, v79, v68
	v_add_f32_e32 v68, 0, v68
	v_cvt_pk_bf16_f32 v146, v76, v77
	v_mfma_f32_32x32x16_bf16 v[96:111], v[128:131], v[230:233], v[96:111]
	v_cvt_pk_bf16_f32 v147, v78, v79
	s_add_i32 s88, s87, s17
	v_lshl_add_u64 v[64:65], v[180:181], 0, s[56:57]
	s_mov_b32 s89, m0
	s_mov_b32 m0, s88
	s_nop 0
	global_load_lds_dwordx4 v[64:65], off
	s_mov_b32 m0, s89
	s_lshl_b32 s88, s86, 1
	v_lshl_add_u64 v[64:65], v[178:179], 0, s[56:57]
	s_add_i32 s88, s88, s16
	s_mov_b32 s89, m0
	s_mov_b32 m0, s88
	s_nop 0
	global_load_lds_dwordx4 v[64:65], off
	s_mov_b32 m0, s89
	v_lshl_add_u64 v[64:65], v[176:177], 0, s[56:57]
	s_addk_i32 s88, 0x2000
	s_mov_b32 s89, m0
	s_mov_b32 m0, s88
	s_nop 0
	global_load_lds_dwordx4 v[64:65], off
	s_mov_b32 m0, s89
	v_add_f32_e32 v193, v193, v68
	s_waitcnt lgkmcnt(12)
	v_mfma_f32_32x32x16_bf16 v[48:63], v[156:159], v[194:197], v[48:63]
	ds_read_b64_tr_b16 v[76:77], v206 offset:32768
	ds_read_b64_tr_b16 v[78:79], v206 offset:33280
	v_exp_f32_e32 v112, v112
	v_exp_f32_e32 v113, v113
	v_mfma_f32_32x32x16_bf16 v[32:47], v[156:159], v[80:83], v[32:47]
	ds_read_b64_tr_b16 v[194:195], v206 offset:36864
	ds_read_b64_tr_b16 v[196:197], v206 offset:37376
	v_exp_f32_e32 v114, v114
	v_exp_f32_e32 v115, v115
	v_add_u32_e32 v242, s86, v234
	v_add_u32_e32 v243, s86, v235
	v_add_u32_e32 v244, s86, v236
	v_add_u32_e32 v245, s86, v237
	ds_read_b128 v[68:71], v242
	ds_read_b128 v[64:67], v242 offset:4096
	s_waitcnt lgkmcnt(14)
	v_mfma_f32_32x32x16_bf16 v[48:63], v[152:155], v[84:87], v[48:63]
	ds_read_b64_tr_b16 v[80:81], v206 offset:33792
	ds_read_b64_tr_b16 v[82:83], v206 offset:34304
	v_exp_f32_e32 v116, v116
	v_exp_f32_e32 v117, v117
	ds_read_b128 v[164:167], v243
	ds_read_b128 v[140:143], v243 offset:4096
	v_mfma_f32_32x32x16_bf16 v[32:47], v[152:155], v[88:91], v[32:47]
	ds_read_b64_tr_b16 v[84:85], v206 offset:37888
	ds_read_b64_tr_b16 v[86:87], v206 offset:38400
	v_exp_f32_e32 v118, v118
	v_exp_f32_e32 v119, v119
	ds_read_b128 v[160:163], v244
	ds_read_b128 v[132:135], v244 offset:4096
	s_waitcnt lgkmcnt(14)
	v_mfma_f32_32x32x16_bf16 v[48:63], v[148:151], v[92:95], v[48:63]
	ds_read_b64_tr_b16 v[88:89], v206 offset:34816
	ds_read_b64_tr_b16 v[90:91], v206 offset:35328
	v_exp_f32_e32 v120, v120
	v_exp_f32_e32 v121, v121
	ds_read_b128 v[136:139], v245
	ds_read_b128 v[128:131], v245 offset:4096
	v_mfma_f32_32x32x16_bf16 v[32:47], v[148:151], v[198:201], v[32:47]
	ds_read_b64_tr_b16 v[92:93], v206 offset:38912
	ds_read_b64_tr_b16 v[94:95], v206 offset:39424
	v_exp_f32_e32 v122, v122
	v_exp_f32_e32 v123, v123
	s_waitcnt lgkmcnt(14)
	v_mfma_f32_32x32x16_bf16 v[48:63], v[144:147], v[202:205], v[48:63]
	ds_read_b64_tr_b16 v[198:199], v206 offset:35840
	ds_read_b64_tr_b16 v[200:201], v206 offset:36352
	v_exp_f32_e32 v124, v124
	v_exp_f32_e32 v125, v125
	v_mfma_f32_32x32x16_bf16 v[32:47], v[144:147], v[72:75], v[32:47]
	ds_read_b64_tr_b16 v[202:203], v206 offset:39936
	ds_read_b64_tr_b16 v[204:205], v206 offset:40448
	v_exp_f32_e32 v126, v126
	v_exp_f32_e32 v127, v127
	s_waitcnt lgkmcnt(14)
	v_mfma_f32_32x32x16_bf16 v[16:31], v[156:159], v[76:79], v[16:31]
	v_exp_f32_e32 v96, v96
	v_exp_f32_e32 v97, v97
	v_mfma_f32_32x32x16_bf16 v[0:15], v[156:159], v[194:197], v[0:15]
	v_exp_f32_e32 v98, v98
	v_exp_f32_e32 v99, v99
	v_mfma_f32_32x32x16_bf16 v[16:31], v[152:155], v[80:83], v[16:31]
	v_exp_f32_e32 v100, v100
	v_exp_f32_e32 v101, v101
	s_waitcnt lgkmcnt(12)
	v_mfma_f32_32x32x16_bf16 v[0:15], v[152:155], v[84:87], v[0:15]
	v_exp_f32_e32 v102, v102
	v_exp_f32_e32 v103, v103
	s_waitcnt lgkmcnt(8)
	v_mfma_f32_32x32x16_bf16 v[16:31], v[148:151], v[88:91], v[16:31]
	v_exp_f32_e32 v104, v104
	v_exp_f32_e32 v105, v105
	s_waitcnt lgkmcnt(4)
	v_mfma_f32_32x32x16_bf16 v[0:15], v[148:151], v[92:95], v[0:15]
	v_exp_f32_e32 v106, v106
	v_exp_f32_e32 v107, v107
	s_waitcnt lgkmcnt(2)
	v_mfma_f32_32x32x16_bf16 v[16:31], v[144:147], v[198:201], v[16:31]
	v_exp_f32_e32 v108, v108
	v_exp_f32_e32 v109, v109
	s_waitcnt lgkmcnt(0)
	v_mfma_f32_32x32x16_bf16 v[0:15], v[144:147], v[202:205], v[0:15]
	v_exp_f32_e32 v110, v110
	v_exp_f32_e32 v111, v111
	s_waitcnt vmcnt(3) lgkmcnt(0)
	s_barrier
	v_mfma_f32_32x32x16_bf16 v[80:95], v[68:71], v[218:221], 0
	s_add_i32 s88, s86, 0x2000
	s_cmpk_lg_i32 s86, 0x4000
	s_cselect_b32 s88, s88, 0
	v_lshl_add_u32 v206, s87, 1, v188
	ds_read_b64_tr_b16 v[194:195], v206 offset:24576
	ds_read_b64_tr_b16 v[196:197], v206 offset:25088
	v_add_f32_e32 v76, v112, v113
	v_add_f32_e32 v76, v114, v76
	v_add_f32_e32 v76, v115, v76
	v_add_f32_e32 v76, v116, v76
	v_add_f32_e32 v76, v117, v76
	v_cvt_pk_bf16_f32 v156, v112, v113
	v_cvt_pk_bf16_f32 v157, v114, v115
	ds_read_b64_tr_b16 v[112:113], v206 offset:28672
	ds_read_b64_tr_b16 v[114:115], v206 offset:29184
	v_add_f32_e32 v72, v118, v76
	v_add_f32_e32 v72, v119, v72
	v_add_f32_e32 v72, v120, v72
	v_add_f32_e32 v144, v121, v72
	v_mfma_f32_32x32x16_bf16 v[64:79], v[64:67], v[218:221], 0
	v_cvt_pk_bf16_f32 v158, v116, v117
	v_cvt_pk_bf16_f32 v159, v118, v119
	ds_read_b64_tr_b16 v[116:117], v206 offset:25600
	ds_read_b64_tr_b16 v[118:119], v206 offset:26112
	v_add_f32_e32 v144, v122, v144
	v_add_f32_e32 v144, v123, v144
	v_add_f32_e32 v144, v124, v144
	v_add_f32_e32 v144, v125, v144
	v_mfma_f32_32x32x16_bf16 v[80:95], v[164:167], v[222:225], v[80:95]
	v_cvt_pk_bf16_f32 v152, v120, v121
	v_cvt_pk_bf16_f32 v153, v122, v123
	ds_read_b64_tr_b16 v[120:121], v206 offset:29696
	ds_read_b64_tr_b16 v[122:123], v206 offset:30208
	v_add_f32_e32 v144, v126, v144
	v_add_f32_e32 v144, v127, v144
	v_add_f32_e32 v144, v96, v144
	v_add_f32_e32 v144, v97, v144
	v_mfma_f32_32x32x16_bf16 v[64:79], v[140:143], v[222:225], v[64:79]
	v_cvt_pk_bf16_f32 v154, v124, v125
	v_cvt_pk_bf16_f32 v155, v126, v127
	ds_read_b64_tr_b16 v[124:125], v206 offset:26624
	ds_read_b64_tr_b16 v[126:127], v206 offset:27136
	v_add_f32_e32 v144, v98, v144
	v_add_f32_e32 v144, v99, v144
	v_add_f32_e32 v144, v100, v144
	v_add_f32_e32 v144, v101, v144
	v_mfma_f32_32x32x16_bf16 v[80:95], v[160:163], v[226:229], v[80:95]
	v_cvt_pk_bf16_f32 v148, v96, v97
	v_cvt_pk_bf16_f32 v149, v98, v99
	ds_read_b64_tr_b16 v[198:199], v206 offset:30720
	ds_read_b64_tr_b16 v[200:201], v206 offset:31232
	v_add_f32_e32 v140, v102, v144
	v_add_f32_e32 v140, v103, v140
	v_add_f32_e32 v140, v104, v140
	v_add_f32_e32 v140, v105, v140
	v_mfma_f32_32x32x16_bf16 v[64:79], v[132:135], v[226:229], v[64:79]
	v_cvt_pk_bf16_f32 v150, v100, v101
	v_cvt_pk_bf16_f32 v151, v102, v103
	ds_read_b64_tr_b16 v[202:203], v206 offset:27648
	ds_read_b64_tr_b16 v[204:205], v206 offset:28160
	v_add_f32_e32 v100, v106, v140
	v_add_f32_e32 v100, v107, v100
	v_add_f32_e32 v100, v108, v100
	v_add_f32_e32 v100, v109, v100
	v_mfma_f32_32x32x16_bf16 v[80:95], v[136:139], v[230:233], v[80:95]
	v_cvt_pk_bf16_f32 v144, v104, v105
	v_cvt_pk_bf16_f32 v145, v106, v107
	ds_read_b64_tr_b16 v[104:105], v206 offset:31744
	ds_read_b64_tr_b16 v[106:107], v206 offset:32256
	v_add_f32_e32 v100, v110, v100
	v_add_f32_e32 v100, v111, v100
	v_add_f32_e32 v100, 0, v100
	v_cvt_pk_bf16_f32 v146, v108, v109
	v_mfma_f32_32x32x16_bf16 v[64:79], v[128:131], v[230:233], v[64:79]
	v_cvt_pk_bf16_f32 v147, v110, v111
	s_add_i32 s87, s86, s17
	s_mov_b32 s89, m0
	s_mov_b32 m0, s87
	s_nop 0
	global_load_lds_dwordx4 v[180:181], off
	s_mov_b32 m0, s89
	s_lshl_b32 s87, s88, 1
	s_add_i32 s87, s87, s16
	s_mov_b32 s89, m0
	s_mov_b32 m0, s87
	s_nop 0
	global_load_lds_dwordx4 v[178:179], off
	s_mov_b32 m0, s89
	s_addk_i32 s87, 0x2000
	s_mov_b32 s89, m0
	s_mov_b32 m0, s87
	s_nop 0
	global_load_lds_dwordx4 v[176:177], off
	s_mov_b32 m0, s89
	v_add_f32_e32 v193, v193, v100
	s_waitcnt lgkmcnt(12)
; #define WAIT_BAR(N) asm volatile("s_waitcnt vmcnt(" #N ") lgkmcnt(0)\n\ts_barrier":::"memory")
;   #define RESC() do{ if(!NOMAX&&resc){ asm volatile("s_waitcnt lgkmcnt(0)":::"memory"); \
;       _Pragma("unroll") for(int d_=0;d_<2*VM;++d_) _Pragma("unroll") for(int r=0;r<16;++r)o[d_][r]*=wsf[crow(r,hi)]; } }while(0)
;   #define ROT() do{sl_prev=sl_cur;sl_cur=sl_next;sl_next=(sl_next==(NSLOT-1)*SLOTB)?0:sl_next+SLOTB;}while(0)
;   #define ENDW(tt) do{ if((tt)+3<NT){ if constexpr(VM==2){WAIT_BAR(3);}else{WAIT_BAR(2);} } else if((tt)+2<NT){ if constexpr(VM==2){WAIT_BAR(2);}else{WAIT_BAR(1);} } else {WAIT_BAR(0);} }while(0)
; template<int THRL,int VM,bool NOMAX> __device__ __forceinline__ void attn_unit(const bf16*Qb,const bf16*__restrict__ Kh,const bf16*__restrict__ Vh,bf16*Ob,const int NT,const int sp,float*wscr,char*shm){
;     ...
;   int t=1;
;   for(;t+5<NT;t+=2){
;     STEP(pB0,pB1,pA0,pA1,t,true,true,true);     if constexpr(VM==2){WAIT_BAR(3);}else{WAIT_BAR(2);} RESC(); ROT();
;     STEP(pA0,pA1,pB0,pB1,t+1,true,true,true);   if constexpr(VM==2){WAIT_BAR(3);}else{WAIT_BAR(2);} RESC(); ROT();
;   }
;     ...
;   for(;t+1<NT;t+=2){
;     STEP(pB0,pB1,pA0,pA1,t,(t+3<NT),(t+1<NT),(t+1<NT));       ENDW(t);   RESC(); ROT();
;     STEP(pA0,pA1,pB0,pB1,t+1,(t+4<NT),(t+2<NT),(t+2<NT));     ENDW(t+1); RESC(); ROT();
	v_mfma_f32_32x32x16_bf16 v[48:63], v[156:159], v[194:197], v[48:63]
	ds_read_b64_tr_b16 v[108:109], v206 offset:32768
	ds_read_b64_tr_b16 v[110:111], v206 offset:33280
	v_exp_f32_e32 v80, v80
	v_exp_f32_e32 v81, v81
	v_mfma_f32_32x32x16_bf16 v[32:47], v[156:159], v[112:115], v[32:47]
	ds_read_b64_tr_b16 v[194:195], v206 offset:36864
	ds_read_b64_tr_b16 v[196:197], v206 offset:37376
	v_exp_f32_e32 v82, v82
	v_exp_f32_e32 v83, v83
	v_add_u32_e32 v242, s88, v234
	v_add_u32_e32 v243, s88, v235
	v_add_u32_e32 v244, s88, v236
	v_add_u32_e32 v245, s88, v237
	ds_read_b128 v[100:103], v242
	ds_read_b128 v[96:99], v242 offset:4096
	s_waitcnt lgkmcnt(14)
	v_mfma_f32_32x32x16_bf16 v[48:63], v[152:155], v[116:119], v[48:63]
	ds_read_b64_tr_b16 v[112:113], v206 offset:33792
	ds_read_b64_tr_b16 v[114:115], v206 offset:34304
	v_exp_f32_e32 v84, v84
	v_exp_f32_e32 v85, v85
	ds_read_b128 v[164:167], v243
	ds_read_b128 v[160:163], v243 offset:4096
	v_mfma_f32_32x32x16_bf16 v[32:47], v[152:155], v[120:123], v[32:47]
	ds_read_b64_tr_b16 v[116:117], v206 offset:37888
	ds_read_b64_tr_b16 v[118:119], v206 offset:38400
	v_exp_f32_e32 v86, v86
	v_exp_f32_e32 v87, v87
	ds_read_b128 v[140:143], v244
	ds_read_b128 v[136:139], v244 offset:4096
	s_waitcnt lgkmcnt(14)
	v_mfma_f32_32x32x16_bf16 v[48:63], v[148:151], v[124:127], v[48:63]
	ds_read_b64_tr_b16 v[120:121], v206 offset:34816
	ds_read_b64_tr_b16 v[122:123], v206 offset:35328
	v_exp_f32_e32 v88, v88
	v_exp_f32_e32 v89, v89
	ds_read_b128 v[132:135], v245
	ds_read_b128 v[128:131], v245 offset:4096
	v_mfma_f32_32x32x16_bf16 v[32:47], v[148:151], v[198:201], v[32:47]
	ds_read_b64_tr_b16 v[124:125], v206 offset:38912
	ds_read_b64_tr_b16 v[126:127], v206 offset:39424
	v_exp_f32_e32 v90, v90
	v_exp_f32_e32 v91, v91
	s_waitcnt lgkmcnt(14)
	v_mfma_f32_32x32x16_bf16 v[48:63], v[144:147], v[202:205], v[48:63]
	ds_read_b64_tr_b16 v[198:199], v206 offset:35840
	ds_read_b64_tr_b16 v[200:201], v206 offset:36352
	v_exp_f32_e32 v92, v92
	v_exp_f32_e32 v93, v93
	v_mfma_f32_32x32x16_bf16 v[32:47], v[144:147], v[104:107], v[32:47]
	ds_read_b64_tr_b16 v[202:203], v206 offset:39936
	ds_read_b64_tr_b16 v[204:205], v206 offset:40448
	v_exp_f32_e32 v94, v94
	v_exp_f32_e32 v95, v95
	s_waitcnt lgkmcnt(14)
	v_mfma_f32_32x32x16_bf16 v[16:31], v[156:159], v[108:111], v[16:31]
	v_exp_f32_e32 v64, v64
	v_exp_f32_e32 v65, v65
	v_mfma_f32_32x32x16_bf16 v[0:15], v[156:159], v[194:197], v[0:15]
	v_exp_f32_e32 v66, v66
	v_exp_f32_e32 v67, v67
	v_mfma_f32_32x32x16_bf16 v[16:31], v[152:155], v[112:115], v[16:31]
	v_exp_f32_e32 v68, v68
	v_exp_f32_e32 v69, v69
	s_waitcnt lgkmcnt(12)
	v_mfma_f32_32x32x16_bf16 v[0:15], v[152:155], v[116:119], v[0:15]
	v_exp_f32_e32 v70, v70
	v_exp_f32_e32 v71, v71
	s_waitcnt lgkmcnt(8)
	v_mfma_f32_32x32x16_bf16 v[16:31], v[148:151], v[120:123], v[16:31]
	v_exp_f32_e32 v72, v72
	v_exp_f32_e32 v73, v73
	s_waitcnt lgkmcnt(4)
	v_mfma_f32_32x32x16_bf16 v[0:15], v[148:151], v[124:127], v[0:15]
	v_exp_f32_e32 v74, v74
	v_exp_f32_e32 v75, v75
	s_waitcnt lgkmcnt(2)
	v_mfma_f32_32x32x16_bf16 v[16:31], v[144:147], v[198:201], v[16:31]
	v_exp_f32_e32 v76, v76
	v_exp_f32_e32 v77, v77
	s_waitcnt lgkmcnt(0)
	v_mfma_f32_32x32x16_bf16 v[0:15], v[144:147], v[202:205], v[0:15]
	v_exp_f32_e32 v78, v78
	v_exp_f32_e32 v79, v79
	s_add_i32 s90, s88, 0x2000
	s_waitcnt vmcnt(3) lgkmcnt(0)
	s_barrier
	s_cmpk_lg_i32 s88, 0x4000
	s_mov_b32 s89, s86
	s_cselect_b32 s86, s90, 0
	s_add_i32 s85, s85, 2
	v_lshl_add_u64 v[176:177], v[176:177], 0, s[58:59]
	v_lshl_add_u64 v[178:179], v[178:179], 0, s[58:59]
	v_lshl_add_u64 v[180:181], v[180:181], 0, s[58:59]
	s_mov_b32 s87, s88
	s_cmp_lt_u32 s85, 57
	s_cbranch_scc1 .LBB0_874
	s_and_b32 s34, s34, 0x3fffffc0
	s_lshl_b32 s34, s34, 2
	s_add_i32 s34, s34, 0
	s_add_i32 s34, s34, 0x12000
	s_cmp_lg_u32 0, -1
	s_cselect_b32 s85, 0, 0
	s_add_i32 s86, s85, 0x6000
	v_add_u32_e32 v104, s86, v191
	v_add3_u32 v176, v104, v190, v192
	v_add_u32_e32 v177, 0x6000, v188
	ds_read_b64_tr_b16 v[178:179], v188 offset:40960
	ds_read_b64_tr_b16 v[180:181], v188 offset:41472
	v_add_f32_e32 v108, v80, v81
	ds_read_b128 v[104:107], v168
	v_add_f32_e32 v108, v82, v108
	v_add_f32_e32 v108, v83, v108
	v_add_f32_e32 v108, v84, v108
	v_add_f32_e32 v108, v85, v108
	v_cvt_pk_bf16_f32 v156, v80, v81
	v_cvt_pk_bf16_f32 v157, v82, v83
	s_waitcnt lgkmcnt(0)
	v_mfma_f32_32x32x16_bf16 v[112:127], v[100:103], v[104:107], 0
	ds_read_b64_tr_b16 v[80:81], v188 offset:45056
	ds_read_b64_tr_b16 v[82:83], v188 offset:45568
	ds_read_b128 v[100:103], v168
	v_add_f32_e32 v104, v86, v108
	v_add_f32_e32 v104, v87, v104
	v_add_f32_e32 v104, v88, v104
	v_add_f32_e32 v144, v89, v104
	v_cvt_pk_bf16_f32 v158, v84, v85
	v_cvt_pk_bf16_f32 v159, v86, v87
	s_waitcnt lgkmcnt(0)
	v_mfma_f32_32x32x16_bf16 v[96:111], v[96:99], v[100:103], 0
	ds_read_b64_tr_b16 v[84:85], v188 offset:41984
	ds_read_b64_tr_b16 v[86:87], v188 offset:42496
	ds_read_b128 v[194:197], v168 offset:1024
	v_add_f32_e32 v144, v90, v144
	v_add_f32_e32 v144, v91, v144
	v_add_f32_e32 v144, v92, v144
	v_add_f32_e32 v144, v93, v144
	v_cvt_pk_bf16_f32 v152, v88, v89
	v_cvt_pk_bf16_f32 v153, v90, v91
	s_waitcnt lgkmcnt(0)
	v_mfma_f32_32x32x16_bf16 v[112:127], v[164:167], v[194:197], v[112:127]
	ds_read_b64_tr_b16 v[88:89], v188 offset:46080
	ds_read_b64_tr_b16 v[90:91], v188 offset:46592
	ds_read_b128 v[164:167], v168 offset:1024
	v_add_f32_e32 v144, v94, v144
	v_add_f32_e32 v144, v95, v144
	v_add_f32_e32 v144, v64, v144
	v_add_f32_e32 v144, v65, v144
	v_cvt_pk_bf16_f32 v154, v92, v93
	v_cvt_pk_bf16_f32 v155, v94, v95
	s_waitcnt lgkmcnt(0)
	v_mfma_f32_32x32x16_bf16 v[96:111], v[160:163], v[164:167], v[96:111]
	ds_read_b64_tr_b16 v[194:195], v188 offset:43008
	ds_read_b64_tr_b16 v[196:197], v188 offset:43520
	ds_read_b128 v[92:95], v168 offset:2048
	v_add_f32_e32 v144, v66, v144
	v_add_f32_e32 v144, v67, v144
	v_add_f32_e32 v144, v68, v144
	v_add_f32_e32 v144, v69, v144
	v_cvt_pk_bf16_f32 v148, v64, v65
	v_cvt_pk_bf16_f32 v149, v66, v67
	s_waitcnt lgkmcnt(0)
	v_mfma_f32_32x32x16_bf16 v[112:127], v[140:143], v[92:95], v[112:127]
	ds_read_b64_tr_b16 v[140:141], v188 offset:47104
	ds_read_b64_tr_b16 v[142:143], v188 offset:47616
	ds_read_b128 v[64:67], v168 offset:2048
	v_add_f32_e32 v92, v70, v144
	v_add_f32_e32 v92, v71, v92
	v_add_f32_e32 v92, v72, v92
	v_add_f32_e32 v92, v73, v92
	v_cvt_pk_bf16_f32 v150, v68, v69
	v_cvt_pk_bf16_f32 v151, v70, v71
	s_waitcnt lgkmcnt(0)
	v_mfma_f32_32x32x16_bf16 v[96:111], v[136:139], v[64:67], v[96:111]
	ds_read_b64_tr_b16 v[136:137], v188 offset:44032
	ds_read_b64_tr_b16 v[138:139], v188 offset:44544
	ds_read_b128 v[64:67], v168 offset:3072
	v_add_f32_e32 v68, v74, v92
	v_add_f32_e32 v68, v75, v68
	v_add_f32_e32 v68, v76, v68
	v_add_f32_e32 v68, v77, v68
	v_cvt_pk_bf16_f32 v144, v72, v73
	v_cvt_pk_bf16_f32 v145, v74, v75
	s_waitcnt lgkmcnt(0)
	v_mfma_f32_32x32x16_bf16 v[112:127], v[132:135], v[64:67], v[112:127]
	ds_read_b64_tr_b16 v[72:73], v188 offset:48128
	ds_read_b64_tr_b16 v[74:75], v188 offset:48640
	ds_read_b128 v[64:67], v168 offset:3072
	v_add_f32_e32 v68, v78, v68
	v_add_f32_e32 v68, v79, v68
	v_add_f32_e32 v68, 0, v68
	v_cvt_pk_bf16_f32 v146, v76, v77
	v_cvt_pk_bf16_f32 v147, v78, v79
	s_waitcnt lgkmcnt(0)
	v_mfma_f32_32x32x16_bf16 v[96:111], v[128:131], v[64:67], v[96:111]
	s_add_i32 s85, s85, s35
	v_lshl_add_u64 v[64:65], v[174:175], 0, s[60:61]
	s_add_i32 s35, s85, 0x4000
	s_mov_b32 s86, m0
	s_mov_b32 m0, s35
	s_nop 0
	global_load_lds_dwordx4 v[64:65], off
	s_mov_b32 m0, s86
	v_lshl_add_u64 v[64:65], v[170:171], 0, s[62:63]
	s_mov_b32 s35, m0
	s_mov_b32 m0, s16
	s_nop 0
	global_load_lds_dwordx4 v[64:65], off
	s_mov_b32 m0, s35
	v_lshl_add_u64 v[64:65], v[172:173], 0, s[62:63]
	s_add_i32 s35, s16, 0x2000
	s_mov_b32 s86, m0
	s_mov_b32 m0, s35
	s_nop 0
	global_load_lds_dwordx4 v[64:65], off
	s_mov_b32 m0, s86
	v_add_f32_e32 v198, v193, v68
	v_mfma_f32_32x32x16_bf16 v[48:63], v[156:159], v[178:181], v[48:63]
	ds_read_b64_tr_b16 v[76:77], v188 offset:49152
	ds_read_b64_tr_b16 v[78:79], v188 offset:49664
	v_exp_f32_e32 v112, v112
	v_exp_f32_e32 v113, v113
	v_mfma_f32_32x32x16_bf16 v[32:47], v[156:159], v[80:83], v[32:47]
	ds_read_b64_tr_b16 v[128:129], v188 offset:53248
	ds_read_b64_tr_b16 v[130:131], v188 offset:53760
	v_exp_f32_e32 v114, v114
	v_exp_f32_e32 v115, v115
	ds_read_b128 v[68:71], v234
	ds_read_b128 v[64:67], v234 offset:4096
	v_mfma_f32_32x32x16_bf16 v[48:63], v[152:155], v[84:87], v[48:63]
	ds_read_b64_tr_b16 v[132:133], v188 offset:50176
	ds_read_b64_tr_b16 v[134:135], v188 offset:50688
	v_exp_f32_e32 v116, v116
	v_exp_f32_e32 v117, v117
	ds_read_b128 v[164:167], v235
	ds_read_b128 v[92:95], v235 offset:4096
	v_mfma_f32_32x32x16_bf16 v[32:47], v[152:155], v[88:91], v[32:47]
	ds_read_b64_tr_b16 v[178:179], v188 offset:54272
	ds_read_b64_tr_b16 v[180:181], v188 offset:54784
	v_exp_f32_e32 v118, v118
	v_exp_f32_e32 v119, v119
	ds_read_b128 v[160:163], v236
	ds_read_b128 v[84:87], v236 offset:4096
	v_mfma_f32_32x32x16_bf16 v[48:63], v[148:151], v[194:197], v[48:63]
	ds_read_b64_tr_b16 v[190:191], v188 offset:51200
	ds_read_b64_tr_b16 v[192:193], v188 offset:51712
	v_exp_f32_e32 v120, v120
	v_exp_f32_e32 v121, v121
	ds_read_b128 v[88:91], v237
	ds_read_b128 v[80:83], v237 offset:4096
	v_mfma_f32_32x32x16_bf16 v[32:47], v[148:151], v[140:143], v[32:47]
	ds_read_b64_tr_b16 v[194:195], v188 offset:55296
	ds_read_b64_tr_b16 v[196:197], v188 offset:55808
	v_exp_f32_e32 v122, v122
	v_exp_f32_e32 v123, v123
	v_mfma_f32_32x32x16_bf16 v[48:63], v[144:147], v[136:139], v[48:63]
	ds_read_b64_tr_b16 v[140:141], v188 offset:52224
	ds_read_b64_tr_b16 v[142:143], v188 offset:52736
	v_exp_f32_e32 v124, v124
	v_exp_f32_e32 v125, v125
	v_mfma_f32_32x32x16_bf16 v[32:47], v[144:147], v[72:75], v[32:47]
	ds_read_b64_tr_b16 v[136:137], v188 offset:56320
	ds_read_b64_tr_b16 v[138:139], v188 offset:56832
	v_exp_f32_e32 v126, v126
	v_exp_f32_e32 v127, v127
	s_waitcnt lgkmcnt(14)
	v_mfma_f32_32x32x16_bf16 v[16:31], v[156:159], v[76:79], v[16:31]
	v_exp_f32_e32 v96, v96
	v_exp_f32_e32 v97, v97
	v_mfma_f32_32x32x16_bf16 v[0:15], v[156:159], v[128:131], v[0:15]
	v_exp_f32_e32 v98, v98
	v_exp_f32_e32 v99, v99
	v_mfma_f32_32x32x16_bf16 v[16:31], v[152:155], v[132:135], v[16:31]
	v_exp_f32_e32 v100, v100
	v_exp_f32_e32 v101, v101
	s_waitcnt lgkmcnt(12)
	v_mfma_f32_32x32x16_bf16 v[0:15], v[152:155], v[178:181], v[0:15]
	v_exp_f32_e32 v102, v102
	v_exp_f32_e32 v103, v103
	s_waitcnt lgkmcnt(8)
	v_mfma_f32_32x32x16_bf16 v[16:31], v[148:151], v[190:193], v[16:31]
	v_exp_f32_e32 v104, v104
	v_exp_f32_e32 v105, v105
	s_waitcnt lgkmcnt(4)
	v_mfma_f32_32x32x16_bf16 v[0:15], v[148:151], v[194:197], v[0:15]
	v_exp_f32_e32 v106, v106
	v_exp_f32_e32 v107, v107
	s_waitcnt lgkmcnt(2)
	v_mfma_f32_32x32x16_bf16 v[16:31], v[144:147], v[140:143], v[16:31]
	v_exp_f32_e32 v108, v108
	v_exp_f32_e32 v109, v109
	s_waitcnt lgkmcnt(0)
	v_mfma_f32_32x32x16_bf16 v[0:15], v[144:147], v[136:139], v[0:15]
	v_exp_f32_e32 v110, v110
	v_exp_f32_e32 v111, v111
	s_waitcnt vmcnt(3) lgkmcnt(0)
	s_barrier
	ds_read_b64_tr_b16 v[178:179], v188 offset:57344
	ds_read_b64_tr_b16 v[180:181], v188 offset:57856
	v_add_f32_e32 v76, v112, v113
	ds_read_b128 v[72:75], v168
	v_add_f32_e32 v76, v114, v76
	v_add_f32_e32 v76, v115, v76
	v_add_f32_e32 v76, v116, v76
	v_add_f32_e32 v76, v117, v76
	v_cvt_pk_bf16_f32 v156, v112, v113
	v_cvt_pk_bf16_f32 v157, v114, v115
	s_waitcnt lgkmcnt(0)
	v_mfma_f32_32x32x16_bf16 v[128:143], v[68:71], v[72:75], 0
	ds_read_b64_tr_b16 v[112:113], v188 offset:61440
	ds_read_b64_tr_b16 v[114:115], v188 offset:61952
	ds_read_b128 v[68:71], v168
	v_add_f32_e32 v72, v118, v76
	v_add_f32_e32 v72, v119, v72
	v_add_f32_e32 v72, v120, v72
	v_add_f32_e32 v144, v121, v72
	s_waitcnt lgkmcnt(0)
	v_mfma_f32_32x32x16_bf16 v[64:79], v[64:67], v[68:71], 0
	v_cvt_pk_bf16_f32 v158, v116, v117
	v_cvt_pk_bf16_f32 v159, v118, v119
	ds_read_b64_tr_b16 v[116:117], v188 offset:58368
	ds_read_b64_tr_b16 v[118:119], v188 offset:58880
	ds_read_b128 v[190:193], v168 offset:1024
	v_add_f32_e32 v144, v122, v144
	v_add_f32_e32 v144, v123, v144
	v_add_f32_e32 v144, v124, v144
	v_add_f32_e32 v144, v125, v144
	v_cvt_pk_bf16_f32 v152, v120, v121
	v_cvt_pk_bf16_f32 v153, v122, v123
	s_waitcnt lgkmcnt(0)
	v_mfma_f32_32x32x16_bf16 v[128:143], v[164:167], v[190:193], v[128:143]
	ds_read_b64_tr_b16 v[120:121], v188 offset:62464
	ds_read_b64_tr_b16 v[122:123], v188 offset:62976
	ds_read_b128 v[164:167], v168 offset:1024
	v_add_f32_e32 v144, v126, v144
	v_add_f32_e32 v144, v127, v144
	v_add_f32_e32 v144, v96, v144
	v_add_f32_e32 v144, v97, v144
	s_waitcnt lgkmcnt(0)
	v_mfma_f32_32x32x16_bf16 v[64:79], v[92:95], v[164:167], v[64:79]
	v_cvt_pk_bf16_f32 v154, v124, v125
	v_cvt_pk_bf16_f32 v155, v126, v127
	ds_read_b64_tr_b16 v[92:93], v188 offset:59392
	ds_read_b64_tr_b16 v[94:95], v188 offset:59904
	ds_read_b128 v[124:127], v168 offset:2048
	v_add_f32_e32 v144, v98, v144
	v_add_f32_e32 v144, v99, v144
	v_add_f32_e32 v144, v100, v144
	v_add_f32_e32 v144, v101, v144
	v_cvt_pk_bf16_f32 v148, v96, v97
	v_cvt_pk_bf16_f32 v149, v98, v99
	s_waitcnt lgkmcnt(0)
	v_mfma_f32_32x32x16_bf16 v[128:143], v[160:163], v[124:127], v[128:143]
	ds_read_b64_tr_b16 v[96:97], v188 offset:63488
	ds_read_b64_tr_b16 v[98:99], v188 offset:64000
	ds_read_b128 v[124:127], v168 offset:2048
	v_add_f32_e32 v144, v102, v144
	v_add_f32_e32 v144, v103, v144
	v_add_f32_e32 v144, v104, v144
	v_add_f32_e32 v144, v105, v144
	s_waitcnt lgkmcnt(0)
	v_mfma_f32_32x32x16_bf16 v[64:79], v[84:87], v[124:127], v[64:79]
	v_cvt_pk_bf16_f32 v150, v100, v101
	v_cvt_pk_bf16_f32 v151, v102, v103
	ds_read_b64_tr_b16 v[100:101], v188 offset:60416
	ds_read_b64_tr_b16 v[102:103], v188 offset:60928
	ds_read_b128 v[84:87], v168 offset:3072
	v_add_f32_e32 v124, v106, v144
	v_add_f32_e32 v124, v107, v124
	v_add_f32_e32 v124, v108, v124
	v_add_f32_e32 v124, v109, v124
	v_cvt_pk_bf16_f32 v144, v104, v105
	v_cvt_pk_bf16_f32 v145, v106, v107
	s_waitcnt lgkmcnt(0)
	v_mfma_f32_32x32x16_bf16 v[128:143], v[88:91], v[84:87], v[128:143]
	ds_read_b64_tr_b16 v[88:89], v188 offset:64512
	ds_read_b64_tr_b16 v[90:91], v188 offset:65024
	ds_read_b128 v[84:87], v168 offset:3072
	v_add_f32_e32 v104, v110, v124
	v_add_f32_e32 v104, v111, v104
	v_add_f32_e32 v104, 0, v104
	v_cvt_pk_bf16_f32 v146, v108, v109
	s_waitcnt lgkmcnt(0)
	v_mfma_f32_32x32x16_bf16 v[64:79], v[80:83], v[84:87], v[64:79]
	v_cvt_pk_bf16_f32 v147, v110, v111
	v_lshl_add_u64 v[80:81], v[174:175], 0, s[64:65]
	s_mov_b32 s86, m0
	s_mov_b32 m0, s17
	s_nop 0
	global_load_lds_dwordx4 v[80:81], off
	s_mov_b32 m0, s86
	v_lshl_add_u64 v[80:81], v[170:171], 0, s[66:67]
	s_add_i32 s17, s85, 0xa000
	s_mov_b32 s86, m0
	s_mov_b32 m0, s17
	s_nop 0
	global_load_lds_dwordx4 v[80:81], off
	s_mov_b32 m0, s86
	v_lshl_add_u64 v[80:81], v[172:173], 0, s[66:67]
	s_add_i32 s17, s85, 0xc000
	s_mov_b32 s86, m0
	s_mov_b32 m0, s17
	s_nop 0
	global_load_lds_dwordx4 v[80:81], off
	s_mov_b32 m0, s86
	v_add_f32_e32 v198, v198, v104
	v_mfma_f32_32x32x16_bf16 v[48:63], v[156:159], v[178:181], v[48:63]
	ds_read_b64_tr_b16 v[104:105], v177 offset:40960
	ds_read_b64_tr_b16 v[106:107], v177 offset:41472
	v_exp_f32_e32 v128, v128
	v_exp_f32_e32 v129, v129
	v_mfma_f32_32x32x16_bf16 v[32:47], v[156:159], v[112:115], v[32:47]
	ds_read_b64_tr_b16 v[108:109], v177 offset:45056
	ds_read_b64_tr_b16 v[110:111], v177 offset:45568
	v_exp_f32_e32 v130, v130
	v_exp_f32_e32 v131, v131
	ds_read_b128 v[84:87], v234 offset:8192
	ds_read_b128 v[80:83], v234 offset:12288
	v_mfma_f32_32x32x16_bf16 v[48:63], v[152:155], v[116:119], v[48:63]
	ds_read_b64_tr_b16 v[178:179], v177 offset:41984
	ds_read_b64_tr_b16 v[180:181], v177 offset:42496
	v_exp_f32_e32 v132, v132
	v_exp_f32_e32 v133, v133
	ds_read_b128 v[164:167], v235 offset:8192
	ds_read_b128 v[124:127], v235 offset:12288
	v_mfma_f32_32x32x16_bf16 v[32:47], v[152:155], v[120:123], v[32:47]
	ds_read_b64_tr_b16 v[190:191], v177 offset:46080
	ds_read_b64_tr_b16 v[192:193], v177 offset:46592
	v_exp_f32_e32 v134, v134
	v_exp_f32_e32 v135, v135
	ds_read_b128 v[160:163], v236 offset:8192
	ds_read_b128 v[116:119], v236 offset:12288
	v_mfma_f32_32x32x16_bf16 v[48:63], v[148:151], v[92:95], v[48:63]
	ds_read_b64_tr_b16 v[194:195], v177 offset:43008
	ds_read_b64_tr_b16 v[196:197], v177 offset:43520
	v_exp_f32_e32 v136, v136
	v_exp_f32_e32 v137, v137
	ds_read_b128 v[120:123], v237 offset:8192
	ds_read_b128 v[112:115], v237 offset:12288
	v_mfma_f32_32x32x16_bf16 v[32:47], v[148:151], v[96:99], v[32:47]
	ds_read_b64_tr_b16 v[92:93], v177 offset:47104
	ds_read_b64_tr_b16 v[94:95], v177 offset:47616
	v_exp_f32_e32 v138, v138
	v_exp_f32_e32 v139, v139
	v_mfma_f32_32x32x16_bf16 v[48:63], v[144:147], v[100:103], v[48:63]
	ds_read_b64_tr_b16 v[96:97], v177 offset:44032
	ds_read_b64_tr_b16 v[98:99], v177 offset:44544
	v_exp_f32_e32 v140, v140
	v_exp_f32_e32 v141, v141
	v_mfma_f32_32x32x16_bf16 v[32:47], v[144:147], v[88:91], v[32:47]
	ds_read_b64_tr_b16 v[100:101], v177 offset:48128
	ds_read_b64_tr_b16 v[102:103], v177 offset:48640
	v_exp_f32_e32 v142, v142
	v_exp_f32_e32 v143, v143
	s_waitcnt lgkmcnt(14)
	v_mfma_f32_32x32x16_bf16 v[16:31], v[156:159], v[104:107], v[16:31]
	v_exp_f32_e32 v64, v64
	v_exp_f32_e32 v65, v65
	v_mfma_f32_32x32x16_bf16 v[0:15], v[156:159], v[108:111], v[0:15]
	v_exp_f32_e32 v66, v66
	v_exp_f32_e32 v67, v67
	v_mfma_f32_32x32x16_bf16 v[16:31], v[152:155], v[178:181], v[16:31]
	v_exp_f32_e32 v68, v68
	v_exp_f32_e32 v69, v69
	s_waitcnt lgkmcnt(12)
	v_mfma_f32_32x32x16_bf16 v[0:15], v[152:155], v[190:193], v[0:15]
	v_exp_f32_e32 v70, v70
	v_exp_f32_e32 v71, v71
	s_waitcnt lgkmcnt(8)
	v_mfma_f32_32x32x16_bf16 v[16:31], v[148:151], v[194:197], v[16:31]
	v_exp_f32_e32 v72, v72
	v_exp_f32_e32 v73, v73
	s_waitcnt lgkmcnt(4)
	v_mfma_f32_32x32x16_bf16 v[0:15], v[148:151], v[92:95], v[0:15]
	v_exp_f32_e32 v74, v74
	v_exp_f32_e32 v75, v75
	s_waitcnt lgkmcnt(2)
	v_mfma_f32_32x32x16_bf16 v[16:31], v[144:147], v[96:99], v[16:31]
	v_exp_f32_e32 v76, v76
	v_exp_f32_e32 v77, v77
	s_waitcnt lgkmcnt(0)
	v_mfma_f32_32x32x16_bf16 v[0:15], v[144:147], v[100:103], v[0:15]
	v_exp_f32_e32 v78, v78
	v_exp_f32_e32 v79, v79
	s_waitcnt vmcnt(3) lgkmcnt(0)
	s_barrier
	ds_read_b64_tr_b16 v[178:179], v188 offset:24576
	ds_read_b64_tr_b16 v[180:181], v188 offset:25088
	v_add_f32_e32 v92, v128, v129
	ds_read_b128 v[88:91], v168
	v_add_f32_e32 v92, v130, v92
	v_add_f32_e32 v92, v131, v92
	v_add_f32_e32 v92, v132, v92
	v_add_f32_e32 v92, v133, v92
	v_cvt_pk_bf16_f32 v156, v128, v129
	v_cvt_pk_bf16_f32 v157, v130, v131
	s_waitcnt lgkmcnt(0)
	v_mfma_f32_32x32x16_bf16 v[96:111], v[84:87], v[88:91], 0
	ds_read_b64_tr_b16 v[128:129], v188 offset:28672
	ds_read_b64_tr_b16 v[130:131], v188 offset:29184
	ds_read_b128 v[84:87], v168
	v_add_f32_e32 v88, v134, v92
	v_add_f32_e32 v88, v135, v88
	v_add_f32_e32 v88, v136, v88
	v_add_f32_e32 v144, v137, v88
	v_cvt_pk_bf16_f32 v158, v132, v133
	v_cvt_pk_bf16_f32 v159, v134, v135
	s_waitcnt lgkmcnt(0)
	v_mfma_f32_32x32x16_bf16 v[80:95], v[80:83], v[84:87], 0
	ds_read_b64_tr_b16 v[132:133], v188 offset:25600
	ds_read_b64_tr_b16 v[134:135], v188 offset:26112
	ds_read_b128 v[190:193], v168 offset:1024
	v_add_f32_e32 v144, v138, v144
	v_add_f32_e32 v144, v139, v144
	v_add_f32_e32 v144, v140, v144
	v_add_f32_e32 v144, v141, v144
	v_cvt_pk_bf16_f32 v152, v136, v137
	v_cvt_pk_bf16_f32 v153, v138, v139
	s_waitcnt lgkmcnt(0)
	v_mfma_f32_32x32x16_bf16 v[96:111], v[164:167], v[190:193], v[96:111]
	ds_read_b64_tr_b16 v[136:137], v188 offset:29696
	ds_read_b64_tr_b16 v[138:139], v188 offset:30208
	ds_read_b128 v[164:167], v168 offset:1024
	v_add_f32_e32 v144, v142, v144
	v_add_f32_e32 v144, v143, v144
	v_add_f32_e32 v144, v64, v144
	v_add_f32_e32 v144, v65, v144
	v_cvt_pk_bf16_f32 v154, v140, v141
	v_cvt_pk_bf16_f32 v155, v142, v143
	s_waitcnt lgkmcnt(0)
	v_mfma_f32_32x32x16_bf16 v[80:95], v[124:127], v[164:167], v[80:95]
	ds_read_b64_tr_b16 v[124:125], v188 offset:26624
	ds_read_b64_tr_b16 v[126:127], v188 offset:27136
	ds_read_b128 v[140:143], v168 offset:2048
	v_add_f32_e32 v144, v66, v144
	v_add_f32_e32 v144, v67, v144
	v_add_f32_e32 v144, v68, v144
	v_add_f32_e32 v144, v69, v144
	v_cvt_pk_bf16_f32 v148, v64, v65
	v_cvt_pk_bf16_f32 v149, v66, v67
	s_waitcnt lgkmcnt(0)
	v_mfma_f32_32x32x16_bf16 v[96:111], v[160:163], v[140:143], v[96:111]
	ds_read_b64_tr_b16 v[190:191], v188 offset:30720
	ds_read_b64_tr_b16 v[192:193], v188 offset:31232
	ds_read_b128 v[64:67], v168 offset:2048
	v_add_f32_e32 v140, v70, v144
	v_add_f32_e32 v140, v71, v140
	v_add_f32_e32 v140, v72, v140
	v_add_f32_e32 v140, v73, v140
	v_cvt_pk_bf16_f32 v150, v68, v69
	v_cvt_pk_bf16_f32 v151, v70, v71
	s_waitcnt lgkmcnt(0)
	v_mfma_f32_32x32x16_bf16 v[80:95], v[116:119], v[64:67], v[80:95]
	ds_read_b64_tr_b16 v[116:117], v188 offset:27648
	ds_read_b64_tr_b16 v[118:119], v188 offset:28160
	ds_read_b128 v[64:67], v168 offset:3072
	v_add_f32_e32 v68, v74, v140
	v_add_f32_e32 v68, v75, v68
	v_add_f32_e32 v68, v76, v68
	v_add_f32_e32 v68, v77, v68
	v_cvt_pk_bf16_f32 v144, v72, v73
	v_cvt_pk_bf16_f32 v145, v74, v75
	s_waitcnt lgkmcnt(0)
	v_mfma_f32_32x32x16_bf16 v[96:111], v[120:123], v[64:67], v[96:111]
	ds_read_b64_tr_b16 v[72:73], v188 offset:31744
	ds_read_b64_tr_b16 v[74:75], v188 offset:32256
	ds_read_b128 v[64:67], v168 offset:3072
	v_add_f32_e32 v68, v78, v68
	v_add_f32_e32 v68, v79, v68
	v_add_f32_e32 v68, 0, v68
	v_cvt_pk_bf16_f32 v146, v76, v77
	v_cvt_pk_bf16_f32 v147, v78, v79
	s_waitcnt lgkmcnt(0)
	v_mfma_f32_32x32x16_bf16 v[80:95], v[112:115], v[64:67], v[80:95]
	v_lshl_add_u64 v[64:65], v[170:171], 0, s[60:61]
	s_add_i32 s17, s85, 0xe000
	s_mov_b32 s86, m0
	s_mov_b32 m0, s17
	s_nop 0
	global_load_lds_dwordx4 v[64:65], off
	s_mov_b32 m0, s86
	v_lshl_add_u64 v[64:65], v[172:173], 0, s[60:61]
	s_add_i32 s85, s85, 0x10000
	s_mov_b32 s17, m0
	s_mov_b32 m0, s85
	s_nop 0
	global_load_lds_dwordx4 v[64:65], off
	s_mov_b32 m0, s17
	v_add_f32_e32 v174, v198, v68
	v_mfma_f32_32x32x16_bf16 v[48:63], v[156:159], v[178:181], v[48:63]
	ds_read_b64_tr_b16 v[76:77], v188 offset:32768
	ds_read_b64_tr_b16 v[78:79], v188 offset:33280
	v_exp_f32_e32 v96, v96
	v_exp_f32_e32 v97, v97
	v_mfma_f32_32x32x16_bf16 v[32:47], v[156:159], v[128:131], v[32:47]
	ds_read_b64_tr_b16 v[112:113], v188 offset:36864
	ds_read_b64_tr_b16 v[114:115], v188 offset:37376
	v_exp_f32_e32 v98, v98
	v_exp_f32_e32 v99, v99
	ds_read_b128 v[68:71], v234 offset:16384
	ds_read_b128 v[64:67], v234 offset:20480
	v_mfma_f32_32x32x16_bf16 v[48:63], v[152:155], v[132:135], v[48:63]
	ds_read_b64_tr_b16 v[120:121], v188 offset:33792
	ds_read_b64_tr_b16 v[122:123], v188 offset:34304
	v_exp_f32_e32 v100, v100
	v_exp_f32_e32 v101, v101
	ds_read_b128 v[164:167], v235 offset:16384
	ds_read_b128 v[140:143], v235 offset:20480
	v_mfma_f32_32x32x16_bf16 v[32:47], v[152:155], v[136:139], v[32:47]
	ds_read_b64_tr_b16 v[178:179], v188 offset:37888
	ds_read_b64_tr_b16 v[180:181], v188 offset:38400
	v_exp_f32_e32 v102, v102
	v_exp_f32_e32 v103, v103
	ds_read_b128 v[160:163], v236 offset:16384
	ds_read_b128 v[132:135], v236 offset:20480
	v_mfma_f32_32x32x16_bf16 v[48:63], v[148:151], v[124:127], v[48:63]
	ds_read_b64_tr_b16 v[194:195], v188 offset:34816
	ds_read_b64_tr_b16 v[196:197], v188 offset:35328
	v_exp_f32_e32 v104, v104
	v_exp_f32_e32 v105, v105
	ds_read_b128 v[136:139], v237 offset:16384
	ds_read_b128 v[128:131], v237 offset:20480
	v_mfma_f32_32x32x16_bf16 v[32:47], v[148:151], v[190:193], v[32:47]
	ds_read_b64_tr_b16 v[124:125], v188 offset:38912
	ds_read_b64_tr_b16 v[126:127], v188 offset:39424
	v_exp_f32_e32 v106, v106
	v_exp_f32_e32 v107, v107
	v_mfma_f32_32x32x16_bf16 v[48:63], v[144:147], v[116:119], v[48:63]
	ds_read_b64_tr_b16 v[190:191], v188 offset:35840
	ds_read_b64_tr_b16 v[192:193], v188 offset:36352
	v_exp_f32_e32 v108, v108
	v_exp_f32_e32 v109, v109
	v_mfma_f32_32x32x16_bf16 v[32:47], v[144:147], v[72:75], v[32:47]
	ds_read_b64_tr_b16 v[116:117], v188 offset:39936
	ds_read_b64_tr_b16 v[118:119], v188 offset:40448
	v_exp_f32_e32 v110, v110
	v_exp_f32_e32 v111, v111
	s_waitcnt lgkmcnt(14)
	v_mfma_f32_32x32x16_bf16 v[16:31], v[156:159], v[76:79], v[16:31]
	v_exp_f32_e32 v80, v80
	v_exp_f32_e32 v81, v81
	v_mfma_f32_32x32x16_bf16 v[0:15], v[156:159], v[112:115], v[0:15]
	v_exp_f32_e32 v82, v82
	v_exp_f32_e32 v83, v83
	v_mfma_f32_32x32x16_bf16 v[16:31], v[152:155], v[120:123], v[16:31]
	v_exp_f32_e32 v84, v84
	v_exp_f32_e32 v85, v85
	s_waitcnt lgkmcnt(12)
	v_mfma_f32_32x32x16_bf16 v[0:15], v[152:155], v[178:181], v[0:15]
	v_exp_f32_e32 v86, v86
	v_exp_f32_e32 v87, v87
	s_waitcnt lgkmcnt(8)
	v_mfma_f32_32x32x16_bf16 v[16:31], v[148:151], v[194:197], v[16:31]
	v_exp_f32_e32 v88, v88
	v_exp_f32_e32 v89, v89
	s_waitcnt lgkmcnt(4)
	v_mfma_f32_32x32x16_bf16 v[0:15], v[148:151], v[124:127], v[0:15]
	v_exp_f32_e32 v90, v90
	v_exp_f32_e32 v91, v91
	s_waitcnt lgkmcnt(2)
	v_mfma_f32_32x32x16_bf16 v[16:31], v[144:147], v[190:193], v[16:31]
	v_exp_f32_e32 v92, v92
	v_exp_f32_e32 v93, v93
	s_waitcnt lgkmcnt(0)
	v_mfma_f32_32x32x16_bf16 v[0:15], v[144:147], v[116:119], v[0:15]
	v_exp_f32_e32 v94, v94
	v_exp_f32_e32 v95, v95
	s_waitcnt vmcnt(2) lgkmcnt(0)
	s_barrier
	ds_read_b64_tr_b16 v[178:179], v188 offset:40960
	ds_read_b64_tr_b16 v[180:181], v188 offset:41472
	v_add_f32_e32 v76, v96, v97
	ds_read_b128 v[72:75], v168
	v_add_f32_e32 v76, v98, v76
	v_add_f32_e32 v76, v99, v76
	v_add_f32_e32 v76, v100, v76
	v_add_f32_e32 v76, v101, v76
	v_cvt_pk_bf16_f32 v156, v96, v97
	v_cvt_pk_bf16_f32 v157, v98, v99
	s_waitcnt lgkmcnt(0)
	v_mfma_f32_32x32x16_bf16 v[112:127], v[68:71], v[72:75], 0
	ds_read_b64_tr_b16 v[96:97], v188 offset:45056
	ds_read_b64_tr_b16 v[98:99], v188 offset:45568
	ds_read_b128 v[68:71], v168
	v_add_f32_e32 v72, v102, v76
	v_add_f32_e32 v72, v103, v72
	v_add_f32_e32 v72, v104, v72
	v_add_f32_e32 v144, v105, v72
	s_waitcnt lgkmcnt(0)
	v_mfma_f32_32x32x16_bf16 v[64:79], v[64:67], v[68:71], 0
	v_cvt_pk_bf16_f32 v158, v100, v101
	v_cvt_pk_bf16_f32 v159, v102, v103
	ds_read_b64_tr_b16 v[100:101], v188 offset:41984
	ds_read_b64_tr_b16 v[102:103], v188 offset:42496
	ds_read_b128 v[190:193], v168 offset:1024
	v_add_f32_e32 v144, v106, v144
	v_add_f32_e32 v144, v107, v144
	v_add_f32_e32 v144, v108, v144
	v_add_f32_e32 v144, v109, v144
	v_cvt_pk_bf16_f32 v152, v104, v105
	v_cvt_pk_bf16_f32 v153, v106, v107
	s_waitcnt lgkmcnt(0)
	v_mfma_f32_32x32x16_bf16 v[112:127], v[164:167], v[190:193], v[112:127]
	ds_read_b64_tr_b16 v[104:105], v188 offset:46080
	ds_read_b64_tr_b16 v[106:107], v188 offset:46592
	ds_read_b128 v[164:167], v168 offset:1024
	v_add_f32_e32 v144, v110, v144
	v_add_f32_e32 v144, v111, v144
	v_add_f32_e32 v144, v80, v144
	v_add_f32_e32 v144, v81, v144
	s_waitcnt lgkmcnt(0)
	v_mfma_f32_32x32x16_bf16 v[64:79], v[140:143], v[164:167], v[64:79]
	v_cvt_pk_bf16_f32 v154, v108, v109
	v_cvt_pk_bf16_f32 v155, v110, v111
	ds_read_b64_tr_b16 v[108:109], v188 offset:43008
	ds_read_b64_tr_b16 v[110:111], v188 offset:43520
	ds_read_b128 v[140:143], v168 offset:2048
	v_add_f32_e32 v144, v82, v144
	v_add_f32_e32 v144, v83, v144
	v_add_f32_e32 v144, v84, v144
	v_add_f32_e32 v144, v85, v144
	v_cvt_pk_bf16_f32 v148, v80, v81
	v_cvt_pk_bf16_f32 v149, v82, v83
	s_waitcnt lgkmcnt(0)
	v_mfma_f32_32x32x16_bf16 v[112:127], v[160:163], v[140:143], v[112:127]
	ds_read_b64_tr_b16 v[190:191], v188 offset:47104
	ds_read_b64_tr_b16 v[192:193], v188 offset:47616
	ds_read_b128 v[80:83], v168 offset:2048
	v_add_f32_e32 v140, v86, v144
	v_add_f32_e32 v140, v87, v140
	v_add_f32_e32 v140, v88, v140
	v_add_f32_e32 v140, v89, v140
	s_waitcnt lgkmcnt(0)
	v_mfma_f32_32x32x16_bf16 v[64:79], v[132:135], v[80:83], v[64:79]
	v_cvt_pk_bf16_f32 v150, v84, v85
	v_cvt_pk_bf16_f32 v151, v86, v87
	ds_read_b64_tr_b16 v[84:85], v188 offset:44032
	ds_read_b64_tr_b16 v[86:87], v188 offset:44544
	ds_read_b128 v[80:83], v168 offset:3072
	v_add_f32_e32 v132, v90, v140
	v_add_f32_e32 v132, v91, v132
	v_add_f32_e32 v132, v92, v132
	v_add_f32_e32 v132, v93, v132
	v_cvt_pk_bf16_f32 v144, v88, v89
	v_cvt_pk_bf16_f32 v145, v90, v91
	s_waitcnt lgkmcnt(0)
	v_mfma_f32_32x32x16_bf16 v[112:127], v[136:139], v[80:83], v[112:127]
	ds_read_b64_tr_b16 v[88:89], v188 offset:48128
	ds_read_b64_tr_b16 v[90:91], v188 offset:48640
	ds_read_b128 v[80:83], v168 offset:3072
	v_add_f32_e32 v132, v94, v132
	v_add_f32_e32 v132, v95, v132
	v_add_f32_e32 v132, 0, v132
	v_cvt_pk_bf16_f32 v146, v92, v93
	s_waitcnt lgkmcnt(0)
	v_mfma_f32_32x32x16_bf16 v[64:79], v[128:131], v[80:83], v[64:79]
	v_cvt_pk_bf16_f32 v147, v94, v95
	v_lshl_add_u64 v[80:81], v[170:171], 0, s[64:65]
	s_mov_b32 s17, m0
	s_mov_b32 m0, s16
	s_nop 0
	global_load_lds_dwordx4 v[80:81], off
	s_mov_b32 m0, s17
	v_lshl_add_u64 v[80:81], v[172:173], 0, s[64:65]
	s_mov_b32 s16, m0
	s_mov_b32 m0, s35
	s_nop 0
	global_load_lds_dwordx4 v[80:81], off
	s_mov_b32 m0, s16
	v_add_f32_e32 v174, v174, v132
	v_mfma_f32_32x32x16_bf16 v[48:63], v[156:159], v[178:181], v[48:63]
	ds_read_b64_tr_b16 v[92:93], v188 offset:49152
	ds_read_b64_tr_b16 v[94:95], v188 offset:49664
	v_exp_f32_e32 v112, v112
	v_exp_f32_e32 v113, v113
	v_mfma_f32_32x32x16_bf16 v[32:47], v[156:159], v[96:99], v[32:47]
	ds_read_b64_tr_b16 v[170:171], v188 offset:53248
	ds_read_b64_tr_b16 v[172:173], v188 offset:53760
	v_exp_f32_e32 v114, v114
	v_exp_f32_e32 v115, v115
	ds_read_b128 v[80:83], v234
	ds_read_b128 v[96:99], v234 offset:4096
	v_mfma_f32_32x32x16_bf16 v[48:63], v[152:155], v[100:103], v[48:63]
	ds_read_b64_tr_b16 v[178:179], v188 offset:50176
	ds_read_b64_tr_b16 v[180:181], v188 offset:50688
	v_exp_f32_e32 v116, v116
	v_exp_f32_e32 v117, v117
	ds_read_b128 v[164:167], v235
	ds_read_b128 v[140:143], v235 offset:4096
	v_mfma_f32_32x32x16_bf16 v[32:47], v[152:155], v[104:107], v[32:47]
	ds_read_b64_tr_b16 v[100:101], v188 offset:54272
	ds_read_b64_tr_b16 v[102:103], v188 offset:54784
	v_exp_f32_e32 v118, v118
	v_exp_f32_e32 v119, v119
	ds_read_b128 v[160:163], v236
	ds_read_b128 v[132:135], v236 offset:4096
	v_mfma_f32_32x32x16_bf16 v[48:63], v[148:151], v[108:111], v[48:63]
	ds_read_b64_tr_b16 v[104:105], v188 offset:51200
	ds_read_b64_tr_b16 v[106:107], v188 offset:51712
	v_exp_f32_e32 v120, v120
	v_exp_f32_e32 v121, v121
	ds_read_b128 v[136:139], v237
	ds_read_b128 v[128:131], v237 offset:4096
	v_mfma_f32_32x32x16_bf16 v[32:47], v[148:151], v[190:193], v[32:47]
	ds_read_b64_tr_b16 v[108:109], v188 offset:55296
	ds_read_b64_tr_b16 v[110:111], v188 offset:55808
	v_exp_f32_e32 v122, v122
	v_exp_f32_e32 v123, v123
	v_mfma_f32_32x32x16_bf16 v[48:63], v[144:147], v[84:87], v[48:63]
	ds_read_b64_tr_b16 v[190:191], v188 offset:52224
	ds_read_b64_tr_b16 v[192:193], v188 offset:52736
	v_exp_f32_e32 v124, v124
	v_exp_f32_e32 v125, v125
	v_mfma_f32_32x32x16_bf16 v[32:47], v[144:147], v[88:91], v[32:47]
	ds_read_b64_tr_b16 v[84:85], v188 offset:56320
	ds_read_b64_tr_b16 v[86:87], v188 offset:56832
	v_exp_f32_e32 v126, v126
	v_exp_f32_e32 v127, v127
	s_waitcnt lgkmcnt(14)
	v_mfma_f32_32x32x16_bf16 v[16:31], v[156:159], v[92:95], v[16:31]
	v_exp_f32_e32 v64, v64
	v_exp_f32_e32 v65, v65
	v_mfma_f32_32x32x16_bf16 v[0:15], v[156:159], v[170:173], v[0:15]
	v_exp_f32_e32 v66, v66
	v_exp_f32_e32 v67, v67
	v_mfma_f32_32x32x16_bf16 v[16:31], v[152:155], v[178:181], v[16:31]
	v_exp_f32_e32 v68, v68
	v_exp_f32_e32 v69, v69
	s_waitcnt lgkmcnt(12)
	v_mfma_f32_32x32x16_bf16 v[0:15], v[152:155], v[100:103], v[0:15]
	v_exp_f32_e32 v70, v70
	v_exp_f32_e32 v71, v71
	s_waitcnt lgkmcnt(8)
	v_mfma_f32_32x32x16_bf16 v[16:31], v[148:151], v[104:107], v[16:31]
	v_exp_f32_e32 v72, v72
	v_exp_f32_e32 v73, v73
	s_waitcnt lgkmcnt(4)
	v_mfma_f32_32x32x16_bf16 v[0:15], v[148:151], v[108:111], v[0:15]
	v_exp_f32_e32 v74, v74
	v_exp_f32_e32 v75, v75
	s_waitcnt lgkmcnt(2)
	v_mfma_f32_32x32x16_bf16 v[16:31], v[144:147], v[190:193], v[16:31]
	v_exp_f32_e32 v76, v76
	v_exp_f32_e32 v77, v77
	s_waitcnt lgkmcnt(0)
	v_mfma_f32_32x32x16_bf16 v[0:15], v[144:147], v[84:87], v[0:15]
	v_exp_f32_e32 v78, v78
	v_exp_f32_e32 v79, v79
	s_waitcnt vmcnt(0) lgkmcnt(0)
	s_barrier
;   #define RESC() do{ if(!NOMAX&&resc){ asm volatile("s_waitcnt lgkmcnt(0)":::"memory"); \
;       _Pragma("unroll") for(int d_=0;d_<2*VM;++d_) _Pragma("unroll") for(int r=0;r<16;++r)o[d_][r]*=wsf[crow(r,hi)]; } }while(0)
; template<int THRL,int VM,bool NOMAX> __device__ __forceinline__ void attn_unit(const bf16*Qb,const bf16*__restrict__ Kh,const bf16*__restrict__ Vh,bf16*Ob,const int NT,const int sp,float*wscr,char*shm){
;     ...
;   STEP(pB0,pB1,pA0,pA1,NT-1,false,false,false); RESC();
	ds_read_b64_tr_b16 v[170:171], v188 offset:57344
	ds_read_b64_tr_b16 v[172:173], v188 offset:57856
	v_add_f32_e32 v88, v112, v113
	ds_read_b128 v[84:87], v168
	v_add_f32_e32 v88, v114, v88
	v_add_f32_e32 v88, v115, v88
	v_add_f32_e32 v88, v116, v88
	v_add_f32_e32 v104, v117, v88
	v_cvt_pk_bf16_f32 v156, v112, v113
	v_cvt_pk_bf16_f32 v157, v114, v115
	s_waitcnt lgkmcnt(0)
	v_mfma_f32_32x32x16_bf16 v[80:95], v[80:83], v[84:87], 0
	ds_read_b64_tr_b16 v[112:113], v188 offset:61440
	ds_read_b64_tr_b16 v[114:115], v188 offset:61952
	ds_read_b128 v[100:103], v168
	v_add_f32_e32 v104, v118, v104
	v_add_f32_e32 v104, v119, v104
	v_add_f32_e32 v104, v120, v104
	v_add_f32_e32 v144, v121, v104
	v_cvt_pk_bf16_f32 v158, v116, v117
	v_cvt_pk_bf16_f32 v159, v118, v119
	s_waitcnt lgkmcnt(0)
	v_mfma_f32_32x32x16_bf16 v[96:111], v[96:99], v[100:103], 0
	ds_read_b64_tr_b16 v[116:117], v188 offset:58368
	ds_read_b64_tr_b16 v[118:119], v188 offset:58880
	ds_read_b128 v[178:181], v168 offset:1024
	v_add_f32_e32 v144, v122, v144
	v_add_f32_e32 v144, v123, v144
	v_add_f32_e32 v144, v124, v144
	v_add_f32_e32 v144, v125, v144
	v_cvt_pk_bf16_f32 v152, v120, v121
	v_cvt_pk_bf16_f32 v153, v122, v123
	s_waitcnt lgkmcnt(0)
	v_mfma_f32_32x32x16_bf16 v[80:95], v[164:167], v[178:181], v[80:95]
	ds_read_b64_tr_b16 v[120:121], v188 offset:62464
	ds_read_b64_tr_b16 v[122:123], v188 offset:62976
	ds_read_b128 v[164:167], v168 offset:1024
	v_add_f32_e32 v144, v126, v144
	v_add_f32_e32 v144, v127, v144
	v_add_f32_e32 v144, v64, v144
	v_add_f32_e32 v144, v65, v144
	v_cvt_pk_bf16_f32 v154, v124, v125
	v_cvt_pk_bf16_f32 v155, v126, v127
	s_waitcnt lgkmcnt(0)
	v_mfma_f32_32x32x16_bf16 v[96:111], v[140:143], v[164:167], v[96:111]
	ds_read_b64_tr_b16 v[124:125], v188 offset:59392
	ds_read_b64_tr_b16 v[126:127], v188 offset:59904
	ds_read_b128 v[140:143], v168 offset:2048
	v_add_f32_e32 v144, v66, v144
	v_add_f32_e32 v144, v67, v144
	v_add_f32_e32 v144, v68, v144
	v_add_f32_e32 v144, v69, v144
	v_cvt_pk_bf16_f32 v148, v64, v65
	v_cvt_pk_bf16_f32 v149, v66, v67
	s_waitcnt lgkmcnt(0)
	v_mfma_f32_32x32x16_bf16 v[80:95], v[160:163], v[140:143], v[80:95]
	ds_read_b64_tr_b16 v[64:65], v188 offset:63488
	ds_read_b64_tr_b16 v[66:67], v188 offset:64000
	ds_read_b128 v[140:143], v168 offset:2048
	v_add_f32_e32 v144, v70, v144
	v_add_f32_e32 v144, v71, v144
	v_add_f32_e32 v144, v72, v144
	v_add_f32_e32 v144, v73, v144
	v_cvt_pk_bf16_f32 v150, v68, v69
	v_cvt_pk_bf16_f32 v151, v70, v71
	s_waitcnt lgkmcnt(0)
	v_mfma_f32_32x32x16_bf16 v[96:111], v[132:135], v[140:143], v[96:111]
	ds_read_b64_tr_b16 v[68:69], v188 offset:60416
	ds_read_b64_tr_b16 v[70:71], v188 offset:60928
	ds_read_b128 v[132:135], v168 offset:3072
	v_add_f32_e32 v140, v74, v144
	v_add_f32_e32 v140, v75, v140
	v_add_f32_e32 v140, v76, v140
	v_add_f32_e32 v140, v77, v140
	v_cvt_pk_bf16_f32 v144, v72, v73
	v_cvt_pk_bf16_f32 v145, v74, v75
	s_waitcnt lgkmcnt(0)
	v_mfma_f32_32x32x16_bf16 v[80:95], v[136:139], v[132:135], v[80:95]
	ds_read_b64_tr_b16 v[72:73], v188 offset:64512
	ds_read_b64_tr_b16 v[74:75], v188 offset:65024
	ds_read_b128 v[132:135], v168 offset:3072
	v_add_f32_e32 v136, v78, v140
	v_add_f32_e32 v136, v79, v136
	v_add_f32_e32 v136, 0, v136
	v_cvt_pk_bf16_f32 v146, v76, v77
	v_cvt_pk_bf16_f32 v147, v78, v79
	s_waitcnt lgkmcnt(0)
	v_mfma_f32_32x32x16_bf16 v[96:111], v[128:131], v[132:135], v[96:111]
	v_mfma_f32_32x32x16_bf16 v[48:63], v[156:159], v[170:173], v[48:63]
	ds_read_b64_tr_b16 v[76:77], v177 offset:40960
	ds_read_b64_tr_b16 v[78:79], v177 offset:41472
	v_exp_f32_e32 v80, v80
	v_exp_f32_e32 v81, v81
	v_mfma_f32_32x32x16_bf16 v[32:47], v[156:159], v[112:115], v[32:47]
	ds_read_b64_tr_b16 v[128:129], v177 offset:45056
	ds_read_b64_tr_b16 v[130:131], v177 offset:45568
	v_exp_f32_e32 v82, v82
	v_exp_f32_e32 v83, v83
	v_mfma_f32_32x32x16_bf16 v[48:63], v[152:155], v[116:119], v[48:63]
	ds_read_b64_tr_b16 v[112:113], v177 offset:41984
	ds_read_b64_tr_b16 v[114:115], v177 offset:42496
	v_exp_f32_e32 v84, v84
	v_exp_f32_e32 v85, v85
	v_mfma_f32_32x32x16_bf16 v[32:47], v[152:155], v[120:123], v[32:47]
	ds_read_b64_tr_b16 v[116:117], v177 offset:46080
	ds_read_b64_tr_b16 v[118:119], v177 offset:46592
	v_exp_f32_e32 v86, v86
	v_exp_f32_e32 v87, v87
	v_mfma_f32_32x32x16_bf16 v[48:63], v[148:151], v[124:127], v[48:63]
	ds_read_b64_tr_b16 v[120:121], v177 offset:43008
	ds_read_b64_tr_b16 v[122:123], v177 offset:43520
	v_exp_f32_e32 v88, v88
	v_exp_f32_e32 v89, v89
	v_mfma_f32_32x32x16_bf16 v[32:47], v[148:151], v[64:67], v[32:47]
	ds_read_b64_tr_b16 v[124:125], v177 offset:47104
	ds_read_b64_tr_b16 v[126:127], v177 offset:47616
	v_exp_f32_e32 v90, v90
	v_exp_f32_e32 v91, v91
	v_mfma_f32_32x32x16_bf16 v[48:63], v[144:147], v[68:71], v[48:63]
	ds_read_b64_tr_b16 v[64:65], v177 offset:44032
	ds_read_b64_tr_b16 v[66:67], v177 offset:44544
	v_exp_f32_e32 v92, v92
	v_exp_f32_e32 v93, v93
	v_mfma_f32_32x32x16_bf16 v[32:47], v[144:147], v[72:75], v[32:47]
	ds_read_b64_tr_b16 v[68:69], v177 offset:48128
	ds_read_b64_tr_b16 v[70:71], v177 offset:48640
	v_exp_f32_e32 v94, v94
	v_exp_f32_e32 v95, v95
	s_waitcnt lgkmcnt(14)
	v_mfma_f32_32x32x16_bf16 v[16:31], v[156:159], v[76:79], v[16:31]
	v_exp_f32_e32 v96, v96
	v_exp_f32_e32 v97, v97
	s_waitcnt lgkmcnt(12)
; #define SBAR() __builtin_amdgcn_sched_barrier(0)
;   #define RESC() do{ if(!NOMAX&&resc){ asm volatile("s_waitcnt lgkmcnt(0)":::"memory"); \
;       _Pragma("unroll") for(int d_=0;d_<2*VM;++d_) _Pragma("unroll") for(int r=0;r<16;++r)o[d_][r]*=wsf[crow(r,hi)]; } }while(0)
;   #define PKW(P,B) cvtpk_s(P[B],P[B+1])
; __device__ __forceinline__ void pv(f32x16*o,int vb,bf16x8 pa0,bf16x8 pa1,bf16x8 pa2,bf16x8 pa3){
;   #pragma unroll
;   for(int d0=0;d0<2;++d0){s16x4 lo[4],hi[4];
;     #pragma unroll
;     for(int ks=0;ks<4;++ks){
;       asm volatile("ds_read_b64_tr_b16 %0,%1 offset:%c2":"=&v"(lo[ks]):"v"(vb),"i"(d0*4096+ks*1024):"memory");
;       asm volatile("ds_read_b64_tr_b16 %0,%1 offset:%c2":"=&v"(hi[ks]):"v"(vb),"i"(d0*4096+ks*1024+512):"memory");}
;     asm volatile("s_waitcnt lgkmcnt(0)":::"memory");SBAR();
;     ...
;     o[d0]=__builtin_amdgcn_mfma_f32_32x32x16_bf16(pa0,PK(0),o[d0],0,0,0);
;     o[d0]=__builtin_amdgcn_mfma_f32_32x32x16_bf16(pa1,PK(1),o[d0],0,0,0);
;     o[d0]=__builtin_amdgcn_mfma_f32_32x32x16_bf16(pa2,PK(2),o[d0],0,0,0);
;     o[d0]=__builtin_amdgcn_mfma_f32_32x32x16_bf16(pa3,PK(3),o[d0],0,0,0);
;     ...
;   }
; }
; template<int THRL,int VM,bool NOMAX> __device__ __forceinline__ void attn_unit(const bf16*Qb,const bf16*__restrict__ Kh,const bf16*__restrict__ Vh,bf16*Ob,const int NT,const int sp,float*wscr,char*shm){
;     ...
;   STEP(pB0,pB1,pA0,pA1,NT-1,false,false,false); RESC();
;   { float sacc=pB0[0]+pB0[1]; _Pragma("unroll") for(int r=2;r<16;++r)sacc+=pB0[r]; _Pragma("unroll") for(int r=0;r<16;++r)sacc+=pB1[r]; l_reg+=sacc;
;     pw0=(u32x4){PKW(pB0,0),PKW(pB0,2),PKW(pB0,4),PKW(pB0,6)};pw1=(u32x4){PKW(pB0,8),PKW(pB0,10),PKW(pB0,12),PKW(pB0,14)};pw2=(u32x4){PKW(pB1,0),PKW(pB1,2),PKW(pB1,4),PKW(pB1,6)};pw3=(u32x4){PKW(pB1,8),PKW(pB1,10),PKW(pB1,12),PKW(pB1,14)};
;     SBAR(); pv(o,vb0+VM*sl_cur,PAF(0),PAF(1),PAF(2),PAF(3)); if constexpr(VM==2) pv(o+2,vb0+VM*sl_cur+8192,PAF(0),PAF(1),PAF(2),PAF(3)); }
;     ...
;   {auto rr=__builtin_amdgcn_permlane32_swap(__float_as_uint(l_reg),__float_as_uint(l_reg),false,false);l_reg=__uint_as_float(rr[0])+__uint_as_float(rr[1]);}
;   if(hi==0)wsf[32+r32]=l_reg;asm volatile("s_waitcnt lgkmcnt(0)":::"memory");
	v_mfma_f32_32x32x16_bf16 v[0:15], v[156:159], v[128:131], v[0:15]
	v_exp_f32_e32 v98, v98
	v_exp_f32_e32 v99, v99
	s_waitcnt lgkmcnt(10)
	v_mfma_f32_32x32x16_bf16 v[16:31], v[152:155], v[112:115], v[16:31]
	v_exp_f32_e32 v100, v100
	v_exp_f32_e32 v101, v101
	s_waitcnt lgkmcnt(8)
	v_mfma_f32_32x32x16_bf16 v[0:15], v[152:155], v[116:119], v[0:15]
	v_exp_f32_e32 v102, v102
	v_exp_f32_e32 v103, v103
	s_waitcnt lgkmcnt(6)
	v_mfma_f32_32x32x16_bf16 v[16:31], v[148:151], v[120:123], v[16:31]
	v_exp_f32_e32 v104, v104
	v_exp_f32_e32 v105, v105
	s_waitcnt lgkmcnt(4)
	v_mfma_f32_32x32x16_bf16 v[0:15], v[148:151], v[124:127], v[0:15]
	v_exp_f32_e32 v106, v106
	v_exp_f32_e32 v107, v107
	s_waitcnt lgkmcnt(2)
	v_mfma_f32_32x32x16_bf16 v[16:31], v[144:147], v[64:67], v[16:31]
	v_exp_f32_e32 v108, v108
	v_exp_f32_e32 v109, v109
	s_waitcnt lgkmcnt(0)
	v_mfma_f32_32x32x16_bf16 v[0:15], v[144:147], v[68:71], v[0:15]
	v_exp_f32_e32 v110, v110
	v_exp_f32_e32 v111, v111
	v_add_f32_e32 v64, v80, v81
	v_add_f32_e32 v64, v82, v64
	v_add_f32_e32 v64, v83, v64
	v_add_f32_e32 v64, v84, v64
	v_add_f32_e32 v64, v85, v64
	v_add_f32_e32 v64, v86, v64
	v_add_f32_e32 v64, v87, v64
	v_add_f32_e32 v64, v88, v64
	v_add_f32_e32 v64, v89, v64
	v_add_f32_e32 v64, v90, v64
	v_add_f32_e32 v64, v91, v64
	v_add_f32_e32 v64, v92, v64
	v_add_f32_e32 v64, v93, v64
	v_add_f32_e32 v64, v94, v64
	v_add_f32_e32 v64, v95, v64
	v_add_f32_e32 v64, v64, v96
	v_add_f32_e32 v64, v97, v64
	v_add_f32_e32 v64, v98, v64
	v_add_f32_e32 v64, v99, v64
	v_add_f32_e32 v64, v100, v64
	v_add_f32_e32 v64, v101, v64
	v_add_f32_e32 v64, v102, v64
	v_add_f32_e32 v64, v103, v64
	v_add_f32_e32 v64, v104, v64
	v_add_f32_e32 v64, v105, v64
	v_add_f32_e32 v64, v106, v64
	v_add_f32_e32 v64, v107, v64
	v_add_f32_e32 v64, v108, v64
	v_add_f32_e32 v64, v109, v64
	v_add_f32_e32 v64, v110, v64
	v_add_f32_e32 v64, v111, v64
	v_add_f32_e32 v65, v174, v136
	v_add_f32_e32 v64, v65, v64
	v_cvt_pk_bf16_f32 v66, v80, v81
	v_cvt_pk_bf16_f32 v67, v82, v83
	v_cvt_pk_bf16_f32 v68, v84, v85
	v_cvt_pk_bf16_f32 v69, v86, v87
	v_cvt_pk_bf16_f32 v70, v88, v89
	v_cvt_pk_bf16_f32 v71, v90, v91
	v_cvt_pk_bf16_f32 v72, v92, v93
	v_cvt_pk_bf16_f32 v73, v94, v95
	v_cvt_pk_bf16_f32 v74, v96, v97
	v_cvt_pk_bf16_f32 v75, v98, v99
	v_cvt_pk_bf16_f32 v76, v100, v101
	v_cvt_pk_bf16_f32 v77, v102, v103
	v_cvt_pk_bf16_f32 v78, v104, v105
	v_cvt_pk_bf16_f32 v79, v106, v107
	v_cvt_pk_bf16_f32 v80, v108, v109
	v_cvt_pk_bf16_f32 v81, v110, v111
	ds_read_b64_tr_b16 v[82:83],v176 offset:0
	ds_read_b64_tr_b16 v[84:85],v176 offset:512
	ds_read_b64_tr_b16 v[86:87],v176 offset:1024
	ds_read_b64_tr_b16 v[88:89],v176 offset:1536
	ds_read_b64_tr_b16 v[90:91],v176 offset:2048
	ds_read_b64_tr_b16 v[92:93],v176 offset:2560
	ds_read_b64_tr_b16 v[94:95],v176 offset:3072
	ds_read_b64_tr_b16 v[96:97],v176 offset:3584
	s_waitcnt lgkmcnt(0)
	s_nop 0
	v_mfma_f32_32x32x16_bf16 v[48:63], v[66:69], v[82:85], v[48:63]
	ds_read_b64_tr_b16 v[82:83],v176 offset:4096
	ds_read_b64_tr_b16 v[84:85],v176 offset:4608
	v_mfma_f32_32x32x16_bf16 v[48:63], v[70:73], v[86:89], v[48:63]
	ds_read_b64_tr_b16 v[86:87],v176 offset:5120
	ds_read_b64_tr_b16 v[88:89],v176 offset:5632
	v_mfma_f32_32x32x16_bf16 v[48:63], v[74:77], v[90:93], v[48:63]
	ds_read_b64_tr_b16 v[90:91],v176 offset:6144
	ds_read_b64_tr_b16 v[92:93],v176 offset:6656
	ds_read_b64_tr_b16 v[98:99],v176 offset:7168
	ds_read_b64_tr_b16 v[100:101],v176 offset:7680
	s_waitcnt lgkmcnt(0)
	v_mfma_f32_32x32x16_bf16 v[48:63], v[78:81], v[94:97], v[48:63]
	v_mfma_f32_32x32x16_bf16 v[32:47], v[66:69], v[82:85], v[32:47]
	v_add_u32_e32 v65, 0x2000, v176
	ds_read_b64_tr_b16 v[82:83],v65 offset:0
	ds_read_b64_tr_b16 v[84:85],v65 offset:512
	v_mfma_f32_32x32x16_bf16 v[32:47], v[70:73], v[86:89], v[32:47]
	ds_read_b64_tr_b16 v[86:87],v65 offset:1024
	ds_read_b64_tr_b16 v[88:89],v65 offset:1536
	v_mfma_f32_32x32x16_bf16 v[32:47], v[74:77], v[90:93], v[32:47]
	ds_read_b64_tr_b16 v[90:91],v65 offset:2048
	ds_read_b64_tr_b16 v[92:93],v65 offset:2560
	ds_read_b64_tr_b16 v[94:95],v65 offset:3072
	ds_read_b64_tr_b16 v[96:97],v65 offset:3584
	s_waitcnt lgkmcnt(0)
	v_mfma_f32_32x32x16_bf16 v[32:47], v[78:81], v[98:101], v[32:47]
	v_mfma_f32_32x32x16_bf16 v[16:31], v[66:69], v[82:85], v[16:31]
	ds_read_b64_tr_b16 v[82:83],v65 offset:4096
	ds_read_b64_tr_b16 v[84:85],v65 offset:4608
	v_mfma_f32_32x32x16_bf16 v[16:31], v[70:73], v[86:89], v[16:31]
	ds_read_b64_tr_b16 v[86:87],v65 offset:5120
	ds_read_b64_tr_b16 v[88:89],v65 offset:5632
	v_mfma_f32_32x32x16_bf16 v[16:31], v[74:77], v[90:93], v[16:31]
	ds_read_b64_tr_b16 v[90:91],v65 offset:6144
	ds_read_b64_tr_b16 v[92:93],v65 offset:6656
	ds_read_b64_tr_b16 v[98:99],v65 offset:7168
	ds_read_b64_tr_b16 v[100:101],v65 offset:7680
	s_waitcnt lgkmcnt(0)
	v_mfma_f32_32x32x16_bf16 v[16:31], v[78:81], v[94:97], v[16:31]
	v_mfma_f32_32x32x16_bf16 v[0:15], v[66:69], v[82:85], v[0:15]
	v_mov_b32_e32 v65, v64
	s_nop 1
	v_permlane32_swap_b32_e32 v64, v65
	v_cmp_gt_u32_e32 vcc, 32, v187
	v_mfma_f32_32x32x16_bf16 v[0:15], v[70:73], v[86:89], v[0:15]
	v_mfma_f32_32x32x16_bf16 v[0:15], v[74:77], v[90:93], v[0:15]
	v_mfma_f32_32x32x16_bf16 v[0:15], v[78:81], v[98:101], v[0:15]
	s_and_saveexec_b64 s[16:17], vcc
	s_cbranch_execz .LBB0_870
	v_add_f32_e32 v64, v64, v65
	v_lshl_add_u32 v65, v186, 2, s34
	ds_write_b32 v65, v64 offset:128
	s_branch .LBB0_870

; #define WAIT_BAR(N) asm volatile("s_waitcnt vmcnt(" #N ") lgkmcnt(0)\n\ts_barrier":::"memory")
;   #define DMA_K(t,slot) glds16(ksrc+(long)(t)*KVBLK*KVP,(unsigned)__builtin_amdgcn_readfirstlane(kdst+(slot)))
;   #define DMA_V(t,slot) do{ glds16(vsrc+(long)(t)*KVBLK*KVP,(unsigned)__builtin_amdgcn_readfirstlane(vdst+VM*(slot))); if constexpr(VM==2) glds16(vsrc+64+(long)(t)*KVBLK*KVP,(unsigned)__builtin_amdgcn_readfirstlane(vdst+VM*(slot)+8192)); }while(0)
; template<int THRL,int VM,bool NOMAX> __device__ __forceinline__ void attn_unit(const bf16*Qb,const bf16*__restrict__ Kh,const bf16*__restrict__ Vh,bf16*Ob,const int NT,const int sp,float*wscr,char*shm){
;     ...
;   const bf16*Qw=Qb+(long)(wid*QBLK)*QOP;
;   const unsigned lds0=(unsigned)(uintptr_t)shm;
;   constexpr int LDS_WS_=LDS_V+3*VM*SLOTB, LDS_OST_=LDS_WS_+NW*64*4;
;   float*wsf=(float*)(shm+LDS_WS_)+wid*64;
;   const bf16*ksrc=Kh+(long)lane*KVP+wid*8;
;   const bf16*vsrc=Vh+(long)(16*(wid&3)+(lane>>2))*KVP+(wid>>2)*32+(lane&3)*8;
;   const unsigned kdst=lds0+LDS_K+wid*1024, vdst=lds0+LDS_V+wid*1024;
;     ...
;   const int vb0=(int)(lds0+LDS_V)+((lane>>4)&1)*32+(lane&3)*8+(4*hi+((lane&15)>>2))*64;
;   const char*Kbase=shm+LDS_K; bf16x8 kf[8];
;   const lds_cptr shm3=(lds_cptr)shm; const lds_cptr kp0=shm3+LDS_K+hi*1024+r32*16; const lds_cptr vp0=shm3+LDS_V+((lane>>4)&1)*32+(lane&3)*8+(4*hi+((lane&15)>>2))*64;
;   if(wid>=4)__builtin_amdgcn_s_setprio(1);
;   DMA_K(0,0);DMA_V(0,0);DMA_K(1,SLOTB);
;   bf16x8 qr[4];
;   #pragma unroll
;   for(int d0=0;d0<4;++d0)qr[d0]=*reinterpret_cast<const bf16x8*>(&Qw[(long)r32*QOP+d0*16+hi*8]);
;   const lds_cptr qpk=shm3+LDS_OST_+wid*4096+lane*16;
;   if constexpr(VM==2){
;     #pragma unroll
;     for(int d0=0;d0<4;++d0)*(__attribute__((address_space(3))) bf16x8*)(const_cast<__attribute__((address_space(3))) char*>(qpk)+d0*1024)=qr[d0]; }
;   float mhat=0.f,l_reg=0.f;f32x16 o[2*VM];
;   #pragma unroll
;   for(int d_=0;d_<2*VM;++d_)o[d_]=f32x16{};
;  f32x16 negm=f32x16{}; if constexpr(VM==1){asm volatile("":"+v"(negm));}
;   bool resc=false;
;     ...
;   f32x16 pA0,pA1,pB0,pB1;
;   int sl_prev=0,sl_cur=0,sl_next=SLOTB;
;     ...
;   DMA_K(2,2*SLOTB);
;   WAIT_BAR(3);
;   qkt(pA0,pA1,Kbase,qr,negm,r32,hi);asm volatile("s_nop 15\n\ts_nop 7":"+v"(pA0),"+v"(pA1));
;   START(pA0,pA1);
;   _Pragma("unroll") for(int r=0;r<16;++r)pA1[r]=__builtin_amdgcn_exp2f(pA1[r]);
;   WAIT_BAR(0);
.LBB0_881:
	s_ashr_i32 s16, s19, 8
	s_ashr_i32 s17, s16, 31
	s_lshl_b32 s33, s19, 19
	s_and_b32 s33, s33, 0xf80000
	s_lshl_b64 s[34:35], s[16:17], 24
	s_add_u32 s17, s20, s34
	s_addc_u32 s34, s21, s35
	s_add_u32 s17, s17, s33
	s_addc_u32 s33, s34, 0
	s_lshl_b32 s34, s19, 2
	s_and_b32 s34, s34, 0x380
	s_add_u32 s50, s17, s34
	s_addc_u32 s33, s33, 0
	s_mul_hi_i32 s17, s16, 0x1400000
	s_mul_i32 s16, s16, 0x1400000
	s_add_u32 s16, s30, s16
	s_addc_u32 s17, s31, s17
	s_and_b32 s34, s19, 0x80
	s_add_u32 s16, s16, s34
	s_addc_u32 s17, s17, 0
	s_lshl_b32 s34, s28, 5
	s_ashr_i32 s35, s34, 31
	v_and_b32_e32 v178, 63, v48
	s_lshl_b64 s[34:35], s[34:35], 11
	s_add_u32 s50, s50, s34
	v_mul_u32_u24_e32 v16, 0x500, v178
	s_addc_u32 s51, s33, s35
	v_lshlrev_b32_e32 v168, 1, v16
	s_lshl_b32 s34, s28, 3
	v_lshl_add_u64 v[16:17], s[16:17], 0, v[168:169]
	s_ashr_i32 s35, s34, 31
	v_lshl_add_u64 v[172:173], s[34:35], 1, v[16:17]
	v_and_b32_e32 v246, 63, v210
	v_lshrrev_b32_e32 v247, 6, v210
	v_lshrrev_b32_e32 v248, 3, v246
	v_lshl_add_u32 v248, v247, 3, v248
	v_and_b32_e32 v249, 1, v247
	v_lshrrev_b32_e32 v250, 4, v246
	v_lshl_or_b32 v249, v249, 2, v250
	v_and_b32_e32 v250, 7, v246
	v_xor_b32_e32 v250, v250, v249
	v_sub_u32_e32 v248, v248, v246
	v_mul_i32_i24_e32 v248, 0xa00, v248
	v_sub_u32_e32 v250, v250, v247
	v_lshl_add_u32 v248, v250, 4, v248
	v_ashrrev_i32_e32 v249, 31, v248
	v_lshl_add_u64 v[172:173], v[248:249], 0, v[172:173]
	s_lshl_b32 s33, s28, 4
	v_bfe_u32 v16, v48, 2, 4
	v_and_or_b32 v16, s33, 48, v16
	v_mul_u32_u24_e32 v16, 0x500, v16
	v_lshlrev_b32_e32 v168, 1, v16
	v_lshl_add_u64 v[16:17], s[16:17], 0, v[168:169]
	s_ashr_i32 s16, s29, 3
	s_andn2_b32 s16, s16, 31
	s_ashr_i32 s17, s16, 31
	v_lshl_add_u64 v[16:17], s[16:17], 1, v[16:17]
	v_lshlrev_b32_e32 v179, 3, v48
	s_lshl_b32 s17, s28, 10
	v_and_b32_e32 v184, 24, v179
	s_cmp_lg_u32 0, -1
	v_lshlrev_b32_e32 v168, 1, v184
	s_cselect_b32 s16, 0, 0
	v_lshl_add_u64 v[88:89], v[16:17], 0, v[168:169]
	s_add_i32 s33, s17, s16
	s_mov_b32 s34, m0
	s_mov_b32 m0, s33
	s_nop 0
	global_load_lds_dwordx4 v[172:173], off
	s_mov_b32 m0, s34
	v_and_b32_e32 v180, 31, v48
	v_lshl_add_u64 v[170:171], v[88:89], 0, s[0:1]
	s_add_i32 s16, s33, 0x6000
	s_mov_b32 s34, m0
	s_mov_b32 m0, s16
	s_nop 0
	global_load_lds_dwordx4 v[170:171], off
	s_mov_b32 m0, s34
	v_lshl_add_u64 v[16:17], v[172:173], 0, s[6:7]
	v_bfe_u32 v181, v48, 5, 1
	s_add_i32 s34, s33, 0x2000
	s_mov_b32 s35, m0
	s_mov_b32 m0, s34
	s_nop 0
	global_load_lds_dwordx4 v[16:17], off
	s_mov_b32 m0, s35
	v_lshlrev_b32_e32 v16, 11, v180
	v_lshl_or_b32 v16, v181, 4, v16
	global_load_dwordx4 v[156:159], v16, s[50:51]
	global_load_dwordx4 v[152:155], v16, s[50:51] offset:32
	global_load_dwordx4 v[148:151], v16, s[50:51] offset:64
	global_load_dwordx4 v[144:147], v16, s[50:51] offset:96
	v_mov_b64_e32 v[30:31], v[14:15]
	v_mov_b64_e32 v[28:29], v[12:13]
	v_mov_b64_e32 v[26:27], v[10:11]
	v_mov_b64_e32 v[24:25], v[8:9]
	v_mov_b64_e32 v[22:23], v[6:7]
	v_mov_b64_e32 v[20:21], v[4:5]
	v_mov_b64_e32 v[18:19], v[2:3]
	v_mov_b64_e32 v[16:17], v[0:1]
	v_lshlrev_b32_e32 v32, 10, v181
	v_lshlrev_b32_e32 v33, 4, v180
	v_add3_u32 v183, 0, v32, v33
	v_bfe_u32 v246, v183, 4, 5
	v_bfe_u32 v247, v183, 10, 1
	v_bfe_u32 v248, v183, 5, 1
	v_bfe_u32 v249, v183, 6, 2
	v_xor_b32_e32 v247, v247, v248
	v_lshlrev_b32_e32 v246, 7, v246
	v_lshl_or_b32 v246, v247, 4, v246
	v_lshl_add_u32 v234, v249, 5, v246
	v_xor_b32_e32 v248, 1, v249
	v_lshl_add_u32 v235, v248, 5, v246
	v_xor_b32_e32 v248, 2, v249
	v_lshl_add_u32 v236, v248, 5, v246
	v_xor_b32_e32 v248, 3, v249
	v_lshl_add_u32 v237, v248, 5, v246
	v_lshl_add_u64 v[32:33], v[172:173], 0, s[8:9]
	s_add_i32 s34, s33, 0x4000
	s_mov_b32 s35, m0
	s_mov_b32 m0, s34
	s_nop 0
	global_load_lds_dwordx4 v[32:33], off
	s_mov_b32 m0, s35
	s_waitcnt vmcnt(3) lgkmcnt(0)
	s_barrier
	ds_read_b128 v[50:53], v234
	v_lshlrev_b32_e32 v49, 1, v48
	v_lshlrev_b32_e32 v48, 4, v48
	v_and_b32_e32 v185, 32, v49
	v_and_b32_e32 v48, 0xc0, v48
	v_lshl_or_b32 v168, v181, 8, v48
	v_add_u32_e32 v48, 0, v185
	v_add3_u32 v182, v48, v184, v168
	v_lshl_add_u64 v[48:49], v[172:173], 0, s[10:11]
	s_add_i32 s53, s33, 0x8000
	v_mov_b32_e32 v186, 0
	s_mov_b32 s34, -1
	s_mov_b32 s54, 0
	s_movk_i32 s52, 0x2000
	s_movk_i32 s35, 0x4000
	v_lshl_add_u64 v[174:175], v[88:89], 0, s[14:15]
	v_lshl_add_u64 v[176:177], v[172:173], 0, s[36:37]
	s_waitcnt vmcnt(3) lgkmcnt(0)
	v_mfma_f32_32x32x16_bf16 v[32:47], v[50:53], v[156:159], v[16:31]
	ds_read_b128 v[50:53], v234 offset:4096
	s_waitcnt lgkmcnt(0)
	v_mfma_f32_32x32x16_bf16 v[16:31], v[50:53], v[156:159], v[16:31]
	ds_read_b128 v[50:53], v235
	s_waitcnt vmcnt(2) lgkmcnt(0)
	v_mfma_f32_32x32x16_bf16 v[32:47], v[50:53], v[152:155], v[32:47]
	ds_read_b128 v[50:53], v235 offset:4096
	s_waitcnt lgkmcnt(0)
	v_mfma_f32_32x32x16_bf16 v[16:31], v[50:53], v[152:155], v[16:31]
	ds_read_b128 v[50:53], v236
	s_waitcnt vmcnt(1) lgkmcnt(0)
	v_mfma_f32_32x32x16_bf16 v[32:47], v[50:53], v[148:151], v[32:47]
	ds_read_b128 v[50:53], v236 offset:4096
	ds_read_b128 v[54:57], v237 offset:4096
	ds_read_b128 v[58:61], v237
	s_waitcnt lgkmcnt(2)
	v_mfma_f32_32x32x16_bf16 v[16:31], v[50:53], v[148:151], v[16:31]
	s_waitcnt vmcnt(0) lgkmcnt(0)
	v_mfma_f32_32x32x16_bf16 v[32:47], v[58:61], v[144:147], v[32:47]
	v_lshl_add_u64 v[58:59], v[88:89], 0, s[12:13]
	v_mfma_f32_32x32x16_bf16 v[16:31], v[54:57], v[144:147], v[16:31]
	s_nop 15
	s_nop 7
	s_waitcnt vmcnt(0) lgkmcnt(0)
	s_barrier
; #define WAIT_BAR(N) asm volatile("s_waitcnt vmcnt(" #N ") lgkmcnt(0)\n\ts_barrier":::"memory")
;   #define DMA_K(t,slot) glds16(ksrc+(long)(t)*KVBLK*KVP,(unsigned)__builtin_amdgcn_readfirstlane(kdst+(slot)))
;   #define DMA_V(t,slot) do{ glds16(vsrc+(long)(t)*KVBLK*KVP,(unsigned)__builtin_amdgcn_readfirstlane(vdst+VM*(slot))); if constexpr(VM==2) glds16(vsrc+64+(long)(t)*KVBLK*KVP,(unsigned)__builtin_amdgcn_readfirstlane(vdst+VM*(slot)+8192)); }while(0)
;   #define ROT() do{sl_prev=sl_cur;sl_cur=sl_next;sl_next=(sl_next==(NSLOT-1)*SLOTB)?0:sl_next+SLOTB;}while(0)
; template<int THRL,int VM,bool NOMAX> __device__ __forceinline__ void attn_unit(const bf16*Qb,const bf16*__restrict__ Kh,const bf16*__restrict__ Vh,bf16*Ob,const int NT,const int sp,float*wscr,char*shm){
;     ...
;   DMA_K(3,0);DMA_V(1,SLOTB);
;   ROT();
;   kload8(kf,kp0+sl_cur);
;   if constexpr(VM==2){WAIT_BAR(3);}else{WAIT_BAR(2);}
;   s16x4 vlo[8],vhi[8]; u32x4 pw0,pw1,pw2,pw3;
	s_mov_b32 s55, m0
	s_mov_b32 m0, s33
	s_nop 0
	global_load_lds_dwordx4 v[48:49], off
	s_mov_b32 m0, s55
	s_nop 0
	s_mov_b32 s55, m0
	s_mov_b32 m0, s53
	s_nop 0
	global_load_lds_dwordx4 v[58:59], off
	s_mov_b32 m0, s55
	ds_read_b128 v[84:87], v234 offset:8192
	ds_read_b128 v[80:83], v234 offset:12288
	ds_read_b128 v[164:167], v235 offset:8192
	ds_read_b128 v[160:163], v235 offset:12288
	ds_read_b128 v[124:127], v236 offset:8192
	ds_read_b128 v[120:123], v236 offset:12288
	ds_read_b128 v[116:119], v237 offset:8192
	ds_read_b128 v[112:115], v237 offset:12288
	s_nop 0
	v_exp_f32_e32 v64, v32
	v_exp_f32_e32 v65, v33
	v_exp_f32_e32 v66, v34
	v_exp_f32_e32 v67, v35
	v_exp_f32_e32 v68, v36
	v_exp_f32_e32 v69, v37
	v_exp_f32_e32 v70, v38
	v_exp_f32_e32 v71, v39
	v_exp_f32_e32 v72, v40
	v_exp_f32_e32 v73, v41
	v_exp_f32_e32 v74, v42
	v_exp_f32_e32 v75, v43
	v_exp_f32_e32 v76, v44
	v_exp_f32_e32 v77, v45
	v_exp_f32_e32 v78, v46
	v_exp_f32_e32 v79, v47
	v_exp_f32_e32 v48, v16
	v_exp_f32_e32 v49, v17
	v_exp_f32_e32 v50, v18
	v_exp_f32_e32 v51, v19
	v_exp_f32_e32 v52, v20
	v_exp_f32_e32 v53, v21
	v_exp_f32_e32 v54, v22
	v_exp_f32_e32 v55, v23
	v_exp_f32_e32 v56, v24
	v_exp_f32_e32 v57, v25
	v_exp_f32_e32 v58, v26
	v_exp_f32_e32 v59, v27
	v_exp_f32_e32 v60, v28
	v_exp_f32_e32 v61, v29
	v_exp_f32_e32 v62, v30
	v_exp_f32_e32 v63, v31
	s_waitcnt vmcnt(2) lgkmcnt(0)
	s_barrier
	v_mov_b32_e32 v16, 0
	v_mov_b32_e32 v17, v186
	v_mov_b32_e32 v18, v186
	v_mov_b32_e32 v19, v186
	v_mov_b32_e32 v20, v186
	v_mov_b32_e32 v21, v186
	v_mov_b32_e32 v22, v186
	v_mov_b32_e32 v23, v186
	v_mov_b32_e32 v24, v186
	v_mov_b32_e32 v25, v186
	v_mov_b32_e32 v26, v186
	v_mov_b32_e32 v27, v186
	v_mov_b32_e32 v28, v186
	v_mov_b32_e32 v29, v186
	v_mov_b32_e32 v30, v186
	v_mov_b32_e32 v31, v186
	v_mov_b32_e32 v32, 0
	v_mov_b32_e32 v33, v186
	v_mov_b32_e32 v34, v186
	v_mov_b32_e32 v35, v186
	v_mov_b32_e32 v36, v186
	v_mov_b32_e32 v37, v186
	v_mov_b32_e32 v38, v186
	v_mov_b32_e32 v39, v186
	v_mov_b32_e32 v40, v186
	v_mov_b32_e32 v41, v186
	v_mov_b32_e32 v42, v186
	v_mov_b32_e32 v43, v186
	v_mov_b32_e32 v44, v186
	v_mov_b32_e32 v45, v186
	v_mov_b32_e32 v46, v186
	v_mov_b32_e32 v47, v186
.LBB0_882:
	v_mfma_f32_32x32x16_bf16 v[96:111], v[84:87], v[156:159], 0
	v_add_u32_e32 v187, s54, v182
	ds_read_b64_tr_b16 v[188:189], v187 offset:24576
	ds_read_b64_tr_b16 v[190:191], v187 offset:25088
	v_add_f32_e32 v88, v64, v65
	v_add_f32_e32 v88, v66, v88
	v_add_f32_e32 v88, v67, v88
	v_add_f32_e32 v88, v68, v88
	v_add_f32_e32 v88, v69, v88
	v_cvt_pk_bf16_f32 v140, v64, v65
	v_cvt_pk_bf16_f32 v141, v66, v67
	ds_read_b64_tr_b16 v[64:65], v187 offset:28672
	ds_read_b64_tr_b16 v[66:67], v187 offset:29184
	v_add_f32_e32 v84, v70, v88
	v_add_f32_e32 v84, v71, v84
	v_add_f32_e32 v84, v72, v84
	v_add_f32_e32 v128, v73, v84
	s_waitcnt lgkmcnt(10)
	v_mfma_f32_32x32x16_bf16 v[80:95], v[80:83], v[156:159], 0
	v_cvt_pk_bf16_f32 v142, v68, v69
	v_cvt_pk_bf16_f32 v143, v70, v71
	ds_read_b64_tr_b16 v[68:69], v187 offset:25600
	ds_read_b64_tr_b16 v[70:71], v187 offset:26112
	v_add_f32_e32 v128, v74, v128
	v_add_f32_e32 v128, v75, v128
	v_add_f32_e32 v128, v76, v128
	v_add_f32_e32 v128, v77, v128
	v_cvt_pk_bf16_f32 v136, v72, v73
	v_cvt_pk_bf16_f32 v137, v74, v75
	s_waitcnt lgkmcnt(11)
	v_mfma_f32_32x32x16_bf16 v[96:111], v[164:167], v[152:155], v[96:111]
	ds_read_b64_tr_b16 v[72:73], v187 offset:29696
	ds_read_b64_tr_b16 v[74:75], v187 offset:30208
	s_waitcnt lgkmcnt(12)
	v_mfma_f32_32x32x16_bf16 v[80:95], v[160:163], v[152:155], v[80:95]
	v_add_f32_e32 v128, v78, v128
	v_add_f32_e32 v128, v79, v128
	v_add_f32_e32 v128, v48, v128
	v_add_f32_e32 v128, v49, v128
	v_cvt_pk_bf16_f32 v138, v76, v77
	v_cvt_pk_bf16_f32 v139, v78, v79
	ds_read_b64_tr_b16 v[76:77], v187 offset:26624
	ds_read_b64_tr_b16 v[78:79], v187 offset:27136
	v_add_f32_e32 v128, v50, v128
	v_add_f32_e32 v128, v51, v128
	v_add_f32_e32 v128, v52, v128
	v_add_f32_e32 v128, v53, v128
	v_cvt_pk_bf16_f32 v132, v48, v49
	v_cvt_pk_bf16_f32 v133, v50, v51
	s_waitcnt lgkmcnt(13)
	v_mfma_f32_32x32x16_bf16 v[96:111], v[124:127], v[148:151], v[96:111]
	ds_read_b64_tr_b16 v[48:49], v187 offset:30720
	ds_read_b64_tr_b16 v[50:51], v187 offset:31232
	s_waitcnt lgkmcnt(14)
	v_mfma_f32_32x32x16_bf16 v[80:95], v[120:123], v[148:151], v[80:95]
	v_add_f32_e32 v124, v54, v128
	v_add_f32_e32 v124, v55, v124
	v_add_f32_e32 v124, v56, v124
	v_add_f32_e32 v124, v57, v124
	v_cvt_pk_bf16_f32 v134, v52, v53
	v_cvt_pk_bf16_f32 v135, v54, v55
	ds_read_b64_tr_b16 v[52:53], v187 offset:27648
	ds_read_b64_tr_b16 v[54:55], v187 offset:28160
	v_add_f32_e32 v120, v58, v124
	v_add_f32_e32 v120, v59, v120
	v_add_f32_e32 v120, v60, v120
	v_add_f32_e32 v120, v61, v120
	v_cvt_pk_bf16_f32 v128, v56, v57
	v_cvt_pk_bf16_f32 v129, v58, v59
	s_waitcnt lgkmcnt(14)
	v_mfma_f32_32x32x16_bf16 v[96:111], v[116:119], v[144:147], v[96:111]
	ds_read_b64_tr_b16 v[56:57], v187 offset:31744
	ds_read_b64_tr_b16 v[58:59], v187 offset:32256
	v_mfma_f32_32x32x16_bf16 v[80:95], v[112:115], v[144:147], v[80:95]
	v_add_f32_e32 v116, v62, v120
	v_add_f32_e32 v116, v63, v116
	v_add_f32_e32 v116, 0, v116
	v_cvt_pk_bf16_f32 v130, v60, v61
	v_cvt_pk_bf16_f32 v131, v62, v63
	v_lshl_add_u64 v[60:61], v[176:177], 0, s[38:39]
	s_add_i32 s53, s52, s33
	s_mov_b32 s54, m0
	s_mov_b32 m0, s53
	s_nop 0
	global_load_lds_dwordx4 v[60:61], off
	s_mov_b32 m0, s54
	v_lshl_add_u64 v[60:61], v[174:175], 0, s[38:39]
	s_add_i32 s53, s35, s16
	s_mov_b32 s54, m0
	s_mov_b32 m0, s53
	s_nop 0
	global_load_lds_dwordx4 v[60:61], off
	s_mov_b32 m0, s54
	v_add_f32_e32 v202, v186, v116
	s_waitcnt lgkmcnt(14)
	v_mfma_f32_32x32x16_bf16 v[16:31], v[140:143], v[188:191], v[16:31]
	v_exp_f32_e32 v96, v96
	v_exp_f32_e32 v97, v97
	v_exp_f32_e32 v98, v98
	v_exp_f32_e32 v99, v99
	s_waitcnt lgkmcnt(12)
	v_mfma_f32_32x32x16_bf16 v[32:47], v[140:143], v[64:67], v[32:47]
	v_exp_f32_e32 v100, v100
	v_exp_f32_e32 v101, v101
	v_exp_f32_e32 v102, v102
	v_exp_f32_e32 v103, v103
	v_add_u32_e32 v242, s35, v234
	v_add_u32_e32 v243, s35, v235
	v_add_u32_e32 v244, s35, v236
	v_add_u32_e32 v245, s35, v237
	ds_read_b128 v[60:63], v242
	ds_read_b128 v[112:115], v242 offset:4096
	s_waitcnt lgkmcnt(12)
	v_mfma_f32_32x32x16_bf16 v[16:31], v[136:139], v[68:71], v[16:31]
	v_exp_f32_e32 v104, v104
	v_exp_f32_e32 v105, v105
	v_exp_f32_e32 v106, v106
	v_exp_f32_e32 v107, v107
	ds_read_b128 v[116:119], v243
	ds_read_b128 v[120:123], v243 offset:4096
	s_waitcnt lgkmcnt(12)
	v_mfma_f32_32x32x16_bf16 v[32:47], v[136:139], v[72:75], v[32:47]
	v_exp_f32_e32 v108, v108
	v_exp_f32_e32 v109, v109
	v_exp_f32_e32 v110, v110
	v_exp_f32_e32 v111, v111
	ds_read_b128 v[124:127], v244
	ds_read_b128 v[160:163], v244 offset:4096
	s_waitcnt lgkmcnt(12)
	v_mfma_f32_32x32x16_bf16 v[16:31], v[132:135], v[76:79], v[16:31]
	v_exp_f32_e32 v80, v80
	v_exp_f32_e32 v81, v81
	v_exp_f32_e32 v82, v82
	v_exp_f32_e32 v83, v83
	ds_read_b128 v[164:167], v245
	ds_read_b128 v[186:189], v245 offset:4096
	s_waitcnt lgkmcnt(12)
	v_mfma_f32_32x32x16_bf16 v[32:47], v[132:135], v[48:51], v[32:47]
	v_exp_f32_e32 v84, v84
	v_exp_f32_e32 v85, v85
	v_exp_f32_e32 v86, v86
	v_exp_f32_e32 v87, v87
	s_waitcnt lgkmcnt(10)
	v_mfma_f32_32x32x16_bf16 v[16:31], v[128:131], v[52:55], v[16:31]
	v_exp_f32_e32 v88, v88
	v_exp_f32_e32 v89, v89
	v_exp_f32_e32 v90, v90
	v_exp_f32_e32 v91, v91
	s_waitcnt lgkmcnt(8)
	v_mfma_f32_32x32x16_bf16 v[32:47], v[128:131], v[56:59], v[32:47]
	v_exp_f32_e32 v92, v92
	v_exp_f32_e32 v93, v93
	v_exp_f32_e32 v94, v94
	v_exp_f32_e32 v95, v95
	s_waitcnt vmcnt(2) lgkmcnt(0)
	s_barrier
	v_mfma_f32_32x32x16_bf16 v[64:79], v[60:63], v[156:159], 0
	s_add_i32 s53, s35, 0x2000
	s_cmpk_lg_i32 s35, 0x4000
	s_cselect_b32 s53, s53, 0
	v_add_u32_e32 v203, s52, v182
	ds_read_b64_tr_b16 v[190:191], v203 offset:24576
	ds_read_b64_tr_b16 v[192:193], v203 offset:25088
	v_add_f32_e32 v48, v96, v97
	v_add_f32_e32 v48, v98, v48
	v_add_f32_e32 v48, v99, v48
	v_add_f32_e32 v48, v100, v48
	v_add_f32_e32 v48, v101, v48
	v_cvt_pk_bf16_f32 v140, v96, v97
	v_cvt_pk_bf16_f32 v141, v98, v99
	ds_read_b64_tr_b16 v[96:97], v203 offset:28672
	ds_read_b64_tr_b16 v[98:99], v203 offset:29184
	v_add_f32_e32 v48, v102, v48
	v_add_f32_e32 v48, v103, v48
	v_add_f32_e32 v48, v104, v48
	v_add_f32_e32 v128, v105, v48
	s_waitcnt lgkmcnt(10)
	v_mfma_f32_32x32x16_bf16 v[48:63], v[112:115], v[156:159], 0
	v_cvt_pk_bf16_f32 v142, v100, v101
	v_cvt_pk_bf16_f32 v143, v102, v103
	ds_read_b64_tr_b16 v[100:101], v203 offset:25600
	ds_read_b64_tr_b16 v[102:103], v203 offset:26112
	s_waitcnt lgkmcnt(11)
	v_mfma_f32_32x32x16_bf16 v[64:79], v[116:119], v[152:155], v[64:79]
	v_add_f32_e32 v112, v106, v128
	v_add_f32_e32 v112, v107, v112
	v_add_f32_e32 v112, v108, v112
	v_add_f32_e32 v112, v109, v112
	v_cvt_pk_bf16_f32 v136, v104, v105
	v_cvt_pk_bf16_f32 v137, v106, v107
	ds_read_b64_tr_b16 v[104:105], v203 offset:29696
	ds_read_b64_tr_b16 v[106:107], v203 offset:30208
	s_waitcnt lgkmcnt(12)
	v_mfma_f32_32x32x16_bf16 v[48:63], v[120:123], v[152:155], v[48:63]
	v_add_f32_e32 v112, v110, v112
	v_add_f32_e32 v112, v111, v112
	v_add_f32_e32 v112, v80, v112
	v_add_f32_e32 v112, v81, v112
	v_cvt_pk_bf16_f32 v138, v108, v109
	v_cvt_pk_bf16_f32 v139, v110, v111
	ds_read_b64_tr_b16 v[108:109], v203 offset:26624
	ds_read_b64_tr_b16 v[110:111], v203 offset:27136
	s_waitcnt lgkmcnt(13)
	v_mfma_f32_32x32x16_bf16 v[64:79], v[124:127], v[148:151], v[64:79]
	v_add_f32_e32 v112, v82, v112
	v_add_f32_e32 v112, v83, v112
	v_add_f32_e32 v112, v84, v112
	v_add_f32_e32 v112, v85, v112
	v_cvt_pk_bf16_f32 v132, v80, v81
	v_cvt_pk_bf16_f32 v133, v82, v83
	ds_read_b64_tr_b16 v[194:195], v203 offset:30720
	ds_read_b64_tr_b16 v[196:197], v203 offset:31232
	s_waitcnt lgkmcnt(14)
	v_mfma_f32_32x32x16_bf16 v[48:63], v[160:163], v[148:151], v[48:63]
	v_add_f32_e32 v80, v86, v112
	v_add_f32_e32 v80, v87, v80
	v_add_f32_e32 v80, v88, v80
	v_add_f32_e32 v80, v89, v80
	v_cvt_pk_bf16_f32 v134, v84, v85
	v_cvt_pk_bf16_f32 v135, v86, v87
	ds_read_b64_tr_b16 v[198:199], v203 offset:27648
	ds_read_b64_tr_b16 v[200:201], v203 offset:28160
	s_waitcnt lgkmcnt(14)
	v_mfma_f32_32x32x16_bf16 v[64:79], v[164:167], v[144:147], v[64:79]
	v_add_f32_e32 v80, v90, v80
	v_add_f32_e32 v80, v91, v80
	v_add_f32_e32 v80, v92, v80
	v_add_f32_e32 v80, v93, v80
	v_cvt_pk_bf16_f32 v128, v88, v89
	v_cvt_pk_bf16_f32 v129, v90, v91
	ds_read_b64_tr_b16 v[88:89], v203 offset:31744
	ds_read_b64_tr_b16 v[90:91], v203 offset:32256
	v_mfma_f32_32x32x16_bf16 v[48:63], v[186:189], v[144:147], v[48:63]
	v_add_f32_e32 v80, v94, v80
	v_add_f32_e32 v80, v95, v80
	v_add_f32_e32 v80, 0, v80
	v_cvt_pk_bf16_f32 v130, v92, v93
	v_cvt_pk_bf16_f32 v131, v94, v95
	s_add_i32 s52, s35, s33
	s_mov_b32 s54, m0
	s_mov_b32 m0, s52
	s_nop 0
	global_load_lds_dwordx4 v[176:177], off
	s_mov_b32 m0, s54
	s_add_i32 s52, s53, s16
	s_mov_b32 s54, m0
	s_mov_b32 m0, s52
	s_nop 0
	global_load_lds_dwordx4 v[174:175], off
	s_mov_b32 m0, s54
	v_add_f32_e32 v186, v202, v80
	s_waitcnt lgkmcnt(14)
	v_mfma_f32_32x32x16_bf16 v[16:31], v[140:143], v[190:193], v[16:31]
	v_exp_f32_e32 v64, v64
	v_exp_f32_e32 v65, v65
	v_exp_f32_e32 v66, v66
	v_exp_f32_e32 v67, v67
	s_waitcnt lgkmcnt(12)
; #define WAIT_BAR(N) asm volatile("s_waitcnt vmcnt(" #N ") lgkmcnt(0)\n\ts_barrier":::"memory")
;   #define RESC() do{ if(!NOMAX&&resc){ asm volatile("s_waitcnt lgkmcnt(0)":::"memory"); \
;       _Pragma("unroll") for(int d_=0;d_<2*VM;++d_) _Pragma("unroll") for(int r=0;r<16;++r)o[d_][r]*=wsf[crow(r,hi)]; } }while(0)
;   #define ROT() do{sl_prev=sl_cur;sl_cur=sl_next;sl_next=(sl_next==(NSLOT-1)*SLOTB)?0:sl_next+SLOTB;}while(0)
;   #define ENDW(tt) do{ if((tt)+3<NT){ if constexpr(VM==2){WAIT_BAR(3);}else{WAIT_BAR(2);} } else if((tt)+2<NT){ if constexpr(VM==2){WAIT_BAR(2);}else{WAIT_BAR(1);} } else {WAIT_BAR(0);} }while(0)
; template<int THRL,int VM,bool NOMAX> __device__ __forceinline__ void attn_unit(const bf16*Qb,const bf16*__restrict__ Kh,const bf16*__restrict__ Vh,bf16*Ob,const int NT,const int sp,float*wscr,char*shm){
;     ...
;   for(;t+5<NT;t+=2){
;     STEP(pB0,pB1,pA0,pA1,t,true,true,true);     if constexpr(VM==2){WAIT_BAR(3);}else{WAIT_BAR(2);} RESC(); ROT();
;     STEP(pA0,pA1,pB0,pB1,t+1,true,true,true);   if constexpr(VM==2){WAIT_BAR(3);}else{WAIT_BAR(2);} RESC(); ROT();
;   }
;     ...
;   for(;t+1<NT;t+=2){
;     STEP(pB0,pB1,pA0,pA1,t,(t+3<NT),(t+1<NT),(t+1<NT));       ENDW(t);   RESC(); ROT();
	v_mfma_f32_32x32x16_bf16 v[32:47], v[140:143], v[96:99], v[32:47]
	v_exp_f32_e32 v68, v68
	v_exp_f32_e32 v69, v69
	v_exp_f32_e32 v70, v70
	v_exp_f32_e32 v71, v71
	v_add_u32_e32 v242, s53, v234
	v_add_u32_e32 v243, s53, v235
	v_add_u32_e32 v244, s53, v236
	v_add_u32_e32 v245, s53, v237
	ds_read_b128 v[84:87], v242
	ds_read_b128 v[80:83], v242 offset:4096
	s_waitcnt lgkmcnt(12)
	v_mfma_f32_32x32x16_bf16 v[16:31], v[136:139], v[100:103], v[16:31]
	v_exp_f32_e32 v72, v72
	v_exp_f32_e32 v73, v73
	v_exp_f32_e32 v74, v74
	v_exp_f32_e32 v75, v75
	ds_read_b128 v[164:167], v243
	ds_read_b128 v[160:163], v243 offset:4096
	s_waitcnt lgkmcnt(12)
	v_mfma_f32_32x32x16_bf16 v[32:47], v[136:139], v[104:107], v[32:47]
	v_exp_f32_e32 v76, v76
	v_exp_f32_e32 v77, v77
	v_exp_f32_e32 v78, v78
	v_exp_f32_e32 v79, v79
	ds_read_b128 v[124:127], v244
	ds_read_b128 v[120:123], v244 offset:4096
	s_waitcnt lgkmcnt(12)
	v_mfma_f32_32x32x16_bf16 v[16:31], v[132:135], v[108:111], v[16:31]
	v_exp_f32_e32 v48, v48
	v_exp_f32_e32 v49, v49
	v_exp_f32_e32 v50, v50
	v_exp_f32_e32 v51, v51
	ds_read_b128 v[116:119], v245
	ds_read_b128 v[112:115], v245 offset:4096
	s_waitcnt lgkmcnt(12)
	v_mfma_f32_32x32x16_bf16 v[32:47], v[132:135], v[194:197], v[32:47]
	v_exp_f32_e32 v52, v52
	v_exp_f32_e32 v53, v53
	v_exp_f32_e32 v54, v54
	v_exp_f32_e32 v55, v55
	s_waitcnt lgkmcnt(10)
	v_mfma_f32_32x32x16_bf16 v[16:31], v[128:131], v[198:201], v[16:31]
	v_exp_f32_e32 v56, v56
	v_exp_f32_e32 v57, v57
	v_exp_f32_e32 v58, v58
	v_exp_f32_e32 v59, v59
	s_waitcnt lgkmcnt(8)
	v_mfma_f32_32x32x16_bf16 v[32:47], v[128:131], v[88:91], v[32:47]
	v_exp_f32_e32 v60, v60
	v_exp_f32_e32 v61, v61
	v_exp_f32_e32 v62, v62
	v_exp_f32_e32 v63, v63
	s_add_i32 s55, s53, 0x2000
	s_waitcnt vmcnt(2) lgkmcnt(0)
	s_barrier
	s_cmpk_lg_i32 s53, 0x4000
	s_mov_b32 s54, s35
	s_cselect_b32 s35, s55, 0
	s_add_i32 s34, s34, 2
	v_lshl_add_u64 v[174:175], v[174:175], 0, s[8:9]
	v_lshl_add_u64 v[176:177], v[176:177], 0, s[8:9]
	s_mov_b32 s52, s53
	s_cmpk_lt_u32 s34, 0x79
	s_cbranch_scc1 .LBB0_882
	s_and_b32 s29, s29, 0x3fffffc0
	s_lshl_b32 s29, s29, 2
	s_add_i32 s29, s29, 0
	s_cmp_lg_u32 0, -1
	s_cselect_b32 s34, 0, 0
	s_add_i32 s35, s34, 0x6000
	v_add3_u32 v174, v185, s35, v184
	ds_read_b64_tr_b16 v[188:189], v182 offset:40960
	ds_read_b64_tr_b16 v[190:191], v182 offset:41472
	v_add_f32_e32 v88, v64, v65
	v_add_f32_e32 v88, v66, v88
	v_add_f32_e32 v88, v67, v88
	v_add_f32_e32 v88, v68, v88
	v_add_f32_e32 v88, v69, v88
	v_cvt_pk_bf16_f32 v140, v64, v65
	v_cvt_pk_bf16_f32 v141, v66, v67
	s_waitcnt lgkmcnt(9)
	v_mfma_f32_32x32x16_bf16 v[96:111], v[84:87], v[156:159], 0
	ds_read_b64_tr_b16 v[64:65], v182 offset:45056
	ds_read_b64_tr_b16 v[66:67], v182 offset:45568
	v_add_f32_e32 v84, v70, v88
	v_add_f32_e32 v84, v71, v84
	v_add_f32_e32 v84, v72, v84
	v_add_f32_e32 v128, v73, v84
	v_cvt_pk_bf16_f32 v142, v68, v69
	v_cvt_pk_bf16_f32 v143, v70, v71
	s_waitcnt lgkmcnt(10)
	v_mfma_f32_32x32x16_bf16 v[80:95], v[80:83], v[156:159], 0
	ds_read_b64_tr_b16 v[68:69], v182 offset:41984
	ds_read_b64_tr_b16 v[70:71], v182 offset:42496
	v_add_f32_e32 v128, v74, v128
	v_add_f32_e32 v128, v75, v128
	v_add_f32_e32 v128, v76, v128
	v_add_f32_e32 v128, v77, v128
	v_cvt_pk_bf16_f32 v136, v72, v73
	v_cvt_pk_bf16_f32 v137, v74, v75
	s_waitcnt lgkmcnt(11)
	v_mfma_f32_32x32x16_bf16 v[96:111], v[164:167], v[152:155], v[96:111]
	ds_read_b64_tr_b16 v[72:73], v182 offset:46080
	ds_read_b64_tr_b16 v[74:75], v182 offset:46592
	v_add_f32_e32 v128, v78, v128
	v_add_f32_e32 v128, v79, v128
	v_add_f32_e32 v128, v48, v128
	v_add_f32_e32 v128, v49, v128
	v_cvt_pk_bf16_f32 v138, v76, v77
	v_cvt_pk_bf16_f32 v139, v78, v79
	s_waitcnt lgkmcnt(12)
	v_mfma_f32_32x32x16_bf16 v[80:95], v[160:163], v[152:155], v[80:95]
	ds_read_b64_tr_b16 v[76:77], v182 offset:43008
	ds_read_b64_tr_b16 v[78:79], v182 offset:43520
	v_add_f32_e32 v128, v50, v128
	v_add_f32_e32 v128, v51, v128
	v_add_f32_e32 v128, v52, v128
	v_add_f32_e32 v128, v53, v128
	v_cvt_pk_bf16_f32 v132, v48, v49
	v_cvt_pk_bf16_f32 v133, v50, v51
	s_waitcnt lgkmcnt(13)
	v_mfma_f32_32x32x16_bf16 v[96:111], v[124:127], v[148:151], v[96:111]
	ds_read_b64_tr_b16 v[48:49], v182 offset:47104
	ds_read_b64_tr_b16 v[50:51], v182 offset:47616
	v_add_f32_e32 v124, v54, v128
	v_add_f32_e32 v124, v55, v124
	v_add_f32_e32 v124, v56, v124
	v_add_f32_e32 v124, v57, v124
	v_cvt_pk_bf16_f32 v134, v52, v53
	v_cvt_pk_bf16_f32 v135, v54, v55
	s_waitcnt lgkmcnt(14)
	v_mfma_f32_32x32x16_bf16 v[80:95], v[120:123], v[148:151], v[80:95]
	ds_read_b64_tr_b16 v[52:53], v182 offset:44032
	ds_read_b64_tr_b16 v[54:55], v182 offset:44544
	v_add_f32_e32 v120, v58, v124
	v_add_f32_e32 v120, v59, v120
	v_add_f32_e32 v120, v60, v120
	v_add_f32_e32 v120, v61, v120
	v_cvt_pk_bf16_f32 v128, v56, v57
	v_cvt_pk_bf16_f32 v129, v58, v59
	s_waitcnt lgkmcnt(14)
	v_mfma_f32_32x32x16_bf16 v[96:111], v[116:119], v[144:147], v[96:111]
	ds_read_b64_tr_b16 v[56:57], v182 offset:48128
	ds_read_b64_tr_b16 v[58:59], v182 offset:48640
	v_add_f32_e32 v116, v62, v120
	v_add_f32_e32 v116, v63, v116
	v_add_f32_e32 v116, 0, v116
	v_cvt_pk_bf16_f32 v130, v60, v61
	v_cvt_pk_bf16_f32 v131, v62, v63
	v_mfma_f32_32x32x16_bf16 v[80:95], v[112:115], v[144:147], v[80:95]
	v_lshl_add_u64 v[60:61], v[172:173], 0, s[40:41]
	s_mov_b32 s35, m0
	s_mov_b32 m0, s33
	s_nop 0
	global_load_lds_dwordx4 v[60:61], off
	s_mov_b32 m0, s35
	s_add_i32 s33, s34, s17
	v_lshl_add_u64 v[60:61], v[170:171], 0, s[42:43]
	s_add_i32 s17, s33, 0x8000
	s_mov_b32 s34, m0
	s_mov_b32 m0, s17
	s_nop 0
	global_load_lds_dwordx4 v[60:61], off
	s_mov_b32 m0, s34
	v_add_f32_e32 v175, v186, v116
	s_waitcnt lgkmcnt(14)
;   #define RESC() do{ if(!NOMAX&&resc){ asm volatile("s_waitcnt lgkmcnt(0)":::"memory"); \
;       _Pragma("unroll") for(int d_=0;d_<2*VM;++d_) _Pragma("unroll") for(int r=0;r<16;++r)o[d_][r]*=wsf[crow(r,hi)]; } }while(0)
;   #define ROT() do{sl_prev=sl_cur;sl_cur=sl_next;sl_next=(sl_next==(NSLOT-1)*SLOTB)?0:sl_next+SLOTB;}while(0)
;   #define ENDW(tt) do{ if((tt)+3<NT){ if constexpr(VM==2){WAIT_BAR(3);}else{WAIT_BAR(2);} } else if((tt)+2<NT){ if constexpr(VM==2){WAIT_BAR(2);}else{WAIT_BAR(1);} } else {WAIT_BAR(0);} }while(0)
; template<int THRL,int VM,bool NOMAX> __device__ __forceinline__ void attn_unit(const bf16*Qb,const bf16*__restrict__ Kh,const bf16*__restrict__ Vh,bf16*Ob,const int NT,const int sp,float*wscr,char*shm){
;     ...
;     STEP(pB0,pB1,pA0,pA1,t,(t+3<NT),(t+1<NT),(t+1<NT));       ENDW(t);   RESC(); ROT();
;     STEP(pA0,pA1,pB0,pB1,t+1,(t+4<NT),(t+2<NT),(t+2<NT));     ENDW(t+1); RESC(); ROT();
	v_mfma_f32_32x32x16_bf16 v[16:31], v[140:143], v[188:191], v[16:31]
	v_exp_f32_e32 v96, v96
	v_exp_f32_e32 v97, v97
	v_exp_f32_e32 v98, v98
	v_exp_f32_e32 v99, v99
	s_waitcnt lgkmcnt(12)
	v_mfma_f32_32x32x16_bf16 v[32:47], v[140:143], v[64:67], v[32:47]
	v_exp_f32_e32 v100, v100
	v_exp_f32_e32 v101, v101
	v_exp_f32_e32 v102, v102
	v_exp_f32_e32 v103, v103
	ds_read_b128 v[60:63], v234 offset:8192
	ds_read_b128 v[64:67], v234 offset:12288
	s_waitcnt lgkmcnt(12)
	v_mfma_f32_32x32x16_bf16 v[16:31], v[136:139], v[68:71], v[16:31]
	v_exp_f32_e32 v104, v104
	v_exp_f32_e32 v105, v105
	v_exp_f32_e32 v106, v106
	v_exp_f32_e32 v107, v107
	ds_read_b128 v[68:71], v235 offset:8192
	ds_read_b128 v[160:163], v235 offset:12288
	s_waitcnt lgkmcnt(12)
	v_mfma_f32_32x32x16_bf16 v[32:47], v[136:139], v[72:75], v[32:47]
	v_exp_f32_e32 v108, v108
	v_exp_f32_e32 v109, v109
	v_exp_f32_e32 v110, v110
	v_exp_f32_e32 v111, v111
	ds_read_b128 v[72:75], v236 offset:8192
	ds_read_b128 v[164:167], v236 offset:12288
	s_waitcnt lgkmcnt(12)
	v_mfma_f32_32x32x16_bf16 v[16:31], v[132:135], v[76:79], v[16:31]
	v_exp_f32_e32 v80, v80
	v_exp_f32_e32 v81, v81
	v_exp_f32_e32 v82, v82
	v_exp_f32_e32 v83, v83
	ds_read_b128 v[76:79], v237 offset:8192
	ds_read_b128 v[184:187], v237 offset:12288
	s_waitcnt lgkmcnt(12)
	v_mfma_f32_32x32x16_bf16 v[32:47], v[132:135], v[48:51], v[32:47]
	v_exp_f32_e32 v84, v84
	v_exp_f32_e32 v85, v85
	v_exp_f32_e32 v86, v86
	v_exp_f32_e32 v87, v87
	s_waitcnt lgkmcnt(10)
	v_mfma_f32_32x32x16_bf16 v[16:31], v[128:131], v[52:55], v[16:31]
	v_exp_f32_e32 v88, v88
	v_exp_f32_e32 v89, v89
	v_exp_f32_e32 v90, v90
	v_exp_f32_e32 v91, v91
	s_waitcnt lgkmcnt(8)
	v_mfma_f32_32x32x16_bf16 v[32:47], v[128:131], v[56:59], v[32:47]
	v_exp_f32_e32 v92, v92
	v_exp_f32_e32 v93, v93
	v_exp_f32_e32 v94, v94
	v_exp_f32_e32 v95, v95
	s_waitcnt vmcnt(2) lgkmcnt(0)
	s_barrier
	ds_read_b64_tr_b16 v[188:189], v182 offset:24576
	ds_read_b64_tr_b16 v[190:191], v182 offset:25088
	v_add_f32_e32 v48, v96, v97
	v_add_f32_e32 v48, v98, v48
	v_add_f32_e32 v48, v99, v48
	v_add_f32_e32 v48, v100, v48
	v_add_f32_e32 v48, v101, v48
	v_cvt_pk_bf16_f32 v140, v96, v97
	v_cvt_pk_bf16_f32 v141, v98, v99
	s_waitcnt lgkmcnt(9)
	v_mfma_f32_32x32x16_bf16 v[112:127], v[60:63], v[156:159], 0
	ds_read_b64_tr_b16 v[96:97], v182 offset:28672
	ds_read_b64_tr_b16 v[98:99], v182 offset:29184
	v_add_f32_e32 v48, v102, v48
	v_add_f32_e32 v48, v103, v48
	v_add_f32_e32 v48, v104, v48
	v_add_f32_e32 v128, v105, v48
	s_waitcnt lgkmcnt(10)
	v_mfma_f32_32x32x16_bf16 v[48:63], v[64:67], v[156:159], 0
	v_cvt_pk_bf16_f32 v142, v100, v101
	v_cvt_pk_bf16_f32 v143, v102, v103
	ds_read_b64_tr_b16 v[64:65], v182 offset:25600
	ds_read_b64_tr_b16 v[66:67], v182 offset:26112
	v_add_f32_e32 v100, v106, v128
	v_add_f32_e32 v100, v107, v100
	v_add_f32_e32 v100, v108, v100
	v_add_f32_e32 v100, v109, v100
	v_cvt_pk_bf16_f32 v136, v104, v105
	v_cvt_pk_bf16_f32 v137, v106, v107
	s_waitcnt lgkmcnt(11)
	v_mfma_f32_32x32x16_bf16 v[112:127], v[68:71], v[152:155], v[112:127]
	ds_read_b64_tr_b16 v[68:69], v182 offset:29696
	ds_read_b64_tr_b16 v[70:71], v182 offset:30208
	s_waitcnt lgkmcnt(12)
	v_mfma_f32_32x32x16_bf16 v[48:63], v[160:163], v[152:155], v[48:63]
	v_add_f32_e32 v100, v110, v100
	v_add_f32_e32 v100, v111, v100
	v_add_f32_e32 v100, v80, v100
	v_add_f32_e32 v104, v81, v100
	v_cvt_pk_bf16_f32 v138, v108, v109
	v_cvt_pk_bf16_f32 v139, v110, v111
	ds_read_b64_tr_b16 v[100:101], v182 offset:26624
	ds_read_b64_tr_b16 v[102:103], v182 offset:27136
	v_add_f32_e32 v104, v82, v104
	v_add_f32_e32 v104, v83, v104
	v_add_f32_e32 v104, v84, v104
	v_add_f32_e32 v104, v85, v104
	v_cvt_pk_bf16_f32 v132, v80, v81
	v_cvt_pk_bf16_f32 v133, v82, v83
	s_waitcnt lgkmcnt(13)
	v_mfma_f32_32x32x16_bf16 v[112:127], v[72:75], v[148:151], v[112:127]
	ds_read_b64_tr_b16 v[72:73], v182 offset:30720
	ds_read_b64_tr_b16 v[74:75], v182 offset:31232
	s_waitcnt lgkmcnt(14)
	v_mfma_f32_32x32x16_bf16 v[48:63], v[164:167], v[148:151], v[48:63]
	v_add_f32_e32 v80, v86, v104
	v_add_f32_e32 v80, v87, v80
	v_add_f32_e32 v80, v88, v80
	v_add_f32_e32 v104, v89, v80
	v_cvt_pk_bf16_f32 v134, v84, v85
	v_cvt_pk_bf16_f32 v135, v86, v87
	ds_read_b64_tr_b16 v[80:81], v182 offset:27648
	ds_read_b64_tr_b16 v[82:83], v182 offset:28160
	v_add_f32_e32 v84, v90, v104
	v_add_f32_e32 v84, v91, v84
	v_add_f32_e32 v84, v92, v84
	v_add_f32_e32 v84, v93, v84
	v_cvt_pk_bf16_f32 v128, v88, v89
	v_cvt_pk_bf16_f32 v129, v90, v91
	s_waitcnt lgkmcnt(14)
	v_mfma_f32_32x32x16_bf16 v[112:127], v[76:79], v[144:147], v[112:127]
	ds_read_b64_tr_b16 v[76:77], v182 offset:31744
	ds_read_b64_tr_b16 v[78:79], v182 offset:32256
	v_mfma_f32_32x32x16_bf16 v[48:63], v[184:187], v[144:147], v[48:63]
	v_add_f32_e32 v84, v94, v84
	v_add_f32_e32 v84, v95, v84
	v_add_f32_e32 v84, 0, v84
	v_cvt_pk_bf16_f32 v130, v92, v93
	v_cvt_pk_bf16_f32 v131, v94, v95
	s_nop 0
	v_add_f32_e32 v175, v175, v84
	v_lshl_add_u64 v[84:85], v[172:173], 0, s[44:45]
	s_add_i32 s34, s33, 0x2000
	s_mov_b32 s35, m0
	s_mov_b32 m0, s34
	s_nop 0
	global_load_lds_dwordx4 v[84:85], off
	s_mov_b32 m0, s35
	v_lshl_add_u64 v[84:85], v[170:171], 0, s[48:49]
	s_add_i32 s33, s33, 0xa000
	s_mov_b32 s34, m0
	s_mov_b32 m0, s33
	s_nop 0
	global_load_lds_dwordx4 v[84:85], off
	s_mov_b32 m0, s34
	s_waitcnt lgkmcnt(14)
	v_mfma_f32_32x32x16_bf16 v[16:31], v[140:143], v[188:191], v[16:31]
	v_exp_f32_e32 v112, v112
	v_exp_f32_e32 v113, v113
	v_exp_f32_e32 v114, v114
	v_exp_f32_e32 v115, v115
	s_waitcnt lgkmcnt(12)
	v_mfma_f32_32x32x16_bf16 v[32:47], v[140:143], v[96:99], v[32:47]
	v_exp_f32_e32 v116, v116
	v_exp_f32_e32 v117, v117
	v_exp_f32_e32 v118, v118
	v_exp_f32_e32 v119, v119
	ds_read_b128 v[84:87], v234 offset:16384
	ds_read_b128 v[96:99], v234 offset:20480
	s_waitcnt lgkmcnt(12)
;   #define RESC() do{ if(!NOMAX&&resc){ asm volatile("s_waitcnt lgkmcnt(0)":::"memory"); \
;       _Pragma("unroll") for(int d_=0;d_<2*VM;++d_) _Pragma("unroll") for(int r=0;r<16;++r)o[d_][r]*=wsf[crow(r,hi)]; } }while(0)
;   #define ROT() do{sl_prev=sl_cur;sl_cur=sl_next;sl_next=(sl_next==(NSLOT-1)*SLOTB)?0:sl_next+SLOTB;}while(0)
;   #define ENDW(tt) do{ if((tt)+3<NT){ if constexpr(VM==2){WAIT_BAR(3);}else{WAIT_BAR(2);} } else if((tt)+2<NT){ if constexpr(VM==2){WAIT_BAR(2);}else{WAIT_BAR(1);} } else {WAIT_BAR(0);} }while(0)
; template<int THRL,int VM,bool NOMAX> __device__ __forceinline__ void attn_unit(const bf16*Qb,const bf16*__restrict__ Kh,const bf16*__restrict__ Vh,bf16*Ob,const int NT,const int sp,float*wscr,char*shm){
;     ...
;     STEP(pB0,pB1,pA0,pA1,t,(t+3<NT),(t+1<NT),(t+1<NT));       ENDW(t);   RESC(); ROT();
;     STEP(pA0,pA1,pB0,pB1,t+1,(t+4<NT),(t+2<NT),(t+2<NT));     ENDW(t+1); RESC(); ROT();
	v_mfma_f32_32x32x16_bf16 v[16:31], v[136:139], v[64:67], v[16:31]
	v_exp_f32_e32 v120, v120
	v_exp_f32_e32 v121, v121
	v_exp_f32_e32 v122, v122
	v_exp_f32_e32 v123, v123
	ds_read_b128 v[104:107], v235 offset:16384
	ds_read_b128 v[108:111], v235 offset:20480
	s_waitcnt lgkmcnt(12)
	v_mfma_f32_32x32x16_bf16 v[32:47], v[136:139], v[68:71], v[32:47]
	v_exp_f32_e32 v124, v124
	v_exp_f32_e32 v125, v125
	v_exp_f32_e32 v126, v126
	v_exp_f32_e32 v127, v127
	ds_read_b128 v[160:163], v236 offset:16384
	ds_read_b128 v[164:167], v236 offset:20480
	s_waitcnt lgkmcnt(12)
	v_mfma_f32_32x32x16_bf16 v[16:31], v[132:135], v[100:103], v[16:31]
	v_exp_f32_e32 v48, v48
	v_exp_f32_e32 v49, v49
	v_exp_f32_e32 v50, v50
	v_exp_f32_e32 v51, v51
	ds_read_b128 v[100:103], v237 offset:16384
	ds_read_b128 v[184:187], v237 offset:20480
	s_waitcnt lgkmcnt(12)
	v_mfma_f32_32x32x16_bf16 v[32:47], v[132:135], v[72:75], v[32:47]
	v_exp_f32_e32 v52, v52
	v_exp_f32_e32 v53, v53
	v_exp_f32_e32 v54, v54
	v_exp_f32_e32 v55, v55
	s_waitcnt lgkmcnt(10)
	v_mfma_f32_32x32x16_bf16 v[16:31], v[128:131], v[80:83], v[16:31]
	v_exp_f32_e32 v56, v56
	v_exp_f32_e32 v57, v57
	v_exp_f32_e32 v58, v58
	v_exp_f32_e32 v59, v59
	s_waitcnt lgkmcnt(8)
	v_mfma_f32_32x32x16_bf16 v[32:47], v[128:131], v[76:79], v[32:47]
	v_exp_f32_e32 v60, v60
	v_exp_f32_e32 v61, v61
	v_exp_f32_e32 v62, v62
	v_exp_f32_e32 v63, v63
	s_waitcnt vmcnt(2) lgkmcnt(0)
	s_barrier
	ds_read_b64_tr_b16 v[188:189], v182 offset:32768
	ds_read_b64_tr_b16 v[190:191], v182 offset:33280
	v_add_f32_e32 v64, v112, v113
	v_add_f32_e32 v64, v114, v64
	v_add_f32_e32 v64, v115, v64
	v_add_f32_e32 v64, v116, v64
	v_add_f32_e32 v64, v117, v64
	v_cvt_pk_bf16_f32 v140, v112, v113
	v_cvt_pk_bf16_f32 v141, v114, v115
	s_waitcnt lgkmcnt(9)
	v_mfma_f32_32x32x16_bf16 v[80:95], v[84:87], v[156:159], 0
	ds_read_b64_tr_b16 v[112:113], v182 offset:36864
	ds_read_b64_tr_b16 v[114:115], v182 offset:37376
	v_add_f32_e32 v64, v118, v64
	v_add_f32_e32 v64, v119, v64
	v_add_f32_e32 v64, v120, v64
	v_add_f32_e32 v128, v121, v64
	v_cvt_pk_bf16_f32 v142, v116, v117
	v_cvt_pk_bf16_f32 v143, v118, v119
	s_waitcnt lgkmcnt(10)
	v_mfma_f32_32x32x16_bf16 v[64:79], v[96:99], v[156:159], 0
	ds_read_b64_tr_b16 v[96:97], v182 offset:33792
	ds_read_b64_tr_b16 v[98:99], v182 offset:34304
	v_add_f32_e32 v116, v122, v128
	v_add_f32_e32 v116, v123, v116
	v_add_f32_e32 v116, v124, v116
	v_add_f32_e32 v116, v125, v116
	v_cvt_pk_bf16_f32 v136, v120, v121
	v_cvt_pk_bf16_f32 v137, v122, v123
	s_waitcnt lgkmcnt(11)
	v_mfma_f32_32x32x16_bf16 v[80:95], v[104:107], v[152:155], v[80:95]
	ds_read_b64_tr_b16 v[104:105], v182 offset:37888
	ds_read_b64_tr_b16 v[106:107], v182 offset:38400
	v_add_f32_e32 v116, v126, v116
	v_add_f32_e32 v116, v127, v116
	v_add_f32_e32 v116, v48, v116
	v_add_f32_e32 v116, v49, v116
	v_cvt_pk_bf16_f32 v138, v124, v125
	v_cvt_pk_bf16_f32 v139, v126, v127
	s_waitcnt lgkmcnt(12)
	v_mfma_f32_32x32x16_bf16 v[64:79], v[108:111], v[152:155], v[64:79]
	ds_read_b64_tr_b16 v[108:109], v182 offset:34816
	ds_read_b64_tr_b16 v[110:111], v182 offset:35328
	v_add_f32_e32 v116, v50, v116
	v_add_f32_e32 v116, v51, v116
	v_add_f32_e32 v116, v52, v116
	v_add_f32_e32 v116, v53, v116
	v_cvt_pk_bf16_f32 v132, v48, v49
	v_cvt_pk_bf16_f32 v133, v50, v51
	s_waitcnt lgkmcnt(13)
	v_mfma_f32_32x32x16_bf16 v[80:95], v[160:163], v[148:151], v[80:95]
	ds_read_b64_tr_b16 v[48:49], v182 offset:38912
	ds_read_b64_tr_b16 v[50:51], v182 offset:39424
	v_add_f32_e32 v116, v54, v116
	v_add_f32_e32 v116, v55, v116
	v_add_f32_e32 v116, v56, v116
	v_add_f32_e32 v116, v57, v116
	v_cvt_pk_bf16_f32 v134, v52, v53
	v_cvt_pk_bf16_f32 v135, v54, v55
	s_waitcnt lgkmcnt(14)
	v_mfma_f32_32x32x16_bf16 v[64:79], v[164:167], v[148:151], v[64:79]
	ds_read_b64_tr_b16 v[52:53], v182 offset:35840
	ds_read_b64_tr_b16 v[54:55], v182 offset:36352
	v_add_f32_e32 v116, v58, v116
	v_add_f32_e32 v116, v59, v116
	v_add_f32_e32 v116, v60, v116
	v_add_f32_e32 v116, v61, v116
	v_cvt_pk_bf16_f32 v128, v56, v57
	v_cvt_pk_bf16_f32 v129, v58, v59
	s_waitcnt lgkmcnt(14)
	v_mfma_f32_32x32x16_bf16 v[80:95], v[100:103], v[144:147], v[80:95]
	ds_read_b64_tr_b16 v[56:57], v182 offset:39936
	ds_read_b64_tr_b16 v[58:59], v182 offset:40448
	v_add_f32_e32 v100, v62, v116
	v_add_f32_e32 v100, v63, v100
	v_add_f32_e32 v100, 0, v100
	v_cvt_pk_bf16_f32 v130, v60, v61
	v_cvt_pk_bf16_f32 v131, v62, v63
	v_mfma_f32_32x32x16_bf16 v[64:79], v[184:187], v[144:147], v[64:79]
	v_lshl_add_u64 v[60:61], v[170:171], 0, s[40:41]
	s_mov_b32 s33, m0
	s_mov_b32 m0, s16
	s_nop 0
	global_load_lds_dwordx4 v[60:61], off
	s_mov_b32 m0, s33
	v_add_f32_e32 v172, v175, v100
	s_waitcnt lgkmcnt(14)
	v_mfma_f32_32x32x16_bf16 v[16:31], v[140:143], v[188:191], v[16:31]
	v_exp_f32_e32 v80, v80
	v_exp_f32_e32 v81, v81
	v_exp_f32_e32 v82, v82
	v_exp_f32_e32 v83, v83
	s_waitcnt lgkmcnt(12)
	v_mfma_f32_32x32x16_bf16 v[32:47], v[140:143], v[112:115], v[32:47]
	v_exp_f32_e32 v84, v84
	v_exp_f32_e32 v85, v85
	v_exp_f32_e32 v86, v86
	v_exp_f32_e32 v87, v87
	ds_read_b128 v[60:63], v234
	ds_read_b128 v[112:115], v234 offset:4096
	s_waitcnt lgkmcnt(12)
	v_mfma_f32_32x32x16_bf16 v[16:31], v[136:139], v[96:99], v[16:31]
	v_exp_f32_e32 v88, v88
	v_exp_f32_e32 v89, v89
	v_exp_f32_e32 v90, v90
	v_exp_f32_e32 v91, v91
	ds_read_b128 v[116:119], v235
	ds_read_b128 v[120:123], v235 offset:4096
	s_waitcnt lgkmcnt(12)
	v_mfma_f32_32x32x16_bf16 v[32:47], v[136:139], v[104:107], v[32:47]
	v_exp_f32_e32 v92, v92
	v_exp_f32_e32 v93, v93
	v_exp_f32_e32 v94, v94
	v_exp_f32_e32 v95, v95
	ds_read_b128 v[124:127], v236
	ds_read_b128 v[160:163], v236 offset:4096
	s_waitcnt lgkmcnt(12)
	v_mfma_f32_32x32x16_bf16 v[16:31], v[132:135], v[108:111], v[16:31]
	v_exp_f32_e32 v64, v64
	v_exp_f32_e32 v65, v65
	v_exp_f32_e32 v66, v66
	v_exp_f32_e32 v67, v67
	ds_read_b128 v[164:167], v237
	ds_read_b128 v[184:187], v237 offset:4096
	s_waitcnt lgkmcnt(12)
	v_mfma_f32_32x32x16_bf16 v[32:47], v[132:135], v[48:51], v[32:47]
	v_exp_f32_e32 v68, v68
	v_exp_f32_e32 v69, v69
	v_exp_f32_e32 v70, v70
	v_exp_f32_e32 v71, v71
	s_waitcnt lgkmcnt(10)
	v_mfma_f32_32x32x16_bf16 v[16:31], v[128:131], v[52:55], v[16:31]
	v_exp_f32_e32 v72, v72
	v_exp_f32_e32 v73, v73
	v_exp_f32_e32 v74, v74
	v_exp_f32_e32 v75, v75
	s_waitcnt lgkmcnt(8)
	v_mfma_f32_32x32x16_bf16 v[32:47], v[128:131], v[56:59], v[32:47]
	v_exp_f32_e32 v76, v76
	v_exp_f32_e32 v77, v77
	v_exp_f32_e32 v78, v78
	v_exp_f32_e32 v79, v79
	s_waitcnt vmcnt(1) lgkmcnt(0)
	s_barrier
;   #define RESC() do{ if(!NOMAX&&resc){ asm volatile("s_waitcnt lgkmcnt(0)":::"memory"); \
;       _Pragma("unroll") for(int d_=0;d_<2*VM;++d_) _Pragma("unroll") for(int r=0;r<16;++r)o[d_][r]*=wsf[crow(r,hi)]; } }while(0)
;   #define ROT() do{sl_prev=sl_cur;sl_cur=sl_next;sl_next=(sl_next==(NSLOT-1)*SLOTB)?0:sl_next+SLOTB;}while(0)
;   #define ENDW(tt) do{ if((tt)+3<NT){ if constexpr(VM==2){WAIT_BAR(3);}else{WAIT_BAR(2);} } else if((tt)+2<NT){ if constexpr(VM==2){WAIT_BAR(2);}else{WAIT_BAR(1);} } else {WAIT_BAR(0);} }while(0)
; template<int THRL,int VM,bool NOMAX> __device__ __forceinline__ void attn_unit(const bf16*Qb,const bf16*__restrict__ Kh,const bf16*__restrict__ Vh,bf16*Ob,const int NT,const int sp,float*wscr,char*shm){
;     ...
;     STEP(pB0,pB1,pA0,pA1,t,(t+3<NT),(t+1<NT),(t+1<NT));       ENDW(t);   RESC(); ROT();
;     STEP(pA0,pA1,pB0,pB1,t+1,(t+4<NT),(t+2<NT),(t+2<NT));     ENDW(t+1); RESC(); ROT();
	ds_read_b64_tr_b16 v[188:189], v182 offset:40960
	ds_read_b64_tr_b16 v[190:191], v182 offset:41472
	v_add_f32_e32 v48, v80, v81
	v_add_f32_e32 v48, v82, v48
	v_add_f32_e32 v48, v83, v48
	v_add_f32_e32 v48, v84, v48
	v_add_f32_e32 v48, v85, v48
	v_cvt_pk_bf16_f32 v140, v80, v81
	v_cvt_pk_bf16_f32 v141, v82, v83
	s_waitcnt lgkmcnt(9)
	v_mfma_f32_32x32x16_bf16 v[96:111], v[60:63], v[156:159], 0
	ds_read_b64_tr_b16 v[80:81], v182 offset:45056
	ds_read_b64_tr_b16 v[82:83], v182 offset:45568
	v_add_f32_e32 v48, v86, v48
	v_add_f32_e32 v48, v87, v48
	v_add_f32_e32 v48, v88, v48
	v_add_f32_e32 v128, v89, v48
	s_waitcnt lgkmcnt(10)
	v_mfma_f32_32x32x16_bf16 v[48:63], v[112:115], v[156:159], 0
	v_cvt_pk_bf16_f32 v142, v84, v85
	v_cvt_pk_bf16_f32 v143, v86, v87
	ds_read_b64_tr_b16 v[84:85], v182 offset:41984
	ds_read_b64_tr_b16 v[86:87], v182 offset:42496
	v_add_f32_e32 v112, v90, v128
	v_add_f32_e32 v112, v91, v112
	v_add_f32_e32 v112, v92, v112
	v_add_f32_e32 v112, v93, v112
	v_cvt_pk_bf16_f32 v136, v88, v89
	v_cvt_pk_bf16_f32 v137, v90, v91
	s_waitcnt lgkmcnt(11)
	v_mfma_f32_32x32x16_bf16 v[96:111], v[116:119], v[152:155], v[96:111]
	ds_read_b64_tr_b16 v[88:89], v182 offset:46080
	ds_read_b64_tr_b16 v[90:91], v182 offset:46592
	s_waitcnt lgkmcnt(12)
	v_mfma_f32_32x32x16_bf16 v[48:63], v[120:123], v[152:155], v[48:63]
	v_add_f32_e32 v112, v94, v112
	v_add_f32_e32 v112, v95, v112
	v_add_f32_e32 v112, v64, v112
	v_add_f32_e32 v112, v65, v112
	v_cvt_pk_bf16_f32 v138, v92, v93
	v_cvt_pk_bf16_f32 v139, v94, v95
	ds_read_b64_tr_b16 v[92:93], v182 offset:43008
	ds_read_b64_tr_b16 v[94:95], v182 offset:43520
	v_add_f32_e32 v112, v66, v112
	v_add_f32_e32 v112, v67, v112
	v_add_f32_e32 v112, v68, v112
	v_add_f32_e32 v112, v69, v112
	v_cvt_pk_bf16_f32 v132, v64, v65
	v_cvt_pk_bf16_f32 v133, v66, v67
	s_waitcnt lgkmcnt(13)
	v_mfma_f32_32x32x16_bf16 v[96:111], v[124:127], v[148:151], v[96:111]
	ds_read_b64_tr_b16 v[64:65], v182 offset:47104
	ds_read_b64_tr_b16 v[66:67], v182 offset:47616
	s_waitcnt lgkmcnt(14)
	v_mfma_f32_32x32x16_bf16 v[48:63], v[160:163], v[148:151], v[48:63]
	v_add_f32_e32 v112, v70, v112
	v_add_f32_e32 v112, v71, v112
	v_add_f32_e32 v112, v72, v112
	v_add_f32_e32 v112, v73, v112
	v_cvt_pk_bf16_f32 v134, v68, v69
	v_cvt_pk_bf16_f32 v135, v70, v71
	ds_read_b64_tr_b16 v[68:69], v182 offset:44032
	ds_read_b64_tr_b16 v[70:71], v182 offset:44544
	v_add_f32_e32 v112, v74, v112
	v_add_f32_e32 v112, v75, v112
	v_add_f32_e32 v112, v76, v112
	v_add_f32_e32 v112, v77, v112
	v_cvt_pk_bf16_f32 v128, v72, v73
	v_cvt_pk_bf16_f32 v129, v74, v75
	s_waitcnt lgkmcnt(14)
	v_mfma_f32_32x32x16_bf16 v[96:111], v[164:167], v[144:147], v[96:111]
	ds_read_b64_tr_b16 v[72:73], v182 offset:48128
	ds_read_b64_tr_b16 v[74:75], v182 offset:48640
	v_mfma_f32_32x32x16_bf16 v[48:63], v[184:187], v[144:147], v[48:63]
	v_add_f32_e32 v112, v78, v112
	v_add_f32_e32 v112, v79, v112
	v_add_f32_e32 v112, 0, v112
	v_cvt_pk_bf16_f32 v130, v76, v77
	v_cvt_pk_bf16_f32 v131, v78, v79
	v_lshl_add_u64 v[76:77], v[170:171], 0, s[44:45]
	s_mov_b32 s16, m0
	s_mov_b32 m0, s17
	s_nop 0
	global_load_lds_dwordx4 v[76:77], off
	s_mov_b32 m0, s16
	v_add_f32_e32 v120, v172, v112
	s_waitcnt lgkmcnt(14)
	v_mfma_f32_32x32x16_bf16 v[16:31], v[140:143], v[188:191], v[16:31]
	v_exp_f32_e32 v96, v96
	v_exp_f32_e32 v97, v97
	v_exp_f32_e32 v98, v98
	v_exp_f32_e32 v99, v99
	s_waitcnt lgkmcnt(12)
	v_mfma_f32_32x32x16_bf16 v[32:47], v[140:143], v[80:83], v[32:47]
	v_exp_f32_e32 v100, v100
	v_exp_f32_e32 v101, v101
	v_exp_f32_e32 v102, v102
	v_exp_f32_e32 v103, v103
	ds_read_b128 v[76:79], v234 offset:8192
	ds_read_b128 v[80:83], v234 offset:12288
	s_waitcnt lgkmcnt(12)
	v_mfma_f32_32x32x16_bf16 v[16:31], v[136:139], v[84:87], v[16:31]
	v_exp_f32_e32 v104, v104
	v_exp_f32_e32 v105, v105
	v_exp_f32_e32 v106, v106
	v_exp_f32_e32 v107, v107
	ds_read_b128 v[122:125], v235 offset:8192
	ds_read_b128 v[160:163], v235 offset:12288
	s_waitcnt lgkmcnt(12)
	v_mfma_f32_32x32x16_bf16 v[32:47], v[136:139], v[88:91], v[32:47]
	v_exp_f32_e32 v108, v108
	v_exp_f32_e32 v109, v109
	v_exp_f32_e32 v110, v110
	v_exp_f32_e32 v111, v111
	ds_read_b128 v[164:167], v236 offset:8192
	ds_read_b128 v[170:173], v236 offset:12288
	s_waitcnt lgkmcnt(12)
	v_mfma_f32_32x32x16_bf16 v[16:31], v[132:135], v[92:95], v[16:31]
	v_exp_f32_e32 v48, v48
	v_exp_f32_e32 v49, v49
	v_exp_f32_e32 v50, v50
	v_exp_f32_e32 v51, v51
	ds_read_b128 v[184:187], v237 offset:8192
	ds_read_b128 v[188:191], v237 offset:12288
	s_waitcnt lgkmcnt(12)
	v_mfma_f32_32x32x16_bf16 v[32:47], v[132:135], v[64:67], v[32:47]
	v_exp_f32_e32 v52, v52
	v_exp_f32_e32 v53, v53
	v_exp_f32_e32 v54, v54
	v_exp_f32_e32 v55, v55
	s_waitcnt lgkmcnt(10)
	v_mfma_f32_32x32x16_bf16 v[16:31], v[128:131], v[68:71], v[16:31]
	v_exp_f32_e32 v56, v56
	v_exp_f32_e32 v57, v57
	v_exp_f32_e32 v58, v58
	v_exp_f32_e32 v59, v59
	s_waitcnt lgkmcnt(8)
	v_mfma_f32_32x32x16_bf16 v[32:47], v[128:131], v[72:75], v[32:47]
	v_exp_f32_e32 v60, v60
	v_exp_f32_e32 v61, v61
	v_exp_f32_e32 v62, v62
	v_exp_f32_e32 v63, v63
	s_waitcnt vmcnt(0) lgkmcnt(0)
	s_barrier
	ds_read_b64_tr_b16 v[112:113], v182 offset:24576
	ds_read_b64_tr_b16 v[114:115], v182 offset:25088
	v_add_f32_e32 v64, v96, v97
	v_add_f32_e32 v64, v98, v64
	v_add_f32_e32 v64, v99, v64
	v_add_f32_e32 v64, v100, v64
	v_add_f32_e32 v84, v101, v64
	v_cvt_pk_bf16_f32 v140, v96, v97
	v_cvt_pk_bf16_f32 v141, v98, v99
	s_waitcnt lgkmcnt(9)
	v_mfma_f32_32x32x16_bf16 v[64:79], v[76:79], v[156:159], 0
	ds_read_b64_tr_b16 v[96:97], v182 offset:28672
	ds_read_b64_tr_b16 v[98:99], v182 offset:29184
	v_add_f32_e32 v84, v102, v84
	v_add_f32_e32 v84, v103, v84
	v_add_f32_e32 v84, v104, v84
	v_add_f32_e32 v121, v105, v84
	v_cvt_pk_bf16_f32 v142, v100, v101
	v_cvt_pk_bf16_f32 v143, v102, v103
	s_waitcnt lgkmcnt(10)
	v_mfma_f32_32x32x16_bf16 v[80:95], v[80:83], v[156:159], 0
	ds_read_b64_tr_b16 v[116:117], v182 offset:25600
	ds_read_b64_tr_b16 v[118:119], v182 offset:26112
	v_add_f32_e32 v100, v106, v121
	v_add_f32_e32 v100, v107, v100
	v_add_f32_e32 v100, v108, v100
	v_add_f32_e32 v121, v109, v100
	v_cvt_pk_bf16_f32 v136, v104, v105
	v_cvt_pk_bf16_f32 v137, v106, v107
	s_waitcnt lgkmcnt(11)
	v_mfma_f32_32x32x16_bf16 v[64:79], v[122:125], v[152:155], v[64:79]
	ds_read_b64_tr_b16 v[100:101], v182 offset:29696
	ds_read_b64_tr_b16 v[102:103], v182 offset:30208
	v_add_f32_e32 v104, v110, v121
	v_add_f32_e32 v104, v111, v104
	v_add_f32_e32 v104, v48, v104
	v_add_f32_e32 v121, v49, v104
	v_cvt_pk_bf16_f32 v138, v108, v109
	v_cvt_pk_bf16_f32 v139, v110, v111
	s_waitcnt lgkmcnt(12)
	v_mfma_f32_32x32x16_bf16 v[80:95], v[160:163], v[152:155], v[80:95]
	ds_read_b64_tr_b16 v[104:105], v182 offset:26624
	ds_read_b64_tr_b16 v[106:107], v182 offset:27136
	v_add_f32_e32 v108, v50, v121
	v_add_f32_e32 v108, v51, v108
	v_add_f32_e32 v108, v52, v108
	v_add_f32_e32 v108, v53, v108
	v_cvt_pk_bf16_f32 v132, v48, v49
	v_cvt_pk_bf16_f32 v133, v50, v51
	s_waitcnt lgkmcnt(13)
	v_mfma_f32_32x32x16_bf16 v[64:79], v[164:167], v[148:151], v[64:79]
	ds_read_b64_tr_b16 v[48:49], v182 offset:30720
	ds_read_b64_tr_b16 v[50:51], v182 offset:31232
	v_add_f32_e32 v108, v54, v108
	v_add_f32_e32 v108, v55, v108
	v_add_f32_e32 v108, v56, v108
	v_add_f32_e32 v121, v57, v108
	v_cvt_pk_bf16_f32 v134, v52, v53
	v_cvt_pk_bf16_f32 v135, v54, v55
	s_waitcnt lgkmcnt(14)
	v_mfma_f32_32x32x16_bf16 v[80:95], v[170:173], v[148:151], v[80:95]
	ds_read_b64_tr_b16 v[108:109], v182 offset:27648
	ds_read_b64_tr_b16 v[110:111], v182 offset:28160
	v_add_f32_e32 v52, v58, v121
	v_add_f32_e32 v52, v59, v52
	v_add_f32_e32 v52, v60, v52
	v_add_f32_e32 v121, v61, v52
	v_cvt_pk_bf16_f32 v128, v56, v57
	v_cvt_pk_bf16_f32 v129, v58, v59
	s_waitcnt lgkmcnt(14)
	v_mfma_f32_32x32x16_bf16 v[64:79], v[184:187], v[144:147], v[64:79]
	ds_read_b64_tr_b16 v[52:53], v182 offset:31744
	ds_read_b64_tr_b16 v[54:55], v182 offset:32256
	v_add_f32_e32 v56, v62, v121
	v_add_f32_e32 v56, v63, v56
	v_add_f32_e32 v56, 0, v56
	v_cvt_pk_bf16_f32 v130, v60, v61
	v_cvt_pk_bf16_f32 v131, v62, v63
	v_mfma_f32_32x32x16_bf16 v[80:95], v[188:191], v[144:147], v[80:95]
	s_nop 3
	v_exp_f32_e32 v64, v64
	v_exp_f32_e32 v65, v65
	v_exp_f32_e32 v66, v66
	v_exp_f32_e32 v67, v67
	s_nop 0
	v_exp_f32_e32 v68, v68
	v_exp_f32_e32 v69, v69
	v_exp_f32_e32 v70, v70
	v_exp_f32_e32 v71, v71
	s_nop 0
	v_exp_f32_e32 v72, v72
	v_exp_f32_e32 v73, v73
	v_exp_f32_e32 v74, v74
	v_exp_f32_e32 v75, v75
	s_nop 0
	v_exp_f32_e32 v76, v76
	v_exp_f32_e32 v77, v77
	v_exp_f32_e32 v78, v78
	v_exp_f32_e32 v79, v79
	v_exp_f32_e32 v80, v80
	v_exp_f32_e32 v81, v81
	v_exp_f32_e32 v82, v82
	v_exp_f32_e32 v83, v83
	s_nop 0
	v_exp_f32_e32 v84, v84
	v_exp_f32_e32 v85, v85
	v_exp_f32_e32 v86, v86
	v_exp_f32_e32 v87, v87
	s_nop 0
	v_exp_f32_e32 v88, v88
	v_exp_f32_e32 v89, v89
	v_exp_f32_e32 v90, v90
	v_exp_f32_e32 v91, v91
	s_nop 0
	v_exp_f32_e32 v92, v92
	v_exp_f32_e32 v93, v93
	v_exp_f32_e32 v94, v94
	v_exp_f32_e32 v95, v95
	s_waitcnt lgkmcnt(14)
; #define SBAR() __builtin_amdgcn_sched_barrier(0)
;   #define RESC() do{ if(!NOMAX&&resc){ asm volatile("s_waitcnt lgkmcnt(0)":::"memory"); \
;       _Pragma("unroll") for(int d_=0;d_<2*VM;++d_) _Pragma("unroll") for(int r=0;r<16;++r)o[d_][r]*=wsf[crow(r,hi)]; } }while(0)
;   #define PKW(P,B) cvtpk_s(P[B],P[B+1])
; __device__ __forceinline__ void pv(f32x16*o,int vb,bf16x8 pa0,bf16x8 pa1,bf16x8 pa2,bf16x8 pa3){
;   #pragma unroll
;   for(int d0=0;d0<2;++d0){s16x4 lo[4],hi[4];
;     #pragma unroll
;     for(int ks=0;ks<4;++ks){
;       asm volatile("ds_read_b64_tr_b16 %0,%1 offset:%c2":"=&v"(lo[ks]):"v"(vb),"i"(d0*4096+ks*1024):"memory");
;       asm volatile("ds_read_b64_tr_b16 %0,%1 offset:%c2":"=&v"(hi[ks]):"v"(vb),"i"(d0*4096+ks*1024+512):"memory");}
;     asm volatile("s_waitcnt lgkmcnt(0)":::"memory");SBAR();
;     ...
;     o[d0]=__builtin_amdgcn_mfma_f32_32x32x16_bf16(pa0,PK(0),o[d0],0,0,0);
;     o[d0]=__builtin_amdgcn_mfma_f32_32x32x16_bf16(pa1,PK(1),o[d0],0,0,0);
;     o[d0]=__builtin_amdgcn_mfma_f32_32x32x16_bf16(pa2,PK(2),o[d0],0,0,0);
;     o[d0]=__builtin_amdgcn_mfma_f32_32x32x16_bf16(pa3,PK(3),o[d0],0,0,0);
;     ...
;   }
; }
; template<int THRL,int VM,bool NOMAX> __device__ __forceinline__ void attn_unit(const bf16*Qb,const bf16*__restrict__ Kh,const bf16*__restrict__ Vh,bf16*Ob,const int NT,const int sp,float*wscr,char*shm){
;     ...
;   STEP(pB0,pB1,pA0,pA1,NT-1,false,false,false); RESC();
;   { float sacc=pB0[0]+pB0[1]; _Pragma("unroll") for(int r=2;r<16;++r)sacc+=pB0[r]; _Pragma("unroll") for(int r=0;r<16;++r)sacc+=pB1[r]; l_reg+=sacc;
;     pw0=(u32x4){PKW(pB0,0),PKW(pB0,2),PKW(pB0,4),PKW(pB0,6)};pw1=(u32x4){PKW(pB0,8),PKW(pB0,10),PKW(pB0,12),PKW(pB0,14)};pw2=(u32x4){PKW(pB1,0),PKW(pB1,2),PKW(pB1,4),PKW(pB1,6)};pw3=(u32x4){PKW(pB1,8),PKW(pB1,10),PKW(pB1,12),PKW(pB1,14)};
;     SBAR(); pv(o,vb0+VM*sl_cur,PAF(0),PAF(1),PAF(2),PAF(3)); if constexpr(VM==2) pv(o+2,vb0+VM*sl_cur+8192,PAF(0),PAF(1),PAF(2),PAF(3)); }
;     ...
;   {auto rr=__builtin_amdgcn_permlane32_swap(__float_as_uint(l_reg),__float_as_uint(l_reg),false,false);l_reg=__uint_as_float(rr[0])+__uint_as_float(rr[1]);}
;   if(hi==0)wsf[32+r32]=l_reg;asm volatile("s_waitcnt lgkmcnt(0)":::"memory");
	v_mfma_f32_32x32x16_bf16 v[16:31], v[140:143], v[112:115], v[16:31]
	v_add_f32_e32 v57, v64, v65
	v_add_f32_e32 v57, v66, v57
	v_add_f32_e32 v57, v67, v57
	v_add_f32_e32 v57, v68, v57
	v_add_f32_e32 v57, v69, v57
	v_add_f32_e32 v57, v70, v57
	v_add_f32_e32 v57, v71, v57
	s_waitcnt lgkmcnt(12)
	v_mfma_f32_32x32x16_bf16 v[32:47], v[140:143], v[96:99], v[32:47]
	v_add_f32_e32 v57, v72, v57
	v_add_f32_e32 v57, v73, v57
	v_add_f32_e32 v57, v74, v57
	v_add_f32_e32 v57, v75, v57
	v_add_f32_e32 v57, v76, v57
	v_add_f32_e32 v57, v77, v57
	v_add_f32_e32 v57, v78, v57
	s_waitcnt lgkmcnt(10)
	v_mfma_f32_32x32x16_bf16 v[16:31], v[136:139], v[116:119], v[16:31]
	v_add_f32_e32 v57, v79, v57
	v_add_f32_e32 v57, v80, v57
	v_add_f32_e32 v57, v81, v57
	v_add_f32_e32 v57, v82, v57
	v_add_f32_e32 v57, v83, v57
	v_add_f32_e32 v57, v84, v57
	v_add_f32_e32 v57, v85, v57
	s_waitcnt lgkmcnt(8)
	v_mfma_f32_32x32x16_bf16 v[32:47], v[136:139], v[100:103], v[32:47]
	v_add_f32_e32 v57, v86, v57
	v_add_f32_e32 v57, v87, v57
	v_add_f32_e32 v57, v88, v57
	v_add_f32_e32 v57, v89, v57
	v_add_f32_e32 v57, v90, v57
	v_add_f32_e32 v57, v91, v57
	v_add_f32_e32 v57, v92, v57
	s_waitcnt lgkmcnt(6)
	v_mfma_f32_32x32x16_bf16 v[16:31], v[132:135], v[104:107], v[16:31]
	v_add_f32_e32 v57, v93, v57
	v_add_f32_e32 v57, v94, v57
	v_add_f32_e32 v57, v95, v57
	v_add_f32_e32 v56, v120, v56
	v_add_f32_e32 v56, v56, v57
	v_cvt_pk_bf16_f32 v58, v64, v65
	v_cvt_pk_bf16_f32 v59, v66, v67
	s_waitcnt lgkmcnt(4)
	v_mfma_f32_32x32x16_bf16 v[32:47], v[132:135], v[48:51], v[32:47]
	v_cvt_pk_bf16_f32 v48, v80, v81
	v_cvt_pk_bf16_f32 v60, v68, v69
	v_cvt_pk_bf16_f32 v61, v70, v71
	v_cvt_pk_bf16_f32 v62, v72, v73
	v_cvt_pk_bf16_f32 v63, v74, v75
	v_cvt_pk_bf16_f32 v64, v76, v77
	v_cvt_pk_bf16_f32 v65, v78, v79
	s_waitcnt lgkmcnt(2)
	v_mfma_f32_32x32x16_bf16 v[16:31], v[128:131], v[108:111], v[16:31]
	v_cvt_pk_bf16_f32 v49, v82, v83
	v_cvt_pk_bf16_f32 v50, v84, v85
	v_cvt_pk_bf16_f32 v51, v86, v87
	v_cvt_pk_bf16_f32 v66, v88, v89
	v_cvt_pk_bf16_f32 v67, v90, v91
	v_cvt_pk_bf16_f32 v68, v92, v93
	v_cvt_pk_bf16_f32 v69, v94, v95
	s_waitcnt lgkmcnt(0)
	v_mfma_f32_32x32x16_bf16 v[32:47], v[128:131], v[52:55], v[32:47]
	v_add3_u32 v57, v174, v168, s18
	ds_read_b64_tr_b16 v[52:53],v57 offset:0
	ds_read_b64_tr_b16 v[54:55],v57 offset:512
	ds_read_b64_tr_b16 v[70:71],v57 offset:1024
	ds_read_b64_tr_b16 v[72:73],v57 offset:1536
	ds_read_b64_tr_b16 v[74:75],v57 offset:2048
	ds_read_b64_tr_b16 v[76:77],v57 offset:2560
	ds_read_b64_tr_b16 v[78:79],v57 offset:3072
	ds_read_b64_tr_b16 v[80:81],v57 offset:3584
	s_waitcnt lgkmcnt(0)
	s_nop 0
	v_mfma_f32_32x32x16_bf16 v[16:31], v[58:61], v[52:55], v[16:31]
	ds_read_b64_tr_b16 v[52:53],v57 offset:4096
	ds_read_b64_tr_b16 v[54:55],v57 offset:4608
	v_mfma_f32_32x32x16_bf16 v[16:31], v[62:65], v[70:73], v[16:31]
	ds_read_b64_tr_b16 v[70:71],v57 offset:5120
	ds_read_b64_tr_b16 v[72:73],v57 offset:5632
	v_mfma_f32_32x32x16_bf16 v[16:31], v[48:51], v[74:77], v[16:31]
	ds_read_b64_tr_b16 v[74:75],v57 offset:6144
	ds_read_b64_tr_b16 v[76:77],v57 offset:6656
	ds_read_b64_tr_b16 v[82:83],v57 offset:7168
	ds_read_b64_tr_b16 v[84:85],v57 offset:7680
	s_waitcnt lgkmcnt(0)
	v_mfma_f32_32x32x16_bf16 v[16:31], v[66:69], v[78:81], v[16:31]
	v_mfma_f32_32x32x16_bf16 v[32:47], v[58:61], v[52:55], v[32:47]
	v_cmp_gt_u32_e32 vcc, 32, v178
	v_mfma_f32_32x32x16_bf16 v[32:47], v[62:65], v[70:73], v[32:47]
	v_mfma_f32_32x32x16_bf16 v[32:47], v[48:51], v[74:77], v[32:47]
	v_mov_b32_e32 v48, v56
	s_nop 1
	v_permlane32_swap_b32_e32 v56, v48
	v_mfma_f32_32x32x16_bf16 v[32:47], v[66:69], v[82:85], v[32:47]
	s_and_saveexec_b64 s[16:17], vcc
	s_cbranch_execz .LBB0_878
	v_add_f32_e32 v48, v56, v48
	v_lshl_add_u32 v49, v180, 2, s29
	ds_write_b32 v49, v48 offset:49280
	s_branch .LBB0_878

; #define WAIT_BAR(N) asm volatile("s_waitcnt vmcnt(" #N ") lgkmcnt(0)\n\ts_barrier":::"memory")
;   #define DMA_K(t,slot) glds16(ksrc+(long)(t)*KVBLK*KVP,(unsigned)__builtin_amdgcn_readfirstlane(kdst+(slot)))
;   #define ROT() do{sl_prev=sl_cur;sl_cur=sl_next;sl_next=(sl_next==(NSLOT-1)*SLOTB)?0:sl_next+SLOTB;}while(0)
; template<int THRL,int VM,bool NOMAX> __device__ __forceinline__ void attn_unit(const bf16*Qb,const bf16*__restrict__ Kh,const bf16*__restrict__ Vh,bf16*Ob,const int NT,const int sp,float*wscr,char*shm){
;     ...
;   const bf16*Qw=Qb+(long)(wid*QBLK)*QOP;
;   const unsigned lds0=(unsigned)(uintptr_t)shm;
;   constexpr int LDS_WS_=LDS_V+3*VM*SLOTB, LDS_OST_=LDS_WS_+NW*64*4;
;   float*wsf=(float*)(shm+LDS_WS_)+wid*64;
;   const bf16*ksrc=Kh+(long)lane*KVP+wid*8;
;   const bf16*vsrc=Vh+(long)(16*(wid&3)+(lane>>2))*KVP+(wid>>2)*32+(lane&3)*8;
;   const unsigned kdst=lds0+LDS_K+wid*1024, vdst=lds0+LDS_V+wid*1024;
;     ...
;   const int vb0=(int)(lds0+LDS_V)+((lane>>4)&1)*32+(lane&3)*8+(4*hi+((lane&15)>>2))*64;
;   const char*Kbase=shm+LDS_K; bf16x8 kf[8];
;   const lds_cptr shm3=(lds_cptr)shm; const lds_cptr kp0=shm3+LDS_K+hi*1024+r32*16; const lds_cptr vp0=shm3+LDS_V+((lane>>4)&1)*32+(lane&3)*8+(4*hi+((lane&15)>>2))*64;
;   if(wid>=4)__builtin_amdgcn_s_setprio(1);
;   DMA_K(0,0);DMA_V(0,0);DMA_K(1,SLOTB);
;   bf16x8 qr[4];
;   #pragma unroll
;   for(int d0=0;d0<4;++d0)qr[d0]=*reinterpret_cast<const bf16x8*>(&Qw[(long)r32*QOP+d0*16+hi*8]);
;   const lds_cptr qpk=shm3+LDS_OST_+wid*4096+lane*16;
;   if constexpr(VM==2){
;     #pragma unroll
;     for(int d0=0;d0<4;++d0)*(__attribute__((address_space(3))) bf16x8*)(const_cast<__attribute__((address_space(3))) char*>(qpk)+d0*1024)=qr[d0]; }
;   float mhat=0.f,l_reg=0.f;f32x16 o[2*VM];
;   #pragma unroll
;   for(int d_=0;d_<2*VM;++d_)o[d_]=f32x16{};
;  f32x16 negm=f32x16{}; if constexpr(VM==1){asm volatile("":"+v"(negm));}
;   bool resc=false;
;     ...
;   f32x16 pA0,pA1,pB0,pB1;
;   int sl_prev=0,sl_cur=0,sl_next=SLOTB;
;     ...
;   DMA_K(2,2*SLOTB);
;   WAIT_BAR(3);
;   qkt(pA0,pA1,Kbase,qr,negm,r32,hi);asm volatile("s_nop 15\n\ts_nop 7":"+v"(pA0),"+v"(pA1));
;   START(pA0,pA1);
;   _Pragma("unroll") for(int r=0;r<16;++r)pA1[r]=__builtin_amdgcn_exp2f(pA1[r]);
;   WAIT_BAR(0);
;   DMA_K(3,0);DMA_V(1,SLOTB);
;   ROT();
;   kload8(kf,kp0+sl_cur);
;   if constexpr(VM==2){WAIT_BAR(3);}else{WAIT_BAR(2);}
.LBB0_890:
	s_ashr_i32 s16, s82, 7
	s_ashr_i32 s17, s16, 31
	s_lshl_b64 s[16:17], s[16:17], 12
	s_add_u32 s33, s16, 0x4000
	s_addc_u32 s17, s17, 0
	s_lshl_b32 s16, s82, 8
	s_and_b32 s16, s16, 0xf00
	s_or_b32 s16, s33, s16
	s_lshl_b64 s[28:29], s[16:17], 11
	s_add_u32 s16, s20, s28
	s_addc_u32 s28, s21, s29
	s_lshl_b32 s29, s82, 3
	s_and_b32 s29, s29, 0x380
	s_add_u32 s34, s16, s29
	s_mul_i32 s16, s17, 0xa00
	s_mul_hi_u32 s17, s33, 0xa00
	s_addc_u32 s35, s28, 0
	s_add_i32 s17, s17, s16
	s_mulk_i32 s33, 0xa00
	s_add_u32 s16, s30, s33
	s_addc_u32 s17, s31, s17
	s_and_b32 s28, s82, 64
	s_lshl_b32 s28, s28, 1
	s_add_u32 s16, s16, s28
	s_addc_u32 s17, s17, 0
	s_lshl_b32 s28, s18, 5
	s_ashr_i32 s29, s28, 31
	v_and_b32_e32 v178, 63, v48
	s_lshl_b64 s[28:29], s[28:29], 11
	s_add_u32 s50, s34, s28
	v_mul_u32_u24_e32 v16, 0x500, v178
	s_addc_u32 s51, s35, s29
	v_lshlrev_b32_e32 v168, 1, v16
	s_lshl_b32 s28, s18, 3
	v_lshl_add_u64 v[16:17], s[16:17], 0, v[168:169]
	s_ashr_i32 s29, s28, 31
	v_lshl_add_u64 v[172:173], s[28:29], 1, v[16:17]
	v_and_b32_e32 v246, 63, v210
	v_lshrrev_b32_e32 v247, 6, v210
	v_lshrrev_b32_e32 v248, 3, v246
	v_lshl_add_u32 v248, v247, 3, v248
	v_and_b32_e32 v249, 1, v247
	v_lshrrev_b32_e32 v250, 4, v246
	v_lshl_or_b32 v249, v249, 2, v250
	v_and_b32_e32 v250, 7, v246
	v_xor_b32_e32 v250, v250, v249
	v_sub_u32_e32 v248, v248, v246
	v_mul_i32_i24_e32 v248, 0xa00, v248
	v_sub_u32_e32 v250, v250, v247
	v_lshl_add_u32 v248, v250, 4, v248
	v_ashrrev_i32_e32 v249, 31, v248
	v_lshl_add_u64 v[172:173], v[248:249], 0, v[172:173]
	s_lshl_b32 s28, s18, 4
	v_bfe_u32 v16, v48, 2, 4
	v_and_or_b32 v16, s28, 48, v16
	v_mul_u32_u24_e32 v16, 0x500, v16
	v_lshlrev_b32_e32 v168, 1, v16
	v_lshl_add_u64 v[16:17], s[16:17], 0, v[168:169]
	s_ashr_i32 s16, s19, 3
	s_andn2_b32 s16, s16, 31
	s_ashr_i32 s17, s16, 31
	v_lshlrev_b32_e32 v179, 3, v48
	s_lshl_b32 s28, s18, 10
	v_and_b32_e32 v183, 24, v179
	s_cmp_lg_u32 0, -1
	v_lshl_add_u64 v[16:17], s[16:17], 1, v[16:17]
	v_lshlrev_b32_e32 v168, 1, v183
	s_cselect_b32 s16, 0, 0
	v_lshl_add_u64 v[88:89], v[16:17], 0, v[168:169]
	s_add_i32 s17, s28, s16
	s_mov_b32 s29, m0
	s_mov_b32 m0, s17
	s_nop 0
	global_load_lds_dwordx4 v[172:173], off
	s_mov_b32 m0, s29
	v_and_b32_e32 v180, 31, v48
	v_lshl_add_u64 v[170:171], v[88:89], 0, s[0:1]
	s_add_i32 s16, s17, 0x6000
	s_mov_b32 s29, m0
	s_mov_b32 m0, s16
	s_nop 0
	global_load_lds_dwordx4 v[170:171], off
	s_mov_b32 m0, s29
	v_lshl_add_u64 v[16:17], v[172:173], 0, s[6:7]
	v_bfe_u32 v181, v48, 5, 1
	s_add_i32 s29, s17, 0x2000
	s_mov_b32 s33, m0
	s_mov_b32 m0, s29
	s_nop 0
	global_load_lds_dwordx4 v[16:17], off
	s_mov_b32 m0, s33
	v_lshlrev_b32_e32 v16, 11, v180
	v_lshl_or_b32 v16, v181, 4, v16
	global_load_dwordx4 v[156:159], v16, s[50:51]
	global_load_dwordx4 v[152:155], v16, s[50:51] offset:32
	global_load_dwordx4 v[148:151], v16, s[50:51] offset:64
	global_load_dwordx4 v[144:147], v16, s[50:51] offset:96
	v_mov_b64_e32 v[30:31], v[14:15]
	v_mov_b64_e32 v[28:29], v[12:13]
	v_mov_b64_e32 v[26:27], v[10:11]
	v_mov_b64_e32 v[24:25], v[8:9]
	v_mov_b64_e32 v[22:23], v[6:7]
	v_mov_b64_e32 v[20:21], v[4:5]
	v_mov_b64_e32 v[18:19], v[2:3]
	v_mov_b64_e32 v[16:17], v[0:1]
	v_lshlrev_b32_e32 v32, 10, v181
	v_lshlrev_b32_e32 v33, 4, v180
	v_add3_u32 v182, 0, v32, v33
	v_bfe_u32 v246, v182, 4, 5
	v_bfe_u32 v247, v182, 10, 1
	v_bfe_u32 v248, v182, 5, 1
	v_bfe_u32 v249, v182, 6, 2
	v_xor_b32_e32 v247, v247, v248
	v_lshlrev_b32_e32 v246, 7, v246
	v_lshl_or_b32 v246, v247, 4, v246
	v_lshl_add_u32 v234, v249, 5, v246
	v_xor_b32_e32 v248, 1, v249
	v_lshl_add_u32 v235, v248, 5, v246
	v_xor_b32_e32 v248, 2, v249
	v_lshl_add_u32 v236, v248, 5, v246
	v_xor_b32_e32 v248, 3, v249
	v_lshl_add_u32 v237, v248, 5, v246
	v_lshl_add_u64 v[32:33], v[172:173], 0, s[8:9]
	s_add_i32 s29, s17, 0x4000
	s_mov_b32 s33, m0
	s_mov_b32 m0, s29
	s_nop 0
	global_load_lds_dwordx4 v[32:33], off
	s_mov_b32 m0, s33
	s_waitcnt vmcnt(3) lgkmcnt(0)
	s_barrier
	ds_read_b128 v[50:53], v234
	v_lshlrev_b32_e32 v49, 1, v48
	v_lshlrev_b32_e32 v48, 4, v48
	v_and_b32_e32 v184, 32, v49
	v_and_b32_e32 v48, 0xc0, v48
	v_lshl_or_b32 v185, v181, 8, v48
	v_add_u32_e32 v48, 0, v184
	v_add3_u32 v168, v48, v183, v185
	v_lshl_add_u64 v[48:49], v[172:173], 0, s[10:11]
	s_add_i32 s35, s17, 0x8000
	v_mov_b32_e32 v186, 0
	s_mov_b32 s29, -1
	s_mov_b32 s52, 0
	s_movk_i32 s34, 0x2000
	s_movk_i32 s33, 0x4000
	v_lshl_add_u64 v[174:175], v[88:89], 0, s[14:15]
	v_lshl_add_u64 v[176:177], v[172:173], 0, s[36:37]
	s_waitcnt vmcnt(3) lgkmcnt(0)
	v_mfma_f32_32x32x16_bf16 v[32:47], v[50:53], v[156:159], v[16:31]
	ds_read_b128 v[50:53], v234 offset:4096
	s_waitcnt lgkmcnt(0)
	v_mfma_f32_32x32x16_bf16 v[16:31], v[50:53], v[156:159], v[16:31]
	ds_read_b128 v[50:53], v235
	s_waitcnt vmcnt(2) lgkmcnt(0)
	v_mfma_f32_32x32x16_bf16 v[32:47], v[50:53], v[152:155], v[32:47]
	ds_read_b128 v[50:53], v235 offset:4096
	s_waitcnt lgkmcnt(0)
	v_mfma_f32_32x32x16_bf16 v[16:31], v[50:53], v[152:155], v[16:31]
	ds_read_b128 v[50:53], v236
	s_waitcnt vmcnt(1) lgkmcnt(0)
	v_mfma_f32_32x32x16_bf16 v[32:47], v[50:53], v[148:151], v[32:47]
	ds_read_b128 v[50:53], v236 offset:4096
	ds_read_b128 v[54:57], v237 offset:4096
	ds_read_b128 v[58:61], v237
	s_waitcnt lgkmcnt(2)
	v_mfma_f32_32x32x16_bf16 v[16:31], v[50:53], v[148:151], v[16:31]
	s_waitcnt vmcnt(0) lgkmcnt(0)
	v_mfma_f32_32x32x16_bf16 v[32:47], v[58:61], v[144:147], v[32:47]
	v_lshl_add_u64 v[58:59], v[88:89], 0, s[12:13]
	v_mfma_f32_32x32x16_bf16 v[16:31], v[54:57], v[144:147], v[16:31]
	s_nop 15
	s_nop 7
	s_waitcnt vmcnt(0) lgkmcnt(0)
	s_barrier
; #define WAIT_BAR(N) asm volatile("s_waitcnt vmcnt(" #N ") lgkmcnt(0)\n\ts_barrier":::"memory")
;   #define DMA_K(t,slot) glds16(ksrc+(long)(t)*KVBLK*KVP,(unsigned)__builtin_amdgcn_readfirstlane(kdst+(slot)))
;   #define DMA_V(t,slot) do{ glds16(vsrc+(long)(t)*KVBLK*KVP,(unsigned)__builtin_amdgcn_readfirstlane(vdst+VM*(slot))); if constexpr(VM==2) glds16(vsrc+64+(long)(t)*KVBLK*KVP,(unsigned)__builtin_amdgcn_readfirstlane(vdst+VM*(slot)+8192)); }while(0)
;   #define ROT() do{sl_prev=sl_cur;sl_cur=sl_next;sl_next=(sl_next==(NSLOT-1)*SLOTB)?0:sl_next+SLOTB;}while(0)
; template<int THRL,int VM,bool NOMAX> __device__ __forceinline__ void attn_unit(const bf16*Qb,const bf16*__restrict__ Kh,const bf16*__restrict__ Vh,bf16*Ob,const int NT,const int sp,float*wscr,char*shm){
;     ...
;   _Pragma("unroll") for(int r=0;r<16;++r)pA1[r]=__builtin_amdgcn_exp2f(pA1[r]);
;   WAIT_BAR(0);
;   DMA_K(3,0);DMA_V(1,SLOTB);
;   ROT();
;   kload8(kf,kp0+sl_cur);
;   if constexpr(VM==2){WAIT_BAR(3);}else{WAIT_BAR(2);}
;   s16x4 vlo[8],vhi[8]; u32x4 pw0,pw1,pw2,pw3;
	s_mov_b32 s53, m0
	s_mov_b32 m0, s17
	s_nop 0
	global_load_lds_dwordx4 v[48:49], off
	s_mov_b32 m0, s53
	s_nop 0
	s_mov_b32 s53, m0
	s_mov_b32 m0, s35
	s_nop 0
	global_load_lds_dwordx4 v[58:59], off
	s_mov_b32 m0, s53
	ds_read_b128 v[84:87], v234 offset:8192
	ds_read_b128 v[80:83], v234 offset:12288
	ds_read_b128 v[164:167], v235 offset:8192
	ds_read_b128 v[160:163], v235 offset:12288
	ds_read_b128 v[124:127], v236 offset:8192
	ds_read_b128 v[120:123], v236 offset:12288
	ds_read_b128 v[116:119], v237 offset:8192
	ds_read_b128 v[112:115], v237 offset:12288
	s_nop 0
	v_exp_f32_e32 v64, v32
	v_exp_f32_e32 v65, v33
	v_exp_f32_e32 v66, v34
	v_exp_f32_e32 v67, v35
	v_exp_f32_e32 v68, v36
	v_exp_f32_e32 v69, v37
	v_exp_f32_e32 v70, v38
	v_exp_f32_e32 v71, v39
	v_exp_f32_e32 v72, v40
	v_exp_f32_e32 v73, v41
	v_exp_f32_e32 v74, v42
	v_exp_f32_e32 v75, v43
	v_exp_f32_e32 v76, v44
	v_exp_f32_e32 v77, v45
	v_exp_f32_e32 v78, v46
	v_exp_f32_e32 v79, v47
	v_exp_f32_e32 v48, v16
	v_exp_f32_e32 v49, v17
	v_exp_f32_e32 v50, v18
	v_exp_f32_e32 v51, v19
	v_exp_f32_e32 v52, v20
	v_exp_f32_e32 v53, v21
	v_exp_f32_e32 v54, v22
	v_exp_f32_e32 v55, v23
	v_exp_f32_e32 v56, v24
	v_exp_f32_e32 v57, v25
	v_exp_f32_e32 v58, v26
	v_exp_f32_e32 v59, v27
	v_exp_f32_e32 v60, v28
	v_exp_f32_e32 v61, v29
	v_exp_f32_e32 v62, v30
	v_exp_f32_e32 v63, v31
	s_waitcnt vmcnt(2) lgkmcnt(0)
	s_barrier
	v_mov_b32_e32 v16, 0
	v_mov_b32_e32 v17, v186
	v_mov_b32_e32 v18, v186
	v_mov_b32_e32 v19, v186
	v_mov_b32_e32 v20, v186
	v_mov_b32_e32 v21, v186
	v_mov_b32_e32 v22, v186
	v_mov_b32_e32 v23, v186
	v_mov_b32_e32 v24, v186
	v_mov_b32_e32 v25, v186
	v_mov_b32_e32 v26, v186
	v_mov_b32_e32 v27, v186
	v_mov_b32_e32 v28, v186
	v_mov_b32_e32 v29, v186
	v_mov_b32_e32 v30, v186
	v_mov_b32_e32 v31, v186
	v_mov_b32_e32 v32, 0
	v_mov_b32_e32 v33, v186
	v_mov_b32_e32 v34, v186
	v_mov_b32_e32 v35, v186
	v_mov_b32_e32 v36, v186
	v_mov_b32_e32 v37, v186
	v_mov_b32_e32 v38, v186
	v_mov_b32_e32 v39, v186
	v_mov_b32_e32 v40, v186
	v_mov_b32_e32 v41, v186
	v_mov_b32_e32 v42, v186
	v_mov_b32_e32 v43, v186
	v_mov_b32_e32 v44, v186
	v_mov_b32_e32 v45, v186
	v_mov_b32_e32 v46, v186
	v_mov_b32_e32 v47, v186
.LBB0_891:
	v_mfma_f32_32x32x16_bf16 v[96:111], v[84:87], v[156:159], 0
	v_add_u32_e32 v187, s52, v168
	ds_read_b64_tr_b16 v[188:189], v187 offset:24576
	ds_read_b64_tr_b16 v[190:191], v187 offset:25088
	v_add_f32_e32 v88, v64, v65
	v_add_f32_e32 v88, v66, v88
	v_add_f32_e32 v88, v67, v88
	v_add_f32_e32 v88, v68, v88
	v_add_f32_e32 v88, v69, v88
	v_cvt_pk_bf16_f32 v140, v64, v65
	v_cvt_pk_bf16_f32 v141, v66, v67
	ds_read_b64_tr_b16 v[64:65], v187 offset:28672
	ds_read_b64_tr_b16 v[66:67], v187 offset:29184
	v_add_f32_e32 v84, v70, v88
	v_add_f32_e32 v84, v71, v84
	v_add_f32_e32 v84, v72, v84
	v_add_f32_e32 v128, v73, v84
	s_waitcnt lgkmcnt(10)
	v_mfma_f32_32x32x16_bf16 v[80:95], v[80:83], v[156:159], 0
	v_cvt_pk_bf16_f32 v142, v68, v69
	v_cvt_pk_bf16_f32 v143, v70, v71
	ds_read_b64_tr_b16 v[68:69], v187 offset:25600
	ds_read_b64_tr_b16 v[70:71], v187 offset:26112
	v_add_f32_e32 v128, v74, v128
	v_add_f32_e32 v128, v75, v128
	v_add_f32_e32 v128, v76, v128
	v_add_f32_e32 v128, v77, v128
	v_cvt_pk_bf16_f32 v136, v72, v73
	v_cvt_pk_bf16_f32 v137, v74, v75
	s_waitcnt lgkmcnt(11)
	v_mfma_f32_32x32x16_bf16 v[96:111], v[164:167], v[152:155], v[96:111]
	ds_read_b64_tr_b16 v[72:73], v187 offset:29696
	ds_read_b64_tr_b16 v[74:75], v187 offset:30208
	s_waitcnt lgkmcnt(12)
	v_mfma_f32_32x32x16_bf16 v[80:95], v[160:163], v[152:155], v[80:95]
	v_add_f32_e32 v128, v78, v128
	v_add_f32_e32 v128, v79, v128
	v_add_f32_e32 v128, v48, v128
	v_add_f32_e32 v128, v49, v128
	v_cvt_pk_bf16_f32 v138, v76, v77
	v_cvt_pk_bf16_f32 v139, v78, v79
	ds_read_b64_tr_b16 v[76:77], v187 offset:26624
	ds_read_b64_tr_b16 v[78:79], v187 offset:27136
	v_add_f32_e32 v128, v50, v128
	v_add_f32_e32 v128, v51, v128
	v_add_f32_e32 v128, v52, v128
	v_add_f32_e32 v128, v53, v128
	v_cvt_pk_bf16_f32 v132, v48, v49
	v_cvt_pk_bf16_f32 v133, v50, v51
	s_waitcnt lgkmcnt(13)
	v_mfma_f32_32x32x16_bf16 v[96:111], v[124:127], v[148:151], v[96:111]
	ds_read_b64_tr_b16 v[48:49], v187 offset:30720
	ds_read_b64_tr_b16 v[50:51], v187 offset:31232
	s_waitcnt lgkmcnt(14)
	v_mfma_f32_32x32x16_bf16 v[80:95], v[120:123], v[148:151], v[80:95]
	v_add_f32_e32 v124, v54, v128
	v_add_f32_e32 v124, v55, v124
	v_add_f32_e32 v124, v56, v124
	v_add_f32_e32 v124, v57, v124
	v_cvt_pk_bf16_f32 v134, v52, v53
	v_cvt_pk_bf16_f32 v135, v54, v55
	ds_read_b64_tr_b16 v[52:53], v187 offset:27648
	ds_read_b64_tr_b16 v[54:55], v187 offset:28160
	v_add_f32_e32 v120, v58, v124
	v_add_f32_e32 v120, v59, v120
	v_add_f32_e32 v120, v60, v120
	v_add_f32_e32 v120, v61, v120
	v_cvt_pk_bf16_f32 v128, v56, v57
	v_cvt_pk_bf16_f32 v129, v58, v59
	s_waitcnt lgkmcnt(14)
	v_mfma_f32_32x32x16_bf16 v[96:111], v[116:119], v[144:147], v[96:111]
	ds_read_b64_tr_b16 v[56:57], v187 offset:31744
	ds_read_b64_tr_b16 v[58:59], v187 offset:32256
	v_mfma_f32_32x32x16_bf16 v[80:95], v[112:115], v[144:147], v[80:95]
	v_add_f32_e32 v116, v62, v120
	v_add_f32_e32 v116, v63, v116
	v_add_f32_e32 v116, 0, v116
	v_cvt_pk_bf16_f32 v130, v60, v61
	v_cvt_pk_bf16_f32 v131, v62, v63
	v_lshl_add_u64 v[60:61], v[176:177], 0, s[38:39]
	s_add_i32 s35, s34, s17
	s_mov_b32 s52, m0
	s_mov_b32 m0, s35
	s_nop 0
	global_load_lds_dwordx4 v[60:61], off
	s_mov_b32 m0, s52
	v_lshl_add_u64 v[60:61], v[174:175], 0, s[38:39]
	s_add_i32 s35, s33, s16
	s_mov_b32 s52, m0
	s_mov_b32 m0, s35
	s_nop 0
	global_load_lds_dwordx4 v[60:61], off
	s_mov_b32 m0, s52
	v_add_f32_e32 v202, v186, v116
	s_waitcnt lgkmcnt(14)
	v_mfma_f32_32x32x16_bf16 v[16:31], v[140:143], v[188:191], v[16:31]
	v_exp_f32_e32 v96, v96
	v_exp_f32_e32 v97, v97
	v_exp_f32_e32 v98, v98
	v_exp_f32_e32 v99, v99
	s_waitcnt lgkmcnt(12)
	v_mfma_f32_32x32x16_bf16 v[32:47], v[140:143], v[64:67], v[32:47]
	v_exp_f32_e32 v100, v100
	v_exp_f32_e32 v101, v101
	v_exp_f32_e32 v102, v102
	v_exp_f32_e32 v103, v103
	v_add_u32_e32 v242, s33, v234
	v_add_u32_e32 v243, s33, v235
	v_add_u32_e32 v244, s33, v236
	v_add_u32_e32 v245, s33, v237
	ds_read_b128 v[60:63], v242
	ds_read_b128 v[112:115], v242 offset:4096
	s_waitcnt lgkmcnt(12)
	v_mfma_f32_32x32x16_bf16 v[16:31], v[136:139], v[68:71], v[16:31]
	v_exp_f32_e32 v104, v104
	v_exp_f32_e32 v105, v105
	v_exp_f32_e32 v106, v106
	v_exp_f32_e32 v107, v107
	ds_read_b128 v[116:119], v243
	ds_read_b128 v[120:123], v243 offset:4096
	s_waitcnt lgkmcnt(12)
	v_mfma_f32_32x32x16_bf16 v[32:47], v[136:139], v[72:75], v[32:47]
	v_exp_f32_e32 v108, v108
	v_exp_f32_e32 v109, v109
	v_exp_f32_e32 v110, v110
	v_exp_f32_e32 v111, v111
	ds_read_b128 v[124:127], v244
	ds_read_b128 v[160:163], v244 offset:4096
	s_waitcnt lgkmcnt(12)
	v_mfma_f32_32x32x16_bf16 v[16:31], v[132:135], v[76:79], v[16:31]
	v_exp_f32_e32 v80, v80
	v_exp_f32_e32 v81, v81
	v_exp_f32_e32 v82, v82
	v_exp_f32_e32 v83, v83
	ds_read_b128 v[164:167], v245
	ds_read_b128 v[186:189], v245 offset:4096
	s_waitcnt lgkmcnt(12)
	v_mfma_f32_32x32x16_bf16 v[32:47], v[132:135], v[48:51], v[32:47]
	v_exp_f32_e32 v84, v84
	v_exp_f32_e32 v85, v85
	v_exp_f32_e32 v86, v86
	v_exp_f32_e32 v87, v87
	s_waitcnt lgkmcnt(10)
	v_mfma_f32_32x32x16_bf16 v[16:31], v[128:131], v[52:55], v[16:31]
	v_exp_f32_e32 v88, v88
	v_exp_f32_e32 v89, v89
	v_exp_f32_e32 v90, v90
	v_exp_f32_e32 v91, v91
	s_waitcnt lgkmcnt(8)
	v_mfma_f32_32x32x16_bf16 v[32:47], v[128:131], v[56:59], v[32:47]
	v_exp_f32_e32 v92, v92
	v_exp_f32_e32 v93, v93
	v_exp_f32_e32 v94, v94
	v_exp_f32_e32 v95, v95
	s_waitcnt vmcnt(2) lgkmcnt(0)
	s_barrier
	v_mfma_f32_32x32x16_bf16 v[64:79], v[60:63], v[156:159], 0
	s_add_i32 s35, s33, 0x2000
	s_cmpk_lg_i32 s33, 0x4000
	s_cselect_b32 s35, s35, 0
	v_add_u32_e32 v203, s34, v168
	ds_read_b64_tr_b16 v[190:191], v203 offset:24576
	ds_read_b64_tr_b16 v[192:193], v203 offset:25088
	v_add_f32_e32 v48, v96, v97
	v_add_f32_e32 v48, v98, v48
	v_add_f32_e32 v48, v99, v48
	v_add_f32_e32 v48, v100, v48
	v_add_f32_e32 v48, v101, v48
	v_cvt_pk_bf16_f32 v140, v96, v97
	v_cvt_pk_bf16_f32 v141, v98, v99
	ds_read_b64_tr_b16 v[96:97], v203 offset:28672
	ds_read_b64_tr_b16 v[98:99], v203 offset:29184
	v_add_f32_e32 v48, v102, v48
	v_add_f32_e32 v48, v103, v48
	v_add_f32_e32 v48, v104, v48
	v_add_f32_e32 v128, v105, v48
	s_waitcnt lgkmcnt(10)
	v_mfma_f32_32x32x16_bf16 v[48:63], v[112:115], v[156:159], 0
	v_cvt_pk_bf16_f32 v142, v100, v101
	v_cvt_pk_bf16_f32 v143, v102, v103
	ds_read_b64_tr_b16 v[100:101], v203 offset:25600
	ds_read_b64_tr_b16 v[102:103], v203 offset:26112
	s_waitcnt lgkmcnt(11)
	v_mfma_f32_32x32x16_bf16 v[64:79], v[116:119], v[152:155], v[64:79]
	v_add_f32_e32 v112, v106, v128
	v_add_f32_e32 v112, v107, v112
	v_add_f32_e32 v112, v108, v112
	v_add_f32_e32 v112, v109, v112
	v_cvt_pk_bf16_f32 v136, v104, v105
	v_cvt_pk_bf16_f32 v137, v106, v107
	ds_read_b64_tr_b16 v[104:105], v203 offset:29696
	ds_read_b64_tr_b16 v[106:107], v203 offset:30208
	s_waitcnt lgkmcnt(12)
	v_mfma_f32_32x32x16_bf16 v[48:63], v[120:123], v[152:155], v[48:63]
	v_add_f32_e32 v112, v110, v112
	v_add_f32_e32 v112, v111, v112
	v_add_f32_e32 v112, v80, v112
	v_add_f32_e32 v112, v81, v112
	v_cvt_pk_bf16_f32 v138, v108, v109
	v_cvt_pk_bf16_f32 v139, v110, v111
	ds_read_b64_tr_b16 v[108:109], v203 offset:26624
	ds_read_b64_tr_b16 v[110:111], v203 offset:27136
	s_waitcnt lgkmcnt(13)
	v_mfma_f32_32x32x16_bf16 v[64:79], v[124:127], v[148:151], v[64:79]
	v_add_f32_e32 v112, v82, v112
	v_add_f32_e32 v112, v83, v112
	v_add_f32_e32 v112, v84, v112
	v_add_f32_e32 v112, v85, v112
	v_cvt_pk_bf16_f32 v132, v80, v81
	v_cvt_pk_bf16_f32 v133, v82, v83
	ds_read_b64_tr_b16 v[194:195], v203 offset:30720
	ds_read_b64_tr_b16 v[196:197], v203 offset:31232
	s_waitcnt lgkmcnt(14)
	v_mfma_f32_32x32x16_bf16 v[48:63], v[160:163], v[148:151], v[48:63]
	v_add_f32_e32 v80, v86, v112
	v_add_f32_e32 v80, v87, v80
	v_add_f32_e32 v80, v88, v80
	v_add_f32_e32 v80, v89, v80
	v_cvt_pk_bf16_f32 v134, v84, v85
	v_cvt_pk_bf16_f32 v135, v86, v87
	ds_read_b64_tr_b16 v[198:199], v203 offset:27648
	ds_read_b64_tr_b16 v[200:201], v203 offset:28160
	s_waitcnt lgkmcnt(14)
	v_mfma_f32_32x32x16_bf16 v[64:79], v[164:167], v[144:147], v[64:79]
	v_add_f32_e32 v80, v90, v80
	v_add_f32_e32 v80, v91, v80
	v_add_f32_e32 v80, v92, v80
	v_add_f32_e32 v80, v93, v80
	v_cvt_pk_bf16_f32 v128, v88, v89
	v_cvt_pk_bf16_f32 v129, v90, v91
	ds_read_b64_tr_b16 v[88:89], v203 offset:31744
	ds_read_b64_tr_b16 v[90:91], v203 offset:32256
	v_mfma_f32_32x32x16_bf16 v[48:63], v[186:189], v[144:147], v[48:63]
	v_add_f32_e32 v80, v94, v80
	v_add_f32_e32 v80, v95, v80
	v_add_f32_e32 v80, 0, v80
	v_cvt_pk_bf16_f32 v130, v92, v93
	v_cvt_pk_bf16_f32 v131, v94, v95
	s_add_i32 s34, s33, s17
	s_mov_b32 s52, m0
	s_mov_b32 m0, s34
	s_nop 0
	global_load_lds_dwordx4 v[176:177], off
	s_mov_b32 m0, s52
	s_add_i32 s34, s35, s16
	s_mov_b32 s52, m0
	s_mov_b32 m0, s34
	s_nop 0
	global_load_lds_dwordx4 v[174:175], off
	s_mov_b32 m0, s52
	v_add_f32_e32 v186, v202, v80
	s_waitcnt lgkmcnt(14)
	v_mfma_f32_32x32x16_bf16 v[16:31], v[140:143], v[190:193], v[16:31]
	v_exp_f32_e32 v64, v64
	v_exp_f32_e32 v65, v65
	v_exp_f32_e32 v66, v66
	v_exp_f32_e32 v67, v67
	s_waitcnt lgkmcnt(12)
; #define WAIT_BAR(N) asm volatile("s_waitcnt vmcnt(" #N ") lgkmcnt(0)\n\ts_barrier":::"memory")
;   #define RESC() do{ if(!NOMAX&&resc){ asm volatile("s_waitcnt lgkmcnt(0)":::"memory"); \
;       _Pragma("unroll") for(int d_=0;d_<2*VM;++d_) _Pragma("unroll") for(int r=0;r<16;++r)o[d_][r]*=wsf[crow(r,hi)]; } }while(0)
;   #define ROT() do{sl_prev=sl_cur;sl_cur=sl_next;sl_next=(sl_next==(NSLOT-1)*SLOTB)?0:sl_next+SLOTB;}while(0)
;   #define ENDW(tt) do{ if((tt)+3<NT){ if constexpr(VM==2){WAIT_BAR(3);}else{WAIT_BAR(2);} } else if((tt)+2<NT){ if constexpr(VM==2){WAIT_BAR(2);}else{WAIT_BAR(1);} } else {WAIT_BAR(0);} }while(0)
; template<int THRL,int VM,bool NOMAX> __device__ __forceinline__ void attn_unit(const bf16*Qb,const bf16*__restrict__ Kh,const bf16*__restrict__ Vh,bf16*Ob,const int NT,const int sp,float*wscr,char*shm){
;     ...
;   int t=1;
;   for(;t+5<NT;t+=2){
;     STEP(pB0,pB1,pA0,pA1,t,true,true,true);     if constexpr(VM==2){WAIT_BAR(3);}else{WAIT_BAR(2);} RESC(); ROT();
;     STEP(pA0,pA1,pB0,pB1,t+1,true,true,true);   if constexpr(VM==2){WAIT_BAR(3);}else{WAIT_BAR(2);} RESC(); ROT();
;   }
;     ...
;   for(;t+1<NT;t+=2){
;     STEP(pB0,pB1,pA0,pA1,t,(t+3<NT),(t+1<NT),(t+1<NT));       ENDW(t);   RESC(); ROT();
;     STEP(pA0,pA1,pB0,pB1,t+1,(t+4<NT),(t+2<NT),(t+2<NT));     ENDW(t+1); RESC(); ROT();
	v_mfma_f32_32x32x16_bf16 v[32:47], v[140:143], v[96:99], v[32:47]
	v_exp_f32_e32 v68, v68
	v_exp_f32_e32 v69, v69
	v_exp_f32_e32 v70, v70
	v_exp_f32_e32 v71, v71
	v_add_u32_e32 v242, s35, v234
	v_add_u32_e32 v243, s35, v235
	v_add_u32_e32 v244, s35, v236
	v_add_u32_e32 v245, s35, v237
	ds_read_b128 v[84:87], v242
	ds_read_b128 v[80:83], v242 offset:4096
	s_waitcnt lgkmcnt(12)
	v_mfma_f32_32x32x16_bf16 v[16:31], v[136:139], v[100:103], v[16:31]
	v_exp_f32_e32 v72, v72
	v_exp_f32_e32 v73, v73
	v_exp_f32_e32 v74, v74
	v_exp_f32_e32 v75, v75
	ds_read_b128 v[164:167], v243
	ds_read_b128 v[160:163], v243 offset:4096
	s_waitcnt lgkmcnt(12)
	v_mfma_f32_32x32x16_bf16 v[32:47], v[136:139], v[104:107], v[32:47]
	v_exp_f32_e32 v76, v76
	v_exp_f32_e32 v77, v77
	v_exp_f32_e32 v78, v78
	v_exp_f32_e32 v79, v79
	ds_read_b128 v[124:127], v244
	ds_read_b128 v[120:123], v244 offset:4096
	s_waitcnt lgkmcnt(12)
	v_mfma_f32_32x32x16_bf16 v[16:31], v[132:135], v[108:111], v[16:31]
	v_exp_f32_e32 v48, v48
	v_exp_f32_e32 v49, v49
	v_exp_f32_e32 v50, v50
	v_exp_f32_e32 v51, v51
	ds_read_b128 v[116:119], v245
	ds_read_b128 v[112:115], v245 offset:4096
	s_waitcnt lgkmcnt(12)
	v_mfma_f32_32x32x16_bf16 v[32:47], v[132:135], v[194:197], v[32:47]
	v_exp_f32_e32 v52, v52
	v_exp_f32_e32 v53, v53
	v_exp_f32_e32 v54, v54
	v_exp_f32_e32 v55, v55
	s_waitcnt lgkmcnt(10)
	v_mfma_f32_32x32x16_bf16 v[16:31], v[128:131], v[198:201], v[16:31]
	v_exp_f32_e32 v56, v56
	v_exp_f32_e32 v57, v57
	v_exp_f32_e32 v58, v58
	v_exp_f32_e32 v59, v59
	s_waitcnt lgkmcnt(8)
	v_mfma_f32_32x32x16_bf16 v[32:47], v[128:131], v[88:91], v[32:47]
	v_exp_f32_e32 v60, v60
	v_exp_f32_e32 v61, v61
	v_exp_f32_e32 v62, v62
	v_exp_f32_e32 v63, v63
	s_add_i32 s53, s35, 0x2000
	s_waitcnt vmcnt(2) lgkmcnt(0)
	s_barrier
	s_cmpk_lg_i32 s35, 0x4000
	s_mov_b32 s52, s33
	s_cselect_b32 s33, s53, 0
	s_add_i32 s29, s29, 2
	v_lshl_add_u64 v[174:175], v[174:175], 0, s[8:9]
	v_lshl_add_u64 v[176:177], v[176:177], 0, s[8:9]
	s_mov_b32 s34, s35
	s_cmp_lt_u32 s29, 57
	s_cbranch_scc1 .LBB0_891
	s_and_b32 s19, s19, 0x3fffffc0
	s_lshl_b32 s19, s19, 2
	s_add_i32 s19, s19, 0
	s_cmp_lg_u32 0, -1
	s_cselect_b32 s29, 0, 0
	s_add_i32 s33, s29, 0x6000
	v_add_u32_e32 v88, s33, v184
	v_add3_u32 v174, v88, v183, v185
	ds_read_b64_tr_b16 v[188:189], v168 offset:32768
	ds_read_b64_tr_b16 v[190:191], v168 offset:33280
	v_add_f32_e32 v88, v64, v65
	v_add_f32_e32 v88, v66, v88
	v_add_f32_e32 v88, v67, v88
	v_add_f32_e32 v88, v68, v88
	v_add_f32_e32 v88, v69, v88
	v_cvt_pk_bf16_f32 v140, v64, v65
	v_cvt_pk_bf16_f32 v141, v66, v67
	s_waitcnt lgkmcnt(9)
	v_mfma_f32_32x32x16_bf16 v[96:111], v[84:87], v[156:159], 0
	ds_read_b64_tr_b16 v[64:65], v168 offset:36864
	ds_read_b64_tr_b16 v[66:67], v168 offset:37376
	v_add_f32_e32 v84, v70, v88
	v_add_f32_e32 v84, v71, v84
	v_add_f32_e32 v84, v72, v84
	v_add_f32_e32 v128, v73, v84
	v_cvt_pk_bf16_f32 v142, v68, v69
	v_cvt_pk_bf16_f32 v143, v70, v71
	s_waitcnt lgkmcnt(10)
	v_mfma_f32_32x32x16_bf16 v[80:95], v[80:83], v[156:159], 0
	ds_read_b64_tr_b16 v[68:69], v168 offset:33792
	ds_read_b64_tr_b16 v[70:71], v168 offset:34304
	v_add_f32_e32 v128, v74, v128
	v_add_f32_e32 v128, v75, v128
	v_add_f32_e32 v128, v76, v128
	v_add_f32_e32 v128, v77, v128
	v_cvt_pk_bf16_f32 v136, v72, v73
	v_cvt_pk_bf16_f32 v137, v74, v75
	s_waitcnt lgkmcnt(11)
	v_mfma_f32_32x32x16_bf16 v[96:111], v[164:167], v[152:155], v[96:111]
	ds_read_b64_tr_b16 v[72:73], v168 offset:37888
	ds_read_b64_tr_b16 v[74:75], v168 offset:38400
	v_add_f32_e32 v128, v78, v128
	v_add_f32_e32 v128, v79, v128
	v_add_f32_e32 v128, v48, v128
	v_add_f32_e32 v128, v49, v128
	v_cvt_pk_bf16_f32 v138, v76, v77
	v_cvt_pk_bf16_f32 v139, v78, v79
	s_waitcnt lgkmcnt(12)
	v_mfma_f32_32x32x16_bf16 v[80:95], v[160:163], v[152:155], v[80:95]
	ds_read_b64_tr_b16 v[76:77], v168 offset:34816
	ds_read_b64_tr_b16 v[78:79], v168 offset:35328
	v_add_f32_e32 v128, v50, v128
	v_add_f32_e32 v128, v51, v128
	v_add_f32_e32 v128, v52, v128
	v_add_f32_e32 v128, v53, v128
	v_cvt_pk_bf16_f32 v132, v48, v49
	v_cvt_pk_bf16_f32 v133, v50, v51
	s_waitcnt lgkmcnt(13)
	v_mfma_f32_32x32x16_bf16 v[96:111], v[124:127], v[148:151], v[96:111]
	ds_read_b64_tr_b16 v[48:49], v168 offset:38912
	ds_read_b64_tr_b16 v[50:51], v168 offset:39424
	v_add_f32_e32 v124, v54, v128
	v_add_f32_e32 v124, v55, v124
	v_add_f32_e32 v124, v56, v124
	v_add_f32_e32 v124, v57, v124
	v_cvt_pk_bf16_f32 v134, v52, v53
	v_cvt_pk_bf16_f32 v135, v54, v55
	s_waitcnt lgkmcnt(14)
	v_mfma_f32_32x32x16_bf16 v[80:95], v[120:123], v[148:151], v[80:95]
	ds_read_b64_tr_b16 v[52:53], v168 offset:35840
	ds_read_b64_tr_b16 v[54:55], v168 offset:36352
	v_add_f32_e32 v120, v58, v124
	v_add_f32_e32 v120, v59, v120
	v_add_f32_e32 v120, v60, v120
	v_add_f32_e32 v120, v61, v120
	v_cvt_pk_bf16_f32 v128, v56, v57
	v_cvt_pk_bf16_f32 v129, v58, v59
	s_waitcnt lgkmcnt(14)
	v_mfma_f32_32x32x16_bf16 v[96:111], v[116:119], v[144:147], v[96:111]
	ds_read_b64_tr_b16 v[56:57], v168 offset:39936
	ds_read_b64_tr_b16 v[58:59], v168 offset:40448
	v_add_f32_e32 v116, v62, v120
	v_add_f32_e32 v116, v63, v116
	v_add_f32_e32 v116, 0, v116
	v_cvt_pk_bf16_f32 v130, v60, v61
	v_cvt_pk_bf16_f32 v131, v62, v63
	v_mfma_f32_32x32x16_bf16 v[80:95], v[112:115], v[144:147], v[80:95]
	s_add_i32 s28, s29, s28
	v_lshl_add_u64 v[60:61], v[172:173], 0, s[40:41]
	s_add_i32 s29, s28, 0x4000
	s_mov_b32 s33, m0
	s_mov_b32 m0, s29
	s_nop 0
	global_load_lds_dwordx4 v[60:61], off
	s_mov_b32 m0, s33
	v_lshl_add_u64 v[60:61], v[170:171], 0, s[42:43]
	s_mov_b32 s29, m0
	s_mov_b32 m0, s16
	s_nop 0
	global_load_lds_dwordx4 v[60:61], off
	s_mov_b32 m0, s29
	v_add_f32_e32 v175, v186, v116
	s_waitcnt lgkmcnt(14)
;   #define RESC() do{ if(!NOMAX&&resc){ asm volatile("s_waitcnt lgkmcnt(0)":::"memory"); \
;       _Pragma("unroll") for(int d_=0;d_<2*VM;++d_) _Pragma("unroll") for(int r=0;r<16;++r)o[d_][r]*=wsf[crow(r,hi)]; } }while(0)
;   #define ROT() do{sl_prev=sl_cur;sl_cur=sl_next;sl_next=(sl_next==(NSLOT-1)*SLOTB)?0:sl_next+SLOTB;}while(0)
;   #define ENDW(tt) do{ if((tt)+3<NT){ if constexpr(VM==2){WAIT_BAR(3);}else{WAIT_BAR(2);} } else if((tt)+2<NT){ if constexpr(VM==2){WAIT_BAR(2);}else{WAIT_BAR(1);} } else {WAIT_BAR(0);} }while(0)
; template<int THRL,int VM,bool NOMAX> __device__ __forceinline__ void attn_unit(const bf16*Qb,const bf16*__restrict__ Kh,const bf16*__restrict__ Vh,bf16*Ob,const int NT,const int sp,float*wscr,char*shm){
;     ...
;     STEP(pB0,pB1,pA0,pA1,t,(t+3<NT),(t+1<NT),(t+1<NT));       ENDW(t);   RESC(); ROT();
;     STEP(pA0,pA1,pB0,pB1,t+1,(t+4<NT),(t+2<NT),(t+2<NT));     ENDW(t+1); RESC(); ROT();
	v_mfma_f32_32x32x16_bf16 v[16:31], v[140:143], v[188:191], v[16:31]
	v_exp_f32_e32 v96, v96
	v_exp_f32_e32 v97, v97
	v_exp_f32_e32 v98, v98
	v_exp_f32_e32 v99, v99
	s_waitcnt lgkmcnt(12)
	v_mfma_f32_32x32x16_bf16 v[32:47], v[140:143], v[64:67], v[32:47]
	v_exp_f32_e32 v100, v100
	v_exp_f32_e32 v101, v101
	v_exp_f32_e32 v102, v102
	v_exp_f32_e32 v103, v103
	ds_read_b128 v[60:63], v234
	ds_read_b128 v[64:67], v234 offset:4096
	s_waitcnt lgkmcnt(12)
	v_mfma_f32_32x32x16_bf16 v[16:31], v[136:139], v[68:71], v[16:31]
	v_exp_f32_e32 v104, v104
	v_exp_f32_e32 v105, v105
	v_exp_f32_e32 v106, v106
	v_exp_f32_e32 v107, v107
	ds_read_b128 v[68:71], v235
	ds_read_b128 v[160:163], v235 offset:4096
	s_waitcnt lgkmcnt(12)
	v_mfma_f32_32x32x16_bf16 v[32:47], v[136:139], v[72:75], v[32:47]
	v_exp_f32_e32 v108, v108
	v_exp_f32_e32 v109, v109
	v_exp_f32_e32 v110, v110
	v_exp_f32_e32 v111, v111
	ds_read_b128 v[72:75], v236
	ds_read_b128 v[164:167], v236 offset:4096
	s_waitcnt lgkmcnt(12)
	v_mfma_f32_32x32x16_bf16 v[16:31], v[132:135], v[76:79], v[16:31]
	v_exp_f32_e32 v80, v80
	v_exp_f32_e32 v81, v81
	v_exp_f32_e32 v82, v82
	v_exp_f32_e32 v83, v83
	ds_read_b128 v[76:79], v237
	ds_read_b128 v[184:187], v237 offset:4096
	s_waitcnt lgkmcnt(12)
	v_mfma_f32_32x32x16_bf16 v[32:47], v[132:135], v[48:51], v[32:47]
	v_exp_f32_e32 v84, v84
	v_exp_f32_e32 v85, v85
	v_exp_f32_e32 v86, v86
	v_exp_f32_e32 v87, v87
	s_waitcnt lgkmcnt(10)
	v_mfma_f32_32x32x16_bf16 v[16:31], v[128:131], v[52:55], v[16:31]
	v_exp_f32_e32 v88, v88
	v_exp_f32_e32 v89, v89
	v_exp_f32_e32 v90, v90
	v_exp_f32_e32 v91, v91
	s_waitcnt lgkmcnt(8)
	v_mfma_f32_32x32x16_bf16 v[32:47], v[128:131], v[56:59], v[32:47]
	v_exp_f32_e32 v92, v92
	v_exp_f32_e32 v93, v93
	v_exp_f32_e32 v94, v94
	v_exp_f32_e32 v95, v95
	s_waitcnt vmcnt(2) lgkmcnt(0)
	s_barrier
	ds_read_b64_tr_b16 v[188:189], v168 offset:40960
	ds_read_b64_tr_b16 v[190:191], v168 offset:41472
	v_add_f32_e32 v48, v96, v97
	v_add_f32_e32 v48, v98, v48
	v_add_f32_e32 v48, v99, v48
	v_add_f32_e32 v48, v100, v48
	v_add_f32_e32 v48, v101, v48
	v_cvt_pk_bf16_f32 v140, v96, v97
	v_cvt_pk_bf16_f32 v141, v98, v99
	s_waitcnt lgkmcnt(9)
	v_mfma_f32_32x32x16_bf16 v[112:127], v[60:63], v[156:159], 0
	ds_read_b64_tr_b16 v[96:97], v168 offset:45056
	ds_read_b64_tr_b16 v[98:99], v168 offset:45568
	v_add_f32_e32 v48, v102, v48
	v_add_f32_e32 v48, v103, v48
	v_add_f32_e32 v48, v104, v48
	v_add_f32_e32 v128, v105, v48
	s_waitcnt lgkmcnt(10)
	v_mfma_f32_32x32x16_bf16 v[48:63], v[64:67], v[156:159], 0
	v_cvt_pk_bf16_f32 v142, v100, v101
	v_cvt_pk_bf16_f32 v143, v102, v103
	ds_read_b64_tr_b16 v[64:65], v168 offset:41984
	ds_read_b64_tr_b16 v[66:67], v168 offset:42496
	v_add_f32_e32 v100, v106, v128
	v_add_f32_e32 v100, v107, v100
	v_add_f32_e32 v100, v108, v100
	v_add_f32_e32 v100, v109, v100
	v_cvt_pk_bf16_f32 v136, v104, v105
	v_cvt_pk_bf16_f32 v137, v106, v107
	s_waitcnt lgkmcnt(11)
	v_mfma_f32_32x32x16_bf16 v[112:127], v[68:71], v[152:155], v[112:127]
	ds_read_b64_tr_b16 v[68:69], v168 offset:46080
	ds_read_b64_tr_b16 v[70:71], v168 offset:46592
	s_waitcnt lgkmcnt(12)
	v_mfma_f32_32x32x16_bf16 v[48:63], v[160:163], v[152:155], v[48:63]
	v_add_f32_e32 v100, v110, v100
	v_add_f32_e32 v100, v111, v100
	v_add_f32_e32 v100, v80, v100
	v_add_f32_e32 v104, v81, v100
	v_cvt_pk_bf16_f32 v138, v108, v109
	v_cvt_pk_bf16_f32 v139, v110, v111
	ds_read_b64_tr_b16 v[100:101], v168 offset:43008
	ds_read_b64_tr_b16 v[102:103], v168 offset:43520
	v_add_f32_e32 v104, v82, v104
	v_add_f32_e32 v104, v83, v104
	v_add_f32_e32 v104, v84, v104
	v_add_f32_e32 v104, v85, v104
	v_cvt_pk_bf16_f32 v132, v80, v81
	v_cvt_pk_bf16_f32 v133, v82, v83
	s_waitcnt lgkmcnt(13)
	v_mfma_f32_32x32x16_bf16 v[112:127], v[72:75], v[148:151], v[112:127]
	ds_read_b64_tr_b16 v[72:73], v168 offset:47104
	ds_read_b64_tr_b16 v[74:75], v168 offset:47616
	s_waitcnt lgkmcnt(14)
	v_mfma_f32_32x32x16_bf16 v[48:63], v[164:167], v[148:151], v[48:63]
	v_add_f32_e32 v80, v86, v104
	v_add_f32_e32 v80, v87, v80
	v_add_f32_e32 v80, v88, v80
	v_add_f32_e32 v104, v89, v80
	v_cvt_pk_bf16_f32 v134, v84, v85
	v_cvt_pk_bf16_f32 v135, v86, v87
	ds_read_b64_tr_b16 v[80:81], v168 offset:44032
	ds_read_b64_tr_b16 v[82:83], v168 offset:44544
	v_add_f32_e32 v84, v90, v104
	v_add_f32_e32 v84, v91, v84
	v_add_f32_e32 v84, v92, v84
	v_add_f32_e32 v84, v93, v84
	v_cvt_pk_bf16_f32 v128, v88, v89
	v_cvt_pk_bf16_f32 v129, v90, v91
	s_waitcnt lgkmcnt(14)
	v_mfma_f32_32x32x16_bf16 v[112:127], v[76:79], v[144:147], v[112:127]
	ds_read_b64_tr_b16 v[76:77], v168 offset:48128
	ds_read_b64_tr_b16 v[78:79], v168 offset:48640
	v_mfma_f32_32x32x16_bf16 v[48:63], v[184:187], v[144:147], v[48:63]
	v_add_f32_e32 v84, v94, v84
	v_add_f32_e32 v84, v95, v84
	v_add_f32_e32 v84, 0, v84
	v_cvt_pk_bf16_f32 v130, v92, v93
	v_cvt_pk_bf16_f32 v131, v94, v95
	s_nop 0
	v_add_f32_e32 v175, v175, v84
	v_lshl_add_u64 v[84:85], v[172:173], 0, s[44:45]
	s_mov_b32 s29, m0
	s_mov_b32 m0, s17
	s_nop 0
	global_load_lds_dwordx4 v[84:85], off
	s_mov_b32 m0, s29
	v_lshl_add_u64 v[84:85], v[170:171], 0, s[48:49]
	s_add_i32 s17, s28, 0x8000
	s_mov_b32 s29, m0
	s_mov_b32 m0, s17
	s_nop 0
	global_load_lds_dwordx4 v[84:85], off
	s_mov_b32 m0, s29
	s_waitcnt lgkmcnt(14)
	v_mfma_f32_32x32x16_bf16 v[16:31], v[140:143], v[188:191], v[16:31]
	v_exp_f32_e32 v112, v112
	v_exp_f32_e32 v113, v113
	v_exp_f32_e32 v114, v114
	v_exp_f32_e32 v115, v115
	s_waitcnt lgkmcnt(12)
	v_mfma_f32_32x32x16_bf16 v[32:47], v[140:143], v[96:99], v[32:47]
	v_exp_f32_e32 v116, v116
	v_exp_f32_e32 v117, v117
	v_exp_f32_e32 v118, v118
	v_exp_f32_e32 v119, v119
	ds_read_b128 v[84:87], v234 offset:8192
	ds_read_b128 v[96:99], v234 offset:12288
	s_waitcnt lgkmcnt(12)
;   #define RESC() do{ if(!NOMAX&&resc){ asm volatile("s_waitcnt lgkmcnt(0)":::"memory"); \
;       _Pragma("unroll") for(int d_=0;d_<2*VM;++d_) _Pragma("unroll") for(int r=0;r<16;++r)o[d_][r]*=wsf[crow(r,hi)]; } }while(0)
;   #define ROT() do{sl_prev=sl_cur;sl_cur=sl_next;sl_next=(sl_next==(NSLOT-1)*SLOTB)?0:sl_next+SLOTB;}while(0)
;   #define ENDW(tt) do{ if((tt)+3<NT){ if constexpr(VM==2){WAIT_BAR(3);}else{WAIT_BAR(2);} } else if((tt)+2<NT){ if constexpr(VM==2){WAIT_BAR(2);}else{WAIT_BAR(1);} } else {WAIT_BAR(0);} }while(0)
; template<int THRL,int VM,bool NOMAX> __device__ __forceinline__ void attn_unit(const bf16*Qb,const bf16*__restrict__ Kh,const bf16*__restrict__ Vh,bf16*Ob,const int NT,const int sp,float*wscr,char*shm){
;     ...
;     STEP(pB0,pB1,pA0,pA1,t,(t+3<NT),(t+1<NT),(t+1<NT));       ENDW(t);   RESC(); ROT();
;     STEP(pA0,pA1,pB0,pB1,t+1,(t+4<NT),(t+2<NT),(t+2<NT));     ENDW(t+1); RESC(); ROT();
	v_mfma_f32_32x32x16_bf16 v[16:31], v[136:139], v[64:67], v[16:31]
	v_exp_f32_e32 v120, v120
	v_exp_f32_e32 v121, v121
	v_exp_f32_e32 v122, v122
	v_exp_f32_e32 v123, v123
	ds_read_b128 v[104:107], v235 offset:8192
	ds_read_b128 v[108:111], v235 offset:12288
	s_waitcnt lgkmcnt(12)
	v_mfma_f32_32x32x16_bf16 v[32:47], v[136:139], v[68:71], v[32:47]
	v_exp_f32_e32 v124, v124
	v_exp_f32_e32 v125, v125
	v_exp_f32_e32 v126, v126
	v_exp_f32_e32 v127, v127
	ds_read_b128 v[160:163], v236 offset:8192
	ds_read_b128 v[164:167], v236 offset:12288
	s_waitcnt lgkmcnt(12)
	v_mfma_f32_32x32x16_bf16 v[16:31], v[132:135], v[100:103], v[16:31]
	v_exp_f32_e32 v48, v48
	v_exp_f32_e32 v49, v49
	v_exp_f32_e32 v50, v50
	v_exp_f32_e32 v51, v51
	ds_read_b128 v[100:103], v237 offset:8192
	ds_read_b128 v[184:187], v237 offset:12288
	s_waitcnt lgkmcnt(12)
	v_mfma_f32_32x32x16_bf16 v[32:47], v[132:135], v[72:75], v[32:47]
	v_exp_f32_e32 v52, v52
	v_exp_f32_e32 v53, v53
	v_exp_f32_e32 v54, v54
	v_exp_f32_e32 v55, v55
	s_waitcnt lgkmcnt(10)
	v_mfma_f32_32x32x16_bf16 v[16:31], v[128:131], v[80:83], v[16:31]
	v_exp_f32_e32 v56, v56
	v_exp_f32_e32 v57, v57
	v_exp_f32_e32 v58, v58
	v_exp_f32_e32 v59, v59
	s_waitcnt lgkmcnt(8)
	v_mfma_f32_32x32x16_bf16 v[32:47], v[128:131], v[76:79], v[32:47]
	v_exp_f32_e32 v60, v60
	v_exp_f32_e32 v61, v61
	v_exp_f32_e32 v62, v62
	v_exp_f32_e32 v63, v63
	s_waitcnt vmcnt(2) lgkmcnt(0)
	s_barrier
	ds_read_b64_tr_b16 v[188:189], v168 offset:24576
	ds_read_b64_tr_b16 v[190:191], v168 offset:25088
	v_add_f32_e32 v64, v112, v113
	v_add_f32_e32 v64, v114, v64
	v_add_f32_e32 v64, v115, v64
	v_add_f32_e32 v64, v116, v64
	v_add_f32_e32 v64, v117, v64
	v_cvt_pk_bf16_f32 v140, v112, v113
	v_cvt_pk_bf16_f32 v141, v114, v115
	s_waitcnt lgkmcnt(9)
	v_mfma_f32_32x32x16_bf16 v[80:95], v[84:87], v[156:159], 0
	ds_read_b64_tr_b16 v[112:113], v168 offset:28672
	ds_read_b64_tr_b16 v[114:115], v168 offset:29184
	v_add_f32_e32 v64, v118, v64
	v_add_f32_e32 v64, v119, v64
	v_add_f32_e32 v64, v120, v64
	v_add_f32_e32 v128, v121, v64
	v_cvt_pk_bf16_f32 v142, v116, v117
	v_cvt_pk_bf16_f32 v143, v118, v119
	s_waitcnt lgkmcnt(10)
	v_mfma_f32_32x32x16_bf16 v[64:79], v[96:99], v[156:159], 0
	ds_read_b64_tr_b16 v[96:97], v168 offset:25600
	ds_read_b64_tr_b16 v[98:99], v168 offset:26112
	v_add_f32_e32 v116, v122, v128
	v_add_f32_e32 v116, v123, v116
	v_add_f32_e32 v116, v124, v116
	v_add_f32_e32 v116, v125, v116
	v_cvt_pk_bf16_f32 v136, v120, v121
	v_cvt_pk_bf16_f32 v137, v122, v123
	s_waitcnt lgkmcnt(11)
	v_mfma_f32_32x32x16_bf16 v[80:95], v[104:107], v[152:155], v[80:95]
	ds_read_b64_tr_b16 v[104:105], v168 offset:29696
	ds_read_b64_tr_b16 v[106:107], v168 offset:30208
	v_add_f32_e32 v116, v126, v116
	v_add_f32_e32 v116, v127, v116
	v_add_f32_e32 v116, v48, v116
	v_add_f32_e32 v116, v49, v116
	v_cvt_pk_bf16_f32 v138, v124, v125
	v_cvt_pk_bf16_f32 v139, v126, v127
	s_waitcnt lgkmcnt(12)
	v_mfma_f32_32x32x16_bf16 v[64:79], v[108:111], v[152:155], v[64:79]
	ds_read_b64_tr_b16 v[108:109], v168 offset:26624
	ds_read_b64_tr_b16 v[110:111], v168 offset:27136
	v_add_f32_e32 v116, v50, v116
	v_add_f32_e32 v116, v51, v116
	v_add_f32_e32 v116, v52, v116
	v_add_f32_e32 v116, v53, v116
	v_cvt_pk_bf16_f32 v132, v48, v49
	v_cvt_pk_bf16_f32 v133, v50, v51
	s_waitcnt lgkmcnt(13)
	v_mfma_f32_32x32x16_bf16 v[80:95], v[160:163], v[148:151], v[80:95]
	ds_read_b64_tr_b16 v[48:49], v168 offset:30720
	ds_read_b64_tr_b16 v[50:51], v168 offset:31232
	v_add_f32_e32 v116, v54, v116
	v_add_f32_e32 v116, v55, v116
	v_add_f32_e32 v116, v56, v116
	v_add_f32_e32 v116, v57, v116
	v_cvt_pk_bf16_f32 v134, v52, v53
	v_cvt_pk_bf16_f32 v135, v54, v55
	s_waitcnt lgkmcnt(14)
	v_mfma_f32_32x32x16_bf16 v[64:79], v[164:167], v[148:151], v[64:79]
	ds_read_b64_tr_b16 v[52:53], v168 offset:27648
	ds_read_b64_tr_b16 v[54:55], v168 offset:28160
	v_add_f32_e32 v116, v58, v116
	v_add_f32_e32 v116, v59, v116
	v_add_f32_e32 v116, v60, v116
	v_add_f32_e32 v116, v61, v116
	v_cvt_pk_bf16_f32 v128, v56, v57
	v_cvt_pk_bf16_f32 v129, v58, v59
	s_waitcnt lgkmcnt(14)
	v_mfma_f32_32x32x16_bf16 v[80:95], v[100:103], v[144:147], v[80:95]
	ds_read_b64_tr_b16 v[56:57], v168 offset:31744
	ds_read_b64_tr_b16 v[58:59], v168 offset:32256
	v_add_f32_e32 v100, v62, v116
	v_add_f32_e32 v100, v63, v100
	v_add_f32_e32 v100, 0, v100
	v_cvt_pk_bf16_f32 v130, v60, v61
	v_cvt_pk_bf16_f32 v131, v62, v63
	v_mfma_f32_32x32x16_bf16 v[64:79], v[184:187], v[144:147], v[64:79]
	v_lshl_add_u64 v[60:61], v[170:171], 0, s[40:41]
	s_add_i32 s28, s28, 0xa000
	s_mov_b32 s17, m0
	s_mov_b32 m0, s28
	s_nop 0
	global_load_lds_dwordx4 v[60:61], off
	s_mov_b32 m0, s17
	v_add_f32_e32 v172, v175, v100
	s_waitcnt lgkmcnt(14)
	v_mfma_f32_32x32x16_bf16 v[16:31], v[140:143], v[188:191], v[16:31]
	v_exp_f32_e32 v80, v80
	v_exp_f32_e32 v81, v81
	v_exp_f32_e32 v82, v82
	v_exp_f32_e32 v83, v83
	s_waitcnt lgkmcnt(12)
	v_mfma_f32_32x32x16_bf16 v[32:47], v[140:143], v[112:115], v[32:47]
	v_exp_f32_e32 v84, v84
	v_exp_f32_e32 v85, v85
	v_exp_f32_e32 v86, v86
	v_exp_f32_e32 v87, v87
	ds_read_b128 v[60:63], v234 offset:16384
	ds_read_b128 v[112:115], v234 offset:20480
	s_waitcnt lgkmcnt(12)
	v_mfma_f32_32x32x16_bf16 v[16:31], v[136:139], v[96:99], v[16:31]
	v_exp_f32_e32 v88, v88
	v_exp_f32_e32 v89, v89
	v_exp_f32_e32 v90, v90
	v_exp_f32_e32 v91, v91
	ds_read_b128 v[116:119], v235 offset:16384
	ds_read_b128 v[120:123], v235 offset:20480
	s_waitcnt lgkmcnt(12)
	v_mfma_f32_32x32x16_bf16 v[32:47], v[136:139], v[104:107], v[32:47]
	v_exp_f32_e32 v92, v92
	v_exp_f32_e32 v93, v93
	v_exp_f32_e32 v94, v94
	v_exp_f32_e32 v95, v95
	ds_read_b128 v[124:127], v236 offset:16384
	ds_read_b128 v[160:163], v236 offset:20480
	s_waitcnt lgkmcnt(12)
	v_mfma_f32_32x32x16_bf16 v[16:31], v[132:135], v[108:111], v[16:31]
	v_exp_f32_e32 v64, v64
	v_exp_f32_e32 v65, v65
	v_exp_f32_e32 v66, v66
	v_exp_f32_e32 v67, v67
	ds_read_b128 v[164:167], v237 offset:16384
	ds_read_b128 v[184:187], v237 offset:20480
	s_waitcnt lgkmcnt(12)
	v_mfma_f32_32x32x16_bf16 v[32:47], v[132:135], v[48:51], v[32:47]
	v_exp_f32_e32 v68, v68
	v_exp_f32_e32 v69, v69
	v_exp_f32_e32 v70, v70
	v_exp_f32_e32 v71, v71
	s_waitcnt lgkmcnt(10)
	v_mfma_f32_32x32x16_bf16 v[16:31], v[128:131], v[52:55], v[16:31]
	v_exp_f32_e32 v72, v72
	v_exp_f32_e32 v73, v73
	v_exp_f32_e32 v74, v74
	v_exp_f32_e32 v75, v75
	s_waitcnt lgkmcnt(8)
	v_mfma_f32_32x32x16_bf16 v[32:47], v[128:131], v[56:59], v[32:47]
	v_exp_f32_e32 v76, v76
	v_exp_f32_e32 v77, v77
	v_exp_f32_e32 v78, v78
	v_exp_f32_e32 v79, v79
	s_waitcnt vmcnt(1) lgkmcnt(0)
	s_barrier
;   #define RESC() do{ if(!NOMAX&&resc){ asm volatile("s_waitcnt lgkmcnt(0)":::"memory"); \
;       _Pragma("unroll") for(int d_=0;d_<2*VM;++d_) _Pragma("unroll") for(int r=0;r<16;++r)o[d_][r]*=wsf[crow(r,hi)]; } }while(0)
;   #define ROT() do{sl_prev=sl_cur;sl_cur=sl_next;sl_next=(sl_next==(NSLOT-1)*SLOTB)?0:sl_next+SLOTB;}while(0)
;   #define ENDW(tt) do{ if((tt)+3<NT){ if constexpr(VM==2){WAIT_BAR(3);}else{WAIT_BAR(2);} } else if((tt)+2<NT){ if constexpr(VM==2){WAIT_BAR(2);}else{WAIT_BAR(1);} } else {WAIT_BAR(0);} }while(0)
; template<int THRL,int VM,bool NOMAX> __device__ __forceinline__ void attn_unit(const bf16*Qb,const bf16*__restrict__ Kh,const bf16*__restrict__ Vh,bf16*Ob,const int NT,const int sp,float*wscr,char*shm){
;     ...
;     STEP(pB0,pB1,pA0,pA1,t,(t+3<NT),(t+1<NT),(t+1<NT));       ENDW(t);   RESC(); ROT();
;     STEP(pA0,pA1,pB0,pB1,t+1,(t+4<NT),(t+2<NT),(t+2<NT));     ENDW(t+1); RESC(); ROT();
	ds_read_b64_tr_b16 v[188:189], v168 offset:32768
	ds_read_b64_tr_b16 v[190:191], v168 offset:33280
	v_add_f32_e32 v48, v80, v81
	v_add_f32_e32 v48, v82, v48
	v_add_f32_e32 v48, v83, v48
	v_add_f32_e32 v48, v84, v48
	v_add_f32_e32 v48, v85, v48
	v_cvt_pk_bf16_f32 v140, v80, v81
	v_cvt_pk_bf16_f32 v141, v82, v83
	s_waitcnt lgkmcnt(9)
	v_mfma_f32_32x32x16_bf16 v[96:111], v[60:63], v[156:159], 0
	ds_read_b64_tr_b16 v[80:81], v168 offset:36864
	ds_read_b64_tr_b16 v[82:83], v168 offset:37376
	v_add_f32_e32 v48, v86, v48
	v_add_f32_e32 v48, v87, v48
	v_add_f32_e32 v48, v88, v48
	v_add_f32_e32 v128, v89, v48
	s_waitcnt lgkmcnt(10)
	v_mfma_f32_32x32x16_bf16 v[48:63], v[112:115], v[156:159], 0
	v_cvt_pk_bf16_f32 v142, v84, v85
	v_cvt_pk_bf16_f32 v143, v86, v87
	ds_read_b64_tr_b16 v[84:85], v168 offset:33792
	ds_read_b64_tr_b16 v[86:87], v168 offset:34304
	v_add_f32_e32 v112, v90, v128
	v_add_f32_e32 v112, v91, v112
	v_add_f32_e32 v112, v92, v112
	v_add_f32_e32 v112, v93, v112
	v_cvt_pk_bf16_f32 v136, v88, v89
	v_cvt_pk_bf16_f32 v137, v90, v91
	s_waitcnt lgkmcnt(11)
	v_mfma_f32_32x32x16_bf16 v[96:111], v[116:119], v[152:155], v[96:111]
	ds_read_b64_tr_b16 v[88:89], v168 offset:37888
	ds_read_b64_tr_b16 v[90:91], v168 offset:38400
	s_waitcnt lgkmcnt(12)
	v_mfma_f32_32x32x16_bf16 v[48:63], v[120:123], v[152:155], v[48:63]
	v_add_f32_e32 v112, v94, v112
	v_add_f32_e32 v112, v95, v112
	v_add_f32_e32 v112, v64, v112
	v_add_f32_e32 v112, v65, v112
	v_cvt_pk_bf16_f32 v138, v92, v93
	v_cvt_pk_bf16_f32 v139, v94, v95
	ds_read_b64_tr_b16 v[92:93], v168 offset:34816
	ds_read_b64_tr_b16 v[94:95], v168 offset:35328
	v_add_f32_e32 v112, v66, v112
	v_add_f32_e32 v112, v67, v112
	v_add_f32_e32 v112, v68, v112
	v_add_f32_e32 v112, v69, v112
	v_cvt_pk_bf16_f32 v132, v64, v65
	v_cvt_pk_bf16_f32 v133, v66, v67
	s_waitcnt lgkmcnt(13)
	v_mfma_f32_32x32x16_bf16 v[96:111], v[124:127], v[148:151], v[96:111]
	ds_read_b64_tr_b16 v[64:65], v168 offset:38912
	ds_read_b64_tr_b16 v[66:67], v168 offset:39424
	s_waitcnt lgkmcnt(14)
	v_mfma_f32_32x32x16_bf16 v[48:63], v[160:163], v[148:151], v[48:63]
	v_add_f32_e32 v112, v70, v112
	v_add_f32_e32 v112, v71, v112
	v_add_f32_e32 v112, v72, v112
	v_add_f32_e32 v112, v73, v112
	v_cvt_pk_bf16_f32 v134, v68, v69
	v_cvt_pk_bf16_f32 v135, v70, v71
	ds_read_b64_tr_b16 v[68:69], v168 offset:35840
	ds_read_b64_tr_b16 v[70:71], v168 offset:36352
	v_add_f32_e32 v112, v74, v112
	v_add_f32_e32 v112, v75, v112
	v_add_f32_e32 v112, v76, v112
	v_add_f32_e32 v112, v77, v112
	v_cvt_pk_bf16_f32 v128, v72, v73
	v_cvt_pk_bf16_f32 v129, v74, v75
	s_waitcnt lgkmcnt(14)
	v_mfma_f32_32x32x16_bf16 v[96:111], v[164:167], v[144:147], v[96:111]
	ds_read_b64_tr_b16 v[72:73], v168 offset:39936
	ds_read_b64_tr_b16 v[74:75], v168 offset:40448
	v_mfma_f32_32x32x16_bf16 v[48:63], v[184:187], v[144:147], v[48:63]
	v_add_f32_e32 v112, v78, v112
	v_add_f32_e32 v112, v79, v112
	v_add_f32_e32 v112, 0, v112
	v_cvt_pk_bf16_f32 v130, v76, v77
	v_cvt_pk_bf16_f32 v131, v78, v79
	v_lshl_add_u64 v[76:77], v[170:171], 0, s[44:45]
	s_mov_b32 s17, m0
	s_mov_b32 m0, s16
	s_nop 0
	global_load_lds_dwordx4 v[76:77], off
	s_mov_b32 m0, s17
	v_add_f32_e32 v120, v172, v112
	s_waitcnt lgkmcnt(14)
	v_mfma_f32_32x32x16_bf16 v[16:31], v[140:143], v[188:191], v[16:31]
	v_exp_f32_e32 v96, v96
	v_exp_f32_e32 v97, v97
	v_exp_f32_e32 v98, v98
	v_exp_f32_e32 v99, v99
	s_waitcnt lgkmcnt(12)
	v_mfma_f32_32x32x16_bf16 v[32:47], v[140:143], v[80:83], v[32:47]
	v_exp_f32_e32 v100, v100
	v_exp_f32_e32 v101, v101
	v_exp_f32_e32 v102, v102
	v_exp_f32_e32 v103, v103
	ds_read_b128 v[76:79], v234
	ds_read_b128 v[80:83], v234 offset:4096
	s_waitcnt lgkmcnt(12)
	v_mfma_f32_32x32x16_bf16 v[16:31], v[136:139], v[84:87], v[16:31]
	v_exp_f32_e32 v104, v104
	v_exp_f32_e32 v105, v105
	v_exp_f32_e32 v106, v106
	v_exp_f32_e32 v107, v107
	ds_read_b128 v[122:125], v235
	ds_read_b128 v[160:163], v235 offset:4096
	s_waitcnt lgkmcnt(12)
	v_mfma_f32_32x32x16_bf16 v[32:47], v[136:139], v[88:91], v[32:47]
	v_exp_f32_e32 v108, v108
	v_exp_f32_e32 v109, v109
	v_exp_f32_e32 v110, v110
	v_exp_f32_e32 v111, v111
	ds_read_b128 v[164:167], v236
	ds_read_b128 v[170:173], v236 offset:4096
	s_waitcnt lgkmcnt(12)
	v_mfma_f32_32x32x16_bf16 v[16:31], v[132:135], v[92:95], v[16:31]
	v_exp_f32_e32 v48, v48
	v_exp_f32_e32 v49, v49
	v_exp_f32_e32 v50, v50
	v_exp_f32_e32 v51, v51
	ds_read_b128 v[184:187], v237
	ds_read_b128 v[188:191], v237 offset:4096
	s_waitcnt lgkmcnt(12)
	v_mfma_f32_32x32x16_bf16 v[32:47], v[132:135], v[64:67], v[32:47]
	v_exp_f32_e32 v52, v52
	v_exp_f32_e32 v53, v53
	v_exp_f32_e32 v54, v54
	v_exp_f32_e32 v55, v55
	s_waitcnt lgkmcnt(10)
	v_mfma_f32_32x32x16_bf16 v[16:31], v[128:131], v[68:71], v[16:31]
	v_exp_f32_e32 v56, v56
	v_exp_f32_e32 v57, v57
	v_exp_f32_e32 v58, v58
	v_exp_f32_e32 v59, v59
	s_waitcnt lgkmcnt(8)
	v_mfma_f32_32x32x16_bf16 v[32:47], v[128:131], v[72:75], v[32:47]
	v_exp_f32_e32 v60, v60
	v_exp_f32_e32 v61, v61
	v_exp_f32_e32 v62, v62
	v_exp_f32_e32 v63, v63
	s_waitcnt vmcnt(0) lgkmcnt(0)
	s_barrier
	ds_read_b64_tr_b16 v[112:113], v168 offset:40960
	ds_read_b64_tr_b16 v[114:115], v168 offset:41472
	v_add_f32_e32 v64, v96, v97
	v_add_f32_e32 v64, v98, v64
	v_add_f32_e32 v64, v99, v64
	v_add_f32_e32 v64, v100, v64
	v_add_f32_e32 v84, v101, v64
	v_cvt_pk_bf16_f32 v140, v96, v97
	v_cvt_pk_bf16_f32 v141, v98, v99
	s_waitcnt lgkmcnt(9)
	v_mfma_f32_32x32x16_bf16 v[64:79], v[76:79], v[156:159], 0
	ds_read_b64_tr_b16 v[96:97], v168 offset:45056
	ds_read_b64_tr_b16 v[98:99], v168 offset:45568
	v_add_f32_e32 v84, v102, v84
	v_add_f32_e32 v84, v103, v84
	v_add_f32_e32 v84, v104, v84
	v_add_f32_e32 v121, v105, v84
	v_cvt_pk_bf16_f32 v142, v100, v101
	v_cvt_pk_bf16_f32 v143, v102, v103
	s_waitcnt lgkmcnt(10)
	v_mfma_f32_32x32x16_bf16 v[80:95], v[80:83], v[156:159], 0
	ds_read_b64_tr_b16 v[116:117], v168 offset:41984
	ds_read_b64_tr_b16 v[118:119], v168 offset:42496
	v_add_f32_e32 v100, v106, v121
	v_add_f32_e32 v100, v107, v100
	v_add_f32_e32 v100, v108, v100
	v_add_f32_e32 v121, v109, v100
	v_cvt_pk_bf16_f32 v136, v104, v105
	v_cvt_pk_bf16_f32 v137, v106, v107
	s_waitcnt lgkmcnt(11)
	v_mfma_f32_32x32x16_bf16 v[64:79], v[122:125], v[152:155], v[64:79]
	ds_read_b64_tr_b16 v[100:101], v168 offset:46080
	ds_read_b64_tr_b16 v[102:103], v168 offset:46592
	v_add_f32_e32 v104, v110, v121
	v_add_f32_e32 v104, v111, v104
	v_add_f32_e32 v104, v48, v104
	v_add_f32_e32 v121, v49, v104
	v_cvt_pk_bf16_f32 v138, v108, v109
	v_cvt_pk_bf16_f32 v139, v110, v111
	s_waitcnt lgkmcnt(12)
	v_mfma_f32_32x32x16_bf16 v[80:95], v[160:163], v[152:155], v[80:95]
	ds_read_b64_tr_b16 v[104:105], v168 offset:43008
	ds_read_b64_tr_b16 v[106:107], v168 offset:43520
	v_add_f32_e32 v108, v50, v121
	v_add_f32_e32 v108, v51, v108
	v_add_f32_e32 v108, v52, v108
	v_add_f32_e32 v108, v53, v108
	v_cvt_pk_bf16_f32 v132, v48, v49
	v_cvt_pk_bf16_f32 v133, v50, v51
	s_waitcnt lgkmcnt(13)
	v_mfma_f32_32x32x16_bf16 v[64:79], v[164:167], v[148:151], v[64:79]
	ds_read_b64_tr_b16 v[48:49], v168 offset:47104
	ds_read_b64_tr_b16 v[50:51], v168 offset:47616
	v_add_f32_e32 v108, v54, v108
	v_add_f32_e32 v108, v55, v108
	v_add_f32_e32 v108, v56, v108
	v_add_f32_e32 v121, v57, v108
	v_cvt_pk_bf16_f32 v134, v52, v53
	v_cvt_pk_bf16_f32 v135, v54, v55
	s_waitcnt lgkmcnt(14)
	v_mfma_f32_32x32x16_bf16 v[80:95], v[170:173], v[148:151], v[80:95]
	ds_read_b64_tr_b16 v[108:109], v168 offset:44032
	ds_read_b64_tr_b16 v[110:111], v168 offset:44544
	v_add_f32_e32 v52, v58, v121
	v_add_f32_e32 v52, v59, v52
	v_add_f32_e32 v52, v60, v52
	v_add_f32_e32 v121, v61, v52
	v_cvt_pk_bf16_f32 v128, v56, v57
	v_cvt_pk_bf16_f32 v129, v58, v59
	s_waitcnt lgkmcnt(14)
	v_mfma_f32_32x32x16_bf16 v[64:79], v[184:187], v[144:147], v[64:79]
	ds_read_b64_tr_b16 v[52:53], v168 offset:48128
	ds_read_b64_tr_b16 v[54:55], v168 offset:48640
	v_add_f32_e32 v56, v62, v121
	v_add_f32_e32 v56, v63, v56
	v_add_f32_e32 v56, 0, v56
	v_cvt_pk_bf16_f32 v130, v60, v61
	v_cvt_pk_bf16_f32 v131, v62, v63
	v_mfma_f32_32x32x16_bf16 v[80:95], v[188:191], v[144:147], v[80:95]
	s_nop 3
	v_exp_f32_e32 v64, v64
	v_exp_f32_e32 v65, v65
	v_exp_f32_e32 v66, v66
	v_exp_f32_e32 v67, v67
	s_nop 0
	v_exp_f32_e32 v68, v68
	v_exp_f32_e32 v69, v69
	v_exp_f32_e32 v70, v70
	v_exp_f32_e32 v71, v71
	s_nop 0
	v_exp_f32_e32 v72, v72
	v_exp_f32_e32 v73, v73
	v_exp_f32_e32 v74, v74
	v_exp_f32_e32 v75, v75
	s_nop 0
	v_exp_f32_e32 v76, v76
	v_exp_f32_e32 v77, v77
	v_exp_f32_e32 v78, v78
	v_exp_f32_e32 v79, v79
	v_exp_f32_e32 v80, v80
	v_exp_f32_e32 v81, v81
	v_exp_f32_e32 v82, v82
	v_exp_f32_e32 v83, v83
	s_nop 0
	v_exp_f32_e32 v84, v84
	v_exp_f32_e32 v85, v85
	v_exp_f32_e32 v86, v86
	v_exp_f32_e32 v87, v87
	s_nop 0
	v_exp_f32_e32 v88, v88
	v_exp_f32_e32 v89, v89
	v_exp_f32_e32 v90, v90
	v_exp_f32_e32 v91, v91
	s_nop 0
	v_exp_f32_e32 v92, v92
	v_exp_f32_e32 v93, v93
	v_exp_f32_e32 v94, v94
	v_exp_f32_e32 v95, v95
	s_waitcnt lgkmcnt(14)
; #define SBAR() __builtin_amdgcn_sched_barrier(0)
;   #define RESC() do{ if(!NOMAX&&resc){ asm volatile("s_waitcnt lgkmcnt(0)":::"memory"); \
;       _Pragma("unroll") for(int d_=0;d_<2*VM;++d_) _Pragma("unroll") for(int r=0;r<16;++r)o[d_][r]*=wsf[crow(r,hi)]; } }while(0)
;   #define PKW(P,B) cvtpk_s(P[B],P[B+1])
; __device__ __forceinline__ void pv(f32x16*o,int vb,bf16x8 pa0,bf16x8 pa1,bf16x8 pa2,bf16x8 pa3){
;   #pragma unroll
;   for(int d0=0;d0<2;++d0){s16x4 lo[4],hi[4];
;     #pragma unroll
;     for(int ks=0;ks<4;++ks){
;       asm volatile("ds_read_b64_tr_b16 %0,%1 offset:%c2":"=&v"(lo[ks]):"v"(vb),"i"(d0*4096+ks*1024):"memory");
;       asm volatile("ds_read_b64_tr_b16 %0,%1 offset:%c2":"=&v"(hi[ks]):"v"(vb),"i"(d0*4096+ks*1024+512):"memory");}
;     asm volatile("s_waitcnt lgkmcnt(0)":::"memory");SBAR();
;     ...
;     o[d0]=__builtin_amdgcn_mfma_f32_32x32x16_bf16(pa0,PK(0),o[d0],0,0,0);
;     o[d0]=__builtin_amdgcn_mfma_f32_32x32x16_bf16(pa1,PK(1),o[d0],0,0,0);
;     o[d0]=__builtin_amdgcn_mfma_f32_32x32x16_bf16(pa2,PK(2),o[d0],0,0,0);
;     o[d0]=__builtin_amdgcn_mfma_f32_32x32x16_bf16(pa3,PK(3),o[d0],0,0,0);
;     ...
;   }
; }
; template<int THRL,int VM,bool NOMAX> __device__ __forceinline__ void attn_unit(const bf16*Qb,const bf16*__restrict__ Kh,const bf16*__restrict__ Vh,bf16*Ob,const int NT,const int sp,float*wscr,char*shm){
;     ...
;   STEP(pB0,pB1,pA0,pA1,NT-1,false,false,false); RESC();
;   { float sacc=pB0[0]+pB0[1]; _Pragma("unroll") for(int r=2;r<16;++r)sacc+=pB0[r]; _Pragma("unroll") for(int r=0;r<16;++r)sacc+=pB1[r]; l_reg+=sacc;
;     pw0=(u32x4){PKW(pB0,0),PKW(pB0,2),PKW(pB0,4),PKW(pB0,6)};pw1=(u32x4){PKW(pB0,8),PKW(pB0,10),PKW(pB0,12),PKW(pB0,14)};pw2=(u32x4){PKW(pB1,0),PKW(pB1,2),PKW(pB1,4),PKW(pB1,6)};pw3=(u32x4){PKW(pB1,8),PKW(pB1,10),PKW(pB1,12),PKW(pB1,14)};
;     SBAR(); pv(o,vb0+VM*sl_cur,PAF(0),PAF(1),PAF(2),PAF(3)); if constexpr(VM==2) pv(o+2,vb0+VM*sl_cur+8192,PAF(0),PAF(1),PAF(2),PAF(3)); }
;     ...
;   {auto rr=__builtin_amdgcn_permlane32_swap(__float_as_uint(l_reg),__float_as_uint(l_reg),false,false);l_reg=__uint_as_float(rr[0])+__uint_as_float(rr[1]);}
;   if(hi==0)wsf[32+r32]=l_reg;asm volatile("s_waitcnt lgkmcnt(0)":::"memory");
	v_mfma_f32_32x32x16_bf16 v[16:31], v[140:143], v[112:115], v[16:31]
	v_add_f32_e32 v57, v64, v65
	v_add_f32_e32 v57, v66, v57
	v_add_f32_e32 v57, v67, v57
	v_add_f32_e32 v57, v68, v57
	v_add_f32_e32 v57, v69, v57
	v_add_f32_e32 v57, v70, v57
	v_add_f32_e32 v57, v71, v57
	s_waitcnt lgkmcnt(12)
	v_mfma_f32_32x32x16_bf16 v[32:47], v[140:143], v[96:99], v[32:47]
	v_add_f32_e32 v57, v72, v57
	v_add_f32_e32 v57, v73, v57
	v_add_f32_e32 v57, v74, v57
	v_add_f32_e32 v57, v75, v57
	v_add_f32_e32 v57, v76, v57
	v_add_f32_e32 v57, v77, v57
	v_add_f32_e32 v57, v78, v57
	s_waitcnt lgkmcnt(10)
	v_mfma_f32_32x32x16_bf16 v[16:31], v[136:139], v[116:119], v[16:31]
	v_add_f32_e32 v57, v79, v57
	v_add_f32_e32 v57, v80, v57
	v_add_f32_e32 v57, v81, v57
	v_add_f32_e32 v57, v82, v57
	v_add_f32_e32 v57, v83, v57
	v_add_f32_e32 v57, v84, v57
	v_add_f32_e32 v57, v85, v57
	s_waitcnt lgkmcnt(8)
	v_mfma_f32_32x32x16_bf16 v[32:47], v[136:139], v[100:103], v[32:47]
	v_add_f32_e32 v57, v86, v57
	v_add_f32_e32 v57, v87, v57
	v_add_f32_e32 v57, v88, v57
	v_add_f32_e32 v57, v89, v57
	v_add_f32_e32 v57, v90, v57
	v_add_f32_e32 v57, v91, v57
	v_add_f32_e32 v57, v92, v57
	s_waitcnt lgkmcnt(6)
	v_mfma_f32_32x32x16_bf16 v[16:31], v[132:135], v[104:107], v[16:31]
	v_add_f32_e32 v57, v93, v57
	v_add_f32_e32 v57, v94, v57
	v_add_f32_e32 v57, v95, v57
	v_add_f32_e32 v56, v120, v56
	v_add_f32_e32 v56, v56, v57
	v_cvt_pk_bf16_f32 v58, v64, v65
	v_cvt_pk_bf16_f32 v59, v66, v67
	s_waitcnt lgkmcnt(4)
	v_mfma_f32_32x32x16_bf16 v[32:47], v[132:135], v[48:51], v[32:47]
	v_cvt_pk_bf16_f32 v48, v80, v81
	v_cvt_pk_bf16_f32 v60, v68, v69
	v_cvt_pk_bf16_f32 v61, v70, v71
	v_cvt_pk_bf16_f32 v62, v72, v73
	v_cvt_pk_bf16_f32 v63, v74, v75
	v_cvt_pk_bf16_f32 v64, v76, v77
	v_cvt_pk_bf16_f32 v65, v78, v79
	s_waitcnt lgkmcnt(2)
	v_mfma_f32_32x32x16_bf16 v[16:31], v[128:131], v[108:111], v[16:31]
	v_cvt_pk_bf16_f32 v49, v82, v83
	v_cvt_pk_bf16_f32 v50, v84, v85
	v_cvt_pk_bf16_f32 v51, v86, v87
	v_cvt_pk_bf16_f32 v66, v88, v89
	v_cvt_pk_bf16_f32 v67, v90, v91
	v_cvt_pk_bf16_f32 v68, v92, v93
	v_cvt_pk_bf16_f32 v69, v94, v95
	s_waitcnt lgkmcnt(0)
	v_mfma_f32_32x32x16_bf16 v[32:47], v[128:131], v[52:55], v[32:47]
	ds_read_b64_tr_b16 v[52:53],v174 offset:0
	ds_read_b64_tr_b16 v[54:55],v174 offset:512
	ds_read_b64_tr_b16 v[70:71],v174 offset:1024
	ds_read_b64_tr_b16 v[72:73],v174 offset:1536
	ds_read_b64_tr_b16 v[74:75],v174 offset:2048
	ds_read_b64_tr_b16 v[76:77],v174 offset:2560
	ds_read_b64_tr_b16 v[78:79],v174 offset:3072
	ds_read_b64_tr_b16 v[80:81],v174 offset:3584
	s_waitcnt lgkmcnt(0)
	s_nop 0
	v_mfma_f32_32x32x16_bf16 v[16:31], v[58:61], v[52:55], v[16:31]
	ds_read_b64_tr_b16 v[52:53],v174 offset:4096
	ds_read_b64_tr_b16 v[54:55],v174 offset:4608
	v_mfma_f32_32x32x16_bf16 v[16:31], v[62:65], v[70:73], v[16:31]
	ds_read_b64_tr_b16 v[70:71],v174 offset:5120
	ds_read_b64_tr_b16 v[72:73],v174 offset:5632
	v_mfma_f32_32x32x16_bf16 v[16:31], v[48:51], v[74:77], v[16:31]
	ds_read_b64_tr_b16 v[74:75],v174 offset:6144
	ds_read_b64_tr_b16 v[76:77],v174 offset:6656
	ds_read_b64_tr_b16 v[82:83],v174 offset:7168
	ds_read_b64_tr_b16 v[84:85],v174 offset:7680
	s_waitcnt lgkmcnt(0)
	v_mfma_f32_32x32x16_bf16 v[16:31], v[66:69], v[78:81], v[16:31]
	v_mfma_f32_32x32x16_bf16 v[32:47], v[58:61], v[52:55], v[32:47]
	v_cmp_gt_u32_e32 vcc, 32, v178
	v_mfma_f32_32x32x16_bf16 v[32:47], v[62:65], v[70:73], v[32:47]
	v_mfma_f32_32x32x16_bf16 v[32:47], v[48:51], v[74:77], v[32:47]
	v_mov_b32_e32 v48, v56
	s_nop 1
	v_permlane32_swap_b32_e32 v56, v48
	v_mfma_f32_32x32x16_bf16 v[32:47], v[66:69], v[82:85], v[32:47]
	s_and_saveexec_b64 s[16:17], vcc
	s_cbranch_execz .LBB0_887
	v_add_f32_e32 v48, v56, v48
	v_lshl_add_u32 v49, v180, 2, s19
	ds_write_b32 v49, v48 offset:49280
	s_branch .LBB0_887
